# two-level barrier on all in-loop sites, barrier scalar loads overlapped with the L2 write-back, 16-byte stores in the layer loop write through (sc0 sc1)
# speedup vs baseline: 1.1124x; 1.0015x over previous
; __device__ __forceinline__ void norm_phase(const float* H, const float* g, bf16_t* HN) {
;     ...
;   for (int row = gw; row < NREAL + 64; row += 2 * nw) {
;     const int row2 = row + nw < NREAL + 64 ? row + nw : row;
;     const float* p = H + (size_t)row * DM + lane * 8; const float* p2 = H + (size_t)row2 * DM + lane * 8; f32x4 v[4], u[4]; float ss = 0.f, ss2 = 0.f;
; #pragma unroll
;     for (int i = 0; i < 4; ++i) { v[i] = *(const f32x4*)(p + 512 * (i >> 1) + 4 * (i & 1)); u[i] = *(const f32x4*)(p2 + 512 * (i >> 1) + 4 * (i & 1)); }
; #pragma unroll
;     for (int i = 0; i < 4; ++i) { ss += v[i][0] * v[i][0] + v[i][1] * v[i][1] + v[i][2] * v[i][2] + v[i][3] * v[i][3]; ss2 += u[i][0] * u[i][0] + u[i][1] * u[i][1] + u[i][2] * u[i][2] + u[i][3] * u[i][3]; }
;     ss = wave_sum(ss); ss2 = wave_sum(ss2); const float rs = rsqrtf(ss * (1.0f / 1024.0f) + 1e-6f), rs2 = rsqrtf(ss2 * (1.0f / 1024.0f) + 1e-6f);
.LBB0_224:
	v_ashrrev_i32_e32 v23, 31, v22
	v_add_u32_e32 v0, s8, v22
	v_lshlrev_b64 v[24:25], 12, v[22:23]
	v_cmp_gt_i32_e32 vcc, s49, v0
	v_lshlrev_b64 v[26:27], 11, v[22:23]
	v_lshl_add_u64 v[38:39], v[18:19], 0, v[24:25]
	v_cndmask_b32_e32 v42, v22, v0, vcc
	v_lshl_add_u64 v[24:25], v[20:21], 0, v[26:27]
	global_load_dwordx4 v[26:29], v[38:39], off
	global_load_dwordx4 v[30:33], v[38:39], off offset:16
	global_load_dwordx4 v[34:37], v[38:39], off offset:2048
	s_nop 0
	global_load_dwordx4 v[38:41], v[38:39], off offset:2064
	v_ashrrev_i32_e32 v43, 31, v42
	v_lshlrev_b64 v[44:45], 12, v[42:43]
	v_lshlrev_b64 v[42:43], 11, v[42:43]
	v_lshl_add_u64 v[54:55], v[18:19], 0, v[44:45]
	v_lshl_add_u64 v[58:59], v[20:21], 0, v[42:43]
	global_load_dwordx4 v[42:45], v[54:55], off
	global_load_dwordx4 v[46:49], v[54:55], off offset:16
	global_load_dwordx4 v[50:53], v[54:55], off offset:2048
	s_nop 0
	global_load_dwordx4 v[54:57], v[54:55], off offset:2064
	v_mov_b32_e32 v60, v210
	v_mov_b32_e32 v61, v210
	v_add_u32_e32 v22, s8, v0
	v_lshlrev_b32_e32 v0, 2, v60
	v_lshlrev_b32_e32 v23, 2, v61
	v_xor_b32_e32 v0, 0x80, v0
	v_xor_b32_e32 v23, 0x80, v23
	v_cmp_lt_i32_e32 vcc, s50, v22
	s_or_b64 s[6:7], vcc, s[6:7]
	s_waitcnt vmcnt(7)
	v_mov_b32_e32 v62, v27
	s_waitcnt vmcnt(6)
	v_mov_b32_e32 v63, v31
	s_waitcnt vmcnt(5)
	v_mov_b32_e32 v70, v35
	s_waitcnt vmcnt(4)
	v_mov_b32_e32 v71, v39
	v_mov_b32_e32 v60, v26
	v_mov_b32_e32 v61, v30
	v_mov_b32_e32 v68, v34
	v_mov_b32_e32 v69, v38
	v_pk_mul_f32 v[62:63], v[62:63], v[62:63]
	v_pk_mul_f32 v[70:71], v[70:71], v[70:71]
	v_pk_fma_f32 v[60:61], v[60:61], v[60:61], v[62:63]
	v_mov_b32_e32 v62, v36
	v_mov_b32_e32 v63, v40
	v_pk_fma_f32 v[68:69], v[68:69], v[68:69], v[70:71]
	v_mov_b32_e32 v64, v28
	v_mov_b32_e32 v65, v32
	v_mov_b32_e32 v70, v37
	v_mov_b32_e32 v71, v41
	v_pk_fma_f32 v[62:63], v[62:63], v[62:63], v[68:69]
	s_waitcnt vmcnt(3)
	v_mov_b32_e32 v68, v43
	s_waitcnt vmcnt(2)
	v_mov_b32_e32 v69, v47
	v_mov_b32_e32 v66, v29
	v_mov_b32_e32 v67, v33
	v_pk_fma_f32 v[60:61], v[64:65], v[64:65], v[60:61]
	v_mov_b32_e32 v64, v42
	v_mov_b32_e32 v65, v46
	v_pk_mul_f32 v[68:69], v[68:69], v[68:69]
	v_pk_fma_f32 v[62:63], v[70:71], v[70:71], v[62:63]
	s_waitcnt vmcnt(1)
	v_mov_b32_e32 v70, v51
	s_waitcnt vmcnt(0)
	v_mov_b32_e32 v71, v55
	v_pk_fma_f32 v[60:61], v[66:67], v[66:67], v[60:61]
	v_mov_b32_e32 v66, v44
	v_mov_b32_e32 v67, v48
	v_pk_fma_f32 v[64:65], v[64:65], v[64:65], v[68:69]
	v_mov_b32_e32 v68, v50
	v_mov_b32_e32 v69, v54
	v_pk_mul_f32 v[70:71], v[70:71], v[70:71]
	v_pk_fma_f32 v[64:65], v[66:67], v[66:67], v[64:65]
	v_pk_fma_f32 v[68:69], v[68:69], v[68:69], v[70:71]
	v_mov_b32_e32 v70, v45
	v_mov_b32_e32 v71, v49
	v_mov_b32_e32 v66, v52
	v_mov_b32_e32 v67, v56
	v_pk_fma_f32 v[66:67], v[66:67], v[66:67], v[68:69]
	v_mov_b32_e32 v68, v53
	v_mov_b32_e32 v69, v57
	v_pk_fma_f32 v[64:65], v[70:71], v[70:71], v[64:65]
	v_mov_b32_e32 v71, v60
	v_pk_fma_f32 v[66:67], v[68:69], v[68:69], v[66:67]
	v_mov_b32_e32 v70, v64
	v_mov_b32_e32 v60, v65
	v_mov_b32_e32 v69, v62
	v_mov_b32_e32 v68, v66
	v_pk_add_f32 v[60:61], v[70:71], v[60:61]
	v_mov_b32_e32 v62, v67
	v_pk_add_f32 v[60:61], v[60:61], v[68:69]
	s_nop 0
	v_pk_add_f32 v[60:61], v[60:61], v[62:63]
	ds_swizzle_b32 v63, v61 offset:swizzle(SWAP,16)
	ds_swizzle_b32 v62, v60 offset:swizzle(SWAP,16)
	s_waitcnt lgkmcnt(0)
	v_pk_add_f32 v[60:61], v[60:61], v[62:63]
	ds_swizzle_b32 v63, v61 offset:swizzle(SWAP,8)
	ds_swizzle_b32 v62, v60 offset:swizzle(SWAP,8)
	s_waitcnt lgkmcnt(0)
	v_pk_add_f32 v[60:61], v[60:61], v[62:63]
	ds_swizzle_b32 v63, v61 offset:swizzle(SWAP,4)
	ds_swizzle_b32 v62, v60 offset:swizzle(SWAP,4)
	s_waitcnt lgkmcnt(0)
	v_pk_add_f32 v[60:61], v[60:61], v[62:63]
	ds_swizzle_b32 v63, v61 offset:swizzle(SWAP,2)
	ds_swizzle_b32 v62, v60 offset:swizzle(SWAP,2)
	s_waitcnt lgkmcnt(0)
	v_pk_add_f32 v[60:61], v[60:61], v[62:63]
	ds_swizzle_b32 v63, v61 offset:swizzle(SWAP,1)
	ds_swizzle_b32 v62, v60 offset:swizzle(SWAP,1)
	s_waitcnt lgkmcnt(0)
	v_pk_add_f32 v[60:61], v[60:61], v[62:63]
	ds_bpermute_b32 v63, v0, v61
	ds_bpermute_b32 v62, v23, v60
	s_waitcnt lgkmcnt(0)
; __device__ __forceinline__ void store8bf(bf16_t* p, f32x4 v0, f32x4 v1) { u32x4 w; w.x = cvt_pk_bf16(v0[0], v0[1]); w.y = cvt_pk_bf16(v0[2], v0[3]); w.z = cvt_pk_bf16(v1[0], v1[1]); w.w = cvt_pk_bf16(v1[2], v1[3]); *(u32x4*)p = w; }
; __device__ __forceinline__ void norm_phase(const float* H, const float* g, bf16_t* HN) {
;     ...
;     ss = wave_sum(ss); ss2 = wave_sum(ss2); const float rs = rsqrtf(ss * (1.0f / 1024.0f) + 1e-6f), rs2 = rsqrtf(ss2 * (1.0f / 1024.0f) + 1e-6f);
;     bf16_t* q = HN + (size_t)row * DM + lane * 8; bf16_t* q2 = HN + (size_t)row2 * DM + lane * 8;
; #pragma unroll
;     for (int i = 0; i < 2; ++i) { store8bf(q + 512 * i, v[2 * i] * rs * gv[2 * i], v[2 * i + 1] * rs * gv[2 * i + 1]); store8bf(q2 + 512 * i, u[2 * i] * rs2 * gv[2 * i], u[2 * i + 1] * rs2 * gv[2 * i + 1]); }
;   }
; __global__ void __launch_bounds__(512) mega(Params P) {
;     ...
;     if (l > 0) { norm_phase(H, P.attn_norm + l * DM, HN); grid.sync(); }
	v_pk_add_f32 v[60:61], v[60:61], v[62:63]
	s_nop 0
	v_pk_fma_f32 v[60:61], v[60:61], s[58:59], v[154:155] op_sel_hi:[1,0,0]
	s_nop 0
	v_mul_f32_e32 v0, 0x4b800000, v61
	v_cmp_gt_f32_e64 s[2:3], s46, v61
	v_mul_f32_e32 v23, 0x4b800000, v60
	v_cmp_gt_f32_e32 vcc, s46, v60
	v_cndmask_b32_e64 v0, v61, v0, s[2:3]
	v_rsq_f32_e32 v0, v0
	v_cndmask_b32_e32 v23, v60, v23, vcc
	v_rsq_f32_e32 v23, v23
	v_mul_f32_e32 v60, 0x45800000, v0
	v_cndmask_b32_e64 v0, v0, v60, s[2:3]
	v_mul_f32_e32 v61, 0x45800000, v23
	v_cndmask_b32_e32 v60, v23, v61, vcc
	v_pk_mul_f32 v[26:27], v[26:27], v[0:1] op_sel_hi:[1,0]
	v_pk_mul_f32 v[28:29], v[28:29], v[0:1] op_sel_hi:[1,0]
	v_pk_mul_f32 v[30:31], v[30:31], v[0:1] op_sel_hi:[1,0]
	v_pk_mul_f32 v[32:33], v[32:33], v[0:1] op_sel_hi:[1,0]
	v_pk_mul_f32 v[42:43], v[42:43], v[60:61] op_sel_hi:[1,0]
	v_pk_mul_f32 v[44:45], v[44:45], v[60:61] op_sel_hi:[1,0]
	v_pk_mul_f32 v[46:47], v[46:47], v[60:61] op_sel_hi:[1,0]
	v_pk_mul_f32 v[48:49], v[48:49], v[60:61] op_sel_hi:[1,0]
	v_pk_mul_f32 v[34:35], v[34:35], v[0:1] op_sel_hi:[1,0]
	v_pk_mul_f32 v[36:37], v[36:37], v[0:1] op_sel_hi:[1,0]
	v_pk_mul_f32 v[38:39], v[38:39], v[0:1] op_sel_hi:[1,0]
	v_pk_mul_f32 v[40:41], v[40:41], v[0:1] op_sel_hi:[1,0]
	v_pk_mul_f32 v[50:51], v[50:51], v[60:61] op_sel_hi:[1,0]
	v_pk_mul_f32 v[52:53], v[52:53], v[60:61] op_sel_hi:[1,0]
	v_pk_mul_f32 v[54:55], v[54:55], v[60:61] op_sel_hi:[1,0]
	v_pk_mul_f32 v[56:57], v[56:57], v[60:61] op_sel_hi:[1,0]
	v_pk_mul_f32 v[28:29], v[8:9], v[28:29]
	v_pk_mul_f32 v[26:27], v[6:7], v[26:27]
	v_pk_mul_f32 v[32:33], v[4:5], v[32:33]
	v_pk_mul_f32 v[30:31], v[2:3], v[30:31]
	v_pk_mul_f32 v[44:45], v[8:9], v[44:45]
	v_pk_mul_f32 v[42:43], v[6:7], v[42:43]
	v_pk_mul_f32 v[48:49], v[4:5], v[48:49]
	v_pk_mul_f32 v[46:47], v[2:3], v[46:47]
	v_pk_mul_f32 v[36:37], v[16:17], v[36:37]
	v_pk_mul_f32 v[34:35], v[14:15], v[34:35]
	v_pk_mul_f32 v[40:41], v[12:13], v[40:41]
	v_pk_mul_f32 v[38:39], v[10:11], v[38:39]
	v_pk_mul_f32 v[52:53], v[16:17], v[52:53]
	v_pk_mul_f32 v[50:51], v[14:15], v[50:51]
	v_pk_mul_f32 v[56:57], v[12:13], v[56:57]
	v_pk_mul_f32 v[54:55], v[10:11], v[54:55]
	v_cvt_pk_bf16_f32 v26, v26, v27
	v_cvt_pk_bf16_f32 v27, v28, v29
	v_cvt_pk_bf16_f32 v28, v30, v31
	v_cvt_pk_bf16_f32 v29, v32, v33
	v_cvt_pk_bf16_f32 v30, v42, v43
	v_cvt_pk_bf16_f32 v31, v44, v45
	v_cvt_pk_bf16_f32 v32, v46, v47
	v_cvt_pk_bf16_f32 v33, v48, v49
	v_cvt_pk_bf16_f32 v34, v34, v35
	v_cvt_pk_bf16_f32 v35, v36, v37
	v_cvt_pk_bf16_f32 v36, v38, v39
	v_cvt_pk_bf16_f32 v37, v40, v41
	v_cvt_pk_bf16_f32 v38, v50, v51
	v_cvt_pk_bf16_f32 v39, v52, v53
	v_cvt_pk_bf16_f32 v40, v54, v55
	v_cvt_pk_bf16_f32 v41, v56, v57
	global_store_dwordx4 v[24:25], v[26:29], off sc0 sc1
	global_store_dwordx4 v[58:59], v[30:33], off sc0 sc1
	global_store_dwordx4 v[24:25], v[34:37], off offset:1024 sc0 sc1
	global_store_dwordx4 v[58:59], v[38:41], off offset:1024 sc0 sc1
	s_andn2_b64 exec, exec, s[6:7]
	s_cbranch_execnz .LBB0_224
.LBB0_225:
	s_or_b64 exec, exec, s[4:5]
	s_barrier
	s_mov_b64 s[2:3], exec
	v_readlane_b32 s0, v253, 57
	v_readlane_b32 s1, v253, 58
	s_and_b64 s[0:1], s[2:3], s[0:1]
	s_mov_b64 exec, s[0:1]
	s_cbranch_execz .LBB0_235
	buffer_wbl2 sc1
	s_load_dwordx2 s[4:5], s[56:57], -0x8
	s_load_dword s0, s[56:57], 0x0
	v_readlane_b32 s1, v253, 55
	s_waitcnt lgkmcnt(0)
	s_and_b32 s1, s1, 7
	s_add_i32 s6, s0, 7
	s_sub_i32 s6, s6, s1
	s_lshr_b32 s6, s6, 3
	s_min_u32 s7, s0, 8
	s_lshl_b32 s1, s1, 2
	s_addk_i32 s1, 0x88
	v_mov_b32_e32 v2, s1
	global_load_dword v0, v1, s[4:5] sc1
	v_mov_b32_e32 v3, 1
	s_waitcnt vmcnt(0)
	v_and_b32_e32 v0, 0xffff0000, v0
	global_atomic_add v3, v2, v3, s[4:5] sc0
	s_waitcnt vmcnt(0)
	v_and_b32_e32 v3, 0xffff, v3
	s_nop 0
	v_readfirstlane_b32 s1, v3
	s_nop 3
	s_add_i32 s0, s6, -1
	s_cmp_lg_u32 s1, s0
	s_cbranch_scc1 .Lgb_poll_0
	s_sub_i32 s1, 0x10000, s6
	v_mov_b32_e32 v3, s1
	global_atomic_add v3, v2, v3, s[4:5] sc0
	s_waitcnt vmcnt(0)
	v_mov_b32_e32 v3, 1
	global_atomic_add v3, v1, v3, s[4:5] sc0
	s_waitcnt vmcnt(0)
	v_and_b32_e32 v3, 0xffff, v3
	s_nop 0
	v_readfirstlane_b32 s1, v3
	s_nop 3
	s_add_i32 s0, s7, -1
	s_cmp_lg_u32 s1, s0
	s_cbranch_scc1 .Lgb_poll_0
	s_sub_i32 s1, 0x10000, s7
	v_mov_b32_e32 v3, s1
	global_atomic_add v1, v3, s[4:5]

; __device__ __forceinline__ void store8bf(bf16_t* p, f32x4 v0, f32x4 v1) { u32x4 w; w.x = cvt_pk_bf16(v0[0], v0[1]); w.y = cvt_pk_bf16(v0[2], v0[3]); w.z = cvt_pk_bf16(v1[0], v1[1]); w.w = cvt_pk_bf16(v1[2], v1[3]); *(u32x4*)p = w; }
;   __device__ __forceinline__ void group(int row, int c32, int fq, f32x4 v0, f32x4 v1) const {
;     ...
;     else if (c32 < 1792) { const int cc = c32 - 1664, g = cc >> 6; store8bf(ks + ((size_t)(b * 2 + g) * E + e) * 64 + (cc & 63) + fq * 8, v0, v1); }
.LBB0_247:
	s_andn2_b64 vcc, exec, s[10:11]
	s_cbranch_vccnz .LBB0_249
	s_add_i32 s7, s6, 0xfffff980
	s_lshr_b32 s7, s7, 6
	v_add_u32_e32 v0, s7, v120
	s_movk_i32 s7, 0x2040
	v_mad_i64_i32 v[124:125], s[10:11], v0, s7, v[26:27]
	v_readlane_b32 s10, v254, 14
	v_lshlrev_b64 v[124:125], 7, v[124:125]
	v_readlane_b32 s11, v254, 15
	s_and_b32 s7, s1, 32
	s_lshl_b32 s90, s7, 1
	v_lshl_add_u64 v[124:125], s[10:11], 0, v[124:125]
	v_lshl_add_u64 v[124:125], v[124:125], 0, s[90:91]
	v_lshlrev_b32_e32 v0, 1, v22
	v_lshl_add_u64 v[128:129], v[124:125], 0, v[0:1]
	v_cvt_pk_bf16_f32 v124, v18, v19
	v_cvt_pk_bf16_f32 v125, v20, v21
	v_cvt_pk_bf16_f32 v126, v56, v57
	v_cvt_pk_bf16_f32 v127, v68, v69
	global_store_dwordx4 v[128:129], v[124:127], off sc0 sc1

; __device__ __forceinline__ void store8bf(bf16_t* p, f32x4 v0, f32x4 v1) { u32x4 w; w.x = cvt_pk_bf16(v0[0], v0[1]); w.y = cvt_pk_bf16(v0[2], v0[3]); w.z = cvt_pk_bf16(v1[0], v1[1]); w.w = cvt_pk_bf16(v1[2], v1[3]); *(u32x4*)p = w; }
;   __device__ __forceinline__ void group(int row, int c32, int fq, f32x4 v0, f32x4 v1) const {
;     ...
;     else if (c32 < 1664) { const int cc = c32 - 1280, h = cc >> 6; store8bf(qs + ((size_t)(b * 6 + h) * E + e) * 64 + (cc & 63) + fq * 8, v0 * QSC_S, v1 * QSC_S); }
.LBB0_250:
	s_andn2_b64 vcc, exec, s[10:11]
	s_cbranch_vccnz .LBB0_252
	s_add_i32 s7, s6, 0xfffffb00
	s_lshr_b32 s7, s7, 6
	v_add_u32_e32 v0, s7, v122
	s_movk_i32 s7, 0x2040
	v_mad_i64_i32 v[124:125], s[10:11], v0, s7, v[26:27]
	v_readlane_b32 s10, v254, 12
	v_lshlrev_b64 v[124:125], 7, v[124:125]
	v_readlane_b32 s11, v254, 13
	s_and_b32 s7, s1, 32
	s_lshl_b32 s90, s7, 1
	v_lshl_add_u64 v[124:125], s[10:11], 0, v[124:125]
	v_lshl_add_u64 v[124:125], v[124:125], 0, s[90:91]
	v_lshlrev_b32_e32 v0, 1, v22
	s_mov_b32 s10, 0x3e38aa3b
	v_lshl_add_u64 v[128:129], v[124:125], 0, v[0:1]
	v_pk_mul_f32 v[126:127], v[20:21], s[10:11] op_sel_hi:[1,0]
	v_pk_mul_f32 v[124:125], v[18:19], s[10:11] op_sel_hi:[1,0]
	v_pk_mul_f32 v[130:131], v[68:69], s[10:11] op_sel_hi:[1,0]
	v_pk_mul_f32 v[132:133], v[56:57], s[10:11] op_sel_hi:[1,0]
	v_cvt_pk_bf16_f32 v124, v124, v125
	v_cvt_pk_bf16_f32 v125, v126, v127
	v_cvt_pk_bf16_f32 v126, v132, v133
	v_cvt_pk_bf16_f32 v127, v130, v131
	global_store_dwordx4 v[128:129], v[124:127], off sc0 sc1

; __device__ __forceinline__ void store8bf(bf16_t* p, f32x4 v0, f32x4 v1) { u32x4 w; w.x = cvt_pk_bf16(v0[0], v0[1]); w.y = cvt_pk_bf16(v0[2], v0[3]); w.z = cvt_pk_bf16(v1[0], v1[1]); w.w = cvt_pk_bf16(v1[2], v1[3]); *(u32x4*)p = w; }
;   __device__ __forceinline__ void group(int row, int c32, int fq, f32x4 v0, f32x4 v1) const {
;     ...
;     else if (c32 < 1024) { const int cc = c32 - 768, h = cc >> 6; store8bf(kd + ((size_t)(b * 4 + h) * E + e) * 64 + (cc & 63) + fq * 8, v0, v1); }
.LBB0_256:
	s_andn2_b64 vcc, exec, s[10:11]
	s_cbranch_vccnz .LBB0_258
	s_add_i32 s7, s6, 0xfffffd00
	s_lshr_b32 s7, s7, 6
	v_add_u32_e32 v0, s7, v123
	s_movk_i32 s7, 0x2040
	v_mad_i64_i32 v[124:125], s[10:11], v0, s7, v[26:27]
	v_readlane_b32 s10, v254, 8
	v_lshlrev_b64 v[124:125], 7, v[124:125]
	v_readlane_b32 s11, v254, 9
	s_and_b32 s7, s1, 32
	s_lshl_b32 s90, s7, 1
	v_lshl_add_u64 v[124:125], s[10:11], 0, v[124:125]
	v_lshl_add_u64 v[124:125], v[124:125], 0, s[90:91]
	v_lshlrev_b32_e32 v0, 1, v22
	v_lshl_add_u64 v[128:129], v[124:125], 0, v[0:1]
	v_cvt_pk_bf16_f32 v124, v18, v19
	v_cvt_pk_bf16_f32 v125, v20, v21
	v_cvt_pk_bf16_f32 v126, v56, v57
	v_cvt_pk_bf16_f32 v127, v68, v69
	global_store_dwordx4 v[128:129], v[124:127], off sc0 sc1

; __device__ __forceinline__ void store8bf(bf16_t* p, f32x4 v0, f32x4 v1) { u32x4 w; w.x = cvt_pk_bf16(v0[0], v0[1]); w.y = cvt_pk_bf16(v0[2], v0[3]); w.z = cvt_pk_bf16(v1[0], v1[1]); w.w = cvt_pk_bf16(v1[2], v1[3]); *(u32x4*)p = w; }
;   __device__ __forceinline__ void group(int row, int c32, int fq, f32x4 v0, f32x4 v1) const {
;     ...
;     if (c32 < 768) { const int cc = c32 - 512, h = cc >> 6; store8bf(qd + ((size_t)(b * 4 + h) * E + e) * 64 + (cc & 63) + fq * 8, v0 * QSC_D, v1 * QSC_D); }
.LBB0_259:
	s_andn2_b64 vcc, exec, s[10:11]
	s_cbranch_vccnz .LBB0_261
	s_add_i32 s7, s6, 0xfffffe00
	s_lshr_b32 s7, s7, 6
	v_add_u32_e32 v0, s7, v123
	s_movk_i32 s7, 0x2040
	v_mad_i64_i32 v[124:125], s[10:11], v0, s7, v[26:27]
	v_readlane_b32 s10, v254, 6
	v_lshlrev_b64 v[124:125], 7, v[124:125]
	v_readlane_b32 s11, v254, 7
	s_and_b32 s7, s1, 32
	s_lshl_b32 s90, s7, 1
	v_lshl_add_u64 v[124:125], s[10:11], 0, v[124:125]
	v_lshl_add_u64 v[124:125], v[124:125], 0, s[90:91]
	v_lshlrev_b32_e32 v0, 1, v22
	s_mov_b32 s10, 0x3e8293ee
	v_lshl_add_u64 v[128:129], v[124:125], 0, v[0:1]
	v_pk_mul_f32 v[126:127], v[20:21], s[10:11] op_sel_hi:[1,0]
	v_pk_mul_f32 v[124:125], v[18:19], s[10:11] op_sel_hi:[1,0]
	v_pk_mul_f32 v[130:131], v[68:69], s[10:11] op_sel_hi:[1,0]
	v_pk_mul_f32 v[132:133], v[56:57], s[10:11] op_sel_hi:[1,0]
	v_cvt_pk_bf16_f32 v124, v124, v125
	v_cvt_pk_bf16_f32 v125, v126, v127
	v_cvt_pk_bf16_f32 v126, v132, v133
	v_cvt_pk_bf16_f32 v127, v130, v131
	global_store_dwordx4 v[128:129], v[124:127], off sc0 sc1

; __device__ __forceinline__ void store8bf(bf16_t* p, f32x4 v0, f32x4 v1) { u32x4 w; w.x = cvt_pk_bf16(v0[0], v0[1]); w.y = cvt_pk_bf16(v0[2], v0[3]); w.z = cvt_pk_bf16(v1[0], v1[1]); w.w = cvt_pk_bf16(v1[2], v1[3]); *(u32x4*)p = w; }
;   __device__ __forceinline__ void group(int row, int c32, int fq, f32x4 v0, f32x4 v1) const {
;     ...
;       if (c32 < 384) store8bf(cqkv + (size_t)row * 512 + c32 + fq * 8, v0, v1);
.LBB0_265:
	s_andn2_b64 vcc, exec, s[10:11]
	s_cbranch_vccnz .LBB0_267
	s_ashr_i32 s7, s6, 31
	v_lshl_add_u64 v[56:57], s[6:7], 1, v[34:35]
	global_store_dwordx4 v[56:57], v[18:21], off sc0 sc1

; __device__ __forceinline__ void store8bf(bf16_t* p, f32x4 v0, f32x4 v1) { u32x4 w; w.x = cvt_pk_bf16(v0[0], v0[1]); w.y = cvt_pk_bf16(v0[2], v0[3]); w.z = cvt_pk_bf16(v1[0], v1[1]); w.w = cvt_pk_bf16(v1[2], v1[3]); *(u32x4*)p = w; }
;   __device__ __forceinline__ void group(int row, int c32, int fq, f32x4 v0, f32x4 v1) const {
;     ...
;     else if (c32 < 1792) { const int cc = c32 - 1664, g = cc >> 6; store8bf(ks + ((size_t)(b * 2 + g) * E + e) * 64 + (cc & 63) + fq * 8, v0, v1); }
.LBB0_276:
	s_andn2_b64 vcc, exec, s[10:11]
	s_cbranch_vccnz .LBB0_278
	s_add_i32 s7, s6, 0xfffffa00
	s_lshr_b32 s7, s7, 6
	v_add_u32_e32 v0, s7, v120
	s_movk_i32 s7, 0x2040
	v_mad_i64_i32 v[58:59], s[10:11], v0, s7, v[26:27]
	v_readlane_b32 s10, v254, 14
	v_lshlrev_b64 v[58:59], 7, v[58:59]
	v_readlane_b32 s11, v254, 15
	s_and_b32 s7, s1, 32
	s_lshl_b32 s90, s7, 1
	v_lshl_add_u64 v[58:59], s[10:11], 0, v[58:59]
	v_lshl_add_u64 v[58:59], v[58:59], 0, s[90:91]
	v_lshlrev_b32_e32 v0, 1, v22
	v_lshl_add_u64 v[62:63], v[58:59], 0, v[0:1]
	v_cvt_pk_bf16_f32 v58, v52, v55
	v_cvt_pk_bf16_f32 v59, v50, v57
	v_cvt_pk_bf16_f32 v60, v54, v53
	v_cvt_pk_bf16_f32 v61, v56, v51
	global_store_dwordx4 v[62:63], v[58:61], off sc0 sc1

; __device__ __forceinline__ void store8bf(bf16_t* p, f32x4 v0, f32x4 v1) { u32x4 w; w.x = cvt_pk_bf16(v0[0], v0[1]); w.y = cvt_pk_bf16(v0[2], v0[3]); w.z = cvt_pk_bf16(v1[0], v1[1]); w.w = cvt_pk_bf16(v1[2], v1[3]); *(u32x4*)p = w; }
;   __device__ __forceinline__ void group(int row, int c32, int fq, f32x4 v0, f32x4 v1) const {
;     ...
;     else if (c32 < 1664) { const int cc = c32 - 1280, h = cc >> 6; store8bf(qs + ((size_t)(b * 6 + h) * E + e) * 64 + (cc & 63) + fq * 8, v0 * QSC_S, v1 * QSC_S); }
.LBB0_279:
	s_andn2_b64 vcc, exec, s[10:11]
	s_cbranch_vccnz .LBB0_281
	s_add_i32 s7, s6, 0xfffffb80
	s_lshr_b32 s7, s7, 6
	v_add_u32_e32 v0, s7, v122
	s_movk_i32 s7, 0x2040
	v_mad_i64_i32 v[58:59], s[10:11], v0, s7, v[26:27]
	v_readlane_b32 s10, v254, 12
	v_lshlrev_b64 v[58:59], 7, v[58:59]
	v_readlane_b32 s11, v254, 13
	s_and_b32 s7, s1, 32
	s_lshl_b32 s90, s7, 1
	v_lshl_add_u64 v[58:59], s[10:11], 0, v[58:59]
	v_lshl_add_u64 v[58:59], v[58:59], 0, s[90:91]
	v_lshlrev_b32_e32 v0, 1, v22
	v_lshl_add_u64 v[62:63], v[58:59], 0, v[0:1]
	v_mov_b32_e32 v58, v50
	v_mov_b32_e32 v59, v57
	s_mov_b32 s10, 0x3e38aa3b
	v_mov_b32_e32 v64, v56
	v_mov_b32_e32 v65, v51
	v_pk_mul_f32 v[60:61], v[58:59], s[10:11] op_sel_hi:[1,0]
	v_pk_mul_f32 v[58:59], v[20:21], s[10:11] op_sel_hi:[1,0]
	v_pk_mul_f32 v[64:65], v[64:65], s[10:11] op_sel_hi:[1,0]
	v_pk_mul_f32 v[66:67], v[18:19], s[10:11] op_sel_hi:[1,0]
	v_cvt_pk_bf16_f32 v58, v58, v59
	v_cvt_pk_bf16_f32 v59, v60, v61
	v_cvt_pk_bf16_f32 v60, v66, v67
	v_cvt_pk_bf16_f32 v61, v64, v65
	global_store_dwordx4 v[62:63], v[58:61], off sc0 sc1

; __device__ __forceinline__ void store8bf(bf16_t* p, f32x4 v0, f32x4 v1) { u32x4 w; w.x = cvt_pk_bf16(v0[0], v0[1]); w.y = cvt_pk_bf16(v0[2], v0[3]); w.z = cvt_pk_bf16(v1[0], v1[1]); w.w = cvt_pk_bf16(v1[2], v1[3]); *(u32x4*)p = w; }
;   __device__ __forceinline__ void group(int row, int c32, int fq, f32x4 v0, f32x4 v1) const {
;     ...
;     else if (c32 < 1024) { const int cc = c32 - 768, h = cc >> 6; store8bf(kd + ((size_t)(b * 4 + h) * E + e) * 64 + (cc & 63) + fq * 8, v0, v1); }
.LBB0_285:
	s_andn2_b64 vcc, exec, s[10:11]
	s_cbranch_vccnz .LBB0_287
	s_add_i32 s7, s6, 0xfffffd80
	s_lshr_b32 s7, s7, 6
	v_add_u32_e32 v0, s7, v123
	s_movk_i32 s7, 0x2040
	v_mad_i64_i32 v[58:59], s[10:11], v0, s7, v[26:27]
	v_readlane_b32 s10, v254, 8
	v_lshlrev_b64 v[58:59], 7, v[58:59]
	v_readlane_b32 s11, v254, 9
	s_and_b32 s7, s1, 32
	s_lshl_b32 s90, s7, 1
	v_lshl_add_u64 v[58:59], s[10:11], 0, v[58:59]
	v_lshl_add_u64 v[58:59], v[58:59], 0, s[90:91]
	v_lshlrev_b32_e32 v0, 1, v22
	v_lshl_add_u64 v[62:63], v[58:59], 0, v[0:1]
	v_cvt_pk_bf16_f32 v58, v52, v55
	v_cvt_pk_bf16_f32 v59, v50, v57
	v_cvt_pk_bf16_f32 v60, v54, v53
	v_cvt_pk_bf16_f32 v61, v56, v51
	global_store_dwordx4 v[62:63], v[58:61], off sc0 sc1

; __device__ __forceinline__ void store8bf(bf16_t* p, f32x4 v0, f32x4 v1) { u32x4 w; w.x = cvt_pk_bf16(v0[0], v0[1]); w.y = cvt_pk_bf16(v0[2], v0[3]); w.z = cvt_pk_bf16(v1[0], v1[1]); w.w = cvt_pk_bf16(v1[2], v1[3]); *(u32x4*)p = w; }
;   __device__ __forceinline__ void group(int row, int c32, int fq, f32x4 v0, f32x4 v1) const {
;     ...
;     if (c32 < 768) { const int cc = c32 - 512, h = cc >> 6; store8bf(qd + ((size_t)(b * 4 + h) * E + e) * 64 + (cc & 63) + fq * 8, v0 * QSC_D, v1 * QSC_D); }
.LBB0_288:
	s_andn2_b64 vcc, exec, s[10:11]
	s_cbranch_vccnz .LBB0_290
	s_add_i32 s7, s6, 0xfffffe80
	s_lshr_b32 s7, s7, 6
	v_add_u32_e32 v0, s7, v123
	s_movk_i32 s7, 0x2040
	v_mad_i64_i32 v[58:59], s[10:11], v0, s7, v[26:27]
	v_readlane_b32 s10, v254, 6
	v_lshlrev_b64 v[58:59], 7, v[58:59]
	v_readlane_b32 s11, v254, 7
	s_and_b32 s7, s1, 32
	s_lshl_b32 s90, s7, 1
	v_lshl_add_u64 v[58:59], s[10:11], 0, v[58:59]
	v_mov_b32_e32 v60, v50
	v_mov_b32_e32 v61, v57
	s_mov_b32 s10, 0x3e8293ee
	v_mov_b32_e32 v62, v56
	v_mov_b32_e32 v63, v51
	v_lshl_add_u64 v[58:59], v[58:59], 0, s[90:91]
	v_lshlrev_b32_e32 v0, 1, v22
	v_pk_mul_f32 v[60:61], v[60:61], s[10:11] op_sel_hi:[1,0]
	v_pk_mul_f32 v[20:21], v[20:21], s[10:11] op_sel_hi:[1,0]
	v_pk_mul_f32 v[62:63], v[62:63], s[10:11] op_sel_hi:[1,0]
	v_pk_mul_f32 v[64:65], v[18:19], s[10:11] op_sel_hi:[1,0]
	v_lshl_add_u64 v[58:59], v[58:59], 0, v[0:1]
	v_cvt_pk_bf16_f32 v18, v20, v21
	v_cvt_pk_bf16_f32 v19, v60, v61
	v_cvt_pk_bf16_f32 v20, v64, v65
	v_cvt_pk_bf16_f32 v21, v62, v63
	global_store_dwordx4 v[58:59], v[18:21], off sc0 sc1

; __device__ __forceinline__ void store8bf(bf16_t* p, f32x4 v0, f32x4 v1) { u32x4 w; w.x = cvt_pk_bf16(v0[0], v0[1]); w.y = cvt_pk_bf16(v0[2], v0[3]); w.z = cvt_pk_bf16(v1[0], v1[1]); w.w = cvt_pk_bf16(v1[2], v1[3]); *(u32x4*)p = w; }
;   __device__ __forceinline__ void operator()(int row, int cb, int fq, f32x4 a, f32x4 b, f32x4 c, f32x4 d) const { group(row, cb, fq, a, b); group(row, cb + 128, fq, c, d); }
;   __device__ __forceinline__ void group(int row, int c32, int fq, f32x4 v0, f32x4 v1) const { e->group(row, c32 + sh, fq, v0, v1); }
;   __device__ __forceinline__ void group(int row, int c32, int fq, f32x4 v0, f32x4 v1) const {
;     ...
;       if (c32 < 384) store8bf(cqkv + (size_t)row * 512 + c32 + fq * 8, v0, v1);
;   __device__ __forceinline__ void operator()(int row, int cb, int fq, f32x4 a, f32x4 b, f32x4 c, f32x4 d) const { group(row, cb, fq, a, b); group(row, cb + 128, fq, c, d); }
.LBB0_296:
	s_ashr_i32 s7, s6, 31
	v_lshl_add_u64 v[60:61], s[6:7], 1, v[34:35]
	global_store_dwordx4 v[60:61], v[18:21], off offset:256 sc0 sc1
	s_cmpk_lg_i32 s6, 0x100
	s_cbranch_scc1 .LBB0_238

; __device__ __forceinline__ void store8bf(bf16_t* p, f32x4 v0, f32x4 v1) { u32x4 w; w.x = cvt_pk_bf16(v0[0], v0[1]); w.y = cvt_pk_bf16(v0[2], v0[3]); w.z = cvt_pk_bf16(v1[0], v1[1]); w.w = cvt_pk_bf16(v1[2], v1[3]); *(u32x4*)p = w; }
;   __device__ __forceinline__ void group(int row, int c32, int fq, f32x4 v0, f32x4 v1) const {
;     ...
;     else if (c32 < 1664) { const int cc = c32 - 1280, h = cc >> 6; store8bf(qs + ((size_t)(b * 6 + h) * E + e) * 64 + (cc & 63) + fq * 8, v0 * QSC_S, v1 * QSC_S); }
.LBB0_322:
	s_andn2_b64 vcc, exec, s[38:39]
	s_cbranch_vccnz .LBB0_324
	v_mad_i32_i24 v134, v133, 6, v149
	v_mov_b32_e32 v131, v1
	s_movk_i32 s1, 0x2040
	v_mad_i64_i32 v[134:135], s[22:23], v134, s1, v[130:131]
	v_readlane_b32 s22, v254, 12
	v_lshlrev_b64 v[134:135], 7, v[134:135]
	v_readlane_b32 s23, v254, 13
	v_lshlrev_b32_e32 v152, 1, v137
	v_mov_b32_e32 v153, v1
	v_lshl_add_u64 v[134:135], s[22:23], 0, v[134:135]
	v_lshl_add_u64 v[134:135], v[134:135], 0, v[152:153]
	v_lshlrev_b32_e32 v152, 1, v139
	s_mov_b32 s22, 0x3e38aa3b
	v_lshl_add_u64 v[134:135], v[134:135], 0, v[152:153]
	v_pk_mul_f32 v[152:153], v[128:129], s[22:23] op_sel_hi:[1,0]
	v_pk_mul_f32 v[158:159], v[126:127], s[22:23] op_sel_hi:[1,0]
	v_pk_mul_f32 v[160:161], v[124:125], s[22:23] op_sel_hi:[1,0]
	v_pk_mul_f32 v[162:163], v[122:123], s[22:23] op_sel_hi:[1,0]
	v_cvt_pk_bf16_f32 v166, v158, v159
	v_cvt_pk_bf16_f32 v167, v152, v153
	v_cvt_pk_bf16_f32 v168, v162, v163
	v_cvt_pk_bf16_f32 v169, v160, v161
	global_store_dwordx4 v[134:135], v[166:169], off sc0 sc1

; __device__ __forceinline__ void store8bf(bf16_t* p, f32x4 v0, f32x4 v1) { u32x4 w; w.x = cvt_pk_bf16(v0[0], v0[1]); w.y = cvt_pk_bf16(v0[2], v0[3]); w.z = cvt_pk_bf16(v1[0], v1[1]); w.w = cvt_pk_bf16(v1[2], v1[3]); *(u32x4*)p = w; }
;   __device__ __forceinline__ void group(int row, int c32, int fq, f32x4 v0, f32x4 v1) const {
;     ...
;     else if (c32 < 1024) { const int cc = c32 - 768, h = cc >> 6; store8bf(kd + ((size_t)(b * 4 + h) * E + e) * 64 + (cc & 63) + fq * 8, v0, v1); }
.LBB0_328:
	s_andn2_b64 vcc, exec, s[38:39]
	s_cbranch_vccnz .LBB0_330
	v_lshl_add_u32 v134, v133, 2, v147
	v_mov_b32_e32 v131, v1
	s_movk_i32 s1, 0x2040
	v_mad_i64_i32 v[134:135], s[22:23], v134, s1, v[130:131]
	v_readlane_b32 s22, v254, 8
	v_lshlrev_b64 v[134:135], 7, v[134:135]
	v_readlane_b32 s23, v254, 9
	v_lshlrev_b32_e32 v152, 1, v137
	v_mov_b32_e32 v153, v1
	v_lshl_add_u64 v[134:135], s[22:23], 0, v[134:135]
	v_lshl_add_u64 v[134:135], v[134:135], 0, v[152:153]
	v_lshlrev_b32_e32 v152, 1, v139
	v_lshl_add_u64 v[134:135], v[134:135], 0, v[152:153]
	v_cvt_pk_bf16_f32 v166, v126, v127
	v_cvt_pk_bf16_f32 v167, v128, v129
	v_cvt_pk_bf16_f32 v168, v122, v123
	v_cvt_pk_bf16_f32 v169, v124, v125
	global_store_dwordx4 v[134:135], v[166:169], off sc0 sc1

; __device__ __forceinline__ void store8bf(bf16_t* p, f32x4 v0, f32x4 v1) { u32x4 w; w.x = cvt_pk_bf16(v0[0], v0[1]); w.y = cvt_pk_bf16(v0[2], v0[3]); w.z = cvt_pk_bf16(v1[0], v1[1]); w.w = cvt_pk_bf16(v1[2], v1[3]); *(u32x4*)p = w; }
;   __device__ __forceinline__ void group(int row, int c32, int fq, f32x4 v0, f32x4 v1) const {
;     ...
;     if (c32 < 768) { const int cc = c32 - 512, h = cc >> 6; store8bf(qd + ((size_t)(b * 4 + h) * E + e) * 64 + (cc & 63) + fq * 8, v0 * QSC_D, v1 * QSC_D); }
.LBB0_331:
	s_andn2_b64 vcc, exec, s[38:39]
	s_cbranch_vccnz .LBB0_333
	v_lshl_add_u32 v133, v133, 2, v146
	v_mov_b32_e32 v131, v1
	s_movk_i32 s1, 0x2040
	v_mad_i64_i32 v[130:131], s[22:23], v133, s1, v[130:131]
	v_readlane_b32 s22, v254, 6
	v_lshlrev_b64 v[130:131], 7, v[130:131]
	v_readlane_b32 s23, v254, 7
	v_lshlrev_b32_e32 v134, 1, v137
	v_mov_b32_e32 v135, v1
	v_lshl_add_u64 v[130:131], s[22:23], 0, v[130:131]
	v_lshl_add_u64 v[130:131], v[130:131], 0, v[134:135]
	v_lshlrev_b32_e32 v134, 1, v139
	s_mov_b32 s22, 0x3e8293ee
	v_lshl_add_u64 v[130:131], v[130:131], 0, v[134:135]
	v_pk_mul_f32 v[134:135], v[128:129], s[22:23] op_sel_hi:[1,0]
	v_pk_mul_f32 v[152:153], v[126:127], s[22:23] op_sel_hi:[1,0]
	v_pk_mul_f32 v[158:159], v[124:125], s[22:23] op_sel_hi:[1,0]
	v_pk_mul_f32 v[160:161], v[122:123], s[22:23] op_sel_hi:[1,0]
	v_cvt_pk_bf16_f32 v166, v152, v153
	v_cvt_pk_bf16_f32 v167, v134, v135
	v_cvt_pk_bf16_f32 v168, v160, v161
	v_cvt_pk_bf16_f32 v169, v158, v159
	global_store_dwordx4 v[130:131], v[166:169], off sc0 sc1

; __device__ __forceinline__ void store8bf(bf16_t* p, f32x4 v0, f32x4 v1) { u32x4 w; w.x = cvt_pk_bf16(v0[0], v0[1]); w.y = cvt_pk_bf16(v0[2], v0[3]); w.z = cvt_pk_bf16(v1[0], v1[1]); w.w = cvt_pk_bf16(v1[2], v1[3]); *(u32x4*)p = w; }
;   __device__ __forceinline__ void group(int row, int c32, int fq, f32x4 v0, f32x4 v1) const {
;     ...
;       if (c32 < 384) store8bf(cqkv + (size_t)row * 512 + c32 + fq * 8, v0, v1);
.LBB0_334:
	s_andn2_b64 vcc, exec, s[8:9]
	s_cbranch_vccnz .LBB0_336
	v_ashrrev_i32_e32 v133, 31, v132
	v_readlane_b32 s8, v254, 0
	v_lshlrev_b64 v[130:131], 10, v[132:133]
	v_readlane_b32 s9, v254, 1
	v_lshlrev_b32_e32 v134, 1, v139
	v_mov_b32_e32 v135, v1
	v_lshl_add_u64 v[130:131], s[8:9], 0, v[130:131]
	v_lshl_add_u64 v[130:131], v[0:1], 1, v[130:131]
	v_cvt_pk_bf16_f32 v166, v126, v127
	v_cvt_pk_bf16_f32 v167, v128, v129
	v_lshl_add_u64 v[130:131], v[130:131], 0, v[134:135]
	v_cvt_pk_bf16_f32 v168, v122, v123
	v_cvt_pk_bf16_f32 v169, v124, v125
	global_store_dwordx4 v[130:131], v[166:169], off sc0 sc1

; __device__ __forceinline__ void store8bf(bf16_t* p, f32x4 v0, f32x4 v1) { u32x4 w; w.x = cvt_pk_bf16(v0[0], v0[1]); w.y = cvt_pk_bf16(v0[2], v0[3]); w.z = cvt_pk_bf16(v1[0], v1[1]); w.w = cvt_pk_bf16(v1[2], v1[3]); *(u32x4*)p = w; }
;   __device__ __forceinline__ void group(int row, int c32, int fq, f32x4 v0, f32x4 v1) const {
;     ...
;     else if (c32 < 1664) { const int cc = c32 - 1280, h = cc >> 6; store8bf(qs + ((size_t)(b * 6 + h) * E + e) * 64 + (cc & 63) + fq * 8, v0 * QSC_S, v1 * QSC_S); }
.LBB0_343:
	s_andn2_b64 vcc, exec, s[38:39]
	s_cbranch_vccnz .LBB0_345
	v_mad_i32_i24 v133, v131, 6, v149
	v_mov_b32_e32 v135, v1
	s_movk_i32 s1, 0x2040
	v_mad_i64_i32 v[152:153], s[22:23], v133, s1, v[134:135]
	v_readlane_b32 s22, v254, 12
	v_lshlrev_b64 v[152:153], 7, v[152:153]
	v_readlane_b32 s23, v254, 13
	v_lshlrev_b32_e32 v158, 1, v137
	v_mov_b32_e32 v159, v1
	v_lshl_add_u64 v[152:153], s[22:23], 0, v[152:153]
	v_lshl_add_u64 v[152:153], v[152:153], 0, v[158:159]
	v_lshlrev_b32_e32 v158, 1, v139
	s_mov_b32 s22, 0x3e38aa3b
	v_lshl_add_u64 v[152:153], v[152:153], 0, v[158:159]
	v_pk_mul_f32 v[158:159], v[120:121], s[22:23] op_sel_hi:[1,0]
	v_pk_mul_f32 v[160:161], v[118:119], s[22:23] op_sel_hi:[1,0]
	v_pk_mul_f32 v[162:163], v[116:117], s[22:23] op_sel_hi:[1,0]
	v_pk_mul_f32 v[164:165], v[114:115], s[22:23] op_sel_hi:[1,0]
	v_cvt_pk_bf16_f32 v166, v160, v161
	v_cvt_pk_bf16_f32 v167, v158, v159
	v_cvt_pk_bf16_f32 v168, v164, v165
	v_cvt_pk_bf16_f32 v169, v162, v163
	global_store_dwordx4 v[152:153], v[166:169], off sc0 sc1

; __device__ __forceinline__ void store8bf(bf16_t* p, f32x4 v0, f32x4 v1) { u32x4 w; w.x = cvt_pk_bf16(v0[0], v0[1]); w.y = cvt_pk_bf16(v0[2], v0[3]); w.z = cvt_pk_bf16(v1[0], v1[1]); w.w = cvt_pk_bf16(v1[2], v1[3]); *(u32x4*)p = w; }
;   __device__ __forceinline__ void group(int row, int c32, int fq, f32x4 v0, f32x4 v1) const {
;     ...
;     else if (c32 < 1024) { const int cc = c32 - 768, h = cc >> 6; store8bf(kd + ((size_t)(b * 4 + h) * E + e) * 64 + (cc & 63) + fq * 8, v0, v1); }
.LBB0_349:
	s_andn2_b64 vcc, exec, s[38:39]
	s_cbranch_vccnz .LBB0_351
	v_lshl_add_u32 v133, v131, 2, v147
	v_mov_b32_e32 v135, v1
	s_movk_i32 s1, 0x2040
	v_mad_i64_i32 v[152:153], s[22:23], v133, s1, v[134:135]
	v_readlane_b32 s22, v254, 8
	v_lshlrev_b64 v[152:153], 7, v[152:153]
	v_readlane_b32 s23, v254, 9
	v_lshlrev_b32_e32 v158, 1, v137
	v_mov_b32_e32 v159, v1
	v_lshl_add_u64 v[152:153], s[22:23], 0, v[152:153]
	v_lshl_add_u64 v[152:153], v[152:153], 0, v[158:159]
	v_lshlrev_b32_e32 v158, 1, v139
	v_lshl_add_u64 v[152:153], v[152:153], 0, v[158:159]
	v_cvt_pk_bf16_f32 v166, v118, v119
	v_cvt_pk_bf16_f32 v167, v120, v121
	v_cvt_pk_bf16_f32 v168, v114, v115
	v_cvt_pk_bf16_f32 v169, v116, v117
	global_store_dwordx4 v[152:153], v[166:169], off sc0 sc1

; __device__ __forceinline__ void store8bf(bf16_t* p, f32x4 v0, f32x4 v1) { u32x4 w; w.x = cvt_pk_bf16(v0[0], v0[1]); w.y = cvt_pk_bf16(v0[2], v0[3]); w.z = cvt_pk_bf16(v1[0], v1[1]); w.w = cvt_pk_bf16(v1[2], v1[3]); *(u32x4*)p = w; }
;   __device__ __forceinline__ void group(int row, int c32, int fq, f32x4 v0, f32x4 v1) const {
;     ...
;     if (c32 < 768) { const int cc = c32 - 512, h = cc >> 6; store8bf(qd + ((size_t)(b * 4 + h) * E + e) * 64 + (cc & 63) + fq * 8, v0 * QSC_D, v1 * QSC_D); }
.LBB0_352:
	s_andn2_b64 vcc, exec, s[38:39]
	s_cbranch_vccnz .LBB0_354
	v_lshl_add_u32 v131, v131, 2, v146
	v_mov_b32_e32 v135, v1
	s_movk_i32 s1, 0x2040
	v_mad_i64_i32 v[134:135], s[22:23], v131, s1, v[134:135]
	v_readlane_b32 s22, v254, 6
	v_lshlrev_b64 v[134:135], 7, v[134:135]
	v_readlane_b32 s23, v254, 7
	v_lshlrev_b32_e32 v152, 1, v137
	v_mov_b32_e32 v153, v1
	v_lshl_add_u64 v[134:135], s[22:23], 0, v[134:135]
	v_lshl_add_u64 v[134:135], v[134:135], 0, v[152:153]
	v_lshlrev_b32_e32 v152, 1, v139
	s_mov_b32 s22, 0x3e8293ee
	v_lshl_add_u64 v[134:135], v[134:135], 0, v[152:153]
	v_pk_mul_f32 v[152:153], v[120:121], s[22:23] op_sel_hi:[1,0]
	v_pk_mul_f32 v[158:159], v[118:119], s[22:23] op_sel_hi:[1,0]
	v_pk_mul_f32 v[160:161], v[116:117], s[22:23] op_sel_hi:[1,0]
	v_pk_mul_f32 v[162:163], v[114:115], s[22:23] op_sel_hi:[1,0]
	v_cvt_pk_bf16_f32 v166, v158, v159
	v_cvt_pk_bf16_f32 v167, v152, v153
	v_cvt_pk_bf16_f32 v168, v162, v163
	v_cvt_pk_bf16_f32 v169, v160, v161
	global_store_dwordx4 v[134:135], v[166:169], off sc0 sc1

; __device__ __forceinline__ void store8bf(bf16_t* p, f32x4 v0, f32x4 v1) { u32x4 w; w.x = cvt_pk_bf16(v0[0], v0[1]); w.y = cvt_pk_bf16(v0[2], v0[3]); w.z = cvt_pk_bf16(v1[0], v1[1]); w.w = cvt_pk_bf16(v1[2], v1[3]); *(u32x4*)p = w; }
;   __device__ __forceinline__ void group(int row, int c32, int fq, f32x4 v0, f32x4 v1) const {
;     ...
;     else if (c32 < 1664) { const int cc = c32 - 1280, h = cc >> 6; store8bf(qs + ((size_t)(b * 6 + h) * E + e) * 64 + (cc & 63) + fq * 8, v0 * QSC_S, v1 * QSC_S); }
.LBB0_362:
	s_andn2_b64 vcc, exec, s[38:39]
	s_cbranch_vccnz .LBB0_364
	v_mad_i32_i24 v133, v131, 6, v149
	v_mov_b32_e32 v135, v1
	s_movk_i32 s1, 0x2040
	v_mad_i64_i32 v[152:153], s[22:23], v133, s1, v[134:135]
	v_readlane_b32 s22, v254, 12
	v_lshlrev_b64 v[152:153], 7, v[152:153]
	v_readlane_b32 s23, v254, 13
	v_lshlrev_b32_e32 v158, 1, v137
	v_mov_b32_e32 v159, v1
	v_lshl_add_u64 v[152:153], s[22:23], 0, v[152:153]
	v_lshl_add_u64 v[152:153], v[152:153], 0, v[158:159]
	v_lshlrev_b32_e32 v158, 1, v139
	s_mov_b32 s22, 0x3e38aa3b
	v_lshl_add_u64 v[152:153], v[152:153], 0, v[158:159]
	v_pk_mul_f32 v[158:159], v[112:113], s[22:23] op_sel_hi:[1,0]
	v_pk_mul_f32 v[160:161], v[110:111], s[22:23] op_sel_hi:[1,0]
	v_pk_mul_f32 v[162:163], v[108:109], s[22:23] op_sel_hi:[1,0]
	v_pk_mul_f32 v[164:165], v[106:107], s[22:23] op_sel_hi:[1,0]
	v_cvt_pk_bf16_f32 v166, v160, v161
	v_cvt_pk_bf16_f32 v167, v158, v159
	v_cvt_pk_bf16_f32 v168, v164, v165
	v_cvt_pk_bf16_f32 v169, v162, v163
	global_store_dwordx4 v[152:153], v[166:169], off sc0 sc1

; __device__ __forceinline__ void store8bf(bf16_t* p, f32x4 v0, f32x4 v1) { u32x4 w; w.x = cvt_pk_bf16(v0[0], v0[1]); w.y = cvt_pk_bf16(v0[2], v0[3]); w.z = cvt_pk_bf16(v1[0], v1[1]); w.w = cvt_pk_bf16(v1[2], v1[3]); *(u32x4*)p = w; }
;   __device__ __forceinline__ void group(int row, int c32, int fq, f32x4 v0, f32x4 v1) const {
;     ...
;     else if (c32 < 1024) { const int cc = c32 - 768, h = cc >> 6; store8bf(kd + ((size_t)(b * 4 + h) * E + e) * 64 + (cc & 63) + fq * 8, v0, v1); }
.LBB0_368:
	s_andn2_b64 vcc, exec, s[38:39]
	s_cbranch_vccnz .LBB0_370
	v_lshl_add_u32 v133, v131, 2, v147
	v_mov_b32_e32 v135, v1
	s_movk_i32 s1, 0x2040
	v_mad_i64_i32 v[152:153], s[22:23], v133, s1, v[134:135]
	v_readlane_b32 s22, v254, 8
	v_lshlrev_b64 v[152:153], 7, v[152:153]
	v_readlane_b32 s23, v254, 9
	v_lshlrev_b32_e32 v158, 1, v137
	v_mov_b32_e32 v159, v1
	v_lshl_add_u64 v[152:153], s[22:23], 0, v[152:153]
	v_lshl_add_u64 v[152:153], v[152:153], 0, v[158:159]
	v_lshlrev_b32_e32 v158, 1, v139
	v_lshl_add_u64 v[152:153], v[152:153], 0, v[158:159]
	v_cvt_pk_bf16_f32 v166, v110, v111
	v_cvt_pk_bf16_f32 v167, v112, v113
	v_cvt_pk_bf16_f32 v168, v106, v107
	v_cvt_pk_bf16_f32 v169, v108, v109
	global_store_dwordx4 v[152:153], v[166:169], off sc0 sc1

; __device__ __forceinline__ void store8bf(bf16_t* p, f32x4 v0, f32x4 v1) { u32x4 w; w.x = cvt_pk_bf16(v0[0], v0[1]); w.y = cvt_pk_bf16(v0[2], v0[3]); w.z = cvt_pk_bf16(v1[0], v1[1]); w.w = cvt_pk_bf16(v1[2], v1[3]); *(u32x4*)p = w; }
;   __device__ __forceinline__ void group(int row, int c32, int fq, f32x4 v0, f32x4 v1) const {
;     ...
;     if (c32 < 768) { const int cc = c32 - 512, h = cc >> 6; store8bf(qd + ((size_t)(b * 4 + h) * E + e) * 64 + (cc & 63) + fq * 8, v0 * QSC_D, v1 * QSC_D); }
.LBB0_371:
	s_andn2_b64 vcc, exec, s[38:39]
	s_cbranch_vccnz .LBB0_373
	v_lshl_add_u32 v131, v131, 2, v146
	v_mov_b32_e32 v135, v1
	s_movk_i32 s1, 0x2040
	v_mad_i64_i32 v[134:135], s[22:23], v131, s1, v[134:135]
	v_readlane_b32 s22, v254, 6
	v_lshlrev_b64 v[134:135], 7, v[134:135]
	v_readlane_b32 s23, v254, 7
	v_lshlrev_b32_e32 v152, 1, v137
	v_mov_b32_e32 v153, v1
	v_lshl_add_u64 v[134:135], s[22:23], 0, v[134:135]
	v_lshl_add_u64 v[134:135], v[134:135], 0, v[152:153]
	v_lshlrev_b32_e32 v152, 1, v139
	s_mov_b32 s22, 0x3e8293ee
	v_lshl_add_u64 v[134:135], v[134:135], 0, v[152:153]
	v_pk_mul_f32 v[152:153], v[112:113], s[22:23] op_sel_hi:[1,0]
	v_pk_mul_f32 v[158:159], v[110:111], s[22:23] op_sel_hi:[1,0]
	v_pk_mul_f32 v[160:161], v[108:109], s[22:23] op_sel_hi:[1,0]
	v_pk_mul_f32 v[162:163], v[106:107], s[22:23] op_sel_hi:[1,0]
	v_cvt_pk_bf16_f32 v166, v158, v159
	v_cvt_pk_bf16_f32 v167, v152, v153
	v_cvt_pk_bf16_f32 v168, v162, v163
	v_cvt_pk_bf16_f32 v169, v160, v161
	global_store_dwordx4 v[134:135], v[166:169], off sc0 sc1

; __device__ __forceinline__ void store8bf(bf16_t* p, f32x4 v0, f32x4 v1) { u32x4 w; w.x = cvt_pk_bf16(v0[0], v0[1]); w.y = cvt_pk_bf16(v0[2], v0[3]); w.z = cvt_pk_bf16(v1[0], v1[1]); w.w = cvt_pk_bf16(v1[2], v1[3]); *(u32x4*)p = w; }
;   __device__ __forceinline__ void group(int row, int c32, int fq, f32x4 v0, f32x4 v1) const {
;     ...
;     else if (c32 < 1664) { const int cc = c32 - 1280, h = cc >> 6; store8bf(qs + ((size_t)(b * 6 + h) * E + e) * 64 + (cc & 63) + fq * 8, v0 * QSC_S, v1 * QSC_S); }
.LBB0_381:
	s_andn2_b64 vcc, exec, s[10:11]
	s_cbranch_vccnz .LBB0_383
	v_mad_i32_i24 v133, v131, 6, v149
	v_mov_b32_e32 v135, v1
	s_movk_i32 s1, 0x2040
	v_mad_i64_i32 v[150:151], s[10:11], v133, s1, v[134:135]
	v_readlane_b32 s10, v254, 12
	v_lshlrev_b64 v[150:151], 7, v[150:151]
	v_readlane_b32 s11, v254, 13
	v_lshlrev_b32_e32 v152, 1, v137
	v_mov_b32_e32 v153, v1
	v_lshl_add_u64 v[150:151], s[10:11], 0, v[150:151]
	v_lshl_add_u64 v[150:151], v[150:151], 0, v[152:153]
	v_lshlrev_b32_e32 v152, 1, v139
	s_mov_b32 s10, 0x3e38aa3b
	v_lshl_add_u64 v[158:159], v[150:151], 0, v[152:153]
	v_pk_mul_f32 v[152:153], v[104:105], s[10:11] op_sel_hi:[1,0]
	v_pk_mul_f32 v[150:151], v[102:103], s[10:11] op_sel_hi:[1,0]
	v_pk_mul_f32 v[160:161], v[100:101], s[10:11] op_sel_hi:[1,0]
	v_pk_mul_f32 v[162:163], v[98:99], s[10:11] op_sel_hi:[1,0]
	v_cvt_pk_bf16_f32 v150, v150, v151
	v_cvt_pk_bf16_f32 v151, v152, v153
	v_cvt_pk_bf16_f32 v152, v162, v163
	v_cvt_pk_bf16_f32 v153, v160, v161
	global_store_dwordx4 v[158:159], v[150:153], off sc0 sc1

; __device__ __forceinline__ void store8bf(bf16_t* p, f32x4 v0, f32x4 v1) { u32x4 w; w.x = cvt_pk_bf16(v0[0], v0[1]); w.y = cvt_pk_bf16(v0[2], v0[3]); w.z = cvt_pk_bf16(v1[0], v1[1]); w.w = cvt_pk_bf16(v1[2], v1[3]); *(u32x4*)p = w; }
;   __device__ __forceinline__ void group(int row, int c32, int fq, f32x4 v0, f32x4 v1) const {
;     ...
;     else if (c32 < 1024) { const int cc = c32 - 768, h = cc >> 6; store8bf(kd + ((size_t)(b * 4 + h) * E + e) * 64 + (cc & 63) + fq * 8, v0, v1); }
.LBB0_387:
	s_andn2_b64 vcc, exec, s[10:11]
	s_cbranch_vccnz .LBB0_389
	v_lshl_add_u32 v133, v131, 2, v147
	v_mov_b32_e32 v135, v1
	s_movk_i32 s1, 0x2040
	v_mad_i64_i32 v[148:149], s[10:11], v133, s1, v[134:135]
	v_readlane_b32 s10, v254, 8
	v_lshlrev_b64 v[148:149], 7, v[148:149]
	v_readlane_b32 s11, v254, 9
	v_lshlrev_b32_e32 v150, 1, v137
	v_mov_b32_e32 v151, v1
	v_lshl_add_u64 v[148:149], s[10:11], 0, v[148:149]
	v_lshl_add_u64 v[148:149], v[148:149], 0, v[150:151]
	v_lshlrev_b32_e32 v150, 1, v139
	v_lshl_add_u64 v[152:153], v[148:149], 0, v[150:151]
	v_cvt_pk_bf16_f32 v148, v102, v103
	v_cvt_pk_bf16_f32 v149, v104, v105
	v_cvt_pk_bf16_f32 v150, v98, v99
	v_cvt_pk_bf16_f32 v151, v100, v101
	global_store_dwordx4 v[152:153], v[148:151], off sc0 sc1

; __device__ __forceinline__ void store8bf(bf16_t* p, f32x4 v0, f32x4 v1) { u32x4 w; w.x = cvt_pk_bf16(v0[0], v0[1]); w.y = cvt_pk_bf16(v0[2], v0[3]); w.z = cvt_pk_bf16(v1[0], v1[1]); w.w = cvt_pk_bf16(v1[2], v1[3]); *(u32x4*)p = w; }
;   __device__ __forceinline__ void group(int row, int c32, int fq, f32x4 v0, f32x4 v1) const {
;     ...
;     if (c32 < 768) { const int cc = c32 - 512, h = cc >> 6; store8bf(qd + ((size_t)(b * 4 + h) * E + e) * 64 + (cc & 63) + fq * 8, v0 * QSC_D, v1 * QSC_D); }
.LBB0_390:
	s_andn2_b64 vcc, exec, s[10:11]
	s_cbranch_vccnz .LBB0_392
	v_lshl_add_u32 v131, v131, 2, v146
	v_mov_b32_e32 v135, v1
	s_movk_i32 s1, 0x2040
	v_mad_i64_i32 v[134:135], s[10:11], v131, s1, v[134:135]
	v_readlane_b32 s10, v254, 6
	v_lshlrev_b64 v[134:135], 7, v[134:135]
	v_readlane_b32 s11, v254, 7
	v_lshlrev_b32_e32 v146, 1, v137
	v_mov_b32_e32 v147, v1
	v_lshl_add_u64 v[134:135], s[10:11], 0, v[134:135]
	v_lshl_add_u64 v[134:135], v[134:135], 0, v[146:147]
	v_lshlrev_b32_e32 v146, 1, v139
	s_mov_b32 s10, 0x3e8293ee
	v_lshl_add_u64 v[134:135], v[134:135], 0, v[146:147]
	v_pk_mul_f32 v[148:149], v[104:105], s[10:11] op_sel_hi:[1,0]
	v_pk_mul_f32 v[146:147], v[102:103], s[10:11] op_sel_hi:[1,0]
	v_pk_mul_f32 v[150:151], v[100:101], s[10:11] op_sel_hi:[1,0]
	v_pk_mul_f32 v[152:153], v[98:99], s[10:11] op_sel_hi:[1,0]
	v_cvt_pk_bf16_f32 v146, v146, v147
	v_cvt_pk_bf16_f32 v147, v148, v149
	v_cvt_pk_bf16_f32 v148, v152, v153
	v_cvt_pk_bf16_f32 v149, v150, v151
	global_store_dwordx4 v[134:135], v[146:149], off sc0 sc1

; __device__ __forceinline__ void store8bf(bf16_t* p, f32x4 v0, f32x4 v1) { u32x4 w; w.x = cvt_pk_bf16(v0[0], v0[1]); w.y = cvt_pk_bf16(v0[2], v0[3]); w.z = cvt_pk_bf16(v1[0], v1[1]); w.w = cvt_pk_bf16(v1[2], v1[3]); *(u32x4*)p = w; }
;   __device__ __forceinline__ void group(int row, int c32, int fq, f32x4 v0, f32x4 v1) const {
;     ...
;       if (c32 < 384) store8bf(cqkv + (size_t)row * 512 + c32 + fq * 8, v0, v1);
.LBB0_395:
	v_ashrrev_i32_e32 v131, 31, v130
	v_readlane_b32 s10, v254, 0
	v_lshlrev_b64 v[130:131], 10, v[130:131]
	v_readlane_b32 s11, v254, 1
	v_lshlrev_b32_e32 v134, 1, v139
	v_mov_b32_e32 v135, v1
	v_lshl_add_u64 v[130:131], s[10:11], 0, v[130:131]
	v_lshl_add_u64 v[130:131], v[0:1], 1, v[130:131]
	v_cvt_pk_bf16_f32 v166, v118, v119
	v_cvt_pk_bf16_f32 v167, v120, v121
	v_lshl_add_u64 v[130:131], v[130:131], 0, v[134:135]
	v_cvt_pk_bf16_f32 v168, v114, v115
	v_cvt_pk_bf16_f32 v169, v116, v117
	global_store_dwordx4 v[130:131], v[166:169], off sc0 sc1
	v_or_b32_e32 v130, 32, v132
	s_and_b64 vcc, exec, s[8:9]
	s_mov_b64 s[10:11], -1
	s_cbranch_vccz .LBB0_356

; __device__ __forceinline__ void store8bf(bf16_t* p, f32x4 v0, f32x4 v1) { u32x4 w; w.x = cvt_pk_bf16(v0[0], v0[1]); w.y = cvt_pk_bf16(v0[2], v0[3]); w.z = cvt_pk_bf16(v1[0], v1[1]); w.w = cvt_pk_bf16(v1[2], v1[3]); *(u32x4*)p = w; }
;   __device__ __forceinline__ void group(int row, int c32, int fq, f32x4 v0, f32x4 v1) const {
;     ...
;       if (c32 < 384) store8bf(cqkv + (size_t)row * 512 + c32 + fq * 8, v0, v1);
.LBB0_397:
	v_ashrrev_i32_e32 v131, 31, v130
	v_readlane_b32 s10, v254, 0
	v_lshlrev_b64 v[130:131], 10, v[130:131]
	v_readlane_b32 s11, v254, 1
	v_lshlrev_b32_e32 v134, 1, v139
	v_mov_b32_e32 v135, v1
	v_lshl_add_u64 v[130:131], s[10:11], 0, v[130:131]
	v_lshl_add_u64 v[130:131], v[0:1], 1, v[130:131]
	v_cvt_pk_bf16_f32 v166, v110, v111
	v_cvt_pk_bf16_f32 v167, v112, v113
	v_lshl_add_u64 v[130:131], v[130:131], 0, v[134:135]
	v_cvt_pk_bf16_f32 v168, v106, v107
	v_cvt_pk_bf16_f32 v169, v108, v109
	global_store_dwordx4 v[130:131], v[166:169], off sc0 sc1
	v_or_b32_e32 v130, 48, v132
	s_and_b64 vcc, exec, s[8:9]
	s_mov_b64 s[8:9], -1
	s_cbranch_vccz .LBB0_375

; __device__ __forceinline__ void store8bf(bf16_t* p, f32x4 v0, f32x4 v1) { u32x4 w; w.x = cvt_pk_bf16(v0[0], v0[1]); w.y = cvt_pk_bf16(v0[2], v0[3]); w.z = cvt_pk_bf16(v1[0], v1[1]); w.w = cvt_pk_bf16(v1[2], v1[3]); *(u32x4*)p = w; }
;   __device__ __forceinline__ void group(int row, int c32, int fq, f32x4 v0, f32x4 v1) const {
;     ...
;       if (c32 < 384) store8bf(cqkv + (size_t)row * 512 + c32 + fq * 8, v0, v1);
.LBB0_399:
	v_ashrrev_i32_e32 v131, 31, v130
	v_readlane_b32 s8, v254, 0
	v_lshlrev_b64 v[130:131], 10, v[130:131]
	v_readlane_b32 s9, v254, 1
	v_lshlrev_b32_e32 v134, 1, v139
	v_mov_b32_e32 v135, v1
	v_lshl_add_u64 v[130:131], s[8:9], 0, v[130:131]
	v_lshl_add_u64 v[130:131], v[0:1], 1, v[130:131]
	v_cvt_pk_bf16_f32 v146, v102, v103
	v_cvt_pk_bf16_f32 v147, v104, v105
	v_lshl_add_u64 v[130:131], v[130:131], 0, v[134:135]
	v_cvt_pk_bf16_f32 v148, v98, v99
	v_cvt_pk_bf16_f32 v149, v100, v101
	global_store_dwordx4 v[130:131], v[146:149], off sc0 sc1

; #define LAS __attribute__((address_space(3)))
; __device__ __forceinline__ unsigned short f2bf(float f) { return (unsigned short)(cvt_pk_bf16(f, f) & 0xffffu); }
;   __device__ __forceinline__ bool vt_info(int c32, int b, bf16_t*& base) const { return e->vt_info(c32 + sh, b, base); }
;     ...
;     const ldsp_t T = (ldsp_t)lds_raw + (wid < 4 ? 32768 + wid * 4608 : 98304 + (wid - 4) * 4608);
; #pragma unroll
;     for (int ai = 0; ai < 2; ++ai)
; #pragma unroll
;       for (int bj = 0; bj < 2; ++bj) {
;         const int c32 = bcol + wc * 32 + bj * HALF, row0 = brow + ai * HALF + wr * 64;
;         int b0, e0; row_be(row0, b0, e0); bf16_t* vbase;
;         if (epi.vt_info(c32, b0, vbase)) {
; #pragma unroll
;           for (int m = 0; m < 4; ++m) { const float sc = epi.row_scale(row0 + m * 16 + fr);
; #pragma unroll
;             for (int n = 0; n < 2; ++n)
; #pragma unroll
;               for (int j = 0; j < 4; ++j) *(LAS bf16_t*)(T + (n * 16 + fq * 4 + j) * 144 + (m * 16 + fr) * 2) = f2bf(acc[ai][bj][m][n][j] * sc); }
;           asm volatile("s_waitcnt lgkmcnt(0)" ::: "memory");
; #pragma unroll
;           for (int q = 0; q < 4; ++q) { const int ch = lane + 64 * q, d = ch >> 3, ec = ch & 7;
;             *(u32x4*)(vbase + (size_t)d * E + e0 + ec * 8) = *(LAS const u32x4*)(T + d * 144 + ec * 16); }
;           asm volatile("s_waitcnt lgkmcnt(0)" ::: "memory");
.LBB0_402:
	s_movk_i32 s15, 0x1200
	v_mul_lo_u32 v131, v142, s15
	v_cndmask_b32_e64 v133, v213, v211, s[4:5]
	v_add3_u32 v131, 0, v131, v133
	v_and_b32_e32 v134, 7, v141
	v_lshl_add_u32 v133, v136, 1, v131
	v_lshl_add_u32 v131, v134, 4, v131
	v_lshlrev_b32_e32 v135, 3, v134
	v_and_b32_e32 v134, 0x1fc0, v144
	v_and_b32_e32 v130, 63, v141
	v_add_u32_e32 v134, 64, v134
	s_movk_i32 s4, 0x240
	v_cndmask_b32_e64 v134, 0, v134, s[6:7]
	v_mad_u32_u24 v143, v143, s4, v133
	v_lshrrev_b32_e32 v133, 3, v130
	v_cndmask_b32_e64 v146, 0, v145, s[6:7]
	s_and_b64 vcc, exec, s[10:11]
	v_lshlrev_b32_e32 v134, 1, v134
	v_lshlrev_b32_e32 v130, 1, v135
	v_mad_u32_u24 v141, v133, s54, v131
	v_mul_u32_u24_e32 v142, 0x2040, v133
	s_cbranch_vccz .LBB0_404
	v_readlane_b32 s24, v253, 16
	v_readlane_b32 s25, v253, 17
	v_readlane_b32 s26, v253, 18
	v_readlane_b32 s27, v253, 19
	v_readlane_b32 s28, v253, 20
	v_readlane_b32 s29, v253, 21
	v_add_u32_e32 v131, s14, v0
	v_readlane_b32 s30, v253, 22
	v_readlane_b32 s31, v253, 23
	s_mov_b64 s[24:25], s[28:29]
	v_lshrrev_b32_e32 v131, 6, v131
	s_mov_b64 s[26:27], s[30:31]
	v_lshl_add_u32 v148, v146, s1, v131
	s_add_u32 s4, s26, s8
	v_ashrrev_i32_e32 v149, 31, v148
	v_cvt_pk_bf16_f32 v126, v126, s0
	v_cvt_pk_bf16_f32 v122, v122, s0
	v_cvt_pk_bf16_f32 v118, v118, s0
	v_cvt_pk_bf16_f32 v114, v114, s0
	v_cvt_pk_bf16_f32 v110, v110, s0
	v_cvt_pk_bf16_f32 v106, v106, s0
	v_cvt_pk_bf16_f32 v102, v102, s0
	v_cvt_pk_bf16_f32 v98, v98, s0
	s_addc_u32 s5, s27, s9
	v_lshlrev_b64 v[148:149], 6, v[148:149]
	ds_write_b16 v143, v126
	v_cvt_pk_bf16_f32 v126, v127, s0
	ds_write_b16 v143, v122 offset:2304
	v_cvt_pk_bf16_f32 v122, v123, s0
	ds_write_b16 v143, v118 offset:32
	v_cvt_pk_bf16_f32 v118, v119, s0
	ds_write_b16 v143, v114 offset:2336
	v_cvt_pk_bf16_f32 v114, v115, s0
	ds_write_b16 v143, v110 offset:64
	v_cvt_pk_bf16_f32 v110, v111, s0
	ds_write_b16 v143, v106 offset:2368
	v_cvt_pk_bf16_f32 v106, v107, s0
	ds_write_b16 v143, v102 offset:96
	v_cvt_pk_bf16_f32 v102, v103, s0
	ds_write_b16 v143, v98 offset:2400
	v_cvt_pk_bf16_f32 v98, v99, s0
	v_or_b32_e32 v131, v148, v137
	v_mov_b64_e32 v[150:151], s[4:5]
	ds_write_b16 v143, v126 offset:144
	v_cvt_pk_bf16_f32 v126, v128, s0
	ds_write_b16 v143, v122 offset:2448
	v_cvt_pk_bf16_f32 v122, v124, s0
	ds_write_b16 v143, v118 offset:176
	v_cvt_pk_bf16_f32 v118, v120, s0
	ds_write_b16 v143, v114 offset:2480
	v_cvt_pk_bf16_f32 v114, v116, s0
	ds_write_b16 v143, v110 offset:208
	v_cvt_pk_bf16_f32 v110, v112, s0
	ds_write_b16 v143, v106 offset:2512
	v_cvt_pk_bf16_f32 v106, v108, s0
	ds_write_b16 v143, v102 offset:240
	v_cvt_pk_bf16_f32 v102, v104, s0
	ds_write_b16 v143, v98 offset:2544
	v_cvt_pk_bf16_f32 v98, v100, s0
	v_mad_u64_u32 v[150:151], s[4:5], v131, s95, v[150:151]
	ds_write_b16 v143, v126 offset:288
	v_cvt_pk_bf16_f32 v126, v129, s0
	ds_write_b16 v143, v122 offset:2592
	v_cvt_pk_bf16_f32 v122, v125, s0
	ds_write_b16 v143, v118 offset:320
	v_cvt_pk_bf16_f32 v118, v121, s0
	ds_write_b16 v143, v114 offset:2624
	v_cvt_pk_bf16_f32 v114, v117, s0
	ds_write_b16 v143, v110 offset:352
	v_cvt_pk_bf16_f32 v110, v113, s0
	ds_write_b16 v143, v106 offset:2656
	v_cvt_pk_bf16_f32 v106, v109, s0
	ds_write_b16 v143, v102 offset:384
	v_cvt_pk_bf16_f32 v102, v105, s0
	ds_write_b16 v143, v98 offset:2688
	v_cvt_pk_bf16_f32 v98, v101, s0
	v_mad_i32_i24 v151, v149, s95, v151
	ds_write_b16 v143, v126 offset:432
	ds_write_b16 v143, v122 offset:2736
	ds_write_b16 v143, v118 offset:464
	ds_write_b16 v143, v114 offset:2768
	ds_write_b16 v143, v110 offset:496
	ds_write_b16 v143, v106 offset:2800
	ds_write_b16 v143, v102 offset:528
	ds_write_b16 v143, v98 offset:2832
	v_mov_b32_e32 v135, v1
	s_waitcnt lgkmcnt(0)
	v_lshl_add_u64 v[98:99], v[150:151], 0, v[134:135]
	v_mov_b32_e32 v131, v1
	v_lshl_add_u64 v[102:103], v[98:99], 0, v[130:131]
	ds_read_b128 v[98:101], v141
	v_lshlrev_b32_e32 v104, 1, v142
	v_mov_b32_e32 v105, v1
	v_lshl_add_u64 v[106:107], v[102:103], 0, v[104:105]
	ds_read_b128 v[102:105], v141 offset:1152
	s_waitcnt lgkmcnt(0)
	global_store_dwordx4 v[106:107], v[98:101], off sc0 sc1
	s_nop 1
	v_add_co_u32_e32 v98, vcc, 0x20000, v106
	s_nop 1
	v_addc_co_u32_e32 v99, vcc, 0, v107, vcc
	global_store_dwordx4 v[98:99], v[102:105], off offset:1024 sc0 sc1
	ds_read_b128 v[98:101], v141 offset:2304
	ds_read_b128 v[102:105], v141 offset:3456
	v_add_co_u32_e32 v108, vcc, 0x40000, v106
	s_nop 1
	v_addc_co_u32_e32 v109, vcc, 0, v107, vcc
	s_waitcnt lgkmcnt(0)
	global_store_dwordx4 v[108:109], v[98:101], off offset:2048 sc0 sc1
	s_nop 1
	v_add_co_u32_e32 v98, vcc, 0x60000, v106
	s_nop 1
	v_addc_co_u32_e32 v99, vcc, 0, v107, vcc
	global_store_dwordx4 v[98:99], v[102:105], off offset:3072 sc0 sc1
	s_waitcnt lgkmcnt(0)

; __device__ __forceinline__ void store8bf(bf16_t* p, f32x4 v0, f32x4 v1) { u32x4 w; w.x = cvt_pk_bf16(v0[0], v0[1]); w.y = cvt_pk_bf16(v0[2], v0[3]); w.z = cvt_pk_bf16(v1[0], v1[1]); w.w = cvt_pk_bf16(v1[2], v1[3]); *(u32x4*)p = w; }
;   __device__ __forceinline__ void group(int row, int c32, int fq, f32x4 v0, f32x4 v1) const {
;     ...
;     else if (c32 < 1664) { const int cc = c32 - 1280, h = cc >> 6; store8bf(qs + ((size_t)(b * 6 + h) * E + e) * 64 + (cc & 63) + fq * 8, v0 * QSC_S, v1 * QSC_S); }
;     else if (c32 < 1792) { const int cc = c32 - 1664, g = cc >> 6; store8bf(ks + ((size_t)(b * 2 + g) * E + e) * 64 + (cc & 63) + fq * 8, v0, v1); }
.LBB0_415:
	s_andn2_b64 vcc, exec, s[42:43]
	s_cbranch_vccnz .LBB0_417
	v_lshl_add_u32 v98, v113, 1, v109
	v_mov_b32_e32 v103, v1
	s_movk_i32 s1, 0x2040
	v_mad_i64_i32 v[98:99], s[22:23], v98, s1, v[102:103]
	v_readlane_b32 s22, v254, 14
	v_lshlrev_b64 v[98:99], 7, v[98:99]
	v_readlane_b32 s23, v254, 15
	v_lshlrev_b32_e32 v100, 1, v137
	v_mov_b32_e32 v101, v1
	v_lshl_add_u64 v[98:99], s[22:23], 0, v[98:99]
	v_lshl_add_u64 v[98:99], v[98:99], 0, v[100:101]
	v_lshlrev_b32_e32 v100, 1, v139
	v_lshl_add_u64 v[104:105], v[98:99], 0, v[100:101]
	v_cvt_pk_bf16_f32 v98, v94, v95
	v_cvt_pk_bf16_f32 v99, v96, v97
	v_cvt_pk_bf16_f32 v100, v90, v91
	v_cvt_pk_bf16_f32 v101, v92, v93
	global_store_dwordx4 v[104:105], v[98:101], off sc0 sc1
.LBB0_417:
	s_andn2_saveexec_b64 s[42:43], s[24:25]
	s_cbranch_execz .LBB0_419
	v_mad_i32_i24 v98, v113, 6, v111
	v_mov_b32_e32 v103, v1
	s_movk_i32 s1, 0x2040
	v_mad_i64_i32 v[98:99], s[22:23], v98, s1, v[102:103]
	v_readlane_b32 s22, v254, 12
	v_lshlrev_b64 v[98:99], 7, v[98:99]
	v_readlane_b32 s23, v254, 13
	v_lshlrev_b32_e32 v100, 1, v137
	v_mov_b32_e32 v101, v1
	v_lshl_add_u64 v[98:99], s[22:23], 0, v[98:99]
	v_lshl_add_u64 v[98:99], v[98:99], 0, v[100:101]
	v_lshlrev_b32_e32 v100, 1, v139
	s_mov_b32 s22, 0x3e38aa3b
	v_lshl_add_u64 v[104:105], v[98:99], 0, v[100:101]
	v_pk_mul_f32 v[100:101], v[96:97], s[22:23] op_sel_hi:[1,0]
	v_pk_mul_f32 v[98:99], v[94:95], s[22:23] op_sel_hi:[1,0]
	v_pk_mul_f32 v[114:115], v[92:93], s[22:23] op_sel_hi:[1,0]
	v_pk_mul_f32 v[116:117], v[90:91], s[22:23] op_sel_hi:[1,0]
	v_cvt_pk_bf16_f32 v98, v98, v99
	v_cvt_pk_bf16_f32 v99, v100, v101
	v_cvt_pk_bf16_f32 v100, v116, v117
	v_cvt_pk_bf16_f32 v101, v114, v115
	global_store_dwordx4 v[104:105], v[98:101], off sc0 sc1

; __device__ __forceinline__ void store8bf(bf16_t* p, f32x4 v0, f32x4 v1) { u32x4 w; w.x = cvt_pk_bf16(v0[0], v0[1]); w.y = cvt_pk_bf16(v0[2], v0[3]); w.z = cvt_pk_bf16(v1[0], v1[1]); w.w = cvt_pk_bf16(v1[2], v1[3]); *(u32x4*)p = w; }
;   __device__ __forceinline__ void group(int row, int c32, int fq, f32x4 v0, f32x4 v1) const {
;     ...
;     else if (c32 < 1024) { const int cc = c32 - 768, h = cc >> 6; store8bf(kd + ((size_t)(b * 4 + h) * E + e) * 64 + (cc & 63) + fq * 8, v0, v1); }
.LBB0_423:
	s_andn2_b64 vcc, exec, s[42:43]
	s_cbranch_vccnz .LBB0_425
	v_lshl_add_u32 v98, v113, 2, v108
	v_mov_b32_e32 v103, v1
	s_movk_i32 s1, 0x2040
	v_mad_i64_i32 v[98:99], s[22:23], v98, s1, v[102:103]
	v_readlane_b32 s22, v254, 8
	v_lshlrev_b64 v[98:99], 7, v[98:99]
	v_readlane_b32 s23, v254, 9
	v_lshlrev_b32_e32 v100, 1, v137
	v_mov_b32_e32 v101, v1
	v_lshl_add_u64 v[98:99], s[22:23], 0, v[98:99]
	v_lshl_add_u64 v[98:99], v[98:99], 0, v[100:101]
	v_lshlrev_b32_e32 v100, 1, v139
	v_lshl_add_u64 v[104:105], v[98:99], 0, v[100:101]
	v_cvt_pk_bf16_f32 v98, v94, v95
	v_cvt_pk_bf16_f32 v99, v96, v97
	v_cvt_pk_bf16_f32 v100, v90, v91
	v_cvt_pk_bf16_f32 v101, v92, v93
	global_store_dwordx4 v[104:105], v[98:101], off sc0 sc1

; __device__ __forceinline__ void store8bf(bf16_t* p, f32x4 v0, f32x4 v1) { u32x4 w; w.x = cvt_pk_bf16(v0[0], v0[1]); w.y = cvt_pk_bf16(v0[2], v0[3]); w.z = cvt_pk_bf16(v1[0], v1[1]); w.w = cvt_pk_bf16(v1[2], v1[3]); *(u32x4*)p = w; }
;   __device__ __forceinline__ void group(int row, int c32, int fq, f32x4 v0, f32x4 v1) const {
;     ...
;     if (c32 < 768) { const int cc = c32 - 512, h = cc >> 6; store8bf(qd + ((size_t)(b * 4 + h) * E + e) * 64 + (cc & 63) + fq * 8, v0 * QSC_D, v1 * QSC_D); }
.LBB0_426:
	s_andn2_b64 vcc, exec, s[42:43]
	s_cbranch_vccnz .LBB0_428
	v_lshl_add_u32 v98, v113, 2, v107
	v_mov_b32_e32 v103, v1
	s_movk_i32 s1, 0x2040
	v_mad_i64_i32 v[98:99], s[22:23], v98, s1, v[102:103]
	v_readlane_b32 s22, v254, 6
	v_lshlrev_b64 v[98:99], 7, v[98:99]
	v_readlane_b32 s23, v254, 7
	v_lshlrev_b32_e32 v100, 1, v137
	v_mov_b32_e32 v101, v1
	v_lshl_add_u64 v[98:99], s[22:23], 0, v[98:99]
	v_lshl_add_u64 v[98:99], v[98:99], 0, v[100:101]
	v_lshlrev_b32_e32 v100, 1, v139
	s_mov_b32 s22, 0x3e8293ee
	v_lshl_add_u64 v[104:105], v[98:99], 0, v[100:101]
	v_pk_mul_f32 v[100:101], v[96:97], s[22:23] op_sel_hi:[1,0]
	v_pk_mul_f32 v[98:99], v[94:95], s[22:23] op_sel_hi:[1,0]
	v_pk_mul_f32 v[114:115], v[92:93], s[22:23] op_sel_hi:[1,0]
	v_pk_mul_f32 v[116:117], v[90:91], s[22:23] op_sel_hi:[1,0]
	v_cvt_pk_bf16_f32 v98, v98, v99
	v_cvt_pk_bf16_f32 v99, v100, v101
	v_cvt_pk_bf16_f32 v100, v116, v117
	v_cvt_pk_bf16_f32 v101, v114, v115
	global_store_dwordx4 v[104:105], v[98:101], off sc0 sc1

; __device__ __forceinline__ void store8bf(bf16_t* p, f32x4 v0, f32x4 v1) { u32x4 w; w.x = cvt_pk_bf16(v0[0], v0[1]); w.y = cvt_pk_bf16(v0[2], v0[3]); w.z = cvt_pk_bf16(v1[0], v1[1]); w.w = cvt_pk_bf16(v1[2], v1[3]); *(u32x4*)p = w; }
;   __device__ __forceinline__ void group(int row, int c32, int fq, f32x4 v0, f32x4 v1) const {
;     ...
;       if (c32 < 384) store8bf(cqkv + (size_t)row * 512 + c32 + fq * 8, v0, v1);
.LBB0_432:
	v_lshl_add_u64 v[104:105], v[0:1], 1, v[104:105]
	v_lshlrev_b32_e32 v114, 1, v139
	v_mov_b32_e32 v115, v1
	v_lshl_add_u64 v[104:105], v[104:105], 0, v[114:115]
	global_store_dwordx4 v[104:105], v[98:101], off offset:256 sc0 sc1

; __device__ __forceinline__ void store8bf(bf16_t* p, f32x4 v0, f32x4 v1) { u32x4 w; w.x = cvt_pk_bf16(v0[0], v0[1]); w.y = cvt_pk_bf16(v0[2], v0[3]); w.z = cvt_pk_bf16(v1[0], v1[1]); w.w = cvt_pk_bf16(v1[2], v1[3]); *(u32x4*)p = w; }
;   __device__ __forceinline__ void group(int row, int c32, int fq, f32x4 v0, f32x4 v1) const {
;     ...
;     else if (c32 < 1664) { const int cc = c32 - 1280, h = cc >> 6; store8bf(qs + ((size_t)(b * 6 + h) * E + e) * 64 + (cc & 63) + fq * 8, v0 * QSC_S, v1 * QSC_S); }
;     else if (c32 < 1792) { const int cc = c32 - 1664, g = cc >> 6; store8bf(ks + ((size_t)(b * 2 + g) * E + e) * 64 + (cc & 63) + fq * 8, v0, v1); }
.LBB0_446:
	s_andn2_b64 vcc, exec, s[42:43]
	s_cbranch_vccnz .LBB0_448
	v_lshl_add_u32 v99, v113, 1, v109
	v_mov_b32_e32 v103, v1
	s_movk_i32 s1, 0x2040
	v_mad_i64_i32 v[100:101], s[22:23], v99, s1, v[102:103]
	v_readlane_b32 s22, v254, 14
	v_lshlrev_b64 v[100:101], 7, v[100:101]
	v_readlane_b32 s23, v254, 15
	v_lshlrev_b32_e32 v104, 1, v137
	v_mov_b32_e32 v105, v1
	v_lshl_add_u64 v[100:101], s[22:23], 0, v[100:101]
	v_lshl_add_u64 v[100:101], v[100:101], 0, v[104:105]
	v_lshlrev_b32_e32 v104, 1, v139
	v_lshl_add_u64 v[100:101], v[100:101], 0, v[104:105]
	v_cvt_pk_bf16_f32 v114, v86, v87
	v_cvt_pk_bf16_f32 v115, v88, v89
	v_cvt_pk_bf16_f32 v116, v82, v83
	v_cvt_pk_bf16_f32 v117, v84, v85
	global_store_dwordx4 v[100:101], v[114:117], off sc0 sc1
.LBB0_448:
	s_andn2_saveexec_b64 s[42:43], s[24:25]
	s_cbranch_execz .LBB0_450
	v_mad_i32_i24 v99, v113, 6, v111
	v_mov_b32_e32 v103, v1
	s_movk_i32 s1, 0x2040
	v_mad_i64_i32 v[100:101], s[22:23], v99, s1, v[102:103]
	v_readlane_b32 s22, v254, 12
	v_lshlrev_b64 v[100:101], 7, v[100:101]
	v_readlane_b32 s23, v254, 13
	v_lshlrev_b32_e32 v104, 1, v137
	v_mov_b32_e32 v105, v1
	v_lshl_add_u64 v[100:101], s[22:23], 0, v[100:101]
	v_lshl_add_u64 v[100:101], v[100:101], 0, v[104:105]
	v_lshlrev_b32_e32 v104, 1, v139
	s_mov_b32 s22, 0x3e38aa3b
	v_lshl_add_u64 v[100:101], v[100:101], 0, v[104:105]
	v_pk_mul_f32 v[104:105], v[88:89], s[22:23] op_sel_hi:[1,0]
	v_pk_mul_f32 v[114:115], v[86:87], s[22:23] op_sel_hi:[1,0]
	v_pk_mul_f32 v[118:119], v[84:85], s[22:23] op_sel_hi:[1,0]
	v_pk_mul_f32 v[116:117], v[82:83], s[22:23] op_sel_hi:[1,0]
	v_cvt_pk_bf16_f32 v114, v114, v115
	v_cvt_pk_bf16_f32 v115, v104, v105
	v_cvt_pk_bf16_f32 v116, v116, v117
	v_cvt_pk_bf16_f32 v117, v118, v119
	global_store_dwordx4 v[100:101], v[114:117], off sc0 sc1

; __device__ __forceinline__ void store8bf(bf16_t* p, f32x4 v0, f32x4 v1) { u32x4 w; w.x = cvt_pk_bf16(v0[0], v0[1]); w.y = cvt_pk_bf16(v0[2], v0[3]); w.z = cvt_pk_bf16(v1[0], v1[1]); w.w = cvt_pk_bf16(v1[2], v1[3]); *(u32x4*)p = w; }
;   __device__ __forceinline__ void group(int row, int c32, int fq, f32x4 v0, f32x4 v1) const {
;     ...
;     else if (c32 < 1024) { const int cc = c32 - 768, h = cc >> 6; store8bf(kd + ((size_t)(b * 4 + h) * E + e) * 64 + (cc & 63) + fq * 8, v0, v1); }
.LBB0_454:
	s_andn2_b64 vcc, exec, s[42:43]
	s_cbranch_vccnz .LBB0_456
	v_lshl_add_u32 v99, v113, 2, v108
	v_mov_b32_e32 v103, v1
	s_movk_i32 s1, 0x2040
	v_mad_i64_i32 v[100:101], s[22:23], v99, s1, v[102:103]
	v_readlane_b32 s22, v254, 8
	v_lshlrev_b64 v[100:101], 7, v[100:101]
	v_readlane_b32 s23, v254, 9
	v_lshlrev_b32_e32 v104, 1, v137
	v_mov_b32_e32 v105, v1
	v_lshl_add_u64 v[100:101], s[22:23], 0, v[100:101]
	v_lshl_add_u64 v[100:101], v[100:101], 0, v[104:105]
	v_lshlrev_b32_e32 v104, 1, v139
	v_lshl_add_u64 v[100:101], v[100:101], 0, v[104:105]
	v_cvt_pk_bf16_f32 v114, v86, v87
	v_cvt_pk_bf16_f32 v115, v88, v89
	v_cvt_pk_bf16_f32 v116, v82, v83
	v_cvt_pk_bf16_f32 v117, v84, v85
	global_store_dwordx4 v[100:101], v[114:117], off sc0 sc1

; __device__ __forceinline__ void store8bf(bf16_t* p, f32x4 v0, f32x4 v1) { u32x4 w; w.x = cvt_pk_bf16(v0[0], v0[1]); w.y = cvt_pk_bf16(v0[2], v0[3]); w.z = cvt_pk_bf16(v1[0], v1[1]); w.w = cvt_pk_bf16(v1[2], v1[3]); *(u32x4*)p = w; }
;   __device__ __forceinline__ void group(int row, int c32, int fq, f32x4 v0, f32x4 v1) const {
;     ...
;     if (c32 < 768) { const int cc = c32 - 512, h = cc >> 6; store8bf(qd + ((size_t)(b * 4 + h) * E + e) * 64 + (cc & 63) + fq * 8, v0 * QSC_D, v1 * QSC_D); }
.LBB0_457:
	s_andn2_b64 vcc, exec, s[42:43]
	s_cbranch_vccnz .LBB0_459
	v_lshl_add_u32 v99, v113, 2, v107
	v_mov_b32_e32 v103, v1
	s_movk_i32 s1, 0x2040
	v_mad_i64_i32 v[100:101], s[22:23], v99, s1, v[102:103]
	v_readlane_b32 s22, v254, 6
	v_lshlrev_b64 v[100:101], 7, v[100:101]
	v_readlane_b32 s23, v254, 7
	v_lshlrev_b32_e32 v104, 1, v137
	v_mov_b32_e32 v105, v1
	v_lshl_add_u64 v[100:101], s[22:23], 0, v[100:101]
	v_lshl_add_u64 v[100:101], v[100:101], 0, v[104:105]
	v_lshlrev_b32_e32 v104, 1, v139
	s_mov_b32 s22, 0x3e8293ee
	v_lshl_add_u64 v[100:101], v[100:101], 0, v[104:105]
	v_pk_mul_f32 v[104:105], v[88:89], s[22:23] op_sel_hi:[1,0]
	v_pk_mul_f32 v[114:115], v[86:87], s[22:23] op_sel_hi:[1,0]
	v_pk_mul_f32 v[118:119], v[84:85], s[22:23] op_sel_hi:[1,0]
	v_pk_mul_f32 v[116:117], v[82:83], s[22:23] op_sel_hi:[1,0]
	v_cvt_pk_bf16_f32 v114, v114, v115
	v_cvt_pk_bf16_f32 v115, v104, v105
	v_cvt_pk_bf16_f32 v116, v116, v117
	v_cvt_pk_bf16_f32 v117, v118, v119
	global_store_dwordx4 v[100:101], v[114:117], off sc0 sc1

; __device__ __forceinline__ void store8bf(bf16_t* p, f32x4 v0, f32x4 v1) { u32x4 w; w.x = cvt_pk_bf16(v0[0], v0[1]); w.y = cvt_pk_bf16(v0[2], v0[3]); w.z = cvt_pk_bf16(v1[0], v1[1]); w.w = cvt_pk_bf16(v1[2], v1[3]); *(u32x4*)p = w; }
;   __device__ __forceinline__ void group(int row, int c32, int fq, f32x4 v0, f32x4 v1) const {
;     ...
;     else if (c32 < 1664) { const int cc = c32 - 1280, h = cc >> 6; store8bf(qs + ((size_t)(b * 6 + h) * E + e) * 64 + (cc & 63) + fq * 8, v0 * QSC_S, v1 * QSC_S); }
;     else if (c32 < 1792) { const int cc = c32 - 1664, g = cc >> 6; store8bf(ks + ((size_t)(b * 2 + g) * E + e) * 64 + (cc & 63) + fq * 8, v0, v1); }
.LBB0_477:
	s_andn2_b64 vcc, exec, s[42:43]
	s_cbranch_vccnz .LBB0_479
	v_lshl_add_u32 v99, v113, 1, v109
	v_mov_b32_e32 v103, v1
	s_movk_i32 s1, 0x2040
	v_mad_i64_i32 v[100:101], s[22:23], v99, s1, v[102:103]
	v_readlane_b32 s22, v254, 14
	v_lshlrev_b64 v[100:101], 7, v[100:101]
	v_readlane_b32 s23, v254, 15
	v_lshlrev_b32_e32 v104, 1, v137
	v_mov_b32_e32 v105, v1
	v_lshl_add_u64 v[100:101], s[22:23], 0, v[100:101]
	v_lshl_add_u64 v[100:101], v[100:101], 0, v[104:105]
	v_lshlrev_b32_e32 v104, 1, v139
	v_lshl_add_u64 v[100:101], v[100:101], 0, v[104:105]
	v_cvt_pk_bf16_f32 v114, v78, v79
	v_cvt_pk_bf16_f32 v115, v80, v81
	v_cvt_pk_bf16_f32 v116, v74, v75
	v_cvt_pk_bf16_f32 v117, v76, v77
	global_store_dwordx4 v[100:101], v[114:117], off sc0 sc1
.LBB0_479:
	s_andn2_saveexec_b64 s[42:43], s[24:25]
	s_cbranch_execz .LBB0_481
	v_mad_i32_i24 v99, v113, 6, v111
	v_mov_b32_e32 v103, v1
	s_movk_i32 s1, 0x2040
	v_mad_i64_i32 v[100:101], s[22:23], v99, s1, v[102:103]
	v_readlane_b32 s22, v254, 12
	v_lshlrev_b64 v[100:101], 7, v[100:101]
	v_readlane_b32 s23, v254, 13
	v_lshlrev_b32_e32 v104, 1, v137
	v_mov_b32_e32 v105, v1
	v_lshl_add_u64 v[100:101], s[22:23], 0, v[100:101]
	v_lshl_add_u64 v[100:101], v[100:101], 0, v[104:105]
	v_lshlrev_b32_e32 v104, 1, v139
	s_mov_b32 s22, 0x3e38aa3b
	v_lshl_add_u64 v[100:101], v[100:101], 0, v[104:105]
	v_pk_mul_f32 v[104:105], v[80:81], s[22:23] op_sel_hi:[1,0]
	v_pk_mul_f32 v[114:115], v[78:79], s[22:23] op_sel_hi:[1,0]
	v_pk_mul_f32 v[118:119], v[76:77], s[22:23] op_sel_hi:[1,0]
	v_pk_mul_f32 v[116:117], v[74:75], s[22:23] op_sel_hi:[1,0]
	v_cvt_pk_bf16_f32 v114, v114, v115
	v_cvt_pk_bf16_f32 v115, v104, v105
	v_cvt_pk_bf16_f32 v116, v116, v117
	v_cvt_pk_bf16_f32 v117, v118, v119
	global_store_dwordx4 v[100:101], v[114:117], off sc0 sc1

; __device__ __forceinline__ void store8bf(bf16_t* p, f32x4 v0, f32x4 v1) { u32x4 w; w.x = cvt_pk_bf16(v0[0], v0[1]); w.y = cvt_pk_bf16(v0[2], v0[3]); w.z = cvt_pk_bf16(v1[0], v1[1]); w.w = cvt_pk_bf16(v1[2], v1[3]); *(u32x4*)p = w; }
;   __device__ __forceinline__ void group(int row, int c32, int fq, f32x4 v0, f32x4 v1) const {
;     ...
;     else if (c32 < 1024) { const int cc = c32 - 768, h = cc >> 6; store8bf(kd + ((size_t)(b * 4 + h) * E + e) * 64 + (cc & 63) + fq * 8, v0, v1); }
.LBB0_485:
	s_andn2_b64 vcc, exec, s[42:43]
	s_cbranch_vccnz .LBB0_487
	v_lshl_add_u32 v99, v113, 2, v108
	v_mov_b32_e32 v103, v1
	s_movk_i32 s1, 0x2040
	v_mad_i64_i32 v[100:101], s[22:23], v99, s1, v[102:103]
	v_readlane_b32 s22, v254, 8
	v_lshlrev_b64 v[100:101], 7, v[100:101]
	v_readlane_b32 s23, v254, 9
	v_lshlrev_b32_e32 v104, 1, v137
	v_mov_b32_e32 v105, v1
	v_lshl_add_u64 v[100:101], s[22:23], 0, v[100:101]
	v_lshl_add_u64 v[100:101], v[100:101], 0, v[104:105]
	v_lshlrev_b32_e32 v104, 1, v139
	v_lshl_add_u64 v[100:101], v[100:101], 0, v[104:105]
	v_cvt_pk_bf16_f32 v114, v78, v79
	v_cvt_pk_bf16_f32 v115, v80, v81
	v_cvt_pk_bf16_f32 v116, v74, v75
	v_cvt_pk_bf16_f32 v117, v76, v77
	global_store_dwordx4 v[100:101], v[114:117], off sc0 sc1

; __device__ __forceinline__ void store8bf(bf16_t* p, f32x4 v0, f32x4 v1) { u32x4 w; w.x = cvt_pk_bf16(v0[0], v0[1]); w.y = cvt_pk_bf16(v0[2], v0[3]); w.z = cvt_pk_bf16(v1[0], v1[1]); w.w = cvt_pk_bf16(v1[2], v1[3]); *(u32x4*)p = w; }
;   __device__ __forceinline__ void group(int row, int c32, int fq, f32x4 v0, f32x4 v1) const {
;     ...
;     if (c32 < 768) { const int cc = c32 - 512, h = cc >> 6; store8bf(qd + ((size_t)(b * 4 + h) * E + e) * 64 + (cc & 63) + fq * 8, v0 * QSC_D, v1 * QSC_D); }
.LBB0_488:
	s_andn2_b64 vcc, exec, s[42:43]
	s_cbranch_vccnz .LBB0_490
	v_lshl_add_u32 v99, v113, 2, v107
	v_mov_b32_e32 v103, v1
	s_movk_i32 s1, 0x2040
	v_mad_i64_i32 v[100:101], s[22:23], v99, s1, v[102:103]
	v_readlane_b32 s22, v254, 6
	v_lshlrev_b64 v[100:101], 7, v[100:101]
	v_readlane_b32 s23, v254, 7
	v_lshlrev_b32_e32 v104, 1, v137
	v_mov_b32_e32 v105, v1
	v_lshl_add_u64 v[100:101], s[22:23], 0, v[100:101]
	v_lshl_add_u64 v[100:101], v[100:101], 0, v[104:105]
	v_lshlrev_b32_e32 v104, 1, v139
	s_mov_b32 s22, 0x3e8293ee
	v_lshl_add_u64 v[100:101], v[100:101], 0, v[104:105]
	v_pk_mul_f32 v[104:105], v[80:81], s[22:23] op_sel_hi:[1,0]
	v_pk_mul_f32 v[114:115], v[78:79], s[22:23] op_sel_hi:[1,0]
	v_pk_mul_f32 v[118:119], v[76:77], s[22:23] op_sel_hi:[1,0]
	v_pk_mul_f32 v[116:117], v[74:75], s[22:23] op_sel_hi:[1,0]
	v_cvt_pk_bf16_f32 v114, v114, v115
	v_cvt_pk_bf16_f32 v115, v104, v105
	v_cvt_pk_bf16_f32 v116, v116, v117
	v_cvt_pk_bf16_f32 v117, v118, v119
	global_store_dwordx4 v[100:101], v[114:117], off sc0 sc1

; __device__ __forceinline__ void store8bf(bf16_t* p, f32x4 v0, f32x4 v1) { u32x4 w; w.x = cvt_pk_bf16(v0[0], v0[1]); w.y = cvt_pk_bf16(v0[2], v0[3]); w.z = cvt_pk_bf16(v1[0], v1[1]); w.w = cvt_pk_bf16(v1[2], v1[3]); *(u32x4*)p = w; }
;   __device__ __forceinline__ void group(int row, int c32, int fq, f32x4 v0, f32x4 v1) const {
;     ...
;     else if (c32 < 1664) { const int cc = c32 - 1280, h = cc >> 6; store8bf(qs + ((size_t)(b * 6 + h) * E + e) * 64 + (cc & 63) + fq * 8, v0 * QSC_S, v1 * QSC_S); }
;     else if (c32 < 1792) { const int cc = c32 - 1664, g = cc >> 6; store8bf(ks + ((size_t)(b * 2 + g) * E + e) * 64 + (cc & 63) + fq * 8, v0, v1); }
.LBB0_508:
	s_andn2_b64 vcc, exec, s[24:25]
	s_cbranch_vccnz .LBB0_510
	v_lshl_add_u32 v99, v113, 1, v109
	v_mov_b32_e32 v103, v1
	s_movk_i32 s1, 0x2040
	v_mad_i64_i32 v[100:101], s[8:9], v99, s1, v[102:103]
	v_readlane_b32 s8, v254, 14
	v_lshlrev_b64 v[100:101], 7, v[100:101]
	v_readlane_b32 s9, v254, 15
	v_lshlrev_b32_e32 v104, 1, v137
	v_mov_b32_e32 v105, v1
	v_lshl_add_u64 v[100:101], s[8:9], 0, v[100:101]
	v_lshl_add_u64 v[100:101], v[100:101], 0, v[104:105]
	v_lshlrev_b32_e32 v104, 1, v139
	v_lshl_add_u64 v[100:101], v[100:101], 0, v[104:105]
	v_cvt_pk_bf16_f32 v114, v70, v71
	v_cvt_pk_bf16_f32 v115, v72, v73
	v_cvt_pk_bf16_f32 v116, v66, v67
	v_cvt_pk_bf16_f32 v117, v68, v69
	global_store_dwordx4 v[100:101], v[114:117], off sc0 sc1
.LBB0_510:
	s_andn2_saveexec_b64 s[8:9], s[10:11]
	s_cbranch_execz .LBB0_512
	v_mad_i32_i24 v99, v113, 6, v111
	v_mov_b32_e32 v103, v1
	s_movk_i32 s1, 0x2040
	v_mad_i64_i32 v[100:101], s[10:11], v99, s1, v[102:103]
	v_readlane_b32 s10, v254, 12
	v_lshlrev_b64 v[100:101], 7, v[100:101]
	v_readlane_b32 s11, v254, 13
	v_lshlrev_b32_e32 v104, 1, v137
	v_mov_b32_e32 v105, v1
	v_lshl_add_u64 v[100:101], s[10:11], 0, v[100:101]
	v_lshl_add_u64 v[100:101], v[100:101], 0, v[104:105]
	v_lshlrev_b32_e32 v104, 1, v139
	s_mov_b32 s10, 0x3e38aa3b
	v_lshl_add_u64 v[100:101], v[100:101], 0, v[104:105]
	v_pk_mul_f32 v[104:105], v[72:73], s[10:11] op_sel_hi:[1,0]
	v_pk_mul_f32 v[114:115], v[70:71], s[10:11] op_sel_hi:[1,0]
	v_pk_mul_f32 v[118:119], v[68:69], s[10:11] op_sel_hi:[1,0]
	v_pk_mul_f32 v[116:117], v[66:67], s[10:11] op_sel_hi:[1,0]
	v_cvt_pk_bf16_f32 v114, v114, v115
	v_cvt_pk_bf16_f32 v115, v104, v105
	v_cvt_pk_bf16_f32 v116, v116, v117
	v_cvt_pk_bf16_f32 v117, v118, v119
	global_store_dwordx4 v[100:101], v[114:117], off sc0 sc1

; __device__ __forceinline__ void store8bf(bf16_t* p, f32x4 v0, f32x4 v1) { u32x4 w; w.x = cvt_pk_bf16(v0[0], v0[1]); w.y = cvt_pk_bf16(v0[2], v0[3]); w.z = cvt_pk_bf16(v1[0], v1[1]); w.w = cvt_pk_bf16(v1[2], v1[3]); *(u32x4*)p = w; }
;   __device__ __forceinline__ void group(int row, int c32, int fq, f32x4 v0, f32x4 v1) const {
;     ...
;     else if (c32 < 1024) { const int cc = c32 - 768, h = cc >> 6; store8bf(kd + ((size_t)(b * 4 + h) * E + e) * 64 + (cc & 63) + fq * 8, v0, v1); }
.LBB0_516:
	s_andn2_b64 vcc, exec, s[40:41]
	s_cbranch_vccnz .LBB0_518
	v_lshl_add_u32 v99, v113, 2, v108
	v_mov_b32_e32 v103, v1
	s_movk_i32 s1, 0x2040
	v_mad_i64_i32 v[100:101], s[8:9], v99, s1, v[102:103]
	v_readlane_b32 s8, v254, 8
	v_lshlrev_b64 v[100:101], 7, v[100:101]
	v_readlane_b32 s9, v254, 9
	v_lshlrev_b32_e32 v104, 1, v137
	v_mov_b32_e32 v105, v1
	v_lshl_add_u64 v[100:101], s[8:9], 0, v[100:101]
	v_lshl_add_u64 v[100:101], v[100:101], 0, v[104:105]
	v_lshlrev_b32_e32 v104, 1, v139
	v_lshl_add_u64 v[100:101], v[100:101], 0, v[104:105]
	v_cvt_pk_bf16_f32 v114, v70, v71
	v_cvt_pk_bf16_f32 v115, v72, v73
	v_cvt_pk_bf16_f32 v116, v66, v67
	v_cvt_pk_bf16_f32 v117, v68, v69
	global_store_dwordx4 v[100:101], v[114:117], off sc0 sc1

; __device__ __forceinline__ void store8bf(bf16_t* p, f32x4 v0, f32x4 v1) { u32x4 w; w.x = cvt_pk_bf16(v0[0], v0[1]); w.y = cvt_pk_bf16(v0[2], v0[3]); w.z = cvt_pk_bf16(v1[0], v1[1]); w.w = cvt_pk_bf16(v1[2], v1[3]); *(u32x4*)p = w; }
;   __device__ __forceinline__ void group(int row, int c32, int fq, f32x4 v0, f32x4 v1) const {
;     ...
;     if (c32 < 768) { const int cc = c32 - 512, h = cc >> 6; store8bf(qd + ((size_t)(b * 4 + h) * E + e) * 64 + (cc & 63) + fq * 8, v0 * QSC_D, v1 * QSC_D); }
.LBB0_519:
	s_andn2_b64 vcc, exec, s[42:43]
	s_cbranch_vccnz .LBB0_521
	v_lshl_add_u32 v99, v113, 2, v107
	v_mov_b32_e32 v103, v1
	s_movk_i32 s1, 0x2040
	v_mad_i64_i32 v[100:101], s[8:9], v99, s1, v[102:103]
	v_readlane_b32 s8, v254, 6
	v_lshlrev_b64 v[100:101], 7, v[100:101]
	v_readlane_b32 s9, v254, 7
	v_lshlrev_b32_e32 v104, 1, v137
	v_mov_b32_e32 v105, v1
	v_lshl_add_u64 v[100:101], s[8:9], 0, v[100:101]
	v_lshl_add_u64 v[100:101], v[100:101], 0, v[104:105]
	v_lshlrev_b32_e32 v104, 1, v139
	s_mov_b32 s8, 0x3e8293ee
	v_lshl_add_u64 v[100:101], v[100:101], 0, v[104:105]
	v_pk_mul_f32 v[104:105], v[72:73], s[8:9] op_sel_hi:[1,0]
	v_pk_mul_f32 v[114:115], v[70:71], s[8:9] op_sel_hi:[1,0]
	v_pk_mul_f32 v[118:119], v[68:69], s[8:9] op_sel_hi:[1,0]
	v_pk_mul_f32 v[116:117], v[66:67], s[8:9] op_sel_hi:[1,0]
	v_cvt_pk_bf16_f32 v114, v114, v115
	v_cvt_pk_bf16_f32 v115, v104, v105
	v_cvt_pk_bf16_f32 v116, v116, v117
	v_cvt_pk_bf16_f32 v117, v118, v119
	global_store_dwordx4 v[100:101], v[114:117], off sc0 sc1

; #define LAS __attribute__((address_space(3)))
; __device__ __forceinline__ unsigned short f2bf(float f) { return (unsigned short)(cvt_pk_bf16(f, f) & 0xffffu); }
;   __device__ __forceinline__ bool vt_info(int c32, int b, bf16_t*& base) const { return e->vt_info(c32 + sh, b, base); }
;     ...
;     const ldsp_t T = (ldsp_t)lds_raw + (wid < 4 ? 32768 + wid * 4608 : 98304 + (wid - 4) * 4608);
; #pragma unroll
;     for (int ai = 0; ai < 2; ++ai)
; #pragma unroll
;       for (int bj = 0; bj < 2; ++bj) {
;         const int c32 = bcol + wc * 32 + bj * HALF, row0 = brow + ai * HALF + wr * 64;
;         int b0, e0; row_be(row0, b0, e0); bf16_t* vbase;
;         if (epi.vt_info(c32, b0, vbase)) {
; #pragma unroll
;           for (int m = 0; m < 4; ++m) { const float sc = epi.row_scale(row0 + m * 16 + fr);
; #pragma unroll
;             for (int n = 0; n < 2; ++n)
; #pragma unroll
;               for (int j = 0; j < 4; ++j) *(LAS bf16_t*)(T + (n * 16 + fq * 4 + j) * 144 + (m * 16 + fr) * 2) = f2bf(acc[ai][bj][m][n][j] * sc); }
;           asm volatile("s_waitcnt lgkmcnt(0)" ::: "memory");
; #pragma unroll
;           for (int q = 0; q < 4; ++q) { const int ch = lane + 64 * q, d = ch >> 3, ec = ch & 7;
;             *(u32x4*)(vbase + (size_t)d * E + e0 + ec * 8) = *(LAS const u32x4*)(T + d * 144 + ec * 16); }
;           asm volatile("s_waitcnt lgkmcnt(0)" ::: "memory");
.LBB0_530:
	s_and_b64 vcc, exec, s[14:15]
	s_cbranch_vccz .LBB0_532
	v_readlane_b32 s6, v254, 10
	v_cvt_pk_bf16_f32 v94, v94, s0
	v_cvt_pk_bf16_f32 v90, v90, s0
	v_cvt_pk_bf16_f32 v86, v86, s0
	v_cvt_pk_bf16_f32 v82, v82, s0
	v_cvt_pk_bf16_f32 v78, v78, s0
	v_cvt_pk_bf16_f32 v74, v74, s0
	v_cvt_pk_bf16_f32 v70, v70, s0
	v_cvt_pk_bf16_f32 v66, v66, s0
	v_lshl_or_b32 v98, v146, 2, v106
	v_readlane_b32 s7, v254, 11
	ds_write_b16 v143, v94
	v_cvt_pk_bf16_f32 v94, v95, s0
	ds_write_b16 v143, v90 offset:2304
	v_cvt_pk_bf16_f32 v90, v91, s0
	ds_write_b16 v143, v86 offset:32
	v_cvt_pk_bf16_f32 v86, v87, s0
	ds_write_b16 v143, v82 offset:2336
	v_cvt_pk_bf16_f32 v82, v83, s0
	ds_write_b16 v143, v78 offset:64
	v_cvt_pk_bf16_f32 v78, v79, s0
	ds_write_b16 v143, v74 offset:2368
	v_cvt_pk_bf16_f32 v74, v75, s0
	ds_write_b16 v143, v70 offset:96
	v_cvt_pk_bf16_f32 v70, v71, s0
	ds_write_b16 v143, v66 offset:2400
	v_cvt_pk_bf16_f32 v66, v67, s0
	v_ashrrev_i32_e32 v100, 31, v98
	v_lshl_or_b32 v101, v98, 6, v137
	v_mov_b64_e32 v[98:99], s[6:7]
	ds_write_b16 v143, v94 offset:144
	v_cvt_pk_bf16_f32 v94, v96, s0
	ds_write_b16 v143, v90 offset:2448
	v_cvt_pk_bf16_f32 v90, v92, s0
	ds_write_b16 v143, v86 offset:176
	v_cvt_pk_bf16_f32 v86, v88, s0
	ds_write_b16 v143, v82 offset:2480
	v_cvt_pk_bf16_f32 v82, v84, s0
	ds_write_b16 v143, v78 offset:208
	v_cvt_pk_bf16_f32 v78, v80, s0
	ds_write_b16 v143, v74 offset:2512
	v_cvt_pk_bf16_f32 v74, v76, s0
	ds_write_b16 v143, v70 offset:240
	v_cvt_pk_bf16_f32 v70, v72, s0
	ds_write_b16 v143, v66 offset:2544
	v_cvt_pk_bf16_f32 v66, v68, s0
	v_mad_u64_u32 v[98:99], s[6:7], v101, s95, v[98:99]
	ds_write_b16 v143, v94 offset:288
	v_cvt_pk_bf16_f32 v94, v97, s0
	ds_write_b16 v143, v90 offset:2592
	v_cvt_pk_bf16_f32 v90, v93, s0
	ds_write_b16 v143, v86 offset:320
	v_cvt_pk_bf16_f32 v86, v89, s0
	ds_write_b16 v143, v82 offset:2624
	v_cvt_pk_bf16_f32 v82, v85, s0
	ds_write_b16 v143, v78 offset:352
	v_cvt_pk_bf16_f32 v78, v81, s0
	ds_write_b16 v143, v74 offset:2656
	v_cvt_pk_bf16_f32 v74, v77, s0
	ds_write_b16 v143, v70 offset:384
	v_cvt_pk_bf16_f32 v70, v73, s0
	ds_write_b16 v143, v66 offset:2688
	v_cvt_pk_bf16_f32 v66, v69, s0
	v_mad_i32_i24 v99, v100, s95, v99
	ds_write_b16 v143, v94 offset:432
	ds_write_b16 v143, v90 offset:2736
	ds_write_b16 v143, v86 offset:464
	ds_write_b16 v143, v82 offset:2768
	ds_write_b16 v143, v78 offset:496
	ds_write_b16 v143, v74 offset:2800
	ds_write_b16 v143, v70 offset:528
	ds_write_b16 v143, v66 offset:2832
	v_mov_b32_e32 v135, v1
	s_waitcnt lgkmcnt(0)
	v_lshl_add_u64 v[66:67], v[98:99], 0, v[134:135]
	v_mov_b32_e32 v131, v1
	v_lshl_add_u64 v[70:71], v[66:67], 0, v[130:131]
	ds_read_b128 v[66:69], v141
	v_lshlrev_b32_e32 v72, 1, v142
	v_mov_b32_e32 v73, v1
	v_lshl_add_u64 v[74:75], v[70:71], 0, v[72:73]
	ds_read_b128 v[70:73], v141 offset:1152
	s_waitcnt lgkmcnt(0)
	global_store_dwordx4 v[74:75], v[66:69], off sc0 sc1
	s_nop 1
	v_add_co_u32_e32 v66, vcc, 0x20000, v74
	s_nop 1
	v_addc_co_u32_e32 v67, vcc, 0, v75, vcc
	global_store_dwordx4 v[66:67], v[70:73], off offset:1024 sc0 sc1
	ds_read_b128 v[66:69], v141 offset:2304
	ds_read_b128 v[70:73], v141 offset:3456
	v_add_co_u32_e32 v76, vcc, 0x40000, v74
	s_nop 1
	v_addc_co_u32_e32 v77, vcc, 0, v75, vcc
	s_waitcnt lgkmcnt(0)
	global_store_dwordx4 v[76:77], v[66:69], off offset:2048 sc0 sc1
	s_nop 1
	v_add_co_u32_e32 v66, vcc, 0x60000, v74
	s_nop 1
	v_addc_co_u32_e32 v67, vcc, 0, v75, vcc
	global_store_dwordx4 v[66:67], v[70:73], off offset:3072 sc0 sc1
	s_waitcnt lgkmcnt(0)

; __device__ __forceinline__ void store8bf(bf16_t* p, f32x4 v0, f32x4 v1) { u32x4 w; w.x = cvt_pk_bf16(v0[0], v0[1]); w.y = cvt_pk_bf16(v0[2], v0[3]); w.z = cvt_pk_bf16(v1[0], v1[1]); w.w = cvt_pk_bf16(v1[2], v1[3]); *(u32x4*)p = w; }
;   __device__ __forceinline__ void group(int row, int c32, int fq, f32x4 v0, f32x4 v1) const {
;     ...
;     else if (c32 < 1664) { const int cc = c32 - 1280, h = cc >> 6; store8bf(qs + ((size_t)(b * 6 + h) * E + e) * 64 + (cc & 63) + fq * 8, v0 * QSC_S, v1 * QSC_S); }
.LBB0_541:
	s_andn2_b64 vcc, exec, s[20:21]
	s_cbranch_vccnz .LBB0_543
	v_mad_i32_i24 v70, v67, 6, v77
	v_mov_b32_e32 v69, v1
	s_movk_i32 s1, 0x2040
	v_mad_i64_i32 v[70:71], s[20:21], v70, s1, v[68:69]
	v_readlane_b32 s20, v254, 12
	v_lshlrev_b64 v[70:71], 7, v[70:71]
	v_readlane_b32 s21, v254, 13
	v_lshlrev_b32_e32 v80, 1, v137
	v_mov_b32_e32 v81, v1
	v_lshl_add_u64 v[70:71], s[20:21], 0, v[70:71]
	v_lshl_add_u64 v[70:71], v[70:71], 0, v[80:81]
	v_lshlrev_b32_e32 v80, 1, v139
	s_mov_b32 s20, 0x3e38aa3b
	v_lshl_add_u64 v[70:71], v[70:71], 0, v[80:81]
	v_pk_mul_f32 v[82:83], v[64:65], s[20:21] op_sel_hi:[1,0]
	v_pk_mul_f32 v[80:81], v[62:63], s[20:21] op_sel_hi:[1,0]
	v_pk_mul_f32 v[84:85], v[60:61], s[20:21] op_sel_hi:[1,0]
	v_pk_mul_f32 v[86:87], v[58:59], s[20:21] op_sel_hi:[1,0]
	v_cvt_pk_bf16_f32 v80, v80, v81
	v_cvt_pk_bf16_f32 v81, v82, v83
	v_cvt_pk_bf16_f32 v82, v86, v87
	v_cvt_pk_bf16_f32 v83, v84, v85
	global_store_dwordx4 v[70:71], v[80:83], off sc0 sc1

; __device__ __forceinline__ void store8bf(bf16_t* p, f32x4 v0, f32x4 v1) { u32x4 w; w.x = cvt_pk_bf16(v0[0], v0[1]); w.y = cvt_pk_bf16(v0[2], v0[3]); w.z = cvt_pk_bf16(v1[0], v1[1]); w.w = cvt_pk_bf16(v1[2], v1[3]); *(u32x4*)p = w; }
;   __device__ __forceinline__ void group(int row, int c32, int fq, f32x4 v0, f32x4 v1) const {
;     ...
;     else if (c32 < 1024) { const int cc = c32 - 768, h = cc >> 6; store8bf(kd + ((size_t)(b * 4 + h) * E + e) * 64 + (cc & 63) + fq * 8, v0, v1); }
.LBB0_547:
	s_andn2_b64 vcc, exec, s[20:21]
	s_cbranch_vccnz .LBB0_549
	v_lshl_add_u32 v70, v67, 2, v75
	v_mov_b32_e32 v69, v1
	s_movk_i32 s1, 0x2040
	v_mad_i64_i32 v[70:71], s[20:21], v70, s1, v[68:69]
	v_readlane_b32 s20, v254, 8
	v_lshlrev_b64 v[70:71], 7, v[70:71]
	v_readlane_b32 s21, v254, 9
	v_lshlrev_b32_e32 v80, 1, v137
	v_mov_b32_e32 v81, v1
	v_lshl_add_u64 v[70:71], s[20:21], 0, v[70:71]
	v_lshl_add_u64 v[70:71], v[70:71], 0, v[80:81]
	v_lshlrev_b32_e32 v80, 1, v139
	v_lshl_add_u64 v[70:71], v[70:71], 0, v[80:81]
	v_cvt_pk_bf16_f32 v80, v62, v63
	v_cvt_pk_bf16_f32 v81, v64, v65
	v_cvt_pk_bf16_f32 v82, v58, v59
	v_cvt_pk_bf16_f32 v83, v60, v61
	global_store_dwordx4 v[70:71], v[80:83], off sc0 sc1

; __device__ __forceinline__ void store8bf(bf16_t* p, f32x4 v0, f32x4 v1) { u32x4 w; w.x = cvt_pk_bf16(v0[0], v0[1]); w.y = cvt_pk_bf16(v0[2], v0[3]); w.z = cvt_pk_bf16(v1[0], v1[1]); w.w = cvt_pk_bf16(v1[2], v1[3]); *(u32x4*)p = w; }
;   __device__ __forceinline__ void group(int row, int c32, int fq, f32x4 v0, f32x4 v1) const {
;     ...
;     if (c32 < 768) { const int cc = c32 - 512, h = cc >> 6; store8bf(qd + ((size_t)(b * 4 + h) * E + e) * 64 + (cc & 63) + fq * 8, v0 * QSC_D, v1 * QSC_D); }
.LBB0_550:
	s_andn2_b64 vcc, exec, s[20:21]
	s_cbranch_vccnz .LBB0_552
	v_lshl_add_u32 v67, v67, 2, v74
	v_mov_b32_e32 v69, v1
	s_movk_i32 s1, 0x2040
	v_mad_i64_i32 v[68:69], s[20:21], v67, s1, v[68:69]
	v_readlane_b32 s20, v254, 6
	v_lshlrev_b64 v[68:69], 7, v[68:69]
	v_readlane_b32 s21, v254, 7
	v_lshlrev_b32_e32 v70, 1, v137
	v_mov_b32_e32 v71, v1
	v_lshl_add_u64 v[68:69], s[20:21], 0, v[68:69]
	v_lshl_add_u64 v[68:69], v[68:69], 0, v[70:71]
	v_lshlrev_b32_e32 v70, 1, v139
	s_mov_b32 s20, 0x3e8293ee
	v_lshl_add_u64 v[80:81], v[68:69], 0, v[70:71]
	v_pk_mul_f32 v[70:71], v[64:65], s[20:21] op_sel_hi:[1,0]
	v_pk_mul_f32 v[68:69], v[62:63], s[20:21] op_sel_hi:[1,0]
	v_pk_mul_f32 v[82:83], v[60:61], s[20:21] op_sel_hi:[1,0]
	v_pk_mul_f32 v[84:85], v[58:59], s[20:21] op_sel_hi:[1,0]
	v_cvt_pk_bf16_f32 v68, v68, v69
	v_cvt_pk_bf16_f32 v69, v70, v71
	v_cvt_pk_bf16_f32 v70, v84, v85
	v_cvt_pk_bf16_f32 v71, v82, v83
	global_store_dwordx4 v[80:81], v[68:71], off sc0 sc1

; __device__ __forceinline__ void store8bf(bf16_t* p, f32x4 v0, f32x4 v1) { u32x4 w; w.x = cvt_pk_bf16(v0[0], v0[1]); w.y = cvt_pk_bf16(v0[2], v0[3]); w.z = cvt_pk_bf16(v1[0], v1[1]); w.w = cvt_pk_bf16(v1[2], v1[3]); *(u32x4*)p = w; }
;   __device__ __forceinline__ void group(int row, int c32, int fq, f32x4 v0, f32x4 v1) const {
;     ...
;       if (c32 < 384) store8bf(cqkv + (size_t)row * 512 + c32 + fq * 8, v0, v1);
.LBB0_553:
	s_andn2_b64 vcc, exec, s[8:9]
	s_cbranch_vccnz .LBB0_555
	v_ashrrev_i32_e32 v67, 31, v66
	v_readlane_b32 s8, v254, 0
	v_lshlrev_b64 v[68:69], 10, v[66:67]
	v_readlane_b32 s9, v254, 1
	v_lshlrev_b32_e32 v80, 1, v139
	v_mov_b32_e32 v81, v1
	v_lshl_add_u64 v[70:71], s[8:9], 0, v[68:69]
	v_lshl_add_u64 v[70:71], v[0:1], 1, v[70:71]
	v_cvt_pk_bf16_f32 v68, v62, v63
	v_cvt_pk_bf16_f32 v69, v64, v65
	v_lshl_add_u64 v[80:81], v[70:71], 0, v[80:81]
	v_cvt_pk_bf16_f32 v70, v58, v59
	v_cvt_pk_bf16_f32 v71, v60, v61
	global_store_dwordx4 v[80:81], v[68:71], off sc0 sc1

; __device__ __forceinline__ void store8bf(bf16_t* p, f32x4 v0, f32x4 v1) { u32x4 w; w.x = cvt_pk_bf16(v0[0], v0[1]); w.y = cvt_pk_bf16(v0[2], v0[3]); w.z = cvt_pk_bf16(v1[0], v1[1]); w.w = cvt_pk_bf16(v1[2], v1[3]); *(u32x4*)p = w; }
;   __device__ __forceinline__ void group(int row, int c32, int fq, f32x4 v0, f32x4 v1) const {
;     ...
;     else if (c32 < 1664) { const int cc = c32 - 1280, h = cc >> 6; store8bf(qs + ((size_t)(b * 6 + h) * E + e) * 64 + (cc & 63) + fq * 8, v0 * QSC_S, v1 * QSC_S); }
.LBB0_566:
	s_andn2_b64 vcc, exec, s[20:21]
	s_cbranch_vccnz .LBB0_568
	v_mad_i32_i24 v69, v67, 6, v77
	v_mov_b32_e32 v71, v1
	s_movk_i32 s1, 0x2040
	v_mad_i64_i32 v[80:81], s[20:21], v69, s1, v[70:71]
	v_readlane_b32 s20, v254, 12
	v_lshlrev_b64 v[80:81], 7, v[80:81]
	v_readlane_b32 s21, v254, 13
	v_lshlrev_b32_e32 v82, 1, v137
	v_mov_b32_e32 v83, v1
	v_lshl_add_u64 v[80:81], s[20:21], 0, v[80:81]
	v_lshl_add_u64 v[80:81], v[80:81], 0, v[82:83]
	v_lshlrev_b32_e32 v82, 1, v139
	s_mov_b32 s20, 0x3e38aa3b
	v_lshl_add_u64 v[84:85], v[80:81], 0, v[82:83]
	v_pk_mul_f32 v[82:83], v[56:57], s[20:21] op_sel_hi:[1,0]
	v_pk_mul_f32 v[80:81], v[54:55], s[20:21] op_sel_hi:[1,0]
	v_pk_mul_f32 v[86:87], v[52:53], s[20:21] op_sel_hi:[1,0]
	v_pk_mul_f32 v[88:89], v[50:51], s[20:21] op_sel_hi:[1,0]
	v_cvt_pk_bf16_f32 v80, v80, v81
	v_cvt_pk_bf16_f32 v81, v82, v83
	v_cvt_pk_bf16_f32 v82, v88, v89
	v_cvt_pk_bf16_f32 v83, v86, v87
	global_store_dwordx4 v[84:85], v[80:83], off sc0 sc1

; __device__ __forceinline__ void store8bf(bf16_t* p, f32x4 v0, f32x4 v1) { u32x4 w; w.x = cvt_pk_bf16(v0[0], v0[1]); w.y = cvt_pk_bf16(v0[2], v0[3]); w.z = cvt_pk_bf16(v1[0], v1[1]); w.w = cvt_pk_bf16(v1[2], v1[3]); *(u32x4*)p = w; }
;   __device__ __forceinline__ void group(int row, int c32, int fq, f32x4 v0, f32x4 v1) const {
;     ...
;     else if (c32 < 1024) { const int cc = c32 - 768, h = cc >> 6; store8bf(kd + ((size_t)(b * 4 + h) * E + e) * 64 + (cc & 63) + fq * 8, v0, v1); }
.LBB0_572:
	s_andn2_b64 vcc, exec, s[20:21]
	s_cbranch_vccnz .LBB0_574
	v_lshl_add_u32 v69, v67, 2, v75
	v_mov_b32_e32 v71, v1
	s_movk_i32 s1, 0x2040
	v_mad_i64_i32 v[80:81], s[20:21], v69, s1, v[70:71]
	v_readlane_b32 s20, v254, 8
	v_lshlrev_b64 v[80:81], 7, v[80:81]
	v_readlane_b32 s21, v254, 9
	v_lshlrev_b32_e32 v82, 1, v137
	v_mov_b32_e32 v83, v1
	v_lshl_add_u64 v[80:81], s[20:21], 0, v[80:81]
	v_lshl_add_u64 v[80:81], v[80:81], 0, v[82:83]
	v_lshlrev_b32_e32 v82, 1, v139
	v_lshl_add_u64 v[84:85], v[80:81], 0, v[82:83]
	v_cvt_pk_bf16_f32 v80, v54, v55
	v_cvt_pk_bf16_f32 v81, v56, v57
	v_cvt_pk_bf16_f32 v82, v50, v51
	v_cvt_pk_bf16_f32 v83, v52, v53
	global_store_dwordx4 v[84:85], v[80:83], off sc0 sc1

; __device__ __forceinline__ void store8bf(bf16_t* p, f32x4 v0, f32x4 v1) { u32x4 w; w.x = cvt_pk_bf16(v0[0], v0[1]); w.y = cvt_pk_bf16(v0[2], v0[3]); w.z = cvt_pk_bf16(v1[0], v1[1]); w.w = cvt_pk_bf16(v1[2], v1[3]); *(u32x4*)p = w; }
;   __device__ __forceinline__ void group(int row, int c32, int fq, f32x4 v0, f32x4 v1) const {
;     ...
;     if (c32 < 768) { const int cc = c32 - 512, h = cc >> 6; store8bf(qd + ((size_t)(b * 4 + h) * E + e) * 64 + (cc & 63) + fq * 8, v0 * QSC_D, v1 * QSC_D); }
.LBB0_575:
	s_andn2_b64 vcc, exec, s[20:21]
	s_cbranch_vccnz .LBB0_577
	v_lshl_add_u32 v67, v67, 2, v74
	v_mov_b32_e32 v71, v1
	s_movk_i32 s1, 0x2040
	v_mad_i64_i32 v[70:71], s[20:21], v67, s1, v[70:71]
	v_readlane_b32 s20, v254, 6
	v_lshlrev_b64 v[70:71], 7, v[70:71]
	v_readlane_b32 s21, v254, 7
	v_lshlrev_b32_e32 v80, 1, v137
	v_mov_b32_e32 v81, v1
	v_lshl_add_u64 v[70:71], s[20:21], 0, v[70:71]
	v_lshl_add_u64 v[70:71], v[70:71], 0, v[80:81]
	v_lshlrev_b32_e32 v80, 1, v139
	s_mov_b32 s20, 0x3e8293ee
	v_lshl_add_u64 v[70:71], v[70:71], 0, v[80:81]
	v_pk_mul_f32 v[82:83], v[56:57], s[20:21] op_sel_hi:[1,0]
	v_pk_mul_f32 v[80:81], v[54:55], s[20:21] op_sel_hi:[1,0]
	v_pk_mul_f32 v[84:85], v[52:53], s[20:21] op_sel_hi:[1,0]
	v_pk_mul_f32 v[86:87], v[50:51], s[20:21] op_sel_hi:[1,0]
	v_cvt_pk_bf16_f32 v80, v80, v81
	v_cvt_pk_bf16_f32 v81, v82, v83
	v_cvt_pk_bf16_f32 v82, v86, v87
	v_cvt_pk_bf16_f32 v83, v84, v85
	global_store_dwordx4 v[70:71], v[80:83], off sc0 sc1

; __device__ __forceinline__ void store8bf(bf16_t* p, f32x4 v0, f32x4 v1) { u32x4 w; w.x = cvt_pk_bf16(v0[0], v0[1]); w.y = cvt_pk_bf16(v0[2], v0[3]); w.z = cvt_pk_bf16(v1[0], v1[1]); w.w = cvt_pk_bf16(v1[2], v1[3]); *(u32x4*)p = w; }
;   __device__ __forceinline__ void group(int row, int c32, int fq, f32x4 v0, f32x4 v1) const {
;     ...
;       if (c32 < 384) store8bf(cqkv + (size_t)row * 512 + c32 + fq * 8, v0, v1);
.LBB0_578:
	s_andn2_b64 vcc, exec, s[18:19]
	s_cbranch_vccnz .LBB0_580
	v_ashrrev_i32_e32 v69, 31, v68
	v_readlane_b32 s18, v254, 0
	v_lshlrev_b64 v[68:69], 10, v[68:69]
	v_readlane_b32 s19, v254, 1
	v_lshlrev_b32_e32 v80, 1, v139
	v_mov_b32_e32 v81, v1
	v_lshl_add_u64 v[70:71], s[18:19], 0, v[68:69]
	v_lshl_add_u64 v[70:71], v[0:1], 1, v[70:71]
	v_cvt_pk_bf16_f32 v68, v54, v55
	v_cvt_pk_bf16_f32 v69, v56, v57
	v_lshl_add_u64 v[80:81], v[70:71], 0, v[80:81]
	v_cvt_pk_bf16_f32 v70, v50, v51
	v_cvt_pk_bf16_f32 v71, v52, v53
	global_store_dwordx4 v[80:81], v[68:71], off sc0 sc1

; __device__ __forceinline__ void store8bf(bf16_t* p, f32x4 v0, f32x4 v1) { u32x4 w; w.x = cvt_pk_bf16(v0[0], v0[1]); w.y = cvt_pk_bf16(v0[2], v0[3]); w.z = cvt_pk_bf16(v1[0], v1[1]); w.w = cvt_pk_bf16(v1[2], v1[3]); *(u32x4*)p = w; }
;   __device__ __forceinline__ void group(int row, int c32, int fq, f32x4 v0, f32x4 v1) const {
;     ...
;     else if (c32 < 1664) { const int cc = c32 - 1280, h = cc >> 6; store8bf(qs + ((size_t)(b * 6 + h) * E + e) * 64 + (cc & 63) + fq * 8, v0 * QSC_S, v1 * QSC_S); }
.LBB0_589:
	s_andn2_b64 vcc, exec, s[20:21]
	s_cbranch_vccnz .LBB0_591
	v_mad_i32_i24 v69, v67, 6, v77
	v_mov_b32_e32 v71, v1
	s_movk_i32 s1, 0x2040
	v_mad_i64_i32 v[80:81], s[20:21], v69, s1, v[70:71]
	v_readlane_b32 s20, v254, 12
	v_lshlrev_b64 v[80:81], 7, v[80:81]
	v_readlane_b32 s21, v254, 13
	v_lshlrev_b32_e32 v82, 1, v137
	v_mov_b32_e32 v83, v1
	v_lshl_add_u64 v[80:81], s[20:21], 0, v[80:81]
	v_lshl_add_u64 v[80:81], v[80:81], 0, v[82:83]
	v_lshlrev_b32_e32 v82, 1, v139
	s_mov_b32 s20, 0x3e38aa3b
	v_lshl_add_u64 v[84:85], v[80:81], 0, v[82:83]
	v_pk_mul_f32 v[82:83], v[48:49], s[20:21] op_sel_hi:[1,0]
	v_pk_mul_f32 v[80:81], v[46:47], s[20:21] op_sel_hi:[1,0]
	v_pk_mul_f32 v[86:87], v[44:45], s[20:21] op_sel_hi:[1,0]
	v_pk_mul_f32 v[88:89], v[42:43], s[20:21] op_sel_hi:[1,0]
	v_cvt_pk_bf16_f32 v80, v80, v81
	v_cvt_pk_bf16_f32 v81, v82, v83
	v_cvt_pk_bf16_f32 v82, v88, v89
	v_cvt_pk_bf16_f32 v83, v86, v87
	global_store_dwordx4 v[84:85], v[80:83], off sc0 sc1

; __device__ __forceinline__ void store8bf(bf16_t* p, f32x4 v0, f32x4 v1) { u32x4 w; w.x = cvt_pk_bf16(v0[0], v0[1]); w.y = cvt_pk_bf16(v0[2], v0[3]); w.z = cvt_pk_bf16(v1[0], v1[1]); w.w = cvt_pk_bf16(v1[2], v1[3]); *(u32x4*)p = w; }
;   __device__ __forceinline__ void group(int row, int c32, int fq, f32x4 v0, f32x4 v1) const {
;     ...
;     else if (c32 < 1024) { const int cc = c32 - 768, h = cc >> 6; store8bf(kd + ((size_t)(b * 4 + h) * E + e) * 64 + (cc & 63) + fq * 8, v0, v1); }
.LBB0_595:
	s_andn2_b64 vcc, exec, s[20:21]
	s_cbranch_vccnz .LBB0_597
	v_lshl_add_u32 v69, v67, 2, v75
	v_mov_b32_e32 v71, v1
	s_movk_i32 s1, 0x2040
	v_mad_i64_i32 v[80:81], s[20:21], v69, s1, v[70:71]
	v_readlane_b32 s20, v254, 8
	v_lshlrev_b64 v[80:81], 7, v[80:81]
	v_readlane_b32 s21, v254, 9
	v_lshlrev_b32_e32 v82, 1, v137
	v_mov_b32_e32 v83, v1
	v_lshl_add_u64 v[80:81], s[20:21], 0, v[80:81]
	v_lshl_add_u64 v[80:81], v[80:81], 0, v[82:83]
	v_lshlrev_b32_e32 v82, 1, v139
	v_lshl_add_u64 v[84:85], v[80:81], 0, v[82:83]
	v_cvt_pk_bf16_f32 v80, v46, v47
	v_cvt_pk_bf16_f32 v81, v48, v49
	v_cvt_pk_bf16_f32 v82, v42, v43
	v_cvt_pk_bf16_f32 v83, v44, v45
	global_store_dwordx4 v[84:85], v[80:83], off sc0 sc1

; __device__ __forceinline__ void store8bf(bf16_t* p, f32x4 v0, f32x4 v1) { u32x4 w; w.x = cvt_pk_bf16(v0[0], v0[1]); w.y = cvt_pk_bf16(v0[2], v0[3]); w.z = cvt_pk_bf16(v1[0], v1[1]); w.w = cvt_pk_bf16(v1[2], v1[3]); *(u32x4*)p = w; }
;   __device__ __forceinline__ void group(int row, int c32, int fq, f32x4 v0, f32x4 v1) const {
;     ...
;     if (c32 < 768) { const int cc = c32 - 512, h = cc >> 6; store8bf(qd + ((size_t)(b * 4 + h) * E + e) * 64 + (cc & 63) + fq * 8, v0 * QSC_D, v1 * QSC_D); }
.LBB0_598:
	s_andn2_b64 vcc, exec, s[20:21]
	s_cbranch_vccnz .LBB0_600
	v_lshl_add_u32 v67, v67, 2, v74
	v_mov_b32_e32 v71, v1
	s_movk_i32 s1, 0x2040
	v_mad_i64_i32 v[70:71], s[20:21], v67, s1, v[70:71]
	v_readlane_b32 s20, v254, 6
	v_lshlrev_b64 v[70:71], 7, v[70:71]
	v_readlane_b32 s21, v254, 7
	v_lshlrev_b32_e32 v80, 1, v137
	v_mov_b32_e32 v81, v1
	v_lshl_add_u64 v[70:71], s[20:21], 0, v[70:71]
	v_lshl_add_u64 v[70:71], v[70:71], 0, v[80:81]
	v_lshlrev_b32_e32 v80, 1, v139
	s_mov_b32 s20, 0x3e8293ee
	v_lshl_add_u64 v[70:71], v[70:71], 0, v[80:81]
	v_pk_mul_f32 v[82:83], v[48:49], s[20:21] op_sel_hi:[1,0]
	v_pk_mul_f32 v[80:81], v[46:47], s[20:21] op_sel_hi:[1,0]
	v_pk_mul_f32 v[84:85], v[44:45], s[20:21] op_sel_hi:[1,0]
	v_pk_mul_f32 v[86:87], v[42:43], s[20:21] op_sel_hi:[1,0]
	v_cvt_pk_bf16_f32 v80, v80, v81
	v_cvt_pk_bf16_f32 v81, v82, v83
	v_cvt_pk_bf16_f32 v82, v86, v87
	v_cvt_pk_bf16_f32 v83, v84, v85
	global_store_dwordx4 v[70:71], v[80:83], off sc0 sc1

; __device__ __forceinline__ void store8bf(bf16_t* p, f32x4 v0, f32x4 v1) { u32x4 w; w.x = cvt_pk_bf16(v0[0], v0[1]); w.y = cvt_pk_bf16(v0[2], v0[3]); w.z = cvt_pk_bf16(v1[0], v1[1]); w.w = cvt_pk_bf16(v1[2], v1[3]); *(u32x4*)p = w; }
;   __device__ __forceinline__ void group(int row, int c32, int fq, f32x4 v0, f32x4 v1) const {
;     ...
;     else if (c32 < 1664) { const int cc = c32 - 1280, h = cc >> 6; store8bf(qs + ((size_t)(b * 6 + h) * E + e) * 64 + (cc & 63) + fq * 8, v0 * QSC_S, v1 * QSC_S); }
.LBB0_608:
	s_andn2_b64 vcc, exec, s[10:11]
	s_cbranch_vccnz .LBB0_610
	v_mad_i32_i24 v69, v67, 6, v77
	v_mov_b32_e32 v71, v1
	s_movk_i32 s1, 0x2040
	v_mad_i64_i32 v[78:79], s[10:11], v69, s1, v[70:71]
	v_readlane_b32 s10, v254, 12
	v_lshlrev_b64 v[78:79], 7, v[78:79]
	v_readlane_b32 s11, v254, 13
	v_lshlrev_b32_e32 v80, 1, v137
	v_mov_b32_e32 v81, v1
	v_lshl_add_u64 v[78:79], s[10:11], 0, v[78:79]
	v_lshl_add_u64 v[78:79], v[78:79], 0, v[80:81]
	v_lshlrev_b32_e32 v80, 1, v139
	s_mov_b32 s10, 0x3e38aa3b
	v_lshl_add_u64 v[82:83], v[78:79], 0, v[80:81]
	v_pk_mul_f32 v[80:81], v[40:41], s[10:11] op_sel_hi:[1,0]
	v_pk_mul_f32 v[78:79], v[38:39], s[10:11] op_sel_hi:[1,0]
	v_pk_mul_f32 v[84:85], v[36:37], s[10:11] op_sel_hi:[1,0]
	v_pk_mul_f32 v[86:87], v[34:35], s[10:11] op_sel_hi:[1,0]
	v_cvt_pk_bf16_f32 v78, v78, v79
	v_cvt_pk_bf16_f32 v79, v80, v81
	v_cvt_pk_bf16_f32 v80, v86, v87
	v_cvt_pk_bf16_f32 v81, v84, v85
	global_store_dwordx4 v[82:83], v[78:81], off sc0 sc1

; __device__ __forceinline__ void store8bf(bf16_t* p, f32x4 v0, f32x4 v1) { u32x4 w; w.x = cvt_pk_bf16(v0[0], v0[1]); w.y = cvt_pk_bf16(v0[2], v0[3]); w.z = cvt_pk_bf16(v1[0], v1[1]); w.w = cvt_pk_bf16(v1[2], v1[3]); *(u32x4*)p = w; }
;   __device__ __forceinline__ void group(int row, int c32, int fq, f32x4 v0, f32x4 v1) const {
;     ...
;     else if (c32 < 1024) { const int cc = c32 - 768, h = cc >> 6; store8bf(kd + ((size_t)(b * 4 + h) * E + e) * 64 + (cc & 63) + fq * 8, v0, v1); }
.LBB0_614:
	s_andn2_b64 vcc, exec, s[14:15]
	s_cbranch_vccnz .LBB0_616
	v_lshl_add_u32 v69, v67, 2, v75
	v_mov_b32_e32 v71, v1
	s_movk_i32 s1, 0x2040
	v_mad_i64_i32 v[76:77], s[10:11], v69, s1, v[70:71]
	v_readlane_b32 s10, v254, 8
	v_lshlrev_b64 v[76:77], 7, v[76:77]
	v_readlane_b32 s11, v254, 9
	v_lshlrev_b32_e32 v78, 1, v137
	v_mov_b32_e32 v79, v1
	v_lshl_add_u64 v[76:77], s[10:11], 0, v[76:77]
	v_lshl_add_u64 v[76:77], v[76:77], 0, v[78:79]
	v_lshlrev_b32_e32 v78, 1, v139
	v_lshl_add_u64 v[80:81], v[76:77], 0, v[78:79]
	v_cvt_pk_bf16_f32 v76, v38, v39
	v_cvt_pk_bf16_f32 v77, v40, v41
	v_cvt_pk_bf16_f32 v78, v34, v35
	v_cvt_pk_bf16_f32 v79, v36, v37
	global_store_dwordx4 v[80:81], v[76:79], off sc0 sc1

; __device__ __forceinline__ void store8bf(bf16_t* p, f32x4 v0, f32x4 v1) { u32x4 w; w.x = cvt_pk_bf16(v0[0], v0[1]); w.y = cvt_pk_bf16(v0[2], v0[3]); w.z = cvt_pk_bf16(v1[0], v1[1]); w.w = cvt_pk_bf16(v1[2], v1[3]); *(u32x4*)p = w; }
;   __device__ __forceinline__ void group(int row, int c32, int fq, f32x4 v0, f32x4 v1) const {
;     ...
;     if (c32 < 768) { const int cc = c32 - 512, h = cc >> 6; store8bf(qd + ((size_t)(b * 4 + h) * E + e) * 64 + (cc & 63) + fq * 8, v0 * QSC_D, v1 * QSC_D); }
.LBB0_617:
	s_andn2_b64 vcc, exec, s[16:17]
	s_cbranch_vccnz .LBB0_619
	v_lshl_add_u32 v67, v67, 2, v74
	v_mov_b32_e32 v71, v1
	s_movk_i32 s1, 0x2040
	v_mad_i64_i32 v[70:71], s[10:11], v67, s1, v[70:71]
	v_readlane_b32 s10, v254, 6
	v_lshlrev_b64 v[70:71], 7, v[70:71]
	v_readlane_b32 s11, v254, 7
	v_lshlrev_b32_e32 v74, 1, v137
	v_mov_b32_e32 v75, v1
	v_lshl_add_u64 v[70:71], s[10:11], 0, v[70:71]
	v_lshl_add_u64 v[70:71], v[70:71], 0, v[74:75]
	v_lshlrev_b32_e32 v74, 1, v139
	s_mov_b32 s10, 0x3e8293ee
	v_lshl_add_u64 v[70:71], v[70:71], 0, v[74:75]
	v_pk_mul_f32 v[76:77], v[40:41], s[10:11] op_sel_hi:[1,0]
	v_pk_mul_f32 v[74:75], v[38:39], s[10:11] op_sel_hi:[1,0]
	v_pk_mul_f32 v[78:79], v[36:37], s[10:11] op_sel_hi:[1,0]
	v_pk_mul_f32 v[80:81], v[34:35], s[10:11] op_sel_hi:[1,0]
	v_cvt_pk_bf16_f32 v74, v74, v75
	v_cvt_pk_bf16_f32 v75, v76, v77
	v_cvt_pk_bf16_f32 v76, v80, v81
	v_cvt_pk_bf16_f32 v77, v78, v79
	global_store_dwordx4 v[70:71], v[74:77], off sc0 sc1

; __device__ __forceinline__ void store8bf(bf16_t* p, f32x4 v0, f32x4 v1) { u32x4 w; w.x = cvt_pk_bf16(v0[0], v0[1]); w.y = cvt_pk_bf16(v0[2], v0[3]); w.z = cvt_pk_bf16(v1[0], v1[1]); w.w = cvt_pk_bf16(v1[2], v1[3]); *(u32x4*)p = w; }
;     ...
;     for (int ai = 0; ai < 2; ++ai)
; #pragma unroll
;       for (int m = 0; m < 4; ++m)
;         epi(brow + ai * HALF + wr * 64 + m * 16 + fr, bcol + wc * 32, fq, acc[ai][0][m][0], acc[ai][0][m][1], acc[ai][1][m][0], acc[ai][1][m][1]);
;   __device__ __forceinline__ void group(int row, int c32, int fq, f32x4 v0, f32x4 v1) const {
;     ...
;       if (c32 < 384) store8bf(cqkv + (size_t)row * 512 + c32 + fq * 8, v0, v1);
.LBB0_624:
	v_ashrrev_i32_e32 v69, 31, v68
	v_readlane_b32 s18, v254, 0
	v_lshlrev_b64 v[68:69], 10, v[68:69]
	v_readlane_b32 s19, v254, 1
	v_lshlrev_b32_e32 v80, 1, v139
	v_mov_b32_e32 v81, v1
	v_lshl_add_u64 v[70:71], s[18:19], 0, v[68:69]
	v_lshl_add_u64 v[70:71], v[0:1], 1, v[70:71]
	v_cvt_pk_bf16_f32 v68, v46, v47
	v_cvt_pk_bf16_f32 v69, v48, v49
	v_lshl_add_u64 v[80:81], v[70:71], 0, v[80:81]
	v_cvt_pk_bf16_f32 v70, v42, v43
	v_cvt_pk_bf16_f32 v71, v44, v45
	global_store_dwordx4 v[80:81], v[68:71], off sc0 sc1
	s_nop 1
	v_or_b32_e32 v68, 48, v66
	s_and_b64 vcc, exec, s[8:9]
	s_mov_b64 s[8:9], -1
	s_cbranch_vccz .LBB0_602

; __device__ __forceinline__ void store8bf(bf16_t* p, f32x4 v0, f32x4 v1) { u32x4 w; w.x = cvt_pk_bf16(v0[0], v0[1]); w.y = cvt_pk_bf16(v0[2], v0[3]); w.z = cvt_pk_bf16(v1[0], v1[1]); w.w = cvt_pk_bf16(v1[2], v1[3]); *(u32x4*)p = w; }
;   __device__ __forceinline__ void group(int row, int c32, int fq, f32x4 v0, f32x4 v1) const {
;     ...
;       if (c32 < 384) store8bf(cqkv + (size_t)row * 512 + c32 + fq * 8, v0, v1);
.LBB0_626:
	v_ashrrev_i32_e32 v69, 31, v68
	v_readlane_b32 s8, v254, 0
	v_lshlrev_b64 v[68:69], 10, v[68:69]
	v_readlane_b32 s9, v254, 1
	v_lshlrev_b32_e32 v74, 1, v139
	v_mov_b32_e32 v75, v1
	v_lshl_add_u64 v[70:71], s[8:9], 0, v[68:69]
	v_lshl_add_u64 v[70:71], v[0:1], 1, v[70:71]
	v_cvt_pk_bf16_f32 v68, v38, v39
	v_cvt_pk_bf16_f32 v69, v40, v41
	v_lshl_add_u64 v[74:75], v[70:71], 0, v[74:75]
	v_cvt_pk_bf16_f32 v70, v34, v35
	v_cvt_pk_bf16_f32 v71, v36, v37
	global_store_dwordx4 v[74:75], v[68:71], off sc0 sc1

; #define LAS __attribute__((address_space(3)))
; __device__ __forceinline__ unsigned short f2bf(float f) { return (unsigned short)(cvt_pk_bf16(f, f) & 0xffffu); }
;   __device__ __forceinline__ bool vt_info(int c32, int b, bf16_t*& base) const { return e->vt_info(c32 + sh, b, base); }
;     ...
;         const int c32 = bcol + wc * 32 + bj * HALF, row0 = brow + ai * HALF + wr * 64;
;         int b0, e0; row_be(row0, b0, e0); bf16_t* vbase;
;         if (epi.vt_info(c32, b0, vbase)) {
; #pragma unroll
;           for (int m = 0; m < 4; ++m) { const float sc = epi.row_scale(row0 + m * 16 + fr);
; #pragma unroll
;             for (int n = 0; n < 2; ++n)
; #pragma unroll
;               for (int j = 0; j < 4; ++j) *(LAS bf16_t*)(T + (n * 16 + fq * 4 + j) * 144 + (m * 16 + fr) * 2) = f2bf(acc[ai][bj][m][n][j] * sc); }
;           asm volatile("s_waitcnt lgkmcnt(0)" ::: "memory");
; #pragma unroll
;           for (int q = 0; q < 4; ++q) { const int ch = lane + 64 * q, d = ch >> 3, ec = ch & 7;
;             *(u32x4*)(vbase + (size_t)d * E + e0 + ec * 8) = *(LAS const u32x4*)(T + d * 144 + ec * 16); }
;           asm volatile("s_waitcnt lgkmcnt(0)" ::: "memory");
.LBB0_629:
	v_and_b32_e32 v67, 0x1fc0, v73
	v_add_u32_e32 v67, 64, v67
	v_cndmask_b32_e64 v67, 0, v67, s[6:7]
	v_cndmask_b32_e64 v70, 0, v72, s[6:7]
	s_and_b64 vcc, exec, s[20:21]
	v_lshlrev_b32_e32 v68, 1, v67
	s_cbranch_vccz .LBB0_633
	v_add_u32_e32 v67, s10, v0
	v_readlane_b32 s12, v253, 16
	v_lshrrev_b32_e32 v67, 6, v67
	v_readlane_b32 s18, v253, 22
	v_lshl_add_u32 v74, v70, s1, v67
	v_readlane_b32 s19, v253, 23
	s_add_u32 s6, s18, s8
	v_ashrrev_i32_e32 v75, 31, v74
	v_cvt_pk_bf16_f32 v62, v62, s0
	v_cvt_pk_bf16_f32 v58, v58, s0
	v_cvt_pk_bf16_f32 v54, v54, s0
	v_cvt_pk_bf16_f32 v50, v50, s0
	v_cvt_pk_bf16_f32 v46, v46, s0
	v_cvt_pk_bf16_f32 v42, v42, s0
	v_cvt_pk_bf16_f32 v38, v38, s0
	v_cvt_pk_bf16_f32 v34, v34, s0
	s_addc_u32 s7, s19, s9
	v_lshlrev_b64 v[74:75], 6, v[74:75]
	ds_write_b16 v143, v62
	v_cvt_pk_bf16_f32 v62, v63, s0
	ds_write_b16 v143, v58 offset:2304
	v_cvt_pk_bf16_f32 v58, v59, s0
	ds_write_b16 v143, v54 offset:32
	v_cvt_pk_bf16_f32 v54, v55, s0
	ds_write_b16 v143, v50 offset:2336
	v_cvt_pk_bf16_f32 v50, v51, s0
	ds_write_b16 v143, v46 offset:64
	v_cvt_pk_bf16_f32 v46, v47, s0
	ds_write_b16 v143, v42 offset:2368
	v_cvt_pk_bf16_f32 v42, v43, s0
	ds_write_b16 v143, v38 offset:96
	v_cvt_pk_bf16_f32 v38, v39, s0
	ds_write_b16 v143, v34 offset:2400
	v_cvt_pk_bf16_f32 v34, v35, s0
	v_or_b32_e32 v67, v74, v137
	v_mov_b64_e32 v[76:77], s[6:7]
	ds_write_b16 v143, v62 offset:144
	v_cvt_pk_bf16_f32 v62, v64, s0
	ds_write_b16 v143, v58 offset:2448
	v_cvt_pk_bf16_f32 v58, v60, s0
	ds_write_b16 v143, v54 offset:176
	v_cvt_pk_bf16_f32 v54, v56, s0
	ds_write_b16 v143, v50 offset:2480
	v_cvt_pk_bf16_f32 v50, v52, s0
	ds_write_b16 v143, v46 offset:208
	v_cvt_pk_bf16_f32 v46, v48, s0
	ds_write_b16 v143, v42 offset:2512
	v_cvt_pk_bf16_f32 v42, v44, s0
	ds_write_b16 v143, v38 offset:240
	v_cvt_pk_bf16_f32 v38, v40, s0
	ds_write_b16 v143, v34 offset:2544
	v_cvt_pk_bf16_f32 v34, v36, s0
	v_mad_u64_u32 v[76:77], s[6:7], v67, s95, v[76:77]
	ds_write_b16 v143, v62 offset:288
	v_cvt_pk_bf16_f32 v62, v65, s0
	ds_write_b16 v143, v58 offset:2592
	v_cvt_pk_bf16_f32 v58, v61, s0
	ds_write_b16 v143, v54 offset:320
	v_cvt_pk_bf16_f32 v54, v57, s0
	ds_write_b16 v143, v50 offset:2624
	v_cvt_pk_bf16_f32 v50, v53, s0
	ds_write_b16 v143, v46 offset:352
	v_cvt_pk_bf16_f32 v46, v49, s0
	ds_write_b16 v143, v42 offset:2656
	v_cvt_pk_bf16_f32 v42, v45, s0
	ds_write_b16 v143, v38 offset:384
	v_cvt_pk_bf16_f32 v38, v41, s0
	ds_write_b16 v143, v34 offset:2688
	v_cvt_pk_bf16_f32 v34, v37, s0
	v_mad_i32_i24 v77, v75, s95, v77
	ds_write_b16 v143, v62 offset:432
	ds_write_b16 v143, v58 offset:2736
	ds_write_b16 v143, v54 offset:464
	ds_write_b16 v143, v50 offset:2768
	ds_write_b16 v143, v46 offset:496
	ds_write_b16 v143, v42 offset:2800
	ds_write_b16 v143, v38 offset:528
	ds_write_b16 v143, v34 offset:2832
	v_mov_b32_e32 v69, v1
	s_waitcnt lgkmcnt(0)
	v_lshl_add_u64 v[34:35], v[76:77], 0, v[68:69]
	v_mov_b32_e32 v131, v1
	v_lshl_add_u64 v[38:39], v[34:35], 0, v[130:131]
	ds_read_b128 v[34:37], v141
	v_lshlrev_b32_e32 v40, 1, v142
	v_mov_b32_e32 v41, v1
	v_lshl_add_u64 v[42:43], v[38:39], 0, v[40:41]
	ds_read_b128 v[38:41], v141 offset:1152
	s_waitcnt lgkmcnt(0)
	global_store_dwordx4 v[42:43], v[34:37], off sc0 sc1
	v_readlane_b32 s13, v253, 17
	v_readlane_b32 s14, v253, 18
	v_add_co_u32_e32 v34, vcc, 0x20000, v42
	v_readlane_b32 s15, v253, 19
	s_nop 0
	v_addc_co_u32_e32 v35, vcc, 0, v43, vcc
	global_store_dwordx4 v[34:35], v[38:41], off offset:1024 sc0 sc1
	ds_read_b128 v[34:37], v141 offset:2304
	ds_read_b128 v[38:41], v141 offset:3456
	v_add_co_u32_e32 v44, vcc, 0x40000, v42
	v_readlane_b32 s16, v253, 20
	s_nop 0
	v_addc_co_u32_e32 v45, vcc, 0, v43, vcc
	s_waitcnt lgkmcnt(0)
	global_store_dwordx4 v[44:45], v[34:37], off offset:2048 sc0 sc1
	v_readlane_b32 s17, v253, 21
	s_nop 0
	v_add_co_u32_e32 v34, vcc, 0x60000, v42
	s_nop 1
	v_addc_co_u32_e32 v35, vcc, 0, v43, vcc
	global_store_dwordx4 v[34:35], v[38:41], off offset:3072 sc0 sc1
	s_waitcnt lgkmcnt(0)
	s_and_b64 vcc, exec, s[4:5]
	s_mov_b64 s[4:5], -1
	s_cbranch_vccz .LBB0_634
; #define LAS __attribute__((address_space(3)))
; __device__ __forceinline__ unsigned short f2bf(float f) { return (unsigned short)(cvt_pk_bf16(f, f) & 0xffffu); }
;   __device__ __forceinline__ bool vt_info(int c32, int b, bf16_t*& base) const { return e->vt_info(c32 + sh, b, base); }
;     ...
;         const int c32 = bcol + wc * 32 + bj * HALF, row0 = brow + ai * HALF + wr * 64;
;         int b0, e0; row_be(row0, b0, e0); bf16_t* vbase;
;         if (epi.vt_info(c32, b0, vbase)) {
; #pragma unroll
;           for (int m = 0; m < 4; ++m) { const float sc = epi.row_scale(row0 + m * 16 + fr);
; #pragma unroll
;             for (int n = 0; n < 2; ++n)
; #pragma unroll
;               for (int j = 0; j < 4; ++j) *(LAS bf16_t*)(T + (n * 16 + fq * 4 + j) * 144 + (m * 16 + fr) * 2) = f2bf(acc[ai][bj][m][n][j] * sc); }
;           asm volatile("s_waitcnt lgkmcnt(0)" ::: "memory");
; #pragma unroll
;           for (int q = 0; q < 4; ++q) { const int ch = lane + 64 * q, d = ch >> 3, ec = ch & 7;
;             *(u32x4*)(vbase + (size_t)d * E + e0 + ec * 8) = *(LAS const u32x4*)(T + d * 144 + ec * 16); }
;           asm volatile("s_waitcnt lgkmcnt(0)" ::: "memory");
.LBB0_631:
	s_and_b64 vcc, exec, s[4:5]
	s_cbranch_vccz .LBB0_759
	v_readlane_b32 s0, v254, 10
	v_lshl_or_b32 v0, v70, 2, v106
	v_readlane_b32 s1, v254, 11
	v_ashrrev_i32_e32 v36, 31, v0
	v_lshl_or_b32 v0, v0, 6, v137
	v_mov_b64_e32 v[34:35], s[0:1]
	v_mad_u64_u32 v[34:35], s[0:1], v0, s95, v[34:35]
	v_mad_i32_i24 v35, v36, s95, v35
	s_nop 0
	v_cvt_pk_bf16_f32 v0, v30, s0
	ds_write_b16 v143, v0
	v_cvt_pk_bf16_f32 v0, v31, s0
	ds_write_b16 v143, v0 offset:144
	v_cvt_pk_bf16_f32 v0, v32, s0
	ds_write_b16 v143, v0 offset:288
	v_cvt_pk_bf16_f32 v0, v33, s0
	ds_write_b16 v143, v0 offset:432
	v_cvt_pk_bf16_f32 v0, v26, s0
	ds_write_b16 v143, v0 offset:2304
	v_cvt_pk_bf16_f32 v0, v27, s0
	ds_write_b16 v143, v0 offset:2448
	v_cvt_pk_bf16_f32 v0, v28, s0
	ds_write_b16 v143, v0 offset:2592
	v_cvt_pk_bf16_f32 v0, v29, s0
	ds_write_b16 v143, v0 offset:2736
	v_cvt_pk_bf16_f32 v0, v22, s0
	ds_write_b16 v143, v0 offset:32
	v_cvt_pk_bf16_f32 v0, v23, s0
	ds_write_b16 v143, v0 offset:176
	v_cvt_pk_bf16_f32 v0, v24, s0
	ds_write_b16 v143, v0 offset:320
	v_cvt_pk_bf16_f32 v0, v25, s0
	ds_write_b16 v143, v0 offset:464
	v_cvt_pk_bf16_f32 v0, v18, s0
	ds_write_b16 v143, v0 offset:2336
	v_cvt_pk_bf16_f32 v0, v19, s0
	ds_write_b16 v143, v0 offset:2480
	v_cvt_pk_bf16_f32 v0, v20, s0
	ds_write_b16 v143, v0 offset:2624
	v_cvt_pk_bf16_f32 v0, v21, s0
	ds_write_b16 v143, v0 offset:2768
	v_cvt_pk_bf16_f32 v0, v14, s0
	ds_write_b16 v143, v0 offset:64
	v_cvt_pk_bf16_f32 v0, v15, s0
	ds_write_b16 v143, v0 offset:208
	v_cvt_pk_bf16_f32 v0, v16, s0
	ds_write_b16 v143, v0 offset:352
	v_cvt_pk_bf16_f32 v0, v17, s0
	ds_write_b16 v143, v0 offset:496
	v_cvt_pk_bf16_f32 v0, v10, s0
	ds_write_b16 v143, v0 offset:2368
	v_cvt_pk_bf16_f32 v0, v11, s0
	ds_write_b16 v143, v0 offset:2512
	v_cvt_pk_bf16_f32 v0, v12, s0
	ds_write_b16 v143, v0 offset:2656
	v_cvt_pk_bf16_f32 v0, v13, s0
	ds_write_b16 v143, v0 offset:2800
	v_cvt_pk_bf16_f32 v0, v6, s0
	ds_write_b16 v143, v0 offset:96
	v_cvt_pk_bf16_f32 v0, v7, s0
	ds_write_b16 v143, v0 offset:240
	v_cvt_pk_bf16_f32 v0, v8, s0
	ds_write_b16 v143, v0 offset:384
	v_cvt_pk_bf16_f32 v0, v9, s0
	ds_write_b16 v143, v0 offset:528
	v_cvt_pk_bf16_f32 v0, v2, s0
	ds_write_b16 v143, v0 offset:2400
	v_cvt_pk_bf16_f32 v0, v3, s0
	ds_write_b16 v143, v0 offset:2544
	v_cvt_pk_bf16_f32 v0, v4, s0
	ds_write_b16 v143, v0 offset:2688
	v_cvt_pk_bf16_f32 v0, v5, s0
	ds_write_b16 v143, v0 offset:2832
	s_waitcnt lgkmcnt(0)
	v_mov_b32_e32 v69, v1
	v_lshl_add_u64 v[6:7], v[34:35], 0, v[68:69]
	v_mov_b32_e32 v131, v1
	ds_read_b128 v[2:5], v141
	v_lshl_add_u64 v[6:7], v[6:7], 0, v[130:131]
	v_lshlrev_b32_e32 v0, 1, v142
	v_lshl_add_u64 v[10:11], v[6:7], 0, v[0:1]
	ds_read_b128 v[6:9], v141 offset:1152
	s_waitcnt lgkmcnt(0)
	global_store_dwordx4 v[10:11], v[2:5], off sc0 sc1
	s_nop 1
	v_add_co_u32_e32 v2, vcc, 0x20000, v10
	s_nop 1
	v_addc_co_u32_e32 v3, vcc, 0, v11, vcc
	global_store_dwordx4 v[2:3], v[6:9], off offset:1024 sc0 sc1
	ds_read_b128 v[2:5], v141 offset:2304
	ds_read_b128 v[6:9], v141 offset:3456
	v_add_co_u32_e32 v12, vcc, 0x40000, v10
	s_nop 1
	v_addc_co_u32_e32 v13, vcc, 0, v11, vcc
	s_waitcnt lgkmcnt(0)
	global_store_dwordx4 v[12:13], v[2:5], off offset:2048 sc0 sc1
	s_nop 1
	v_add_co_u32_e32 v2, vcc, 0x60000, v10
	s_nop 1
	v_addc_co_u32_e32 v3, vcc, 0, v11, vcc
	global_store_dwordx4 v[2:3], v[6:9], off offset:3072 sc0 sc1
	s_waitcnt lgkmcnt(0)
	v_cndmask_b32_e64 v0, 0, 1, s[2:3]
	v_cmp_ne_u32_e64 s[4:5], 1, v0
	s_andn2_b64 vcc, exec, s[2:3]
	s_cbranch_vccnz .LBB0_300
	s_branch .LBB0_760

; __device__ __forceinline__ void store8bf(bf16_t* p, f32x4 v0, f32x4 v1) { u32x4 w; w.x = cvt_pk_bf16(v0[0], v0[1]); w.y = cvt_pk_bf16(v0[2], v0[3]); w.z = cvt_pk_bf16(v1[0], v1[1]); w.w = cvt_pk_bf16(v1[2], v1[3]); *(u32x4*)p = w; }
;   __device__ __forceinline__ void group(int row, int c32, int fq, f32x4 v0, f32x4 v1) const {
;     ...
;     else if (c32 < 1664) { const int cc = c32 - 1280, h = cc >> 6; store8bf(qs + ((size_t)(b * 6 + h) * E + e) * 64 + (cc & 63) + fq * 8, v0 * QSC_S, v1 * QSC_S); }
;     else if (c32 < 1792) { const int cc = c32 - 1664, g = cc >> 6; store8bf(ks + ((size_t)(b * 2 + g) * E + e) * 64 + (cc & 63) + fq * 8, v0, v1); }
.LBB0_644:
	s_andn2_b64 vcc, exec, s[42:43]
	s_cbranch_vccnz .LBB0_646
	v_lshl_add_u32 v34, v42, 1, v109
	v_mov_b32_e32 v39, v1
	s_movk_i32 s0, 0x2040
	v_mad_i64_i32 v[34:35], s[0:1], v34, s0, v[38:39]
	v_readlane_b32 s0, v254, 14
	v_lshlrev_b64 v[34:35], 7, v[34:35]
	v_readlane_b32 s1, v254, 15
	v_lshlrev_b32_e32 v36, 1, v137
	v_mov_b32_e32 v37, v1
	v_lshl_add_u64 v[34:35], s[0:1], 0, v[34:35]
	v_lshl_add_u64 v[34:35], v[34:35], 0, v[36:37]
	v_lshlrev_b32_e32 v36, 1, v139
	v_lshl_add_u64 v[40:41], v[34:35], 0, v[36:37]
	v_cvt_pk_bf16_f32 v34, v30, v31
	v_cvt_pk_bf16_f32 v35, v32, v33
	v_cvt_pk_bf16_f32 v36, v26, v27
	v_cvt_pk_bf16_f32 v37, v28, v29
	global_store_dwordx4 v[40:41], v[34:37], off sc0 sc1
.LBB0_646:
	s_andn2_saveexec_b64 s[42:43], s[68:69]
	s_cbranch_execz .LBB0_648
	v_mad_i32_i24 v34, v42, 6, v111
	v_mov_b32_e32 v39, v1
	s_movk_i32 s0, 0x2040
	v_mad_i64_i32 v[34:35], s[0:1], v34, s0, v[38:39]
	v_readlane_b32 s0, v254, 12
	v_lshlrev_b64 v[34:35], 7, v[34:35]
	v_readlane_b32 s1, v254, 13
	v_lshlrev_b32_e32 v36, 1, v137
	v_mov_b32_e32 v37, v1
	v_lshl_add_u64 v[34:35], s[0:1], 0, v[34:35]
	v_lshl_add_u64 v[34:35], v[34:35], 0, v[36:37]
	v_lshlrev_b32_e32 v36, 1, v139
	s_mov_b32 s0, 0x3e38aa3b
	v_lshl_add_u64 v[40:41], v[34:35], 0, v[36:37]
	v_pk_mul_f32 v[36:37], v[32:33], s[0:1] op_sel_hi:[1,0]
	v_pk_mul_f32 v[34:35], v[30:31], s[0:1] op_sel_hi:[1,0]
	v_pk_mul_f32 v[44:45], v[28:29], s[0:1] op_sel_hi:[1,0]
	v_pk_mul_f32 v[46:47], v[26:27], s[0:1] op_sel_hi:[1,0]
	v_cvt_pk_bf16_f32 v34, v34, v35
	v_cvt_pk_bf16_f32 v35, v36, v37
	v_cvt_pk_bf16_f32 v36, v46, v47
	v_cvt_pk_bf16_f32 v37, v44, v45
	global_store_dwordx4 v[40:41], v[34:37], off sc0 sc1

; __device__ __forceinline__ void store8bf(bf16_t* p, f32x4 v0, f32x4 v1) { u32x4 w; w.x = cvt_pk_bf16(v0[0], v0[1]); w.y = cvt_pk_bf16(v0[2], v0[3]); w.z = cvt_pk_bf16(v1[0], v1[1]); w.w = cvt_pk_bf16(v1[2], v1[3]); *(u32x4*)p = w; }
;   __device__ __forceinline__ void group(int row, int c32, int fq, f32x4 v0, f32x4 v1) const {
;     ...
;     else if (c32 < 1024) { const int cc = c32 - 768, h = cc >> 6; store8bf(kd + ((size_t)(b * 4 + h) * E + e) * 64 + (cc & 63) + fq * 8, v0, v1); }
.LBB0_652:
	s_andn2_b64 vcc, exec, s[42:43]
	s_cbranch_vccnz .LBB0_654
	v_lshl_add_u32 v34, v42, 2, v108
	v_mov_b32_e32 v39, v1
	s_movk_i32 s0, 0x2040
	v_mad_i64_i32 v[34:35], s[0:1], v34, s0, v[38:39]
	v_readlane_b32 s0, v254, 8
	v_lshlrev_b64 v[34:35], 7, v[34:35]
	v_readlane_b32 s1, v254, 9
	v_lshlrev_b32_e32 v36, 1, v137
	v_mov_b32_e32 v37, v1
	v_lshl_add_u64 v[34:35], s[0:1], 0, v[34:35]
	v_lshl_add_u64 v[34:35], v[34:35], 0, v[36:37]
	v_lshlrev_b32_e32 v36, 1, v139
	v_lshl_add_u64 v[40:41], v[34:35], 0, v[36:37]
	v_cvt_pk_bf16_f32 v34, v30, v31
	v_cvt_pk_bf16_f32 v35, v32, v33
	v_cvt_pk_bf16_f32 v36, v26, v27
	v_cvt_pk_bf16_f32 v37, v28, v29
	global_store_dwordx4 v[40:41], v[34:37], off sc0 sc1

; __device__ __forceinline__ void store8bf(bf16_t* p, f32x4 v0, f32x4 v1) { u32x4 w; w.x = cvt_pk_bf16(v0[0], v0[1]); w.y = cvt_pk_bf16(v0[2], v0[3]); w.z = cvt_pk_bf16(v1[0], v1[1]); w.w = cvt_pk_bf16(v1[2], v1[3]); *(u32x4*)p = w; }
;   __device__ __forceinline__ void group(int row, int c32, int fq, f32x4 v0, f32x4 v1) const {
;     ...
;     if (c32 < 768) { const int cc = c32 - 512, h = cc >> 6; store8bf(qd + ((size_t)(b * 4 + h) * E + e) * 64 + (cc & 63) + fq * 8, v0 * QSC_D, v1 * QSC_D); }
.LBB0_655:
	s_andn2_b64 vcc, exec, s[42:43]
	s_cbranch_vccnz .LBB0_657
	v_lshl_add_u32 v34, v42, 2, v107
	v_mov_b32_e32 v39, v1
	s_movk_i32 s0, 0x2040
	v_mad_i64_i32 v[34:35], s[0:1], v34, s0, v[38:39]
	v_readlane_b32 s0, v254, 6
	v_lshlrev_b64 v[34:35], 7, v[34:35]
	v_readlane_b32 s1, v254, 7
	v_lshlrev_b32_e32 v36, 1, v137
	v_mov_b32_e32 v37, v1
	v_lshl_add_u64 v[34:35], s[0:1], 0, v[34:35]
	v_lshl_add_u64 v[34:35], v[34:35], 0, v[36:37]
	v_lshlrev_b32_e32 v36, 1, v139
	s_mov_b32 s0, 0x3e8293ee
	v_lshl_add_u64 v[40:41], v[34:35], 0, v[36:37]
	v_pk_mul_f32 v[36:37], v[32:33], s[0:1] op_sel_hi:[1,0]
	v_pk_mul_f32 v[34:35], v[30:31], s[0:1] op_sel_hi:[1,0]
	v_pk_mul_f32 v[44:45], v[28:29], s[0:1] op_sel_hi:[1,0]
	v_pk_mul_f32 v[46:47], v[26:27], s[0:1] op_sel_hi:[1,0]
	v_cvt_pk_bf16_f32 v34, v34, v35
	v_cvt_pk_bf16_f32 v35, v36, v37
	v_cvt_pk_bf16_f32 v36, v46, v47
	v_cvt_pk_bf16_f32 v37, v44, v45
	global_store_dwordx4 v[40:41], v[34:37], off sc0 sc1

; __device__ __forceinline__ void store8bf(bf16_t* p, f32x4 v0, f32x4 v1) { u32x4 w; w.x = cvt_pk_bf16(v0[0], v0[1]); w.y = cvt_pk_bf16(v0[2], v0[3]); w.z = cvt_pk_bf16(v1[0], v1[1]); w.w = cvt_pk_bf16(v1[2], v1[3]); *(u32x4*)p = w; }
;   __device__ __forceinline__ void operator()(int row, int cb, int fq, f32x4 a, f32x4 b, f32x4 c, f32x4 d) const { group(row, cb, fq, a, b); group(row, cb + 128, fq, c, d); }
;   __device__ __forceinline__ void group(int row, int c32, int fq, f32x4 v0, f32x4 v1) const { e->group(row, c32 + sh, fq, v0, v1); }
;   __device__ __forceinline__ void group(int row, int c32, int fq, f32x4 v0, f32x4 v1) const {
;     ...
;       if (c32 < 384) store8bf(cqkv + (size_t)row * 512 + c32 + fq * 8, v0, v1);
;   __device__ __forceinline__ void operator()(int row, int cb, int fq, f32x4 a, f32x4 b, f32x4 c, f32x4 d) const { group(row, cb, fq, a, b); group(row, cb + 128, fq, c, d); }
.LBB0_661:
	v_lshl_add_u64 v[40:41], v[0:1], 1, v[40:41]
	v_lshlrev_b32_e32 v44, 1, v139
	v_mov_b32_e32 v45, v1
	v_lshl_add_u64 v[40:41], v[40:41], 0, v[44:45]
	global_store_dwordx4 v[40:41], v[34:37], off offset:256 sc0 sc1

; __device__ __forceinline__ void store8bf(bf16_t* p, f32x4 v0, f32x4 v1) { u32x4 w; w.x = cvt_pk_bf16(v0[0], v0[1]); w.y = cvt_pk_bf16(v0[2], v0[3]); w.z = cvt_pk_bf16(v1[0], v1[1]); w.w = cvt_pk_bf16(v1[2], v1[3]); *(u32x4*)p = w; }
;   __device__ __forceinline__ void group(int row, int c32, int fq, f32x4 v0, f32x4 v1) const {
;     ...
;     else if (c32 < 1664) { const int cc = c32 - 1280, h = cc >> 6; store8bf(qs + ((size_t)(b * 6 + h) * E + e) * 64 + (cc & 63) + fq * 8, v0 * QSC_S, v1 * QSC_S); }
;     else if (c32 < 1792) { const int cc = c32 - 1664, g = cc >> 6; store8bf(ks + ((size_t)(b * 2 + g) * E + e) * 64 + (cc & 63) + fq * 8, v0, v1); }
.LBB0_675:
	s_andn2_b64 vcc, exec, s[42:43]
	s_cbranch_vccnz .LBB0_677
	v_lshl_add_u32 v35, v42, 1, v109
	v_mov_b32_e32 v39, v1
	s_movk_i32 s0, 0x2040
	v_mad_i64_i32 v[36:37], s[0:1], v35, s0, v[38:39]
	v_readlane_b32 s0, v254, 14
	v_lshlrev_b64 v[36:37], 7, v[36:37]
	v_readlane_b32 s1, v254, 15
	v_lshlrev_b32_e32 v40, 1, v137
	v_mov_b32_e32 v41, v1
	v_lshl_add_u64 v[36:37], s[0:1], 0, v[36:37]
	v_lshl_add_u64 v[36:37], v[36:37], 0, v[40:41]
	v_lshlrev_b32_e32 v40, 1, v139
	v_lshl_add_u64 v[36:37], v[36:37], 0, v[40:41]
	v_cvt_pk_bf16_f32 v44, v22, v23
	v_cvt_pk_bf16_f32 v45, v24, v25
	v_cvt_pk_bf16_f32 v46, v18, v19
	v_cvt_pk_bf16_f32 v47, v20, v21
	global_store_dwordx4 v[36:37], v[44:47], off sc0 sc1
.LBB0_677:
	s_andn2_saveexec_b64 s[42:43], s[68:69]
	s_cbranch_execz .LBB0_679
	v_mad_i32_i24 v35, v42, 6, v111
	v_mov_b32_e32 v39, v1
	s_movk_i32 s0, 0x2040
	v_mad_i64_i32 v[36:37], s[0:1], v35, s0, v[38:39]
	v_readlane_b32 s0, v254, 12
	v_lshlrev_b64 v[36:37], 7, v[36:37]
	v_readlane_b32 s1, v254, 13
	v_lshlrev_b32_e32 v40, 1, v137
	v_mov_b32_e32 v41, v1
	v_lshl_add_u64 v[36:37], s[0:1], 0, v[36:37]
	v_lshl_add_u64 v[36:37], v[36:37], 0, v[40:41]
	v_lshlrev_b32_e32 v40, 1, v139
	s_mov_b32 s0, 0x3e38aa3b
	v_lshl_add_u64 v[36:37], v[36:37], 0, v[40:41]
	v_pk_mul_f32 v[40:41], v[24:25], s[0:1] op_sel_hi:[1,0]
	v_pk_mul_f32 v[44:45], v[22:23], s[0:1] op_sel_hi:[1,0]
	v_pk_mul_f32 v[48:49], v[20:21], s[0:1] op_sel_hi:[1,0]
	v_pk_mul_f32 v[46:47], v[18:19], s[0:1] op_sel_hi:[1,0]
	v_cvt_pk_bf16_f32 v44, v44, v45
	v_cvt_pk_bf16_f32 v45, v40, v41
	v_cvt_pk_bf16_f32 v46, v46, v47
	v_cvt_pk_bf16_f32 v47, v48, v49
	global_store_dwordx4 v[36:37], v[44:47], off sc0 sc1

; __device__ __forceinline__ void store8bf(bf16_t* p, f32x4 v0, f32x4 v1) { u32x4 w; w.x = cvt_pk_bf16(v0[0], v0[1]); w.y = cvt_pk_bf16(v0[2], v0[3]); w.z = cvt_pk_bf16(v1[0], v1[1]); w.w = cvt_pk_bf16(v1[2], v1[3]); *(u32x4*)p = w; }
;   __device__ __forceinline__ void group(int row, int c32, int fq, f32x4 v0, f32x4 v1) const {
;     ...
;     else if (c32 < 1024) { const int cc = c32 - 768, h = cc >> 6; store8bf(kd + ((size_t)(b * 4 + h) * E + e) * 64 + (cc & 63) + fq * 8, v0, v1); }
.LBB0_683:
	s_andn2_b64 vcc, exec, s[42:43]
	s_cbranch_vccnz .LBB0_685
	v_lshl_add_u32 v35, v42, 2, v108
	v_mov_b32_e32 v39, v1
	s_movk_i32 s0, 0x2040
	v_mad_i64_i32 v[36:37], s[0:1], v35, s0, v[38:39]
	v_readlane_b32 s0, v254, 8
	v_lshlrev_b64 v[36:37], 7, v[36:37]
	v_readlane_b32 s1, v254, 9
	v_lshlrev_b32_e32 v40, 1, v137
	v_mov_b32_e32 v41, v1
	v_lshl_add_u64 v[36:37], s[0:1], 0, v[36:37]
	v_lshl_add_u64 v[36:37], v[36:37], 0, v[40:41]
	v_lshlrev_b32_e32 v40, 1, v139
	v_lshl_add_u64 v[36:37], v[36:37], 0, v[40:41]
	v_cvt_pk_bf16_f32 v44, v22, v23
	v_cvt_pk_bf16_f32 v45, v24, v25
	v_cvt_pk_bf16_f32 v46, v18, v19
	v_cvt_pk_bf16_f32 v47, v20, v21
	global_store_dwordx4 v[36:37], v[44:47], off sc0 sc1

; __device__ __forceinline__ void store8bf(bf16_t* p, f32x4 v0, f32x4 v1) { u32x4 w; w.x = cvt_pk_bf16(v0[0], v0[1]); w.y = cvt_pk_bf16(v0[2], v0[3]); w.z = cvt_pk_bf16(v1[0], v1[1]); w.w = cvt_pk_bf16(v1[2], v1[3]); *(u32x4*)p = w; }
;   __device__ __forceinline__ void group(int row, int c32, int fq, f32x4 v0, f32x4 v1) const {
;     ...
;     if (c32 < 768) { const int cc = c32 - 512, h = cc >> 6; store8bf(qd + ((size_t)(b * 4 + h) * E + e) * 64 + (cc & 63) + fq * 8, v0 * QSC_D, v1 * QSC_D); }
.LBB0_686:
	s_andn2_b64 vcc, exec, s[42:43]
	s_cbranch_vccnz .LBB0_688
	v_lshl_add_u32 v35, v42, 2, v107
	v_mov_b32_e32 v39, v1
	s_movk_i32 s0, 0x2040
	v_mad_i64_i32 v[36:37], s[0:1], v35, s0, v[38:39]
	v_readlane_b32 s0, v254, 6
	v_lshlrev_b64 v[36:37], 7, v[36:37]
	v_readlane_b32 s1, v254, 7
	v_lshlrev_b32_e32 v40, 1, v137
	v_mov_b32_e32 v41, v1
	v_lshl_add_u64 v[36:37], s[0:1], 0, v[36:37]
	v_lshl_add_u64 v[36:37], v[36:37], 0, v[40:41]
	v_lshlrev_b32_e32 v40, 1, v139
	s_mov_b32 s0, 0x3e8293ee
	v_lshl_add_u64 v[36:37], v[36:37], 0, v[40:41]
	v_pk_mul_f32 v[40:41], v[24:25], s[0:1] op_sel_hi:[1,0]
	v_pk_mul_f32 v[44:45], v[22:23], s[0:1] op_sel_hi:[1,0]
	v_pk_mul_f32 v[48:49], v[20:21], s[0:1] op_sel_hi:[1,0]
	v_pk_mul_f32 v[46:47], v[18:19], s[0:1] op_sel_hi:[1,0]
	v_cvt_pk_bf16_f32 v44, v44, v45
	v_cvt_pk_bf16_f32 v45, v40, v41
	v_cvt_pk_bf16_f32 v46, v46, v47
	v_cvt_pk_bf16_f32 v47, v48, v49
	global_store_dwordx4 v[36:37], v[44:47], off sc0 sc1

; __device__ __forceinline__ void store8bf(bf16_t* p, f32x4 v0, f32x4 v1) { u32x4 w; w.x = cvt_pk_bf16(v0[0], v0[1]); w.y = cvt_pk_bf16(v0[2], v0[3]); w.z = cvt_pk_bf16(v1[0], v1[1]); w.w = cvt_pk_bf16(v1[2], v1[3]); *(u32x4*)p = w; }
;   __device__ __forceinline__ void operator()(int row, int cb, int fq, f32x4 a, f32x4 b, f32x4 c, f32x4 d) const { group(row, cb, fq, a, b); group(row, cb + 128, fq, c, d); }
;   __device__ __forceinline__ void group(int row, int c32, int fq, f32x4 v0, f32x4 v1) const { e->group(row, c32 + sh, fq, v0, v1); }
;   __device__ __forceinline__ void group(int row, int c32, int fq, f32x4 v0, f32x4 v1) const {
;     ...
;       if (c32 < 384) store8bf(cqkv + (size_t)row * 512 + c32 + fq * 8, v0, v1);
;   __device__ __forceinline__ void operator()(int row, int cb, int fq, f32x4 a, f32x4 b, f32x4 c, f32x4 d) const { group(row, cb, fq, a, b); group(row, cb + 128, fq, c, d); }
.LBB0_692:
	v_mov_b32_e32 v44, v0
	v_mov_b32_e32 v45, v1
	v_lshl_add_u64 v[40:41], v[44:45], 1, v[40:41]
	v_lshlrev_b32_e32 v44, 1, v139
	v_lshl_add_u64 v[40:41], v[40:41], 0, v[44:45]
	global_store_dwordx4 v[40:41], v[34:37], off offset:256 sc0 sc1

; __device__ __forceinline__ void store8bf(bf16_t* p, f32x4 v0, f32x4 v1) { u32x4 w; w.x = cvt_pk_bf16(v0[0], v0[1]); w.y = cvt_pk_bf16(v0[2], v0[3]); w.z = cvt_pk_bf16(v1[0], v1[1]); w.w = cvt_pk_bf16(v1[2], v1[3]); *(u32x4*)p = w; }
;   __device__ __forceinline__ void group(int row, int c32, int fq, f32x4 v0, f32x4 v1) const {
;     ...
;     else if (c32 < 1664) { const int cc = c32 - 1280, h = cc >> 6; store8bf(qs + ((size_t)(b * 6 + h) * E + e) * 64 + (cc & 63) + fq * 8, v0 * QSC_S, v1 * QSC_S); }
;     else if (c32 < 1792) { const int cc = c32 - 1664, g = cc >> 6; store8bf(ks + ((size_t)(b * 2 + g) * E + e) * 64 + (cc & 63) + fq * 8, v0, v1); }
.LBB0_706:
	s_andn2_b64 vcc, exec, s[42:43]
	s_cbranch_vccnz .LBB0_708
	v_lshl_add_u32 v35, v42, 1, v109
	v_mov_b32_e32 v39, v1
	s_movk_i32 s0, 0x2040
	v_mad_i64_i32 v[36:37], s[0:1], v35, s0, v[38:39]
	v_readlane_b32 s0, v254, 14
	v_lshlrev_b64 v[36:37], 7, v[36:37]
	v_readlane_b32 s1, v254, 15
	v_lshlrev_b32_e32 v40, 1, v137
	v_mov_b32_e32 v41, v1
	v_lshl_add_u64 v[36:37], s[0:1], 0, v[36:37]
	v_lshl_add_u64 v[36:37], v[36:37], 0, v[40:41]
	v_lshlrev_b32_e32 v40, 1, v139
	v_lshl_add_u64 v[36:37], v[36:37], 0, v[40:41]
	v_cvt_pk_bf16_f32 v44, v14, v15
	v_cvt_pk_bf16_f32 v45, v16, v17
	v_cvt_pk_bf16_f32 v46, v10, v11
	v_cvt_pk_bf16_f32 v47, v12, v13
	global_store_dwordx4 v[36:37], v[44:47], off sc0 sc1
.LBB0_708:
	s_andn2_saveexec_b64 s[42:43], s[68:69]
	s_cbranch_execz .LBB0_710
	v_mad_i32_i24 v35, v42, 6, v111
	v_mov_b32_e32 v39, v1
	s_movk_i32 s0, 0x2040
	v_mad_i64_i32 v[36:37], s[0:1], v35, s0, v[38:39]
	v_readlane_b32 s0, v254, 12
	v_lshlrev_b64 v[36:37], 7, v[36:37]
	v_readlane_b32 s1, v254, 13
	v_lshlrev_b32_e32 v40, 1, v137
	v_mov_b32_e32 v41, v1
	v_lshl_add_u64 v[36:37], s[0:1], 0, v[36:37]
	v_lshl_add_u64 v[36:37], v[36:37], 0, v[40:41]
	v_lshlrev_b32_e32 v40, 1, v139
	s_mov_b32 s0, 0x3e38aa3b
	v_lshl_add_u64 v[36:37], v[36:37], 0, v[40:41]
	v_pk_mul_f32 v[40:41], v[16:17], s[0:1] op_sel_hi:[1,0]
	v_pk_mul_f32 v[44:45], v[14:15], s[0:1] op_sel_hi:[1,0]
	v_pk_mul_f32 v[48:49], v[12:13], s[0:1] op_sel_hi:[1,0]
	v_pk_mul_f32 v[46:47], v[10:11], s[0:1] op_sel_hi:[1,0]
	v_cvt_pk_bf16_f32 v44, v44, v45
	v_cvt_pk_bf16_f32 v45, v40, v41
	v_cvt_pk_bf16_f32 v46, v46, v47
	v_cvt_pk_bf16_f32 v47, v48, v49
	global_store_dwordx4 v[36:37], v[44:47], off sc0 sc1

; __device__ __forceinline__ void store8bf(bf16_t* p, f32x4 v0, f32x4 v1) { u32x4 w; w.x = cvt_pk_bf16(v0[0], v0[1]); w.y = cvt_pk_bf16(v0[2], v0[3]); w.z = cvt_pk_bf16(v1[0], v1[1]); w.w = cvt_pk_bf16(v1[2], v1[3]); *(u32x4*)p = w; }
;   __device__ __forceinline__ void group(int row, int c32, int fq, f32x4 v0, f32x4 v1) const {
;     ...
;     else if (c32 < 1024) { const int cc = c32 - 768, h = cc >> 6; store8bf(kd + ((size_t)(b * 4 + h) * E + e) * 64 + (cc & 63) + fq * 8, v0, v1); }
.LBB0_714:
	s_andn2_b64 vcc, exec, s[42:43]
	s_cbranch_vccnz .LBB0_716
	v_lshl_add_u32 v35, v42, 2, v108
	v_mov_b32_e32 v39, v1
	s_movk_i32 s0, 0x2040
	v_mad_i64_i32 v[36:37], s[0:1], v35, s0, v[38:39]
	v_readlane_b32 s0, v254, 8
	v_lshlrev_b64 v[36:37], 7, v[36:37]
	v_readlane_b32 s1, v254, 9
	v_lshlrev_b32_e32 v40, 1, v137
	v_mov_b32_e32 v41, v1
	v_lshl_add_u64 v[36:37], s[0:1], 0, v[36:37]
	v_lshl_add_u64 v[36:37], v[36:37], 0, v[40:41]
	v_lshlrev_b32_e32 v40, 1, v139
	v_lshl_add_u64 v[36:37], v[36:37], 0, v[40:41]
	v_cvt_pk_bf16_f32 v44, v14, v15
	v_cvt_pk_bf16_f32 v45, v16, v17
	v_cvt_pk_bf16_f32 v46, v10, v11
	v_cvt_pk_bf16_f32 v47, v12, v13
	global_store_dwordx4 v[36:37], v[44:47], off sc0 sc1

; __device__ __forceinline__ void store8bf(bf16_t* p, f32x4 v0, f32x4 v1) { u32x4 w; w.x = cvt_pk_bf16(v0[0], v0[1]); w.y = cvt_pk_bf16(v0[2], v0[3]); w.z = cvt_pk_bf16(v1[0], v1[1]); w.w = cvt_pk_bf16(v1[2], v1[3]); *(u32x4*)p = w; }
;   __device__ __forceinline__ void group(int row, int c32, int fq, f32x4 v0, f32x4 v1) const {
;     ...
;     if (c32 < 768) { const int cc = c32 - 512, h = cc >> 6; store8bf(qd + ((size_t)(b * 4 + h) * E + e) * 64 + (cc & 63) + fq * 8, v0 * QSC_D, v1 * QSC_D); }
.LBB0_717:
	s_andn2_b64 vcc, exec, s[42:43]
	s_cbranch_vccnz .LBB0_719
	v_lshl_add_u32 v35, v42, 2, v107
	v_mov_b32_e32 v39, v1
	s_movk_i32 s0, 0x2040
	v_mad_i64_i32 v[36:37], s[0:1], v35, s0, v[38:39]
	v_readlane_b32 s0, v254, 6
	v_lshlrev_b64 v[36:37], 7, v[36:37]
	v_readlane_b32 s1, v254, 7
	v_lshlrev_b32_e32 v40, 1, v137
	v_mov_b32_e32 v41, v1
	v_lshl_add_u64 v[36:37], s[0:1], 0, v[36:37]
	v_lshl_add_u64 v[36:37], v[36:37], 0, v[40:41]
	v_lshlrev_b32_e32 v40, 1, v139
	s_mov_b32 s0, 0x3e8293ee
	v_lshl_add_u64 v[36:37], v[36:37], 0, v[40:41]
	v_pk_mul_f32 v[40:41], v[16:17], s[0:1] op_sel_hi:[1,0]
	v_pk_mul_f32 v[44:45], v[14:15], s[0:1] op_sel_hi:[1,0]
	v_pk_mul_f32 v[48:49], v[12:13], s[0:1] op_sel_hi:[1,0]
	v_pk_mul_f32 v[46:47], v[10:11], s[0:1] op_sel_hi:[1,0]
	v_cvt_pk_bf16_f32 v44, v44, v45
	v_cvt_pk_bf16_f32 v45, v40, v41
	v_cvt_pk_bf16_f32 v46, v46, v47
	v_cvt_pk_bf16_f32 v47, v48, v49
	global_store_dwordx4 v[36:37], v[44:47], off sc0 sc1

; __device__ __forceinline__ void store8bf(bf16_t* p, f32x4 v0, f32x4 v1) { u32x4 w; w.x = cvt_pk_bf16(v0[0], v0[1]); w.y = cvt_pk_bf16(v0[2], v0[3]); w.z = cvt_pk_bf16(v1[0], v1[1]); w.w = cvt_pk_bf16(v1[2], v1[3]); *(u32x4*)p = w; }
;   __device__ __forceinline__ void group(int row, int c32, int fq, f32x4 v0, f32x4 v1) const {
;     ...
;     else if (c32 < 1664) { const int cc = c32 - 1280, h = cc >> 6; store8bf(qs + ((size_t)(b * 6 + h) * E + e) * 64 + (cc & 63) + fq * 8, v0 * QSC_S, v1 * QSC_S); }
;     else if (c32 < 1792) { const int cc = c32 - 1664, g = cc >> 6; store8bf(ks + ((size_t)(b * 2 + g) * E + e) * 64 + (cc & 63) + fq * 8, v0, v1); }
.LBB0_737:
	s_andn2_b64 vcc, exec, s[18:19]
	s_cbranch_vccnz .LBB0_739
	v_lshl_add_u32 v35, v44, 1, v109
	v_mov_b32_e32 v39, v1
	s_movk_i32 s0, 0x2040
	v_mad_i64_i32 v[36:37], s[0:1], v35, s0, v[38:39]
	v_readlane_b32 s0, v254, 14
	v_lshlrev_b64 v[36:37], 7, v[36:37]
	v_readlane_b32 s1, v254, 15
	v_lshlrev_b32_e32 v40, 1, v137
	v_mov_b32_e32 v41, v1
	v_lshl_add_u64 v[36:37], s[0:1], 0, v[36:37]
	v_lshl_add_u64 v[36:37], v[36:37], 0, v[40:41]
	v_lshlrev_b32_e32 v40, 1, v139
	v_lshl_add_u64 v[36:37], v[36:37], 0, v[40:41]
	v_cvt_pk_bf16_f32 v40, v6, v7
	v_cvt_pk_bf16_f32 v41, v8, v9
	v_cvt_pk_bf16_f32 v42, v2, v3
	v_cvt_pk_bf16_f32 v43, v4, v5
	global_store_dwordx4 v[36:37], v[40:43], off sc0 sc1
.LBB0_739:
	s_andn2_saveexec_b64 s[6:7], s[8:9]
	s_cbranch_execz .LBB0_741
	v_mad_i32_i24 v35, v44, 6, v111
	v_mov_b32_e32 v39, v1
	s_movk_i32 s0, 0x2040
	v_mad_i64_i32 v[36:37], s[0:1], v35, s0, v[38:39]
	v_readlane_b32 s0, v254, 12
	v_lshlrev_b64 v[36:37], 7, v[36:37]
	v_readlane_b32 s1, v254, 13
	v_lshlrev_b32_e32 v40, 1, v137
	v_mov_b32_e32 v41, v1
	v_lshl_add_u64 v[36:37], s[0:1], 0, v[36:37]
	v_lshl_add_u64 v[36:37], v[36:37], 0, v[40:41]
	v_lshlrev_b32_e32 v40, 1, v139
	s_mov_b32 s0, 0x3e38aa3b
	v_lshl_add_u64 v[36:37], v[36:37], 0, v[40:41]
	v_pk_mul_f32 v[42:43], v[8:9], s[0:1] op_sel_hi:[1,0]
	v_pk_mul_f32 v[40:41], v[6:7], s[0:1] op_sel_hi:[1,0]
	v_pk_mul_f32 v[46:47], v[4:5], s[0:1] op_sel_hi:[1,0]
	v_pk_mul_f32 v[48:49], v[2:3], s[0:1] op_sel_hi:[1,0]
	v_cvt_pk_bf16_f32 v40, v40, v41
	v_cvt_pk_bf16_f32 v41, v42, v43
	v_cvt_pk_bf16_f32 v42, v48, v49
	v_cvt_pk_bf16_f32 v43, v46, v47
	global_store_dwordx4 v[36:37], v[40:43], off sc0 sc1

; __device__ __forceinline__ void store8bf(bf16_t* p, f32x4 v0, f32x4 v1) { u32x4 w; w.x = cvt_pk_bf16(v0[0], v0[1]); w.y = cvt_pk_bf16(v0[2], v0[3]); w.z = cvt_pk_bf16(v1[0], v1[1]); w.w = cvt_pk_bf16(v1[2], v1[3]); *(u32x4*)p = w; }
;   __device__ __forceinline__ void group(int row, int c32, int fq, f32x4 v0, f32x4 v1) const {
;     ...
;     else if (c32 < 1024) { const int cc = c32 - 768, h = cc >> 6; store8bf(kd + ((size_t)(b * 4 + h) * E + e) * 64 + (cc & 63) + fq * 8, v0, v1); }
.LBB0_745:
	s_andn2_b64 vcc, exec, s[24:25]
	s_cbranch_vccnz .LBB0_747
	v_lshl_add_u32 v35, v44, 2, v108
	v_mov_b32_e32 v39, v1
	s_movk_i32 s0, 0x2040
	v_mad_i64_i32 v[36:37], s[0:1], v35, s0, v[38:39]
	v_readlane_b32 s0, v254, 8
	v_lshlrev_b64 v[36:37], 7, v[36:37]
	v_readlane_b32 s1, v254, 9
	v_lshlrev_b32_e32 v40, 1, v137
	v_mov_b32_e32 v41, v1
	v_lshl_add_u64 v[36:37], s[0:1], 0, v[36:37]
	v_lshl_add_u64 v[36:37], v[36:37], 0, v[40:41]
	v_lshlrev_b32_e32 v40, 1, v139
	v_lshl_add_u64 v[36:37], v[36:37], 0, v[40:41]
	v_cvt_pk_bf16_f32 v40, v6, v7
	v_cvt_pk_bf16_f32 v41, v8, v9
	v_cvt_pk_bf16_f32 v42, v2, v3
	v_cvt_pk_bf16_f32 v43, v4, v5
	global_store_dwordx4 v[36:37], v[40:43], off sc0 sc1

; __device__ __forceinline__ void store8bf(bf16_t* p, f32x4 v0, f32x4 v1) { u32x4 w; w.x = cvt_pk_bf16(v0[0], v0[1]); w.y = cvt_pk_bf16(v0[2], v0[3]); w.z = cvt_pk_bf16(v1[0], v1[1]); w.w = cvt_pk_bf16(v1[2], v1[3]); *(u32x4*)p = w; }
;   __device__ __forceinline__ void group(int row, int c32, int fq, f32x4 v0, f32x4 v1) const {
;     ...
;     if (c32 < 768) { const int cc = c32 - 512, h = cc >> 6; store8bf(qd + ((size_t)(b * 4 + h) * E + e) * 64 + (cc & 63) + fq * 8, v0 * QSC_D, v1 * QSC_D); }
.LBB0_748:
	s_andn2_b64 vcc, exec, s[38:39]
	s_cbranch_vccnz .LBB0_750
	v_lshl_add_u32 v35, v44, 2, v107
	v_mov_b32_e32 v39, v1
	s_movk_i32 s0, 0x2040
	v_mad_i64_i32 v[36:37], s[0:1], v35, s0, v[38:39]
	v_readlane_b32 s0, v254, 6
	v_lshlrev_b64 v[36:37], 7, v[36:37]
	v_readlane_b32 s1, v254, 7
	v_lshlrev_b32_e32 v40, 1, v137
	v_mov_b32_e32 v41, v1
	v_lshl_add_u64 v[36:37], s[0:1], 0, v[36:37]
	v_lshl_add_u64 v[36:37], v[36:37], 0, v[40:41]
	v_lshlrev_b32_e32 v40, 1, v139
	s_mov_b32 s0, 0x3e8293ee
	v_lshl_add_u64 v[36:37], v[36:37], 0, v[40:41]
	v_pk_mul_f32 v[42:43], v[8:9], s[0:1] op_sel_hi:[1,0]
	v_pk_mul_f32 v[40:41], v[6:7], s[0:1] op_sel_hi:[1,0]
	v_pk_mul_f32 v[46:47], v[4:5], s[0:1] op_sel_hi:[1,0]
	v_pk_mul_f32 v[48:49], v[2:3], s[0:1] op_sel_hi:[1,0]
	v_cvt_pk_bf16_f32 v40, v40, v41
	v_cvt_pk_bf16_f32 v41, v42, v43
	v_cvt_pk_bf16_f32 v42, v48, v49
	v_cvt_pk_bf16_f32 v43, v46, v47
	global_store_dwordx4 v[36:37], v[40:43], off sc0 sc1

; __device__ __forceinline__ void store8bf(bf16_t* p, f32x4 v0, f32x4 v1) { u32x4 w; w.x = cvt_pk_bf16(v0[0], v0[1]); w.y = cvt_pk_bf16(v0[2], v0[3]); w.z = cvt_pk_bf16(v1[0], v1[1]); w.w = cvt_pk_bf16(v1[2], v1[3]); *(u32x4*)p = w; }
;   __device__ __forceinline__ void operator()(int row, int cb, int fq, f32x4 a, f32x4 b, f32x4 c, f32x4 d) const { group(row, cb, fq, a, b); group(row, cb + 128, fq, c, d); }
;   __device__ __forceinline__ void group(int row, int c32, int fq, f32x4 v0, f32x4 v1) const { e->group(row, c32 + sh, fq, v0, v1); }
;   __device__ __forceinline__ void group(int row, int c32, int fq, f32x4 v0, f32x4 v1) const {
;     ...
;       if (c32 < 384) store8bf(cqkv + (size_t)row * 512 + c32 + fq * 8, v0, v1);
;   __device__ __forceinline__ void operator()(int row, int cb, int fq, f32x4 a, f32x4 b, f32x4 c, f32x4 d) const { group(row, cb, fq, a, b); group(row, cb + 128, fq, c, d); }
.LBB0_754:
	v_mov_b32_e32 v46, v0
	v_mov_b32_e32 v47, v1
	v_lshl_add_u64 v[42:43], v[46:47], 1, v[42:43]
	v_lshlrev_b32_e32 v46, 1, v139
	v_lshl_add_u64 v[42:43], v[42:43], 0, v[46:47]
	global_store_dwordx4 v[42:43], v[34:37], off offset:256 sc0 sc1

; __global__ void __launch_bounds__(512) mega(Params P) {
;     ...
;     grid.sync();
.LBB0_769:
	s_waitcnt vmcnt(0) lgkmcnt(0)
	s_barrier
	s_mov_b64 s[2:3], exec
	v_readlane_b32 s0, v253, 57
	v_readlane_b32 s1, v253, 58
	s_and_b64 s[0:1], s[2:3], s[0:1]
	s_mov_b64 exec, s[0:1]
	s_cbranch_execz .LBB0_779
	buffer_wbl2 sc1
	s_load_dwordx2 s[4:5], s[56:57], -0x8
	s_load_dword s0, s[56:57], 0x0
	v_readlane_b32 s1, v253, 55
	s_waitcnt lgkmcnt(0)
	s_and_b32 s1, s1, 7
	s_add_i32 s6, s0, 7
	s_sub_i32 s6, s6, s1
	s_lshr_b32 s6, s6, 3
	s_min_u32 s7, s0, 8
	s_lshl_b32 s1, s1, 2
	s_addk_i32 s1, 0x88
	v_mov_b32_e32 v2, s1
	global_load_dword v0, v1, s[4:5] sc1
	v_mov_b32_e32 v3, 1
	s_waitcnt vmcnt(0)
	v_and_b32_e32 v0, 0xffff0000, v0
	global_atomic_add v3, v2, v3, s[4:5] sc0
	s_waitcnt vmcnt(0)
	v_and_b32_e32 v3, 0xffff, v3
	s_nop 0
	v_readfirstlane_b32 s1, v3
	s_nop 3
	s_add_i32 s0, s6, -1
	s_cmp_lg_u32 s1, s0
	s_cbranch_scc1 .Lgb_poll_1
	s_sub_i32 s1, 0x10000, s6
	v_mov_b32_e32 v3, s1
	global_atomic_add v3, v2, v3, s[4:5] sc0
	s_waitcnt vmcnt(0)
	v_mov_b32_e32 v3, 1
	global_atomic_add v3, v1, v3, s[4:5] sc0
	s_waitcnt vmcnt(0)
	v_and_b32_e32 v3, 0xffff, v3
	s_nop 0
	v_readfirstlane_b32 s1, v3
	s_nop 3
	s_add_i32 s0, s7, -1
	s_cmp_lg_u32 s1, s0
	s_cbranch_scc1 .Lgb_poll_1
	s_sub_i32 s1, 0x10000, s7
	v_mov_b32_e32 v3, s1
	global_atomic_add v1, v3, s[4:5]

; __device__ __forceinline__ void store8bf(bf16_t* p, f32x4 v0, f32x4 v1) { u32x4 w; w.x = cvt_pk_bf16(v0[0], v0[1]); w.y = cvt_pk_bf16(v0[2], v0[3]); w.z = cvt_pk_bf16(v1[0], v1[1]); w.w = cvt_pk_bf16(v1[2], v1[3]); *(u32x4*)p = w; }
;   __device__ __forceinline__ void group(int row, int c32, int fq, f32x4 v0, f32x4 v1) const {
;     ...
;       const int h = c32 / 96, part = (c32 - h * 96) >> 5; const float sc = rs * QSC_A;
;       bf16_t* p = qa + ((size_t)(b * 6 + h) * E + e) * 96 + part * 32 + fq * 4;
;       if (part < 2) store8bf(qa + ((size_t)(b * 6 + h) * E + e) * 96 + part * 32 + fq * 8, v0 * sc, v1 * sc);
.LBB0_786:
	s_andn2_b64 vcc, exec, s[10:11]
	s_cbranch_vccnz .LBB0_788
	s_movk_i32 s10, 0x2040
	v_mad_i64_i32 v[8:9], s[10:11], v8, s10, v[24:25]
	v_readlane_b32 s10, v254, 4
	v_readlane_b32 s11, v254, 5
	s_lshl_b32 s90, s15, 6
	v_mov_b32_e32 v14, v104
	v_mov_b64_e32 v[10:11], s[10:11]
	v_mad_u64_u32 v[10:11], s[10:11], v8, s47, v[10:11]
	v_mad_i32_i24 v11, v9, s47, v11
	v_lshl_add_u64 v[8:9], v[10:11], 0, s[90:91]
	v_lshlrev_b32_e32 v10, 1, v0
	v_mov_b32_e32 v11, v1
	v_lshl_add_u64 v[12:13], v[8:9], 0, v[10:11]
	v_mov_b32_e32 v8, v86
	v_mov_b32_e32 v9, v105
	v_mov_b32_e32 v15, v87
	v_pk_mul_f32 v[10:11], v[8:9], v[6:7] op_sel_hi:[1,0]
	v_pk_mul_f32 v[8:9], v[108:109], v[6:7] op_sel_hi:[1,0]
	v_pk_mul_f32 v[14:15], v[14:15], v[6:7] op_sel_hi:[1,0]
	v_pk_mul_f32 v[16:17], v[106:107], v[6:7] op_sel_hi:[1,0]
	v_cvt_pk_bf16_f32 v8, v8, v9
	v_cvt_pk_bf16_f32 v9, v10, v11
	v_cvt_pk_bf16_f32 v10, v16, v17
	v_cvt_pk_bf16_f32 v11, v14, v15
	global_store_dwordx4 v[12:13], v[8:11], off sc0 sc1

; __device__ __forceinline__ void store8bf(bf16_t* p, f32x4 v0, f32x4 v1) { u32x4 w; w.x = cvt_pk_bf16(v0[0], v0[1]); w.y = cvt_pk_bf16(v0[2], v0[3]); w.z = cvt_pk_bf16(v1[0], v1[1]); w.w = cvt_pk_bf16(v1[2], v1[3]); *(u32x4*)p = w; }
;   __device__ __forceinline__ void group(int row, int c32, int fq, f32x4 v0, f32x4 v1) const {
;     ...
;       const int h = c32 / 96, part = (c32 - h * 96) >> 5; const float sc = rs * QSC_A;
;       bf16_t* p = qa + ((size_t)(b * 6 + h) * E + e) * 96 + part * 32 + fq * 4;
;       if (part < 2) store8bf(qa + ((size_t)(b * 6 + h) * E + e) * 96 + part * 32 + fq * 8, v0 * sc, v1 * sc);
.LBB0_793:
	s_andn2_b64 vcc, exec, s[10:11]
	s_cbranch_vccnz .LBB0_795
	v_lshlrev_b32_e32 v12, 1, v0
	v_mov_b32_e32 v13, v1
	v_lshl_add_u64 v[12:13], v[10:11], 0, v[12:13]
	v_mov_b32_e32 v10, v86
	v_mov_b32_e32 v11, v105
	v_mov_b32_e32 v105, v87
	v_pk_mul_f32 v[10:11], v[10:11], v[8:9] op_sel_hi:[1,0]
	v_pk_mul_f32 v[14:15], v[108:109], v[8:9] op_sel_hi:[1,0]
	v_pk_mul_f32 v[16:17], v[104:105], v[8:9] op_sel_hi:[1,0]
	v_pk_mul_f32 v[18:19], v[106:107], v[8:9] op_sel_hi:[1,0]
	v_cvt_pk_bf16_f32 v8, v14, v15
	v_cvt_pk_bf16_f32 v9, v10, v11
	v_cvt_pk_bf16_f32 v10, v18, v19
	v_cvt_pk_bf16_f32 v11, v16, v17
	global_store_dwordx4 v[12:13], v[8:11], off sc0 sc1

; __device__ __forceinline__ void store8bf(bf16_t* p, f32x4 v0, f32x4 v1) { u32x4 w; w.x = cvt_pk_bf16(v0[0], v0[1]); w.y = cvt_pk_bf16(v0[2], v0[3]); w.z = cvt_pk_bf16(v1[0], v1[1]); w.w = cvt_pk_bf16(v1[2], v1[3]); *(u32x4*)p = w; }
;   __device__ __forceinline__ void group(int row, int c32, int fq, f32x4 v0, f32x4 v1) const {
;     ...
;       const int h = c32 / 96, part = (c32 - h * 96) >> 5; const float sc = rs * QSC_A;
;       bf16_t* p = qa + ((size_t)(b * 6 + h) * E + e) * 96 + part * 32 + fq * 4;
;       if (part < 2) store8bf(qa + ((size_t)(b * 6 + h) * E + e) * 96 + part * 32 + fq * 8, v0 * sc, v1 * sc);
.LBB0_798:
	s_andn2_b64 vcc, exec, s[10:11]
	s_cbranch_vccnz .LBB0_800
	s_movk_i32 s10, 0x2040
	v_mad_i64_i32 v[20:21], s[10:11], v20, s10, v[24:25]
	v_readlane_b32 s10, v254, 4
	v_readlane_b32 s11, v254, 5
	s_lshl_b32 s90, s14, 6
	v_mov_b32_e32 v38, v10
	v_mov_b64_e32 v[34:35], s[10:11]
	v_mad_u64_u32 v[34:35], s[10:11], v20, s47, v[34:35]
	v_mad_i32_i24 v35, v21, s47, v35
	v_lshl_add_u64 v[20:21], v[34:35], 0, s[90:91]
	v_lshlrev_b32_e32 v34, 1, v0
	v_mov_b32_e32 v35, v1
	v_lshl_add_u64 v[20:21], v[20:21], 0, v[34:35]
	v_mov_b32_e32 v34, v8
	v_mov_b32_e32 v35, v11
	v_mov_b32_e32 v39, v9
	v_pk_mul_f32 v[36:37], v[34:35], v[6:7] op_sel_hi:[1,0]
	v_pk_mul_f32 v[34:35], v[14:15], v[6:7] op_sel_hi:[1,0]
	v_pk_mul_f32 v[38:39], v[38:39], v[6:7] op_sel_hi:[1,0]
	v_pk_mul_f32 v[40:41], v[12:13], v[6:7] op_sel_hi:[1,0]
	v_cvt_pk_bf16_f32 v34, v34, v35
	v_cvt_pk_bf16_f32 v35, v36, v37
	v_cvt_pk_bf16_f32 v36, v40, v41
	v_cvt_pk_bf16_f32 v37, v38, v39
	global_store_dwordx4 v[20:21], v[34:37], off sc0 sc1

; __device__ __forceinline__ void store8bf(bf16_t* p, f32x4 v0, f32x4 v1) { u32x4 w; w.x = cvt_pk_bf16(v0[0], v0[1]); w.y = cvt_pk_bf16(v0[2], v0[3]); w.z = cvt_pk_bf16(v1[0], v1[1]); w.w = cvt_pk_bf16(v1[2], v1[3]); *(u32x4*)p = w; }
;   __device__ __forceinline__ void group(int row, int c32, int fq, f32x4 v0, f32x4 v1) const {
;     ...
;       const int h = c32 / 96, part = (c32 - h * 96) >> 5; const float sc = rs * QSC_A;
;       bf16_t* p = qa + ((size_t)(b * 6 + h) * E + e) * 96 + part * 32 + fq * 4;
;       if (part < 2) store8bf(qa + ((size_t)(b * 6 + h) * E + e) * 96 + part * 32 + fq * 8, v0 * sc, v1 * sc);
.LBB0_805:
	s_andn2_b64 vcc, exec, s[10:11]
	s_cbranch_vccnz .LBB0_781
	v_mov_b32_e32 v18, v8
	v_mov_b32_e32 v19, v11
	v_mov_b32_e32 v11, v9
	v_lshlrev_b32_e32 v16, 1, v0
	v_mov_b32_e32 v17, v1
	v_pk_mul_f32 v[18:19], v[18:19], v[6:7] op_sel_hi:[1,0]
	v_pk_mul_f32 v[14:15], v[14:15], v[6:7] op_sel_hi:[1,0]
	v_pk_mul_f32 v[10:11], v[10:11], v[6:7] op_sel_hi:[1,0]
	v_pk_mul_f32 v[8:9], v[12:13], v[6:7] op_sel_hi:[1,0]
	v_lshl_add_u64 v[16:17], v[20:21], 0, v[16:17]
	v_cvt_pk_bf16_f32 v6, v14, v15
	v_cvt_pk_bf16_f32 v7, v18, v19
	v_cvt_pk_bf16_f32 v8, v8, v9
	v_cvt_pk_bf16_f32 v9, v10, v11
	global_store_dwordx4 v[16:17], v[6:9], off sc0 sc1
	s_branch .LBB0_781

; __device__ __forceinline__ void store8bf(bf16_t* p, f32x4 v0, f32x4 v1) { u32x4 w; w.x = cvt_pk_bf16(v0[0], v0[1]); w.y = cvt_pk_bf16(v0[2], v0[3]); w.z = cvt_pk_bf16(v1[0], v1[1]); w.w = cvt_pk_bf16(v1[2], v1[3]); *(u32x4*)p = w; }
;   __device__ __forceinline__ void group(int row, int c32, int fq, f32x4 v0, f32x4 v1) const {
;     ...
;       const int cc = c32 - 768, h = cc >> 7, part = (cc & 127) >> 5;
;       if (part < 2) store8bf(ka + ((size_t)(b * 6 + h) * E + e) * 96 + part * 32 + fq * 8, v0 * rs, v1 * rs);
.LBB0_814:
	s_andn2_b64 vcc, exec, s[6:7]
	s_cbranch_vccnz .LBB0_816
	s_movk_i32 s6, 0x2040
	v_mad_i64_i32 v[8:9], s[6:7], v8, s6, v[24:25]
	v_readlane_b32 s6, v254, 4
	v_readlane_b32 s7, v254, 5
	s_lshl_b32 s90, s10, 6
	v_mov_b32_e32 v14, v104
	v_mov_b64_e32 v[10:11], s[6:7]
	v_mad_u64_u32 v[10:11], s[6:7], v8, s47, v[10:11]
	v_mad_i32_i24 v11, v9, s47, v11
	v_lshl_add_u64 v[8:9], v[10:11], 0, s[90:91]
	v_lshlrev_b32_e32 v10, 1, v0
	v_mov_b32_e32 v11, v1
	v_lshl_add_u64 v[12:13], v[8:9], 0, v[10:11]
	v_mov_b32_e32 v8, v86
	v_mov_b32_e32 v9, v105
	v_mov_b32_e32 v15, v87
	v_pk_mul_f32 v[10:11], v[8:9], v[6:7] op_sel_hi:[1,0]
	v_pk_mul_f32 v[8:9], v[108:109], v[6:7] op_sel_hi:[1,0]
	v_pk_mul_f32 v[14:15], v[14:15], v[6:7] op_sel_hi:[1,0]
	v_pk_mul_f32 v[16:17], v[106:107], v[6:7] op_sel_hi:[1,0]
	v_cvt_pk_bf16_f32 v8, v8, v9
	v_cvt_pk_bf16_f32 v9, v10, v11
	v_cvt_pk_bf16_f32 v10, v16, v17
	v_cvt_pk_bf16_f32 v11, v14, v15
	global_store_dwordx4 v[12:13], v[8:11], off sc0 sc1

; __device__ __forceinline__ void store8bf(bf16_t* p, f32x4 v0, f32x4 v1) { u32x4 w; w.x = cvt_pk_bf16(v0[0], v0[1]); w.y = cvt_pk_bf16(v0[2], v0[3]); w.z = cvt_pk_bf16(v1[0], v1[1]); w.w = cvt_pk_bf16(v1[2], v1[3]); *(u32x4*)p = w; }
;   __device__ __forceinline__ void group(int row, int c32, int fq, f32x4 v0, f32x4 v1) const {
;     ...
;       const int cc = c32 - 768, h = cc >> 7, part = (cc & 127) >> 5;
;       if (part < 2) store8bf(ka + ((size_t)(b * 6 + h) * E + e) * 96 + part * 32 + fq * 8, v0 * rs, v1 * rs);
.LBB0_821:
	s_andn2_b64 vcc, exec, s[6:7]
	s_cbranch_vccnz .LBB0_823
	v_lshlrev_b32_e32 v12, 1, v0
	v_mov_b32_e32 v13, v1
	v_lshl_add_u64 v[12:13], v[10:11], 0, v[12:13]
	v_mov_b32_e32 v10, v86
	v_mov_b32_e32 v11, v105
	v_mov_b32_e32 v105, v87
	v_pk_mul_f32 v[10:11], v[10:11], v[8:9] op_sel_hi:[1,0]
	v_pk_mul_f32 v[14:15], v[108:109], v[8:9] op_sel_hi:[1,0]
	v_pk_mul_f32 v[16:17], v[104:105], v[8:9] op_sel_hi:[1,0]
	v_pk_mul_f32 v[18:19], v[106:107], v[8:9] op_sel_hi:[1,0]
	v_cvt_pk_bf16_f32 v8, v14, v15
	v_cvt_pk_bf16_f32 v9, v10, v11
	v_cvt_pk_bf16_f32 v10, v18, v19
	v_cvt_pk_bf16_f32 v11, v16, v17
	global_store_dwordx4 v[12:13], v[8:11], off offset:1536 sc0 sc1

; __device__ __forceinline__ void store8bf(bf16_t* p, f32x4 v0, f32x4 v1) { u32x4 w; w.x = cvt_pk_bf16(v0[0], v0[1]); w.y = cvt_pk_bf16(v0[2], v0[3]); w.z = cvt_pk_bf16(v1[0], v1[1]); w.w = cvt_pk_bf16(v1[2], v1[3]); *(u32x4*)p = w; }
;   __device__ __forceinline__ void group(int row, int c32, int fq, f32x4 v0, f32x4 v1) const {
;     ...
;       const int cc = c32 - 768, h = cc >> 7, part = (cc & 127) >> 5;
;       if (part < 2) store8bf(ka + ((size_t)(b * 6 + h) * E + e) * 96 + part * 32 + fq * 8, v0 * rs, v1 * rs);
.LBB0_826:
	s_andn2_b64 vcc, exec, s[6:7]
	s_cbranch_vccnz .LBB0_828
	s_movk_i32 s6, 0x2040
	v_mad_i64_i32 v[20:21], s[6:7], v20, s6, v[24:25]
	v_readlane_b32 s6, v254, 4
	v_readlane_b32 s7, v254, 5
	s_lshl_b32 s90, s10, 6
	v_mov_b32_e32 v38, v10
	v_mov_b64_e32 v[34:35], s[6:7]
	v_mad_u64_u32 v[34:35], s[6:7], v20, s47, v[34:35]
	v_mad_i32_i24 v35, v21, s47, v35
	v_lshl_add_u64 v[20:21], v[34:35], 0, s[90:91]
	v_lshlrev_b32_e32 v34, 1, v0
	v_mov_b32_e32 v35, v1
	v_lshl_add_u64 v[20:21], v[20:21], 0, v[34:35]
	v_mov_b32_e32 v34, v8
	v_mov_b32_e32 v35, v11
	v_mov_b32_e32 v39, v9
	v_pk_mul_f32 v[36:37], v[34:35], v[6:7] op_sel_hi:[1,0]
	v_pk_mul_f32 v[34:35], v[14:15], v[6:7] op_sel_hi:[1,0]
	v_pk_mul_f32 v[38:39], v[38:39], v[6:7] op_sel_hi:[1,0]
	v_pk_mul_f32 v[40:41], v[12:13], v[6:7] op_sel_hi:[1,0]
	v_cvt_pk_bf16_f32 v34, v34, v35
	v_cvt_pk_bf16_f32 v35, v36, v37
	v_cvt_pk_bf16_f32 v36, v40, v41
	v_cvt_pk_bf16_f32 v37, v38, v39
	global_store_dwordx4 v[20:21], v[34:37], off sc0 sc1

; __device__ __forceinline__ void store8bf(bf16_t* p, f32x4 v0, f32x4 v1) { u32x4 w; w.x = cvt_pk_bf16(v0[0], v0[1]); w.y = cvt_pk_bf16(v0[2], v0[3]); w.z = cvt_pk_bf16(v1[0], v1[1]); w.w = cvt_pk_bf16(v1[2], v1[3]); *(u32x4*)p = w; }
;   __device__ __forceinline__ void group(int row, int c32, int fq, f32x4 v0, f32x4 v1) const {
;     ...
;       const int cc = c32 - 768, h = cc >> 7, part = (cc & 127) >> 5;
;       if (part < 2) store8bf(ka + ((size_t)(b * 6 + h) * E + e) * 96 + part * 32 + fq * 8, v0 * rs, v1 * rs);
.LBB0_833:
	s_andn2_b64 vcc, exec, s[6:7]
	s_cbranch_vccnz .LBB0_809
	v_mov_b32_e32 v18, v8
	v_mov_b32_e32 v19, v11
	v_mov_b32_e32 v11, v9
	v_lshlrev_b32_e32 v16, 1, v0
	v_mov_b32_e32 v17, v1
	v_pk_mul_f32 v[18:19], v[18:19], v[6:7] op_sel_hi:[1,0]
	v_pk_mul_f32 v[14:15], v[14:15], v[6:7] op_sel_hi:[1,0]
	v_pk_mul_f32 v[10:11], v[10:11], v[6:7] op_sel_hi:[1,0]
	v_pk_mul_f32 v[8:9], v[12:13], v[6:7] op_sel_hi:[1,0]
	v_lshl_add_u64 v[16:17], v[20:21], 0, v[16:17]
	v_cvt_pk_bf16_f32 v6, v14, v15
	v_cvt_pk_bf16_f32 v7, v18, v19
	v_cvt_pk_bf16_f32 v8, v8, v9
	v_cvt_pk_bf16_f32 v9, v10, v11
	global_store_dwordx4 v[16:17], v[6:9], off offset:1792 sc0 sc1
	s_branch .LBB0_809

; #define LAS __attribute__((address_space(3)))
; __device__ __forceinline__ void store4bf(bf16_t* p, f32x4 v) { u32x2 w; w.x = cvt_pk_bf16(v[0], v[1]); w.y = cvt_pk_bf16(v[2], v[3]); *(u32x2*)p = w; }
; __device__ __forceinline__ void store8bf(bf16_t* p, f32x4 v0, f32x4 v1) { u32x4 w; w.x = cvt_pk_bf16(v0[0], v0[1]); w.y = cvt_pk_bf16(v0[2], v0[3]); w.z = cvt_pk_bf16(v1[0], v1[1]); w.w = cvt_pk_bf16(v1[2], v1[3]); *(u32x4*)p = w; }
;   __device__ __forceinline__ void group(int row, int c32, int fq, f32x4 v0, f32x4 v1) const { e->group(row, c32 + sh, fq, v0, v1); }
;   __device__ __forceinline__ void group(int row, int c32, int fq, f32x4 v0, f32x4 v1) const {
;     int b, e; if (!row_be(row, b, e)) return;
;     const float rs = use_direct ? rs_direct : ((LAS const float*)(lds_raw + RS_OFF))[row - brow];
;     if (c32 < 768) {
;       if (c32 >= 576) return;
;       const int h = c32 / 96, part = (c32 - h * 96) >> 5; const float sc = rs * QSC_A;
;       bf16_t* p = qa + ((size_t)(b * 6 + h) * E + e) * 96 + part * 32 + fq * 4;
;       if (part < 2) store8bf(qa + ((size_t)(b * 6 + h) * E + e) * 96 + part * 32 + fq * 8, v0 * sc, v1 * sc);
;       else { const float2* rp = rope + pos_of_e(e) * 16 + fq * 4; f32x4 o0, o1;
; #pragma unroll
;         for (int j = 0; j < 4; ++j) { const float2 cs = rp[j]; o0[j] = (v0[j] * cs.x - v1[j] * cs.y) * sc; o1[j] = (v1[j] * cs.x + v0[j] * cs.y) * sc; }
;         store4bf(p, o0); store4bf(p + 16, o1); }
;     } else {
;       const int cc = c32 - 768, h = cc >> 7, part = (cc & 127) >> 5;
;       if (part < 2) store8bf(ka + ((size_t)(b * 6 + h) * E + e) * 96 + part * 32 + fq * 8, v0 * rs, v1 * rs);
.LBB0_945:
	s_or_b64 exec, exec, s[4:5]
	v_lshlrev_b32_e32 v10, 6, v131
	v_bfe_u32 v136, v134, 4, 2
	v_add_u32_e32 v145, s20, v10
	s_mov_b32 s0, 0x8000
	v_cmp_gt_i32_e64 s[6:7], 4, v135
	v_lshlrev_b32_e32 v0, 5, v132
	v_lshlrev_b32_e32 v131, 3, v136
	v_cmp_gt_i32_e32 vcc, s0, v145
	v_ashrrev_i32_e32 v147, 13, v145
	v_or_b32_e32 v146, v145, v130
	v_cmp_gt_u32_e64 s[4:5], 2, v132
	s_lshr_b32 s1, s8, 7
	s_and_saveexec_b64 s[8:9], s[4:5]
	s_xor_b64 s[12:13], exec, s[8:9]
	s_cbranch_execz .LBB0_971
	s_movk_i32 s0, 0x7fff
	v_cmp_lt_i32_e64 s[8:9], s0, v146
	s_and_saveexec_b64 s[16:17], s[8:9]
	s_xor_b64 s[8:9], exec, s[16:17]
	v_cmp_gt_u32_e64 s[14:15], s49, v145
	s_or_saveexec_b64 s[8:9], s[8:9]
	v_mov_b32_e32 v133, 0
	v_mov_b32_e32 v132, v130
	s_xor_b64 exec, exec, s[8:9]
	v_and_b32_e32 v10, 0x1fcf, v146
	v_add_u32_e32 v132, 64, v10
	v_mul_i32_i24_e32 v133, 6, v147
	s_or_b64 s[14:15], s[14:15], exec
	s_or_b64 exec, exec, s[8:9]
	s_and_saveexec_b64 s[8:9], s[14:15]
	s_cbranch_execz .LBB0_952
	v_subrev_u32_e32 v10, s20, v146
	v_add_u32_e32 v11, s1, v133
	v_mov_b32_e32 v133, v1
	s_movk_i32 s0, 0x2040
	v_lshl_add_u32 v10, v10, 2, 0
	v_mad_i64_i32 v[12:13], s[14:15], v11, s0, v[132:133]
	v_add_u32_e32 v10, 0x20000, v10
	v_readlane_b32 s14, v254, 4
	ds_read_b32 v10, v10
	v_readlane_b32 s15, v254, 5
	s_waitcnt lgkmcnt(0)
	v_pk_mul_f32 v[126:127], v[126:127], v[10:11] op_sel_hi:[1,0]
	v_mov_b64_e32 v[132:133], s[14:15]
	v_mad_u64_u32 v[132:133], s[14:15], v12, s47, v[132:133]
	v_mad_i32_i24 v133, v13, s47, v133
	v_lshlrev_b32_e32 v12, 1, v0
	v_mov_b32_e32 v13, v1
	v_lshl_add_u64 v[12:13], v[132:133], 0, v[12:13]
	v_lshlrev_b32_e32 v132, 1, v131
	v_mov_b32_e32 v133, v1
	v_lshl_add_u64 v[132:133], v[12:13], 0, v[132:133]
	v_pk_mul_f32 v[12:13], v[128:129], v[10:11] op_sel_hi:[1,0]
	v_pk_mul_f32 v[124:125], v[124:125], v[10:11] op_sel_hi:[1,0]
	v_pk_mul_f32 v[122:123], v[122:123], v[10:11] op_sel_hi:[1,0]
	v_cvt_pk_bf16_f32 v10, v126, v127
	v_cvt_pk_bf16_f32 v11, v12, v13
	v_cvt_pk_bf16_f32 v12, v122, v123
	v_cvt_pk_bf16_f32 v13, v124, v125
	global_store_dwordx4 v[132:133], v[10:13], off sc0 sc1
.LBB0_952:
	s_or_b64 exec, exec, s[8:9]
	v_or_b32_e32 v123, 16, v146
	s_movk_i32 s0, 0x7fff
	v_cmp_lt_i32_e64 s[8:9], s0, v123
	s_and_saveexec_b64 s[16:17], s[8:9]
	s_xor_b64 s[8:9], exec, s[16:17]
	v_cmp_gt_u32_e64 s[14:15], s49, v145
	s_or_saveexec_b64 s[8:9], s[8:9]
	v_mov_b32_e32 v124, 6
	v_mov_b32_e32 v122, v130
	s_xor_b64 exec, exec, s[8:9]
	v_and_b32_e32 v10, 0x1fdf, v123
	v_add_u32_e32 v122, 64, v10
	v_mul_i32_i24_e32 v124, 6, v147
	s_or_b64 s[14:15], s[14:15], exec
	s_or_b64 exec, exec, s[8:9]
	s_and_saveexec_b64 s[8:9], s[14:15]
	s_cbranch_execz .LBB0_958
	v_subrev_u32_e32 v10, s20, v123
	v_add_u32_e32 v11, s1, v124
	v_mov_b32_e32 v123, v1
	s_movk_i32 s0, 0x2040
	v_lshl_add_u32 v10, v10, 2, 0
	v_mad_i64_i32 v[12:13], s[14:15], v11, s0, v[122:123]
	v_add_u32_e32 v10, 0x20000, v10
	v_readlane_b32 s14, v254, 4
	ds_read_b32 v10, v10
	v_readlane_b32 s15, v254, 5
	s_waitcnt lgkmcnt(0)
	v_pk_mul_f32 v[118:119], v[118:119], v[10:11] op_sel_hi:[1,0]
	v_mov_b64_e32 v[122:123], s[14:15]
	v_mad_u64_u32 v[122:123], s[14:15], v12, s47, v[122:123]
	v_mad_i32_i24 v123, v13, s47, v123
	v_lshlrev_b32_e32 v12, 1, v0
	v_mov_b32_e32 v13, v1
	v_lshl_add_u64 v[12:13], v[122:123], 0, v[12:13]
	v_lshlrev_b32_e32 v122, 1, v131
	v_mov_b32_e32 v123, v1
	v_lshl_add_u64 v[122:123], v[12:13], 0, v[122:123]
	v_pk_mul_f32 v[12:13], v[120:121], v[10:11] op_sel_hi:[1,0]
	v_pk_mul_f32 v[116:117], v[116:117], v[10:11] op_sel_hi:[1,0]
	v_pk_mul_f32 v[114:115], v[114:115], v[10:11] op_sel_hi:[1,0]
	v_cvt_pk_bf16_f32 v10, v118, v119
	v_cvt_pk_bf16_f32 v11, v12, v13
	v_cvt_pk_bf16_f32 v12, v114, v115
	v_cvt_pk_bf16_f32 v13, v116, v117
	global_store_dwordx4 v[122:123], v[10:13], off sc0 sc1
; #define LAS __attribute__((address_space(3)))
; __device__ __forceinline__ void store4bf(bf16_t* p, f32x4 v) { u32x2 w; w.x = cvt_pk_bf16(v[0], v[1]); w.y = cvt_pk_bf16(v[2], v[3]); *(u32x2*)p = w; }
; __device__ __forceinline__ void store8bf(bf16_t* p, f32x4 v0, f32x4 v1) { u32x4 w; w.x = cvt_pk_bf16(v0[0], v0[1]); w.y = cvt_pk_bf16(v0[2], v0[3]); w.z = cvt_pk_bf16(v1[0], v1[1]); w.w = cvt_pk_bf16(v1[2], v1[3]); *(u32x4*)p = w; }
;   __device__ __forceinline__ void group(int row, int c32, int fq, f32x4 v0, f32x4 v1) const { e->group(row, c32 + sh, fq, v0, v1); }
;   __device__ __forceinline__ void group(int row, int c32, int fq, f32x4 v0, f32x4 v1) const {
;     int b, e; if (!row_be(row, b, e)) return;
;     const float rs = use_direct ? rs_direct : ((LAS const float*)(lds_raw + RS_OFF))[row - brow];
;     if (c32 < 768) {
;       if (c32 >= 576) return;
;       const int h = c32 / 96, part = (c32 - h * 96) >> 5; const float sc = rs * QSC_A;
;       bf16_t* p = qa + ((size_t)(b * 6 + h) * E + e) * 96 + part * 32 + fq * 4;
;       if (part < 2) store8bf(qa + ((size_t)(b * 6 + h) * E + e) * 96 + part * 32 + fq * 8, v0 * sc, v1 * sc);
;       else { const float2* rp = rope + pos_of_e(e) * 16 + fq * 4; f32x4 o0, o1;
; #pragma unroll
;         for (int j = 0; j < 4; ++j) { const float2 cs = rp[j]; o0[j] = (v0[j] * cs.x - v1[j] * cs.y) * sc; o1[j] = (v1[j] * cs.x + v0[j] * cs.y) * sc; }
;         store4bf(p, o0); store4bf(p + 16, o1); }
;     } else {
;       const int cc = c32 - 768, h = cc >> 7, part = (cc & 127) >> 5;
;       if (part < 2) store8bf(ka + ((size_t)(b * 6 + h) * E + e) * 96 + part * 32 + fq * 8, v0 * rs, v1 * rs);
.LBB0_958:
	s_or_b64 exec, exec, s[8:9]
	v_or_b32_e32 v115, 32, v146
	s_movk_i32 s0, 0x7fff
	v_cmp_lt_i32_e64 s[8:9], s0, v115
	s_and_saveexec_b64 s[16:17], s[8:9]
	s_xor_b64 s[8:9], exec, s[16:17]
	v_cmp_gt_u32_e64 s[14:15], s49, v145
	s_or_saveexec_b64 s[8:9], s[8:9]
	v_mov_b32_e32 v116, 12
	v_mov_b32_e32 v114, v130
	s_xor_b64 exec, exec, s[8:9]
	v_and_b32_e32 v10, 0x1fef, v115
	v_add_u32_e32 v114, 64, v10
	v_mul_i32_i24_e32 v116, 6, v147
	s_or_b64 s[14:15], s[14:15], exec
	s_or_b64 exec, exec, s[8:9]
	s_and_saveexec_b64 s[8:9], s[14:15]
	s_cbranch_execz .LBB0_964
	v_subrev_u32_e32 v10, s20, v115
	v_add_u32_e32 v11, s1, v116
	v_mov_b32_e32 v115, v1
	s_movk_i32 s0, 0x2040
	v_lshl_add_u32 v10, v10, 2, 0
	v_mad_i64_i32 v[12:13], s[14:15], v11, s0, v[114:115]
	v_add_u32_e32 v10, 0x20000, v10
	v_readlane_b32 s14, v254, 4
	ds_read_b32 v10, v10
	v_readlane_b32 s15, v254, 5
	s_waitcnt lgkmcnt(0)
	v_pk_mul_f32 v[110:111], v[110:111], v[10:11] op_sel_hi:[1,0]
	v_mov_b64_e32 v[114:115], s[14:15]
	v_mad_u64_u32 v[114:115], s[14:15], v12, s47, v[114:115]
	v_mad_i32_i24 v115, v13, s47, v115
	v_lshlrev_b32_e32 v12, 1, v0
	v_mov_b32_e32 v13, v1
	v_lshl_add_u64 v[12:13], v[114:115], 0, v[12:13]
	v_lshlrev_b32_e32 v114, 1, v131
	v_mov_b32_e32 v115, v1
	v_lshl_add_u64 v[114:115], v[12:13], 0, v[114:115]
	v_pk_mul_f32 v[12:13], v[112:113], v[10:11] op_sel_hi:[1,0]
	v_pk_mul_f32 v[108:109], v[108:109], v[10:11] op_sel_hi:[1,0]
	v_pk_mul_f32 v[106:107], v[106:107], v[10:11] op_sel_hi:[1,0]
	v_cvt_pk_bf16_f32 v10, v110, v111
	v_cvt_pk_bf16_f32 v11, v12, v13
	v_cvt_pk_bf16_f32 v12, v106, v107
	v_cvt_pk_bf16_f32 v13, v108, v109
	global_store_dwordx4 v[114:115], v[10:13], off sc0 sc1
.LBB0_964:
	s_or_b64 exec, exec, s[8:9]
	v_or_b32_e32 v107, 48, v146
	s_movk_i32 s0, 0x7fff
	v_cmp_lt_i32_e64 s[8:9], s0, v107
	s_and_saveexec_b64 s[16:17], s[8:9]
	s_xor_b64 s[8:9], exec, s[16:17]
	v_cmp_gt_u32_e64 s[14:15], s49, v145
	s_or_saveexec_b64 s[8:9], s[8:9]
	v_mov_b32_e32 v108, 18
	v_mov_b32_e32 v106, v130
	s_xor_b64 exec, exec, s[8:9]
	v_and_b32_e32 v10, 0x1fff, v107
	v_add_u32_e32 v106, 64, v10
	v_mul_i32_i24_e32 v108, 6, v147
	s_or_b64 s[14:15], s[14:15], exec
	s_or_b64 exec, exec, s[8:9]
	s_and_saveexec_b64 s[8:9], s[14:15]
	s_cbranch_execz .LBB0_970
	v_subrev_u32_e32 v10, s20, v107
	v_add_u32_e32 v11, s1, v108
	v_mov_b32_e32 v107, v1
	s_movk_i32 s0, 0x2040
	v_lshl_add_u32 v10, v10, 2, 0
	v_mad_i64_i32 v[12:13], s[14:15], v11, s0, v[106:107]
	v_add_u32_e32 v10, 0x20000, v10
	v_readlane_b32 s14, v254, 4
	ds_read_b32 v10, v10
	v_readlane_b32 s15, v254, 5
	s_waitcnt lgkmcnt(0)
	v_pk_mul_f32 v[102:103], v[102:103], v[10:11] op_sel_hi:[1,0]
	v_mov_b64_e32 v[106:107], s[14:15]
	v_mad_u64_u32 v[106:107], s[14:15], v12, s47, v[106:107]
	v_mad_i32_i24 v107, v13, s47, v107
	v_lshlrev_b32_e32 v12, 1, v0
	v_mov_b32_e32 v13, v1
	v_lshl_add_u64 v[12:13], v[106:107], 0, v[12:13]
	v_lshlrev_b32_e32 v106, 1, v131
	v_mov_b32_e32 v107, v1
	v_lshl_add_u64 v[106:107], v[12:13], 0, v[106:107]
	v_pk_mul_f32 v[12:13], v[104:105], v[10:11] op_sel_hi:[1,0]
	v_pk_mul_f32 v[100:101], v[100:101], v[10:11] op_sel_hi:[1,0]
	v_pk_mul_f32 v[98:99], v[98:99], v[10:11] op_sel_hi:[1,0]
	v_cvt_pk_bf16_f32 v10, v102, v103
	v_cvt_pk_bf16_f32 v11, v12, v13
	v_cvt_pk_bf16_f32 v12, v98, v99
	v_cvt_pk_bf16_f32 v13, v100, v101
	global_store_dwordx4 v[106:107], v[10:13], off sc0 sc1

; #define LAS __attribute__((address_space(3)))
; __device__ __forceinline__ unsigned short f2bf(float f) { return (unsigned short)(cvt_pk_bf16(f, f) & 0xffffu); }
;   __device__ __forceinline__ bool vt_info(int c32, int b, bf16_t*& base) const { return e->vt_info(c32 + sh, b, base); }
;     ...
;         const int c32 = bcol + wc * 32 + bj * HALF, row0 = brow + ai * HALF + wr * 64;
;         int b0, e0; row_be(row0, b0, e0); bf16_t* vbase;
;         if (epi.vt_info(c32, b0, vbase)) {
; #pragma unroll
;           for (int m = 0; m < 4; ++m) { const float sc = epi.row_scale(row0 + m * 16 + fr);
; #pragma unroll
;             for (int n = 0; n < 2; ++n)
; #pragma unroll
;               for (int j = 0; j < 4; ++j) *(LAS bf16_t*)(T + (n * 16 + fq * 4 + j) * 144 + (m * 16 + fr) * 2) = f2bf(acc[ai][bj][m][n][j] * sc); }
;           asm volatile("s_waitcnt lgkmcnt(0)" ::: "memory");
; #pragma unroll
;           for (int q = 0; q < 4; ++q) { const int ch = lane + 64 * q, d = ch >> 3, ec = ch & 7;
;             *(u32x4*)(vbase + (size_t)d * E + e0 + ec * 8) = *(LAS const u32x4*)(T + d * 144 + ec * 16); }
;           asm volatile("s_waitcnt lgkmcnt(0)" ::: "memory");
.LBB0_971:
	s_or_saveexec_b64 s[8:9], s[12:13]
	s_movk_i32 s0, 0x1200
	v_mul_lo_u32 v11, v135, s0
	v_cndmask_b32_e64 v12, v213, v211, s[6:7]
	v_and_b32_e32 v132, 0x1fc0, v145
	v_and_b32_e32 v10, 63, v134
	v_add3_u32 v11, 0, v11, v12
	v_and_b32_e32 v12, 7, v134
	v_add_u32_e32 v132, 64, v132
	v_lshl_add_u32 v13, v12, 4, v11
	v_lshlrev_b32_e32 v12, 3, v12
	v_cndmask_b32_e32 v132, 0, v132, vcc
	v_subrev_u32_e32 v133, s20, v146
	v_lshlrev_b32_e32 v135, 1, v130
	v_mul_u32_u24_e32 v137, 0x240, v136
	v_lshrrev_b32_e32 v10, 3, v10
	v_cndmask_b32_e32 v149, 0, v147, vcc
	v_subrev_u32_e32 v134, 64, v0
	v_lshlrev_b32_e32 v136, 1, v132
	v_lshl_add_u32 v148, v133, 2, 0
	v_add3_u32 v144, v11, v135, v137
	v_lshlrev_b32_e32 v132, 1, v12
	v_mad_u32_u24 v138, v10, s54, v13
	v_mul_u32_u24_e32 v139, 0x2040, v10
	s_xor_b64 exec, exec, s[8:9]
	s_cbranch_execz .LBB0_973
	v_mad_i32_i24 v10, v149, 6, s1
	v_ashrrev_i32_e32 v11, 31, v10
	v_readlane_b32 s6, v254, 26
	v_lshlrev_b64 v[10:11], 6, v[10:11]
	v_mov_b32_e32 v135, v1
	v_readlane_b32 s7, v254, 27
	v_lshl_add_u64 v[10:11], v[10:11], 0, v[134:135]
	v_add_u32_e32 v133, 0x20000, v148
	v_mov_b64_e32 v[12:13], s[6:7]
	v_mad_u64_u32 v[12:13], s[6:7], v10, s95, v[12:13]
	v_mad_i32_i24 v13, v11, s95, v13
	ds_read2_b32 v[10:11], v133 offset1:16
	v_mov_b32_e32 v137, v1
	s_waitcnt lgkmcnt(0)
	v_mul_f32_e32 v126, v126, v10
	v_cvt_pk_bf16_f32 v126, v126, s0
	ds_write_b16 v144, v126
	v_mul_f32_e32 v126, v127, v10
	v_mul_f32_e32 v122, v122, v10
	v_cvt_pk_bf16_f32 v126, v126, s0
	v_cvt_pk_bf16_f32 v122, v122, s0
	ds_write_b16 v144, v126 offset:144
	v_mul_f32_e32 v126, v128, v10
	ds_write_b16 v144, v122 offset:2304
	v_mul_f32_e32 v122, v123, v10
	v_cvt_pk_bf16_f32 v126, v126, s0
	v_cvt_pk_bf16_f32 v122, v122, s0
	ds_write_b16 v144, v126 offset:288
	v_mul_f32_e32 v126, v129, v10
	ds_write_b16 v144, v122 offset:2448
	v_mul_f32_e32 v122, v124, v10
	v_mul_f32_e32 v10, v125, v10
	v_cvt_pk_bf16_f32 v10, v10, s0
	ds_write_b16 v144, v10 offset:2736
	v_mul_f32_e32 v10, v118, v11
	v_cvt_pk_bf16_f32 v10, v10, s0
	ds_write_b16 v144, v10 offset:32
	v_mul_f32_e32 v10, v119, v11
	v_cvt_pk_bf16_f32 v10, v10, s0
	ds_write_b16 v144, v10 offset:176
	v_mul_f32_e32 v10, v120, v11
	v_cvt_pk_bf16_f32 v10, v10, s0
	ds_write_b16 v144, v10 offset:320
	v_mul_f32_e32 v10, v121, v11
	v_cvt_pk_bf16_f32 v10, v10, s0
	ds_write_b16 v144, v10 offset:464
	v_mul_f32_e32 v10, v114, v11
	v_cvt_pk_bf16_f32 v10, v10, s0
	ds_write_b16 v144, v10 offset:2336
	v_mul_f32_e32 v10, v115, v11
	v_cvt_pk_bf16_f32 v10, v10, s0
	ds_write_b16 v144, v10 offset:2480
	v_mul_f32_e32 v10, v116, v11
	v_cvt_pk_bf16_f32 v10, v10, s0
	ds_write_b16 v144, v10 offset:2624
	v_mul_f32_e32 v10, v117, v11
	v_cvt_pk_bf16_f32 v10, v10, s0
	ds_write_b16 v144, v10 offset:2768
	ds_read2_b32 v[10:11], v133 offset0:32 offset1:48
	v_cvt_pk_bf16_f32 v126, v126, s0
	v_cvt_pk_bf16_f32 v122, v122, s0
	ds_write_b16 v144, v126 offset:432
	ds_write_b16 v144, v122 offset:2592
	s_waitcnt lgkmcnt(0)
	v_mul_f32_e32 v110, v110, v10
	v_cvt_pk_bf16_f32 v110, v110, s0
	ds_write_b16 v144, v110 offset:64
	v_mul_f32_e32 v110, v111, v10
	v_mul_f32_e32 v106, v106, v10
	v_cvt_pk_bf16_f32 v110, v110, s0
	v_cvt_pk_bf16_f32 v106, v106, s0
	ds_write_b16 v144, v110 offset:208
	v_mul_f32_e32 v110, v112, v10
	ds_write_b16 v144, v106 offset:2368
	v_mul_f32_e32 v106, v107, v10
	v_cvt_pk_bf16_f32 v110, v110, s0
	v_cvt_pk_bf16_f32 v106, v106, s0
	ds_write_b16 v144, v110 offset:352
	v_mul_f32_e32 v110, v113, v10
	ds_write_b16 v144, v106 offset:2512
	v_mul_f32_e32 v106, v108, v10
	v_mul_f32_e32 v10, v109, v10
	v_cvt_pk_bf16_f32 v10, v10, s0
	ds_write_b16 v144, v10 offset:2800
	v_mul_f32_e32 v10, v102, v11
	v_cvt_pk_bf16_f32 v10, v10, s0
	ds_write_b16 v144, v10 offset:96
	v_mul_f32_e32 v10, v103, v11
	v_cvt_pk_bf16_f32 v10, v10, s0
	ds_write_b16 v144, v10 offset:240
	v_mul_f32_e32 v10, v104, v11
	v_cvt_pk_bf16_f32 v10, v10, s0
	ds_write_b16 v144, v10 offset:384
	v_mul_f32_e32 v10, v105, v11
	v_cvt_pk_bf16_f32 v10, v10, s0
	ds_write_b16 v144, v10 offset:528
	v_mul_f32_e32 v10, v98, v11
	v_cvt_pk_bf16_f32 v10, v10, s0
	ds_write_b16 v144, v10 offset:2400
	v_mul_f32_e32 v10, v99, v11
	v_cvt_pk_bf16_f32 v10, v10, s0
	ds_write_b16 v144, v10 offset:2544
	v_mul_f32_e32 v10, v100, v11
	v_cvt_pk_bf16_f32 v10, v10, s0
	ds_write_b16 v144, v10 offset:2688
	v_mul_f32_e32 v10, v101, v11
	v_cvt_pk_bf16_f32 v110, v110, s0
	v_cvt_pk_bf16_f32 v106, v106, s0
	v_cvt_pk_bf16_f32 v10, v10, s0
	ds_write_b16 v144, v110 offset:496
	ds_write_b16 v144, v106 offset:2656
	ds_write_b16 v144, v10 offset:2832
	s_waitcnt lgkmcnt(0)
	v_lshl_add_u64 v[10:11], v[12:13], 0, v[136:137]
	v_mov_b32_e32 v133, v1
	v_lshl_add_u64 v[98:99], v[10:11], 0, v[132:133]
	ds_read_b128 v[10:13], v138
	v_lshlrev_b32_e32 v100, 1, v139
	v_mov_b32_e32 v101, v1
	v_lshl_add_u64 v[98:99], v[98:99], 0, v[100:101]
	v_add_co_u32_e32 v100, vcc, 0x20000, v98
	s_waitcnt lgkmcnt(0)
	global_store_dwordx4 v[98:99], v[10:13], off sc0 sc1
	ds_read_b128 v[10:13], v138 offset:1152
	v_addc_co_u32_e32 v101, vcc, 0, v99, vcc
	s_waitcnt lgkmcnt(0)
	global_store_dwordx4 v[100:101], v[10:13], off offset:1024 sc0 sc1
	ds_read_b128 v[10:13], v138 offset:2304
	v_add_co_u32_e32 v100, vcc, 0x40000, v98
	s_nop 1
	v_addc_co_u32_e32 v101, vcc, 0, v99, vcc
	s_waitcnt lgkmcnt(0)
	global_store_dwordx4 v[100:101], v[10:13], off offset:2048 sc0 sc1
	ds_read_b128 v[10:13], v138 offset:3456
	v_add_co_u32_e32 v98, vcc, 0x60000, v98
	s_nop 1
	v_addc_co_u32_e32 v99, vcc, 0, v99, vcc
	s_waitcnt lgkmcnt(0)
	global_store_dwordx4 v[98:99], v[10:13], off offset:3072 sc0 sc1
	s_waitcnt lgkmcnt(0)
; #define LAS __attribute__((address_space(3)))
; __device__ __forceinline__ void store4bf(bf16_t* p, f32x4 v) { u32x2 w; w.x = cvt_pk_bf16(v[0], v[1]); w.y = cvt_pk_bf16(v[2], v[3]); *(u32x2*)p = w; }
; __device__ __forceinline__ void store8bf(bf16_t* p, f32x4 v0, f32x4 v1) { u32x4 w; w.x = cvt_pk_bf16(v0[0], v0[1]); w.y = cvt_pk_bf16(v0[2], v0[3]); w.z = cvt_pk_bf16(v1[0], v1[1]); w.w = cvt_pk_bf16(v1[2], v1[3]); *(u32x4*)p = w; }
;   __device__ __forceinline__ void group(int row, int c32, int fq, f32x4 v0, f32x4 v1) const { e->group(row, c32 + sh, fq, v0, v1); }
;   __device__ __forceinline__ void group(int row, int c32, int fq, f32x4 v0, f32x4 v1) const {
;     int b, e; if (!row_be(row, b, e)) return;
;     const float rs = use_direct ? rs_direct : ((LAS const float*)(lds_raw + RS_OFF))[row - brow];
;     if (c32 < 768) {
;       if (c32 >= 576) return;
;       const int h = c32 / 96, part = (c32 - h * 96) >> 5; const float sc = rs * QSC_A;
;       bf16_t* p = qa + ((size_t)(b * 6 + h) * E + e) * 96 + part * 32 + fq * 4;
;       if (part < 2) store8bf(qa + ((size_t)(b * 6 + h) * E + e) * 96 + part * 32 + fq * 8, v0 * sc, v1 * sc);
;       else { const float2* rp = rope + pos_of_e(e) * 16 + fq * 4; f32x4 o0, o1;
; #pragma unroll
;         for (int j = 0; j < 4; ++j) { const float2 cs = rp[j]; o0[j] = (v0[j] * cs.x - v1[j] * cs.y) * sc; o1[j] = (v1[j] * cs.x + v0[j] * cs.y) * sc; }
;         store4bf(p, o0); store4bf(p + 16, o1); }
;     } else {
;       const int cc = c32 - 768, h = cc >> 7, part = (cc & 127) >> 5;
;       if (part < 2) store8bf(ka + ((size_t)(b * 6 + h) * E + e) * 96 + part * 32 + fq * 8, v0 * rs, v1 * rs);
.LBB0_973:
	s_or_b64 exec, exec, s[8:9]
	s_lshr_b32 s0, s10, 7
	s_and_saveexec_b64 s[6:7], s[4:5]
	s_xor_b64 s[6:7], exec, s[6:7]
	s_cbranch_execz .LBB0_999
	s_movk_i32 s8, 0x7fff
	v_cmp_lt_i32_e32 vcc, s8, v146
	s_and_saveexec_b64 s[8:9], vcc
	s_xor_b64 s[8:9], exec, s[8:9]
	v_cmp_gt_u32_e64 s[10:11], s49, v145
	s_or_saveexec_b64 s[8:9], s[8:9]
	v_mov_b32_e32 v99, 0
	v_mul_i32_i24_e32 v100, 6, v147
	v_mov_b32_e32 v98, v130
	s_xor_b64 exec, exec, s[8:9]
	v_and_b32_e32 v10, 0x1fcf, v146
	v_add_u32_e32 v98, 64, v10
	v_mul_i32_i24_e32 v99, 6, v147
	s_or_b64 s[10:11], s[10:11], exec
	s_or_b64 exec, exec, s[8:9]
	s_and_saveexec_b64 s[8:9], s[10:11]
	s_cbranch_execz .LBB0_980
	v_add_u32_e32 v11, s0, v99
	v_mov_b32_e32 v99, v1
	s_movk_i32 s10, 0x2040
	v_mad_i64_i32 v[12:13], s[10:11], v11, s10, v[98:99]
	v_add_u32_e32 v10, 0x20000, v148
	v_readlane_b32 s10, v254, 4
	ds_read_b32 v10, v10
	v_readlane_b32 s11, v254, 5
	s_waitcnt lgkmcnt(0)
	v_pk_mul_f32 v[94:95], v[94:95], v[10:11] op_sel_hi:[1,0]
	v_mov_b64_e32 v[98:99], s[10:11]
	v_mad_u64_u32 v[98:99], s[10:11], v12, s47, v[98:99]
	v_mad_i32_i24 v99, v13, s47, v99
	v_lshlrev_b32_e32 v12, 1, v0
	v_mov_b32_e32 v13, v1
	v_lshl_add_u64 v[12:13], v[98:99], 0, v[12:13]
	v_lshlrev_b32_e32 v98, 1, v131
	v_mov_b32_e32 v99, v1
	v_lshl_add_u64 v[98:99], v[12:13], 0, v[98:99]
	v_pk_mul_f32 v[12:13], v[96:97], v[10:11] op_sel_hi:[1,0]
	v_pk_mul_f32 v[92:93], v[92:93], v[10:11] op_sel_hi:[1,0]
	v_pk_mul_f32 v[90:91], v[90:91], v[10:11] op_sel_hi:[1,0]
	v_cvt_pk_bf16_f32 v10, v94, v95
	v_cvt_pk_bf16_f32 v11, v12, v13
	v_cvt_pk_bf16_f32 v12, v90, v91
	v_cvt_pk_bf16_f32 v13, v92, v93
	global_store_dwordx4 v[98:99], v[10:13], off sc0 sc1
.LBB0_980:
	s_or_b64 exec, exec, s[8:9]
	v_or_b32_e32 v91, 16, v146
	s_movk_i32 s8, 0x7fff
	v_cmp_lt_i32_e32 vcc, s8, v91
	s_and_saveexec_b64 s[8:9], vcc
	s_xor_b64 s[8:9], exec, s[8:9]
	v_cmp_gt_u32_e64 s[10:11], s49, v145
	s_or_saveexec_b64 s[8:9], s[8:9]
	v_mov_b32_e32 v92, 6
	v_mov_b32_e32 v90, v130
	s_xor_b64 exec, exec, s[8:9]
	v_and_b32_e32 v10, 0x1fdf, v91
	v_add_u32_e32 v90, 64, v10
	v_mul_i32_i24_e32 v92, 6, v147
	s_or_b64 s[10:11], s[10:11], exec
	s_or_b64 exec, exec, s[8:9]
	s_and_saveexec_b64 s[8:9], s[10:11]
	s_cbranch_execz .LBB0_986
	v_subrev_u32_e32 v10, s20, v91
	v_add_u32_e32 v11, s0, v92
	v_mov_b32_e32 v91, v1
	s_movk_i32 s10, 0x2040
	v_lshl_add_u32 v10, v10, 2, 0
	v_mad_i64_i32 v[12:13], s[10:11], v11, s10, v[90:91]
	v_add_u32_e32 v10, 0x20000, v10
	v_readlane_b32 s10, v254, 4
	ds_read_b32 v10, v10
	v_readlane_b32 s11, v254, 5
	s_waitcnt lgkmcnt(0)
	v_pk_mul_f32 v[86:87], v[86:87], v[10:11] op_sel_hi:[1,0]
	v_mov_b64_e32 v[90:91], s[10:11]
	v_mad_u64_u32 v[90:91], s[10:11], v12, s47, v[90:91]
	v_mad_i32_i24 v91, v13, s47, v91
	v_lshlrev_b32_e32 v12, 1, v0
	v_mov_b32_e32 v13, v1
	v_lshl_add_u64 v[12:13], v[90:91], 0, v[12:13]
	v_lshlrev_b32_e32 v90, 1, v131
	v_mov_b32_e32 v91, v1
	v_lshl_add_u64 v[90:91], v[12:13], 0, v[90:91]
	v_pk_mul_f32 v[12:13], v[88:89], v[10:11] op_sel_hi:[1,0]
	v_pk_mul_f32 v[84:85], v[84:85], v[10:11] op_sel_hi:[1,0]
	v_pk_mul_f32 v[82:83], v[82:83], v[10:11] op_sel_hi:[1,0]
	v_cvt_pk_bf16_f32 v10, v86, v87
	v_cvt_pk_bf16_f32 v11, v12, v13
	v_cvt_pk_bf16_f32 v12, v82, v83
	v_cvt_pk_bf16_f32 v13, v84, v85
	global_store_dwordx4 v[90:91], v[10:13], off sc0 sc1
.LBB0_986:
	s_or_b64 exec, exec, s[8:9]
	v_or_b32_e32 v83, 32, v146
	s_movk_i32 s8, 0x7fff
	v_cmp_lt_i32_e32 vcc, s8, v83
	s_and_saveexec_b64 s[8:9], vcc
	s_xor_b64 s[8:9], exec, s[8:9]
	v_cmp_gt_u32_e64 s[10:11], s49, v145
	s_or_saveexec_b64 s[8:9], s[8:9]
	v_mov_b32_e32 v84, 12
	v_mov_b32_e32 v82, v130
	s_xor_b64 exec, exec, s[8:9]
	v_and_b32_e32 v10, 0x1fef, v83
	v_add_u32_e32 v82, 64, v10
	v_mul_i32_i24_e32 v84, 6, v147
	s_or_b64 s[10:11], s[10:11], exec
	s_or_b64 exec, exec, s[8:9]
	s_and_saveexec_b64 s[8:9], s[10:11]
	s_cbranch_execz .LBB0_992
	v_subrev_u32_e32 v10, s20, v83
	v_add_u32_e32 v11, s0, v84
	v_mov_b32_e32 v83, v1
	s_movk_i32 s10, 0x2040
	v_lshl_add_u32 v10, v10, 2, 0
	v_mad_i64_i32 v[12:13], s[10:11], v11, s10, v[82:83]
	v_add_u32_e32 v10, 0x20000, v10
	v_readlane_b32 s10, v254, 4
	ds_read_b32 v10, v10
	v_readlane_b32 s11, v254, 5
	s_waitcnt lgkmcnt(0)
	v_pk_mul_f32 v[78:79], v[78:79], v[10:11] op_sel_hi:[1,0]
	v_mov_b64_e32 v[82:83], s[10:11]
	v_mad_u64_u32 v[82:83], s[10:11], v12, s47, v[82:83]
	v_mad_i32_i24 v83, v13, s47, v83
	v_lshlrev_b32_e32 v12, 1, v0
	v_mov_b32_e32 v13, v1
	v_lshl_add_u64 v[12:13], v[82:83], 0, v[12:13]
	v_lshlrev_b32_e32 v82, 1, v131
	v_mov_b32_e32 v83, v1
	v_lshl_add_u64 v[82:83], v[12:13], 0, v[82:83]
	v_pk_mul_f32 v[12:13], v[80:81], v[10:11] op_sel_hi:[1,0]
	v_pk_mul_f32 v[76:77], v[76:77], v[10:11] op_sel_hi:[1,0]
	v_pk_mul_f32 v[74:75], v[74:75], v[10:11] op_sel_hi:[1,0]
	v_cvt_pk_bf16_f32 v10, v78, v79
	v_cvt_pk_bf16_f32 v11, v12, v13
	v_cvt_pk_bf16_f32 v12, v74, v75
	v_cvt_pk_bf16_f32 v13, v76, v77
	global_store_dwordx4 v[82:83], v[10:13], off sc0 sc1
.LBB0_992:
	s_or_b64 exec, exec, s[8:9]
	v_or_b32_e32 v75, 48, v146
	s_movk_i32 s8, 0x7fff
	v_cmp_lt_i32_e32 vcc, s8, v75
	s_and_saveexec_b64 s[8:9], vcc
	s_xor_b64 s[8:9], exec, s[8:9]
	v_cmp_gt_u32_e64 s[10:11], s49, v145
	s_or_saveexec_b64 s[8:9], s[8:9]
	v_mov_b32_e32 v76, 18
	v_mov_b32_e32 v74, v130
	s_xor_b64 exec, exec, s[8:9]
	v_and_b32_e32 v10, 0x1fff, v75
	v_add_u32_e32 v74, 64, v10
	s_or_b64 s[10:11], s[10:11], exec
	v_mov_b32_e32 v76, v100
	s_or_b64 exec, exec, s[8:9]
	s_and_saveexec_b64 s[8:9], s[10:11]
	s_cbranch_execz .LBB0_998
	v_subrev_u32_e32 v10, s20, v75
	v_add_u32_e32 v11, s0, v76
	v_mov_b32_e32 v75, v1
	s_movk_i32 s10, 0x2040
	v_lshl_add_u32 v10, v10, 2, 0
	v_mad_i64_i32 v[12:13], s[10:11], v11, s10, v[74:75]
	v_add_u32_e32 v10, 0x20000, v10
	v_readlane_b32 s10, v254, 4
	ds_read_b32 v10, v10
	v_readlane_b32 s11, v254, 5
	s_waitcnt lgkmcnt(0)
	v_pk_mul_f32 v[70:71], v[70:71], v[10:11] op_sel_hi:[1,0]
	v_mov_b64_e32 v[74:75], s[10:11]
	v_mad_u64_u32 v[74:75], s[10:11], v12, s47, v[74:75]
	v_mad_i32_i24 v75, v13, s47, v75
	v_lshlrev_b32_e32 v12, 1, v0
	v_mov_b32_e32 v13, v1
	v_lshl_add_u64 v[12:13], v[74:75], 0, v[12:13]
	v_lshlrev_b32_e32 v74, 1, v131
	v_mov_b32_e32 v75, v1
	v_lshl_add_u64 v[74:75], v[12:13], 0, v[74:75]
	v_pk_mul_f32 v[12:13], v[72:73], v[10:11] op_sel_hi:[1,0]
	v_pk_mul_f32 v[68:69], v[68:69], v[10:11] op_sel_hi:[1,0]
	v_pk_mul_f32 v[66:67], v[66:67], v[10:11] op_sel_hi:[1,0]
	v_cvt_pk_bf16_f32 v10, v70, v71
	v_cvt_pk_bf16_f32 v11, v12, v13
	v_cvt_pk_bf16_f32 v12, v66, v67
	v_cvt_pk_bf16_f32 v13, v68, v69
	global_store_dwordx4 v[74:75], v[10:13], off sc0 sc1

; #define LAS __attribute__((address_space(3)))
; __device__ __forceinline__ unsigned short f2bf(float f) { return (unsigned short)(cvt_pk_bf16(f, f) & 0xffffu); }
;   __device__ __forceinline__ bool vt_info(int c32, int b, bf16_t*& base) const { return e->vt_info(c32 + sh, b, base); }
;     ...
;         const int c32 = bcol + wc * 32 + bj * HALF, row0 = brow + ai * HALF + wr * 64;
;         int b0, e0; row_be(row0, b0, e0); bf16_t* vbase;
;         if (epi.vt_info(c32, b0, vbase)) {
; #pragma unroll
;           for (int m = 0; m < 4; ++m) { const float sc = epi.row_scale(row0 + m * 16 + fr);
; #pragma unroll
;             for (int n = 0; n < 2; ++n)
; #pragma unroll
;               for (int j = 0; j < 4; ++j) *(LAS bf16_t*)(T + (n * 16 + fq * 4 + j) * 144 + (m * 16 + fr) * 2) = f2bf(acc[ai][bj][m][n][j] * sc); }
;           asm volatile("s_waitcnt lgkmcnt(0)" ::: "memory");
; #pragma unroll
;           for (int q = 0; q < 4; ++q) { const int ch = lane + 64 * q, d = ch >> 3, ec = ch & 7;
;             *(u32x4*)(vbase + (size_t)d * E + e0 + ec * 8) = *(LAS const u32x4*)(T + d * 144 + ec * 16); }
;           asm volatile("s_waitcnt lgkmcnt(0)" ::: "memory");
.LBB0_999:
	s_andn2_saveexec_b64 s[6:7], s[6:7]
	s_cbranch_execz .LBB0_1001
	v_mad_i32_i24 v10, v149, 6, s0
	v_ashrrev_i32_e32 v11, 31, v10
	v_readlane_b32 s8, v254, 26
	v_lshlrev_b64 v[10:11], 6, v[10:11]
	v_mov_b32_e32 v135, v1
	v_readlane_b32 s9, v254, 27
	v_lshl_add_u64 v[10:11], v[10:11], 0, v[134:135]
	v_add_u32_e32 v98, 0x20000, v148
	v_mov_b64_e32 v[12:13], s[8:9]
	v_mad_u64_u32 v[12:13], s[8:9], v10, s95, v[12:13]
	v_mad_i32_i24 v13, v11, s95, v13
	ds_read2_b32 v[10:11], v98 offset1:16
	v_mov_b32_e32 v137, v1
	v_mov_b32_e32 v133, v1
	s_waitcnt lgkmcnt(0)
	v_mul_f32_e32 v94, v94, v10
	v_cvt_pk_bf16_f32 v94, v94, s0
	ds_write_b16 v144, v94
	v_mul_f32_e32 v94, v95, v10
	v_mul_f32_e32 v90, v90, v10
	v_cvt_pk_bf16_f32 v94, v94, s0
	v_cvt_pk_bf16_f32 v90, v90, s0
	ds_write_b16 v144, v94 offset:144
	v_mul_f32_e32 v94, v96, v10
	ds_write_b16 v144, v90 offset:2304
	v_mul_f32_e32 v90, v91, v10
	v_cvt_pk_bf16_f32 v94, v94, s0
	v_cvt_pk_bf16_f32 v90, v90, s0
	ds_write_b16 v144, v94 offset:288
	v_mul_f32_e32 v94, v97, v10
	ds_write_b16 v144, v90 offset:2448
	v_mul_f32_e32 v90, v92, v10
	v_mul_f32_e32 v10, v93, v10
	v_cvt_pk_bf16_f32 v10, v10, s0
	ds_write_b16 v144, v10 offset:2736
	v_mul_f32_e32 v10, v86, v11
	v_cvt_pk_bf16_f32 v10, v10, s0
	ds_write_b16 v144, v10 offset:32
	v_mul_f32_e32 v10, v87, v11
	v_cvt_pk_bf16_f32 v10, v10, s0
	ds_write_b16 v144, v10 offset:176
	v_mul_f32_e32 v10, v88, v11
	v_cvt_pk_bf16_f32 v10, v10, s0
	ds_write_b16 v144, v10 offset:320
	v_mul_f32_e32 v10, v89, v11
	v_cvt_pk_bf16_f32 v10, v10, s0
	ds_write_b16 v144, v10 offset:464
	v_mul_f32_e32 v10, v82, v11
	v_cvt_pk_bf16_f32 v10, v10, s0
	ds_write_b16 v144, v10 offset:2336
	v_mul_f32_e32 v10, v83, v11
	v_cvt_pk_bf16_f32 v10, v10, s0
	ds_write_b16 v144, v10 offset:2480
	v_mul_f32_e32 v10, v84, v11
	v_cvt_pk_bf16_f32 v10, v10, s0
	ds_write_b16 v144, v10 offset:2624
	v_mul_f32_e32 v10, v85, v11
	v_cvt_pk_bf16_f32 v10, v10, s0
	ds_write_b16 v144, v10 offset:2768
	ds_read2_b32 v[10:11], v98 offset0:32 offset1:48
	v_cvt_pk_bf16_f32 v94, v94, s0
	v_cvt_pk_bf16_f32 v90, v90, s0
	ds_write_b16 v144, v94 offset:432
	ds_write_b16 v144, v90 offset:2592
	s_waitcnt lgkmcnt(0)
	v_mul_f32_e32 v78, v78, v10
	v_cvt_pk_bf16_f32 v78, v78, s0
	ds_write_b16 v144, v78 offset:64
	v_mul_f32_e32 v78, v79, v10
	v_mul_f32_e32 v74, v74, v10
	v_cvt_pk_bf16_f32 v78, v78, s0
	v_cvt_pk_bf16_f32 v74, v74, s0
	ds_write_b16 v144, v78 offset:208
	v_mul_f32_e32 v78, v80, v10
	ds_write_b16 v144, v74 offset:2368
	v_mul_f32_e32 v74, v75, v10
	v_cvt_pk_bf16_f32 v78, v78, s0
	v_cvt_pk_bf16_f32 v74, v74, s0
	ds_write_b16 v144, v78 offset:352
	v_mul_f32_e32 v78, v81, v10
	ds_write_b16 v144, v74 offset:2512
	v_mul_f32_e32 v74, v76, v10
	v_mul_f32_e32 v10, v77, v10
	v_cvt_pk_bf16_f32 v10, v10, s0
	ds_write_b16 v144, v10 offset:2800
	v_mul_f32_e32 v10, v70, v11
	v_cvt_pk_bf16_f32 v10, v10, s0
	ds_write_b16 v144, v10 offset:96
	v_mul_f32_e32 v10, v71, v11
	v_cvt_pk_bf16_f32 v10, v10, s0
	ds_write_b16 v144, v10 offset:240
	v_mul_f32_e32 v10, v72, v11
	v_cvt_pk_bf16_f32 v10, v10, s0
	ds_write_b16 v144, v10 offset:384
	v_mul_f32_e32 v10, v73, v11
	v_cvt_pk_bf16_f32 v10, v10, s0
	ds_write_b16 v144, v10 offset:528
	v_mul_f32_e32 v10, v66, v11
	v_cvt_pk_bf16_f32 v10, v10, s0
	ds_write_b16 v144, v10 offset:2400
	v_mul_f32_e32 v10, v67, v11
	v_cvt_pk_bf16_f32 v10, v10, s0
	ds_write_b16 v144, v10 offset:2544
	v_mul_f32_e32 v10, v68, v11
	v_cvt_pk_bf16_f32 v10, v10, s0
	ds_write_b16 v144, v10 offset:2688
	v_mul_f32_e32 v10, v69, v11
	v_cvt_pk_bf16_f32 v78, v78, s0
	v_cvt_pk_bf16_f32 v74, v74, s0
	v_cvt_pk_bf16_f32 v10, v10, s0
	ds_write_b16 v144, v78 offset:496
	ds_write_b16 v144, v74 offset:2656
	ds_write_b16 v144, v10 offset:2832
	s_waitcnt lgkmcnt(0)
	v_lshl_add_u64 v[10:11], v[12:13], 0, v[136:137]
	v_lshl_add_u64 v[66:67], v[10:11], 0, v[132:133]
	ds_read_b128 v[10:13], v138
	v_lshlrev_b32_e32 v68, 1, v139
	v_mov_b32_e32 v69, v1
	v_lshl_add_u64 v[66:67], v[66:67], 0, v[68:69]
	v_add_co_u32_e32 v68, vcc, 0x20000, v66
	s_waitcnt lgkmcnt(0)
	global_store_dwordx4 v[66:67], v[10:13], off sc0 sc1
	ds_read_b128 v[10:13], v138 offset:1152
	v_addc_co_u32_e32 v69, vcc, 0, v67, vcc
	s_waitcnt lgkmcnt(0)
	global_store_dwordx4 v[68:69], v[10:13], off offset:1024 sc0 sc1
	ds_read_b128 v[10:13], v138 offset:2304
	v_add_co_u32_e32 v68, vcc, 0x40000, v66
	s_nop 1
	v_addc_co_u32_e32 v69, vcc, 0, v67, vcc
	s_waitcnt lgkmcnt(0)
	global_store_dwordx4 v[68:69], v[10:13], off offset:2048 sc0 sc1
	ds_read_b128 v[10:13], v138 offset:3456
	v_add_co_u32_e32 v66, vcc, 0x60000, v66
	s_nop 1
	v_addc_co_u32_e32 v67, vcc, 0, v67, vcc
	s_waitcnt lgkmcnt(0)
	global_store_dwordx4 v[66:67], v[10:13], off offset:3072 sc0 sc1
	s_waitcnt lgkmcnt(0)
.LBB0_1001:
	s_or_b64 exec, exec, s[6:7]
	v_add_u32_e32 v68, 0x80, v145
	s_mov_b32 s6, 0x8000
	v_cmp_gt_i32_e32 vcc, s6, v68
	v_ashrrev_i32_e32 v70, 13, v68
	v_or_b32_e32 v69, v68, v130
	s_and_saveexec_b64 s[6:7], s[4:5]
	s_xor_b64 s[8:9], exec, s[6:7]
	s_cbranch_execz .LBB0_1023
	s_movk_i32 s6, 0x7fff
	v_cmp_lt_i32_e64 s[6:7], s6, v69
	s_and_saveexec_b64 s[12:13], s[6:7]
	s_xor_b64 s[6:7], exec, s[12:13]
	v_cmp_gt_u32_e64 s[10:11], s49, v68
	s_or_saveexec_b64 s[6:7], s[6:7]
	v_mov_b32_e32 v67, 0
	v_mov_b32_e32 v66, v130
	s_xor_b64 exec, exec, s[6:7]
	v_and_b32_e32 v10, 0x1fcf, v69
	v_add_u32_e32 v66, 64, v10
	v_mul_i32_i24_e32 v67, 6, v70
	s_or_b64 s[10:11], s[10:11], exec
	s_or_b64 exec, exec, s[6:7]
	s_and_saveexec_b64 s[6:7], s[10:11]
	s_cbranch_execz .LBB0_1008
	v_subrev_u32_e32 v10, s20, v69
	v_add_u32_e32 v11, s1, v67
	v_mov_b32_e32 v67, v1
	s_movk_i32 s10, 0x2040
	v_lshl_add_u32 v10, v10, 2, 0
	v_mad_i64_i32 v[12:13], s[10:11], v11, s10, v[66:67]
	v_add_u32_e32 v10, 0x20000, v10
	v_readlane_b32 s10, v254, 4
	ds_read_b32 v10, v10
	v_readlane_b32 s11, v254, 5
	s_waitcnt lgkmcnt(0)
	v_pk_mul_f32 v[62:63], v[62:63], v[10:11] op_sel_hi:[1,0]
	v_mov_b64_e32 v[66:67], s[10:11]
	v_mad_u64_u32 v[66:67], s[10:11], v12, s47, v[66:67]
	v_mad_i32_i24 v67, v13, s47, v67
	v_lshlrev_b32_e32 v12, 1, v0
	v_mov_b32_e32 v13, v1
	v_lshl_add_u64 v[12:13], v[66:67], 0, v[12:13]
	v_lshlrev_b32_e32 v66, 1, v131
	v_mov_b32_e32 v67, v1
	v_lshl_add_u64 v[66:67], v[12:13], 0, v[66:67]
	v_pk_mul_f32 v[12:13], v[64:65], v[10:11] op_sel_hi:[1,0]
	v_pk_mul_f32 v[60:61], v[60:61], v[10:11] op_sel_hi:[1,0]
	v_pk_mul_f32 v[58:59], v[58:59], v[10:11] op_sel_hi:[1,0]
	v_cvt_pk_bf16_f32 v10, v62, v63
	v_cvt_pk_bf16_f32 v11, v12, v13
	v_cvt_pk_bf16_f32 v12, v58, v59
	v_cvt_pk_bf16_f32 v13, v60, v61
	global_store_dwordx4 v[66:67], v[10:13], off sc0 sc1

; #define LAS __attribute__((address_space(3)))
; __device__ __forceinline__ void store4bf(bf16_t* p, f32x4 v) { u32x2 w; w.x = cvt_pk_bf16(v[0], v[1]); w.y = cvt_pk_bf16(v[2], v[3]); *(u32x2*)p = w; }
; __device__ __forceinline__ void store8bf(bf16_t* p, f32x4 v0, f32x4 v1) { u32x4 w; w.x = cvt_pk_bf16(v0[0], v0[1]); w.y = cvt_pk_bf16(v0[2], v0[3]); w.z = cvt_pk_bf16(v1[0], v1[1]); w.w = cvt_pk_bf16(v1[2], v1[3]); *(u32x4*)p = w; }
;   __device__ __forceinline__ void group(int row, int c32, int fq, f32x4 v0, f32x4 v1) const { e->group(row, c32 + sh, fq, v0, v1); }
;   __device__ __forceinline__ void group(int row, int c32, int fq, f32x4 v0, f32x4 v1) const {
;     int b, e; if (!row_be(row, b, e)) return;
;     const float rs = use_direct ? rs_direct : ((LAS const float*)(lds_raw + RS_OFF))[row - brow];
;     if (c32 < 768) {
;       if (c32 >= 576) return;
;       const int h = c32 / 96, part = (c32 - h * 96) >> 5; const float sc = rs * QSC_A;
;       bf16_t* p = qa + ((size_t)(b * 6 + h) * E + e) * 96 + part * 32 + fq * 4;
;       if (part < 2) store8bf(qa + ((size_t)(b * 6 + h) * E + e) * 96 + part * 32 + fq * 8, v0 * sc, v1 * sc);
;       else { const float2* rp = rope + pos_of_e(e) * 16 + fq * 4; f32x4 o0, o1;
; #pragma unroll
;         for (int j = 0; j < 4; ++j) { const float2 cs = rp[j]; o0[j] = (v0[j] * cs.x - v1[j] * cs.y) * sc; o1[j] = (v1[j] * cs.x + v0[j] * cs.y) * sc; }
;         store4bf(p, o0); store4bf(p + 16, o1); }
;     } else {
;       const int cc = c32 - 768, h = cc >> 7, part = (cc & 127) >> 5;
;       if (part < 2) store8bf(ka + ((size_t)(b * 6 + h) * E + e) * 96 + part * 32 + fq * 8, v0 * rs, v1 * rs);
.LBB0_1011:
	v_subrev_u32_e32 v10, s20, v59
	v_mad_i32_i24 v11, v60, 6, s1
	v_mov_b32_e32 v59, v1
	s_movk_i32 s10, 0x2040
	v_lshl_add_u32 v10, v10, 2, 0
	v_mad_i64_i32 v[12:13], s[10:11], v11, s10, v[58:59]
	v_add_u32_e32 v10, 0x20000, v10
	v_readlane_b32 s10, v254, 4
	ds_read_b32 v10, v10
	v_readlane_b32 s11, v254, 5
	s_waitcnt lgkmcnt(0)
	v_pk_mul_f32 v[54:55], v[54:55], v[10:11] op_sel_hi:[1,0]
	v_mov_b64_e32 v[58:59], s[10:11]
	v_mad_u64_u32 v[58:59], s[10:11], v12, s47, v[58:59]
	v_mad_i32_i24 v59, v13, s47, v59
	v_lshlrev_b32_e32 v12, 1, v0
	v_mov_b32_e32 v13, v1
	v_lshl_add_u64 v[12:13], v[58:59], 0, v[12:13]
	v_lshlrev_b32_e32 v58, 1, v131
	v_mov_b32_e32 v59, v1
	v_lshl_add_u64 v[58:59], v[12:13], 0, v[58:59]
	v_pk_mul_f32 v[12:13], v[56:57], v[10:11] op_sel_hi:[1,0]
	v_pk_mul_f32 v[52:53], v[52:53], v[10:11] op_sel_hi:[1,0]
	v_pk_mul_f32 v[50:51], v[50:51], v[10:11] op_sel_hi:[1,0]
	v_cvt_pk_bf16_f32 v10, v54, v55
	v_cvt_pk_bf16_f32 v11, v12, v13
	v_cvt_pk_bf16_f32 v12, v50, v51
	v_cvt_pk_bf16_f32 v13, v52, v53
	global_store_dwordx4 v[58:59], v[10:13], off sc0 sc1

; #define LAS __attribute__((address_space(3)))
; __device__ __forceinline__ void store4bf(bf16_t* p, f32x4 v) { u32x2 w; w.x = cvt_pk_bf16(v[0], v[1]); w.y = cvt_pk_bf16(v[2], v[3]); *(u32x2*)p = w; }
; __device__ __forceinline__ void store8bf(bf16_t* p, f32x4 v0, f32x4 v1) { u32x4 w; w.x = cvt_pk_bf16(v0[0], v0[1]); w.y = cvt_pk_bf16(v0[2], v0[3]); w.z = cvt_pk_bf16(v1[0], v1[1]); w.w = cvt_pk_bf16(v1[2], v1[3]); *(u32x4*)p = w; }
;   __device__ __forceinline__ void group(int row, int c32, int fq, f32x4 v0, f32x4 v1) const { e->group(row, c32 + sh, fq, v0, v1); }
;   __device__ __forceinline__ void group(int row, int c32, int fq, f32x4 v0, f32x4 v1) const {
;     int b, e; if (!row_be(row, b, e)) return;
;     const float rs = use_direct ? rs_direct : ((LAS const float*)(lds_raw + RS_OFF))[row - brow];
;     if (c32 < 768) {
;       if (c32 >= 576) return;
;       const int h = c32 / 96, part = (c32 - h * 96) >> 5; const float sc = rs * QSC_A;
;       bf16_t* p = qa + ((size_t)(b * 6 + h) * E + e) * 96 + part * 32 + fq * 4;
;       if (part < 2) store8bf(qa + ((size_t)(b * 6 + h) * E + e) * 96 + part * 32 + fq * 8, v0 * sc, v1 * sc);
;       else { const float2* rp = rope + pos_of_e(e) * 16 + fq * 4; f32x4 o0, o1;
; #pragma unroll
;         for (int j = 0; j < 4; ++j) { const float2 cs = rp[j]; o0[j] = (v0[j] * cs.x - v1[j] * cs.y) * sc; o1[j] = (v1[j] * cs.x + v0[j] * cs.y) * sc; }
;         store4bf(p, o0); store4bf(p + 16, o1); }
;     } else {
;       const int cc = c32 - 768, h = cc >> 7, part = (cc & 127) >> 5;
;       if (part < 2) store8bf(ka + ((size_t)(b * 6 + h) * E + e) * 96 + part * 32 + fq * 8, v0 * rs, v1 * rs);
.LBB0_1015:
	v_subrev_u32_e32 v10, s20, v51
	v_mad_i32_i24 v11, v52, 6, s1
	v_mov_b32_e32 v51, v1
	s_movk_i32 s10, 0x2040
	v_lshl_add_u32 v10, v10, 2, 0
	v_mad_i64_i32 v[12:13], s[10:11], v11, s10, v[50:51]
	v_add_u32_e32 v10, 0x20000, v10
	v_readlane_b32 s10, v254, 4
	ds_read_b32 v10, v10
	v_readlane_b32 s11, v254, 5
	s_waitcnt lgkmcnt(0)
	v_pk_mul_f32 v[46:47], v[46:47], v[10:11] op_sel_hi:[1,0]
	v_mov_b64_e32 v[50:51], s[10:11]
	v_mad_u64_u32 v[50:51], s[10:11], v12, s47, v[50:51]
	v_mad_i32_i24 v51, v13, s47, v51
	v_lshlrev_b32_e32 v12, 1, v0
	v_mov_b32_e32 v13, v1
	v_lshl_add_u64 v[12:13], v[50:51], 0, v[12:13]
	v_lshlrev_b32_e32 v50, 1, v131
	v_mov_b32_e32 v51, v1
	v_lshl_add_u64 v[50:51], v[12:13], 0, v[50:51]
	v_pk_mul_f32 v[12:13], v[48:49], v[10:11] op_sel_hi:[1,0]
	v_pk_mul_f32 v[44:45], v[44:45], v[10:11] op_sel_hi:[1,0]
	v_pk_mul_f32 v[42:43], v[42:43], v[10:11] op_sel_hi:[1,0]
	v_cvt_pk_bf16_f32 v10, v46, v47
	v_cvt_pk_bf16_f32 v11, v12, v13
	v_cvt_pk_bf16_f32 v12, v42, v43
	v_cvt_pk_bf16_f32 v13, v44, v45
	global_store_dwordx4 v[50:51], v[10:13], off sc0 sc1
.LBB0_1016:
	s_or_b64 exec, exec, s[6:7]
	v_or_b32_e32 v43, 48, v69
	s_movk_i32 s6, 0x7fff
	v_cmp_lt_i32_e64 s[6:7], s6, v43
	s_and_saveexec_b64 s[12:13], s[6:7]
	s_xor_b64 s[6:7], exec, s[12:13]
	v_cmp_gt_u32_e64 s[10:11], s49, v68
	s_or_saveexec_b64 s[6:7], s[6:7]
	v_mov_b32_e32 v44, 18
	v_mov_b32_e32 v42, v130
	s_xor_b64 exec, exec, s[6:7]
	v_and_b32_e32 v10, 0x1fff, v43
	v_add_u32_e32 v42, 64, v10
	v_mul_i32_i24_e32 v44, 6, v70
	s_or_b64 s[10:11], s[10:11], exec
	s_or_b64 exec, exec, s[6:7]
	s_and_saveexec_b64 s[6:7], s[10:11]
	s_cbranch_execz .LBB0_1022
	v_subrev_u32_e32 v10, s20, v43
	v_add_u32_e32 v11, s1, v44
	v_mov_b32_e32 v43, v1
	s_movk_i32 s10, 0x2040
	v_lshl_add_u32 v10, v10, 2, 0
	v_mad_i64_i32 v[12:13], s[10:11], v11, s10, v[42:43]
	v_add_u32_e32 v10, 0x20000, v10
	v_readlane_b32 s10, v254, 4
	ds_read_b32 v10, v10
	v_readlane_b32 s11, v254, 5
	s_waitcnt lgkmcnt(0)
	v_pk_mul_f32 v[38:39], v[38:39], v[10:11] op_sel_hi:[1,0]
	v_mov_b64_e32 v[42:43], s[10:11]
	v_mad_u64_u32 v[42:43], s[10:11], v12, s47, v[42:43]
	v_mad_i32_i24 v43, v13, s47, v43
	v_lshlrev_b32_e32 v12, 1, v0
	v_mov_b32_e32 v13, v1
	v_lshl_add_u64 v[12:13], v[42:43], 0, v[12:13]
	v_lshlrev_b32_e32 v42, 1, v131
	v_mov_b32_e32 v43, v1
	v_lshl_add_u64 v[42:43], v[12:13], 0, v[42:43]
	v_pk_mul_f32 v[12:13], v[40:41], v[10:11] op_sel_hi:[1,0]
	v_pk_mul_f32 v[36:37], v[36:37], v[10:11] op_sel_hi:[1,0]
	v_pk_mul_f32 v[34:35], v[34:35], v[10:11] op_sel_hi:[1,0]
	v_cvt_pk_bf16_f32 v10, v38, v39
	v_cvt_pk_bf16_f32 v11, v12, v13
	v_cvt_pk_bf16_f32 v12, v34, v35
	v_cvt_pk_bf16_f32 v13, v36, v37
	global_store_dwordx4 v[42:43], v[10:13], off sc0 sc1

; #define LAS __attribute__((address_space(3)))
; __device__ __forceinline__ unsigned short f2bf(float f) { return (unsigned short)(cvt_pk_bf16(f, f) & 0xffffu); }
;   __device__ __forceinline__ bool vt_info(int c32, int b, bf16_t*& base) const { return e->vt_info(c32 + sh, b, base); }
;     ...
;         const int c32 = bcol + wc * 32 + bj * HALF, row0 = brow + ai * HALF + wr * 64;
;         int b0, e0; row_be(row0, b0, e0); bf16_t* vbase;
;         if (epi.vt_info(c32, b0, vbase)) {
; #pragma unroll
;           for (int m = 0; m < 4; ++m) { const float sc = epi.row_scale(row0 + m * 16 + fr);
; #pragma unroll
;             for (int n = 0; n < 2; ++n)
; #pragma unroll
;               for (int j = 0; j < 4; ++j) *(LAS bf16_t*)(T + (n * 16 + fq * 4 + j) * 144 + (m * 16 + fr) * 2) = f2bf(acc[ai][bj][m][n][j] * sc); }
;           asm volatile("s_waitcnt lgkmcnt(0)" ::: "memory");
; #pragma unroll
;           for (int q = 0; q < 4; ++q) { const int ch = lane + 64 * q, d = ch >> 3, ec = ch & 7;
;             *(u32x4*)(vbase + (size_t)d * E + e0 + ec * 8) = *(LAS const u32x4*)(T + d * 144 + ec * 16); }
;           asm volatile("s_waitcnt lgkmcnt(0)" ::: "memory");
.LBB0_1023:
	s_or_saveexec_b64 s[6:7], s[8:9]
	v_and_b32_e32 v10, 0x1fc0, v68
	v_add_u32_e32 v10, 64, v10
	v_cndmask_b32_e32 v10, 0, v10, vcc
	v_subrev_u32_e32 v11, s20, v69
	v_cndmask_b32_e32 v72, 0, v70, vcc
	v_lshlrev_b32_e32 v66, 1, v10
	v_lshl_add_u32 v71, v11, 2, 0
	s_xor_b64 exec, exec, s[6:7]
	s_cbranch_execz .LBB0_1153
	v_mad_i32_i24 v10, v72, 6, s1
	v_ashrrev_i32_e32 v11, 31, v10
	v_readlane_b32 s8, v254, 26
	v_lshlrev_b64 v[10:11], 6, v[10:11]
	v_mov_b32_e32 v135, v1
	v_readlane_b32 s9, v254, 27
	v_lshl_add_u64 v[10:11], v[10:11], 0, v[134:135]
	v_add_u32_e32 v67, 0x20000, v71
	v_mov_b64_e32 v[12:13], s[8:9]
	v_mad_u64_u32 v[12:13], s[8:9], v10, s95, v[12:13]
	v_mad_i32_i24 v13, v11, s95, v13
	ds_read2_b32 v[10:11], v67 offset1:16
	v_mov_b32_e32 v133, v1
	s_waitcnt lgkmcnt(0)
	v_mul_f32_e32 v62, v62, v10
	v_cvt_pk_bf16_f32 v62, v62, s0
	ds_write_b16 v144, v62
	v_mul_f32_e32 v62, v63, v10
	v_mul_f32_e32 v58, v58, v10
	v_cvt_pk_bf16_f32 v62, v62, s0
	v_cvt_pk_bf16_f32 v58, v58, s0
	ds_write_b16 v144, v62 offset:144
	v_mul_f32_e32 v62, v64, v10
	ds_write_b16 v144, v58 offset:2304
	v_mul_f32_e32 v58, v59, v10
	v_cvt_pk_bf16_f32 v62, v62, s0
	v_cvt_pk_bf16_f32 v58, v58, s0
	ds_write_b16 v144, v62 offset:288
	v_mul_f32_e32 v62, v65, v10
	ds_write_b16 v144, v58 offset:2448
	v_mul_f32_e32 v58, v60, v10
	v_mul_f32_e32 v10, v61, v10
	v_cvt_pk_bf16_f32 v10, v10, s0
	ds_write_b16 v144, v10 offset:2736
	v_mul_f32_e32 v10, v54, v11
	v_cvt_pk_bf16_f32 v10, v10, s0
	ds_write_b16 v144, v10 offset:32
	v_mul_f32_e32 v10, v55, v11
	v_cvt_pk_bf16_f32 v10, v10, s0
	ds_write_b16 v144, v10 offset:176
	v_mul_f32_e32 v10, v56, v11
	v_cvt_pk_bf16_f32 v10, v10, s0
	ds_write_b16 v144, v10 offset:320
	v_mul_f32_e32 v10, v57, v11
	v_cvt_pk_bf16_f32 v10, v10, s0
	ds_write_b16 v144, v10 offset:464
	v_mul_f32_e32 v10, v50, v11
	v_cvt_pk_bf16_f32 v10, v10, s0
	ds_write_b16 v144, v10 offset:2336
	v_mul_f32_e32 v10, v51, v11
	v_cvt_pk_bf16_f32 v10, v10, s0
	ds_write_b16 v144, v10 offset:2480
	v_mul_f32_e32 v10, v52, v11
	v_cvt_pk_bf16_f32 v10, v10, s0
	ds_write_b16 v144, v10 offset:2624
	v_mul_f32_e32 v10, v53, v11
	v_cvt_pk_bf16_f32 v10, v10, s0
	ds_write_b16 v144, v10 offset:2768
	ds_read2_b32 v[10:11], v67 offset0:32 offset1:48
	v_cvt_pk_bf16_f32 v62, v62, s0
	v_cvt_pk_bf16_f32 v58, v58, s0
	ds_write_b16 v144, v62 offset:432
	ds_write_b16 v144, v58 offset:2592
	s_waitcnt lgkmcnt(0)
	v_mul_f32_e32 v46, v46, v10
	v_cvt_pk_bf16_f32 v46, v46, s0
	ds_write_b16 v144, v46 offset:64
	v_mul_f32_e32 v46, v47, v10
	v_mul_f32_e32 v42, v42, v10
	v_cvt_pk_bf16_f32 v46, v46, s0
	v_cvt_pk_bf16_f32 v42, v42, s0
	ds_write_b16 v144, v46 offset:208
	v_mul_f32_e32 v46, v48, v10
	ds_write_b16 v144, v42 offset:2368
	v_mul_f32_e32 v42, v43, v10
	v_cvt_pk_bf16_f32 v46, v46, s0
	v_cvt_pk_bf16_f32 v42, v42, s0
	ds_write_b16 v144, v46 offset:352
	v_mul_f32_e32 v46, v49, v10
	ds_write_b16 v144, v42 offset:2512
	v_mul_f32_e32 v42, v44, v10
	v_mul_f32_e32 v10, v45, v10
	v_cvt_pk_bf16_f32 v10, v10, s0
	ds_write_b16 v144, v10 offset:2800
	v_mul_f32_e32 v10, v38, v11
	v_cvt_pk_bf16_f32 v10, v10, s0
	ds_write_b16 v144, v10 offset:96
	v_mul_f32_e32 v10, v39, v11
	v_cvt_pk_bf16_f32 v10, v10, s0
	ds_write_b16 v144, v10 offset:240
	v_mul_f32_e32 v10, v40, v11
	v_cvt_pk_bf16_f32 v10, v10, s0
	ds_write_b16 v144, v10 offset:384
	v_mul_f32_e32 v10, v41, v11
	v_cvt_pk_bf16_f32 v10, v10, s0
	ds_write_b16 v144, v10 offset:528
	v_mul_f32_e32 v10, v34, v11
	v_cvt_pk_bf16_f32 v10, v10, s0
	ds_write_b16 v144, v10 offset:2400
	v_mul_f32_e32 v10, v35, v11
	v_cvt_pk_bf16_f32 v10, v10, s0
	ds_write_b16 v144, v10 offset:2544
	v_mul_f32_e32 v10, v36, v11
	v_cvt_pk_bf16_f32 v10, v10, s0
	ds_write_b16 v144, v10 offset:2688
	v_mul_f32_e32 v10, v37, v11
	v_cvt_pk_bf16_f32 v46, v46, s0
	v_cvt_pk_bf16_f32 v42, v42, s0
	v_cvt_pk_bf16_f32 v10, v10, s0
	ds_write_b16 v144, v46 offset:496
	ds_write_b16 v144, v42 offset:2656
	ds_write_b16 v144, v10 offset:2832
	v_mov_b32_e32 v67, v1
	s_waitcnt lgkmcnt(0)
	v_lshl_add_u64 v[10:11], v[12:13], 0, v[66:67]
	v_lshl_add_u64 v[34:35], v[10:11], 0, v[132:133]
	ds_read_b128 v[10:13], v138
	v_lshlrev_b32_e32 v36, 1, v139
	v_mov_b32_e32 v37, v1
	v_lshl_add_u64 v[34:35], v[34:35], 0, v[36:37]
	v_add_co_u32_e32 v36, vcc, 0x20000, v34
	s_waitcnt lgkmcnt(0)
	global_store_dwordx4 v[34:35], v[10:13], off sc0 sc1
	ds_read_b128 v[10:13], v138 offset:1152
	v_addc_co_u32_e32 v37, vcc, 0, v35, vcc
	s_waitcnt lgkmcnt(0)
	global_store_dwordx4 v[36:37], v[10:13], off offset:1024 sc0 sc1
	ds_read_b128 v[10:13], v138 offset:2304
	v_add_co_u32_e32 v36, vcc, 0x40000, v34
	s_nop 1
	v_addc_co_u32_e32 v37, vcc, 0, v35, vcc
	s_waitcnt lgkmcnt(0)
	global_store_dwordx4 v[36:37], v[10:13], off offset:2048 sc0 sc1
	ds_read_b128 v[10:13], v138 offset:3456
	v_add_co_u32_e32 v34, vcc, 0x60000, v34
	s_nop 1
	v_addc_co_u32_e32 v35, vcc, 0, v35, vcc
	s_waitcnt lgkmcnt(0)
	global_store_dwordx4 v[34:35], v[10:13], off offset:3072 sc0 sc1
	s_waitcnt lgkmcnt(0)
	s_or_b64 exec, exec, s[6:7]
	s_and_saveexec_b64 s[6:7], s[4:5]
	s_xor_b64 s[4:5], exec, s[6:7]
	s_cbranch_execnz .LBB0_1154

; #define LAS __attribute__((address_space(3)))
; __device__ __forceinline__ unsigned short f2bf(float f) { return (unsigned short)(cvt_pk_bf16(f, f) & 0xffffu); }
;   __device__ __forceinline__ bool vt_info(int c32, int b, bf16_t*& base) const { return e->vt_info(c32 + sh, b, base); }
;     ...
;         const int c32 = bcol + wc * 32 + bj * HALF, row0 = brow + ai * HALF + wr * 64;
;         int b0, e0; row_be(row0, b0, e0); bf16_t* vbase;
;         if (epi.vt_info(c32, b0, vbase)) {
; #pragma unroll
;           for (int m = 0; m < 4; ++m) { const float sc = epi.row_scale(row0 + m * 16 + fr);
; #pragma unroll
;             for (int n = 0; n < 2; ++n)
; #pragma unroll
;               for (int j = 0; j < 4; ++j) *(LAS bf16_t*)(T + (n * 16 + fq * 4 + j) * 144 + (m * 16 + fr) * 2) = f2bf(acc[ai][bj][m][n][j] * sc); }
;           asm volatile("s_waitcnt lgkmcnt(0)" ::: "memory");
; #pragma unroll
;           for (int q = 0; q < 4; ++q) { const int ch = lane + 64 * q, d = ch >> 3, ec = ch & 7;
;             *(u32x4*)(vbase + (size_t)d * E + e0 + ec * 8) = *(LAS const u32x4*)(T + d * 144 + ec * 16); }
;           asm volatile("s_waitcnt lgkmcnt(0)" ::: "memory");
.LBB0_1026:
	v_mad_i32_i24 v10, v72, 6, s0
	v_ashrrev_i32_e32 v11, 31, v10
	v_readlane_b32 s0, v254, 26
	v_lshlrev_b64 v[10:11], 6, v[10:11]
	v_mov_b32_e32 v135, v1
	v_readlane_b32 s1, v254, 27
	v_lshl_add_u64 v[10:11], v[10:11], 0, v[134:135]
	v_add_u32_e32 v0, 0x20000, v71
	v_mov_b64_e32 v[12:13], s[0:1]
	v_mad_u64_u32 v[12:13], s[0:1], v10, s95, v[12:13]
	v_mad_i32_i24 v13, v11, s95, v13
	ds_read2_b32 v[10:11], v0 offset1:16
	v_mov_b32_e32 v67, v1
	v_mov_b32_e32 v133, v1
	s_waitcnt lgkmcnt(0)
	v_mul_f32_e32 v30, v30, v10
	v_cvt_pk_bf16_f32 v30, v30, s0
	ds_write_b16 v144, v30
	v_mul_f32_e32 v30, v31, v10
	v_mul_f32_e32 v26, v26, v10
	v_cvt_pk_bf16_f32 v30, v30, s0
	v_cvt_pk_bf16_f32 v26, v26, s0
	ds_write_b16 v144, v30 offset:144
	v_mul_f32_e32 v30, v32, v10
	ds_write_b16 v144, v26 offset:2304
	v_mul_f32_e32 v26, v27, v10
	v_cvt_pk_bf16_f32 v30, v30, s0
	v_cvt_pk_bf16_f32 v26, v26, s0
	ds_write_b16 v144, v30 offset:288
	v_mul_f32_e32 v30, v33, v10
	ds_write_b16 v144, v26 offset:2448
	v_mul_f32_e32 v26, v28, v10
	v_mul_f32_e32 v10, v29, v10
	v_cvt_pk_bf16_f32 v10, v10, s0
	ds_write_b16 v144, v10 offset:2736
	v_mul_f32_e32 v10, v22, v11
	v_cvt_pk_bf16_f32 v10, v10, s0
	ds_write_b16 v144, v10 offset:32
	v_mul_f32_e32 v10, v23, v11
	v_cvt_pk_bf16_f32 v10, v10, s0
	ds_write_b16 v144, v10 offset:176
	v_mul_f32_e32 v10, v24, v11
	v_cvt_pk_bf16_f32 v10, v10, s0
	ds_write_b16 v144, v10 offset:320
	v_mul_f32_e32 v10, v25, v11
	v_cvt_pk_bf16_f32 v10, v10, s0
	ds_write_b16 v144, v10 offset:464
	v_mul_f32_e32 v10, v18, v11
	v_cvt_pk_bf16_f32 v10, v10, s0
	ds_write_b16 v144, v10 offset:2336
	v_mul_f32_e32 v10, v19, v11
	v_cvt_pk_bf16_f32 v10, v10, s0
	ds_write_b16 v144, v10 offset:2480
	v_mul_f32_e32 v10, v20, v11
	v_cvt_pk_bf16_f32 v10, v10, s0
	ds_write_b16 v144, v10 offset:2624
	v_mul_f32_e32 v10, v21, v11
	v_cvt_pk_bf16_f32 v10, v10, s0
	ds_write_b16 v144, v10 offset:2768
	ds_read2_b32 v[10:11], v0 offset0:32 offset1:48
	v_cvt_pk_bf16_f32 v30, v30, s0
	v_cvt_pk_bf16_f32 v26, v26, s0
	ds_write_b16 v144, v30 offset:432
	ds_write_b16 v144, v26 offset:2592
	s_waitcnt lgkmcnt(0)
	v_mul_f32_e32 v0, v14, v10
	v_cvt_pk_bf16_f32 v0, v0, s0
	ds_write_b16 v144, v0 offset:64
	v_mul_f32_e32 v0, v15, v10
	v_cvt_pk_bf16_f32 v0, v0, s0
	ds_write_b16 v144, v0 offset:208
	v_mul_f32_e32 v0, v16, v10
	v_cvt_pk_bf16_f32 v0, v0, s0
	ds_write_b16 v144, v0 offset:352
	v_mul_f32_e32 v0, v17, v10
	v_cvt_pk_bf16_f32 v0, v0, s0
	ds_write_b16 v144, v0 offset:496
	v_mul_f32_e32 v0, v150, v10
	v_cvt_pk_bf16_f32 v0, v0, s0
	ds_write_b16 v144, v0 offset:2368
	v_mul_f32_e32 v0, v151, v10
	v_cvt_pk_bf16_f32 v0, v0, s0
	ds_write_b16 v144, v0 offset:2512
	v_mul_f32_e32 v0, v152, v10
	v_cvt_pk_bf16_f32 v0, v0, s0
	ds_write_b16 v144, v0 offset:2656
	v_mul_f32_e32 v0, v153, v10
	v_cvt_pk_bf16_f32 v0, v0, s0
	ds_write_b16 v144, v0 offset:2800
	v_mul_f32_e32 v0, v6, v11
	v_cvt_pk_bf16_f32 v0, v0, s0
	ds_write_b16 v144, v0 offset:96
	v_mul_f32_e32 v0, v7, v11
	v_cvt_pk_bf16_f32 v0, v0, s0
	ds_write_b16 v144, v0 offset:240
	v_mul_f32_e32 v0, v8, v11
	v_cvt_pk_bf16_f32 v0, v0, s0
	ds_write_b16 v144, v0 offset:384
	v_mul_f32_e32 v0, v9, v11
	v_cvt_pk_bf16_f32 v0, v0, s0
	ds_write_b16 v144, v0 offset:528
	v_mul_f32_e32 v0, v2, v11
	v_cvt_pk_bf16_f32 v0, v0, s0
	ds_write_b16 v144, v0 offset:2400
	v_mul_f32_e32 v0, v3, v11
	v_cvt_pk_bf16_f32 v0, v0, s0
	ds_write_b16 v144, v0 offset:2544
	v_mul_f32_e32 v0, v4, v11
	v_cvt_pk_bf16_f32 v0, v0, s0
	ds_write_b16 v144, v0 offset:2688
	v_mul_f32_e32 v0, v5, v11
	v_cvt_pk_bf16_f32 v0, v0, s0
	ds_write_b16 v144, v0 offset:2832
	s_waitcnt lgkmcnt(0)
	v_lshl_add_u64 v[2:3], v[12:13], 0, v[66:67]
	v_lshl_add_u64 v[6:7], v[2:3], 0, v[132:133]
	ds_read_b128 v[2:5], v138
	v_lshlrev_b32_e32 v8, 1, v139
	v_mov_b32_e32 v9, v1
	v_lshl_add_u64 v[6:7], v[6:7], 0, v[8:9]
	v_add_co_u32_e32 v8, vcc, 0x20000, v6
	s_waitcnt lgkmcnt(0)
	global_store_dwordx4 v[6:7], v[2:5], off sc0 sc1
	ds_read_b128 v[2:5], v138 offset:1152
	v_addc_co_u32_e32 v9, vcc, 0, v7, vcc
	s_waitcnt lgkmcnt(0)
	global_store_dwordx4 v[8:9], v[2:5], off offset:1024 sc0 sc1
	ds_read_b128 v[2:5], v138 offset:2304
	v_add_co_u32_e32 v8, vcc, 0x40000, v6
	s_nop 1
	v_addc_co_u32_e32 v9, vcc, 0, v7, vcc
	s_waitcnt lgkmcnt(0)
	global_store_dwordx4 v[8:9], v[2:5], off offset:2048 sc0 sc1
	ds_read_b128 v[2:5], v138 offset:3456
	v_add_co_u32_e32 v6, vcc, 0x60000, v6
	s_nop 1
	v_addc_co_u32_e32 v7, vcc, 0, v7, vcc
	s_waitcnt lgkmcnt(0)
	global_store_dwordx4 v[6:7], v[2:5], off offset:3072 sc0 sc1
	s_waitcnt lgkmcnt(0)

; __device__ __forceinline__ void store8bf(bf16_t* p, f32x4 v0, f32x4 v1) { u32x4 w; w.x = cvt_pk_bf16(v0[0], v0[1]); w.y = cvt_pk_bf16(v0[2], v0[3]); w.z = cvt_pk_bf16(v1[0], v1[1]); w.w = cvt_pk_bf16(v1[2], v1[3]); *(u32x4*)p = w; }
;   __device__ __forceinline__ void group(int row, int c32, int fq, f32x4 v0, f32x4 v1) const {
;     ...
;       const int h = c32 / 96, part = (c32 - h * 96) >> 5; const float sc = rs * QSC_A;
;       bf16_t* p = qa + ((size_t)(b * 6 + h) * E + e) * 96 + part * 32 + fq * 4;
;       if (part < 2) store8bf(qa + ((size_t)(b * 6 + h) * E + e) * 96 + part * 32 + fq * 8, v0 * sc, v1 * sc);
.LBB0_1040:
	s_andn2_saveexec_b64 s[0:1], s[12:13]
	s_cbranch_execz .LBB0_1042
	v_lshlrev_b32_e32 v150, 1, v144
	v_mov_b32_e32 v151, v1
	v_pk_mul_f32 v[124:125], v[124:125], v[136:137] op_sel_hi:[1,0]
	v_pk_mul_f32 v[122:123], v[122:123], v[136:137] op_sel_hi:[1,0]
	v_pk_mul_f32 v[128:129], v[128:129], v[136:137] op_sel_hi:[1,0]
	v_pk_mul_f32 v[126:127], v[126:127], v[136:137] op_sel_hi:[1,0]
	v_lshl_add_u64 v[138:139], v[138:139], 0, v[150:151]
	v_cvt_pk_bf16_f32 v122, v122, v123
	v_cvt_pk_bf16_f32 v123, v124, v125
	v_cvt_pk_bf16_f32 v124, v126, v127
	v_cvt_pk_bf16_f32 v125, v128, v129
	global_store_dwordx4 v[138:139], v[122:125], off sc0 sc1

; __device__ __forceinline__ void store8bf(bf16_t* p, f32x4 v0, f32x4 v1) { u32x4 w; w.x = cvt_pk_bf16(v0[0], v0[1]); w.y = cvt_pk_bf16(v0[2], v0[3]); w.z = cvt_pk_bf16(v1[0], v1[1]); w.w = cvt_pk_bf16(v1[2], v1[3]); *(u32x4*)p = w; }
;   __device__ __forceinline__ void group(int row, int c32, int fq, f32x4 v0, f32x4 v1) const {
;     ...
;       const int h = c32 / 96, part = (c32 - h * 96) >> 5; const float sc = rs * QSC_A;
;       bf16_t* p = qa + ((size_t)(b * 6 + h) * E + e) * 96 + part * 32 + fq * 4;
;       if (part < 2) store8bf(qa + ((size_t)(b * 6 + h) * E + e) * 96 + part * 32 + fq * 8, v0 * sc, v1 * sc);
.LBB0_1049:
	s_andn2_saveexec_b64 s[0:1], s[12:13]
	s_cbranch_execz .LBB0_1051
	v_lshlrev_b32_e32 v128, 1, v144
	v_mov_b32_e32 v129, v1
	v_pk_mul_f32 v[116:117], v[116:117], v[122:123] op_sel_hi:[1,0]
	v_pk_mul_f32 v[114:115], v[114:115], v[122:123] op_sel_hi:[1,0]
	v_pk_mul_f32 v[120:121], v[120:121], v[122:123] op_sel_hi:[1,0]
	v_pk_mul_f32 v[118:119], v[118:119], v[122:123] op_sel_hi:[1,0]
	v_lshl_add_u64 v[124:125], v[124:125], 0, v[128:129]
	v_cvt_pk_bf16_f32 v114, v114, v115
	v_cvt_pk_bf16_f32 v115, v116, v117
	v_cvt_pk_bf16_f32 v116, v118, v119
	v_cvt_pk_bf16_f32 v117, v120, v121
	global_store_dwordx4 v[124:125], v[114:117], off sc0 sc1

; __device__ __forceinline__ void store8bf(bf16_t* p, f32x4 v0, f32x4 v1) { u32x4 w; w.x = cvt_pk_bf16(v0[0], v0[1]); w.y = cvt_pk_bf16(v0[2], v0[3]); w.z = cvt_pk_bf16(v1[0], v1[1]); w.w = cvt_pk_bf16(v1[2], v1[3]); *(u32x4*)p = w; }
;   __device__ __forceinline__ void group(int row, int c32, int fq, f32x4 v0, f32x4 v1) const {
;     ...
;       const int h = c32 / 96, part = (c32 - h * 96) >> 5; const float sc = rs * QSC_A;
;       bf16_t* p = qa + ((size_t)(b * 6 + h) * E + e) * 96 + part * 32 + fq * 4;
;       if (part < 2) store8bf(qa + ((size_t)(b * 6 + h) * E + e) * 96 + part * 32 + fq * 8, v0 * sc, v1 * sc);
.LBB0_1058:
	s_andn2_saveexec_b64 s[0:1], s[16:17]
	s_cbranch_execz .LBB0_1060
	v_lshlrev_b32_e32 v120, 1, v144
	v_mov_b32_e32 v121, v1
	v_pk_mul_f32 v[108:109], v[108:109], v[114:115] op_sel_hi:[1,0]
	v_pk_mul_f32 v[106:107], v[106:107], v[114:115] op_sel_hi:[1,0]
	v_pk_mul_f32 v[112:113], v[112:113], v[114:115] op_sel_hi:[1,0]
	v_pk_mul_f32 v[110:111], v[110:111], v[114:115] op_sel_hi:[1,0]
	v_lshl_add_u64 v[116:117], v[116:117], 0, v[120:121]
	v_cvt_pk_bf16_f32 v106, v106, v107
	v_cvt_pk_bf16_f32 v107, v108, v109
	v_cvt_pk_bf16_f32 v108, v110, v111
	v_cvt_pk_bf16_f32 v109, v112, v113
	global_store_dwordx4 v[116:117], v[106:109], off sc0 sc1

; __device__ __forceinline__ void store8bf(bf16_t* p, f32x4 v0, f32x4 v1) { u32x4 w; w.x = cvt_pk_bf16(v0[0], v0[1]); w.y = cvt_pk_bf16(v0[2], v0[3]); w.z = cvt_pk_bf16(v1[0], v1[1]); w.w = cvt_pk_bf16(v1[2], v1[3]); *(u32x4*)p = w; }
;   __device__ __forceinline__ void group(int row, int c32, int fq, f32x4 v0, f32x4 v1) const {
;     ...
;       const int h = c32 / 96, part = (c32 - h * 96) >> 5; const float sc = rs * QSC_A;
;       bf16_t* p = qa + ((size_t)(b * 6 + h) * E + e) * 96 + part * 32 + fq * 4;
;       if (part < 2) store8bf(qa + ((size_t)(b * 6 + h) * E + e) * 96 + part * 32 + fq * 8, v0 * sc, v1 * sc);
.LBB0_1067:
	s_andn2_saveexec_b64 s[0:1], s[18:19]
	s_cbranch_execz .LBB0_1069
	v_lshlrev_b32_e32 v112, 1, v144
	v_mov_b32_e32 v113, v1
	v_pk_mul_f32 v[100:101], v[100:101], v[106:107] op_sel_hi:[1,0]
	v_pk_mul_f32 v[98:99], v[98:99], v[106:107] op_sel_hi:[1,0]
	v_pk_mul_f32 v[104:105], v[104:105], v[106:107] op_sel_hi:[1,0]
	v_pk_mul_f32 v[102:103], v[102:103], v[106:107] op_sel_hi:[1,0]
	v_lshl_add_u64 v[108:109], v[108:109], 0, v[112:113]
	v_cvt_pk_bf16_f32 v98, v98, v99
	v_cvt_pk_bf16_f32 v99, v100, v101
	v_cvt_pk_bf16_f32 v100, v102, v103
	v_cvt_pk_bf16_f32 v101, v104, v105
	global_store_dwordx4 v[108:109], v[98:101], off sc0 sc1

; __device__ __forceinline__ void store8bf(bf16_t* p, f32x4 v0, f32x4 v1) { u32x4 w; w.x = cvt_pk_bf16(v0[0], v0[1]); w.y = cvt_pk_bf16(v0[2], v0[3]); w.z = cvt_pk_bf16(v1[0], v1[1]); w.w = cvt_pk_bf16(v1[2], v1[3]); *(u32x4*)p = w; }
;   __device__ __forceinline__ void group(int row, int c32, int fq, f32x4 v0, f32x4 v1) const {
;     ...
;       const int h = c32 / 96, part = (c32 - h * 96) >> 5; const float sc = rs * QSC_A;
;       bf16_t* p = qa + ((size_t)(b * 6 + h) * E + e) * 96 + part * 32 + fq * 4;
;       if (part < 2) store8bf(qa + ((size_t)(b * 6 + h) * E + e) * 96 + part * 32 + fq * 8, v0 * sc, v1 * sc);
.LBB0_1076:
	s_andn2_saveexec_b64 s[0:1], s[24:25]
	s_cbranch_execz .LBB0_1078
	v_lshlrev_b32_e32 v104, 1, v144
	v_mov_b32_e32 v105, v1
	v_pk_mul_f32 v[92:93], v[92:93], v[100:101] op_sel_hi:[1,0]
	v_pk_mul_f32 v[90:91], v[90:91], v[100:101] op_sel_hi:[1,0]
	v_pk_mul_f32 v[96:97], v[96:97], v[100:101] op_sel_hi:[1,0]
	v_pk_mul_f32 v[94:95], v[94:95], v[100:101] op_sel_hi:[1,0]
	v_lshl_add_u64 v[102:103], v[102:103], 0, v[104:105]
	v_cvt_pk_bf16_f32 v90, v90, v91
	v_cvt_pk_bf16_f32 v91, v92, v93
	v_cvt_pk_bf16_f32 v92, v94, v95
	v_cvt_pk_bf16_f32 v93, v96, v97
	global_store_dwordx4 v[102:103], v[90:93], off offset:256 sc0 sc1

; __device__ __forceinline__ void store8bf(bf16_t* p, f32x4 v0, f32x4 v1) { u32x4 w; w.x = cvt_pk_bf16(v0[0], v0[1]); w.y = cvt_pk_bf16(v0[2], v0[3]); w.z = cvt_pk_bf16(v1[0], v1[1]); w.w = cvt_pk_bf16(v1[2], v1[3]); *(u32x4*)p = w; }
;   __device__ __forceinline__ void group(int row, int c32, int fq, f32x4 v0, f32x4 v1) const {
;     ...
;       const int h = c32 / 96, part = (c32 - h * 96) >> 5; const float sc = rs * QSC_A;
;       bf16_t* p = qa + ((size_t)(b * 6 + h) * E + e) * 96 + part * 32 + fq * 4;
;       if (part < 2) store8bf(qa + ((size_t)(b * 6 + h) * E + e) * 96 + part * 32 + fq * 8, v0 * sc, v1 * sc);
.LBB0_1085:
	s_andn2_saveexec_b64 s[0:1], s[18:19]
	s_cbranch_execz .LBB0_1087
	v_lshlrev_b32_e32 v94, 1, v144
	v_mov_b32_e32 v95, v1
	v_pk_mul_f32 v[84:85], v[84:85], v[90:91] op_sel_hi:[1,0]
	v_pk_mul_f32 v[82:83], v[82:83], v[90:91] op_sel_hi:[1,0]
	v_pk_mul_f32 v[88:89], v[88:89], v[90:91] op_sel_hi:[1,0]
	v_pk_mul_f32 v[86:87], v[86:87], v[90:91] op_sel_hi:[1,0]
	v_lshl_add_u64 v[92:93], v[92:93], 0, v[94:95]
	v_cvt_pk_bf16_f32 v82, v82, v83
	v_cvt_pk_bf16_f32 v83, v84, v85
	v_cvt_pk_bf16_f32 v84, v86, v87
	v_cvt_pk_bf16_f32 v85, v88, v89
	global_store_dwordx4 v[92:93], v[82:85], off offset:256 sc0 sc1

; __device__ __forceinline__ void store8bf(bf16_t* p, f32x4 v0, f32x4 v1) { u32x4 w; w.x = cvt_pk_bf16(v0[0], v0[1]); w.y = cvt_pk_bf16(v0[2], v0[3]); w.z = cvt_pk_bf16(v1[0], v1[1]); w.w = cvt_pk_bf16(v1[2], v1[3]); *(u32x4*)p = w; }
;   __device__ __forceinline__ void group(int row, int c32, int fq, f32x4 v0, f32x4 v1) const {
;     ...
;       const int h = c32 / 96, part = (c32 - h * 96) >> 5; const float sc = rs * QSC_A;
;       bf16_t* p = qa + ((size_t)(b * 6 + h) * E + e) * 96 + part * 32 + fq * 4;
;       if (part < 2) store8bf(qa + ((size_t)(b * 6 + h) * E + e) * 96 + part * 32 + fq * 8, v0 * sc, v1 * sc);
.LBB0_1094:
	s_andn2_saveexec_b64 s[0:1], s[16:17]
	s_cbranch_execz .LBB0_1096
	v_lshlrev_b32_e32 v86, 1, v144
	v_mov_b32_e32 v87, v1
	v_pk_mul_f32 v[76:77], v[76:77], v[82:83] op_sel_hi:[1,0]
	v_pk_mul_f32 v[74:75], v[74:75], v[82:83] op_sel_hi:[1,0]
	v_pk_mul_f32 v[80:81], v[80:81], v[82:83] op_sel_hi:[1,0]
	v_pk_mul_f32 v[78:79], v[78:79], v[82:83] op_sel_hi:[1,0]
	v_lshl_add_u64 v[84:85], v[84:85], 0, v[86:87]
	v_cvt_pk_bf16_f32 v74, v74, v75
	v_cvt_pk_bf16_f32 v75, v76, v77
	v_cvt_pk_bf16_f32 v76, v78, v79
	v_cvt_pk_bf16_f32 v77, v80, v81
	global_store_dwordx4 v[84:85], v[74:77], off offset:256 sc0 sc1

; __device__ __forceinline__ void store8bf(bf16_t* p, f32x4 v0, f32x4 v1) { u32x4 w; w.x = cvt_pk_bf16(v0[0], v0[1]); w.y = cvt_pk_bf16(v0[2], v0[3]); w.z = cvt_pk_bf16(v1[0], v1[1]); w.w = cvt_pk_bf16(v1[2], v1[3]); *(u32x4*)p = w; }
;   __device__ __forceinline__ void group(int row, int c32, int fq, f32x4 v0, f32x4 v1) const {
;     ...
;       const int h = c32 / 96, part = (c32 - h * 96) >> 5; const float sc = rs * QSC_A;
;       bf16_t* p = qa + ((size_t)(b * 6 + h) * E + e) * 96 + part * 32 + fq * 4;
;       if (part < 2) store8bf(qa + ((size_t)(b * 6 + h) * E + e) * 96 + part * 32 + fq * 8, v0 * sc, v1 * sc);
.LBB0_1103:
	s_andn2_saveexec_b64 s[0:1], s[14:15]
	s_cbranch_execz .LBB0_1105
	v_lshlrev_b32_e32 v78, 1, v144
	v_mov_b32_e32 v79, v1
	v_pk_mul_f32 v[68:69], v[68:69], v[74:75] op_sel_hi:[1,0]
	v_pk_mul_f32 v[66:67], v[66:67], v[74:75] op_sel_hi:[1,0]
	v_pk_mul_f32 v[72:73], v[72:73], v[74:75] op_sel_hi:[1,0]
	v_pk_mul_f32 v[70:71], v[70:71], v[74:75] op_sel_hi:[1,0]
	v_lshl_add_u64 v[76:77], v[76:77], 0, v[78:79]
	v_cvt_pk_bf16_f32 v66, v66, v67
	v_cvt_pk_bf16_f32 v67, v68, v69
	v_cvt_pk_bf16_f32 v68, v70, v71
	v_cvt_pk_bf16_f32 v69, v72, v73
	global_store_dwordx4 v[76:77], v[66:69], off offset:256 sc0 sc1

; __device__ __forceinline__ void store8bf(bf16_t* p, f32x4 v0, f32x4 v1) { u32x4 w; w.x = cvt_pk_bf16(v0[0], v0[1]); w.y = cvt_pk_bf16(v0[2], v0[3]); w.z = cvt_pk_bf16(v1[0], v1[1]); w.w = cvt_pk_bf16(v1[2], v1[3]); *(u32x4*)p = w; }
;   __device__ __forceinline__ void group(int row, int c32, int fq, f32x4 v0, f32x4 v1) const {
;     ...
;       const int h = c32 / 96, part = (c32 - h * 96) >> 5; const float sc = rs * QSC_A;
;       bf16_t* p = qa + ((size_t)(b * 6 + h) * E + e) * 96 + part * 32 + fq * 4;
;       if (part < 2) store8bf(qa + ((size_t)(b * 6 + h) * E + e) * 96 + part * 32 + fq * 8, v0 * sc, v1 * sc);
.LBB0_1112:
	s_andn2_saveexec_b64 s[0:1], s[16:17]
	s_cbranch_execz .LBB0_1114
	v_lshlrev_b32_e32 v74, 1, v144
	v_mov_b32_e32 v75, v1
	v_pk_mul_f32 v[60:61], v[60:61], v[66:67] op_sel_hi:[1,0]
	v_pk_mul_f32 v[58:59], v[58:59], v[66:67] op_sel_hi:[1,0]
	v_pk_mul_f32 v[64:65], v[64:65], v[66:67] op_sel_hi:[1,0]
	v_pk_mul_f32 v[62:63], v[62:63], v[66:67] op_sel_hi:[1,0]
	v_lshl_add_u64 v[68:69], v[68:69], 0, v[74:75]
	v_cvt_pk_bf16_f32 v58, v58, v59
	v_cvt_pk_bf16_f32 v59, v60, v61
	v_cvt_pk_bf16_f32 v60, v62, v63
	v_cvt_pk_bf16_f32 v61, v64, v65
	global_store_dwordx4 v[68:69], v[58:61], off sc0 sc1

; __device__ __forceinline__ void store8bf(bf16_t* p, f32x4 v0, f32x4 v1) { u32x4 w; w.x = cvt_pk_bf16(v0[0], v0[1]); w.y = cvt_pk_bf16(v0[2], v0[3]); w.z = cvt_pk_bf16(v1[0], v1[1]); w.w = cvt_pk_bf16(v1[2], v1[3]); *(u32x4*)p = w; }
;   __device__ __forceinline__ void group(int row, int c32, int fq, f32x4 v0, f32x4 v1) const {
;     ...
;       const int h = c32 / 96, part = (c32 - h * 96) >> 5; const float sc = rs * QSC_A;
;       bf16_t* p = qa + ((size_t)(b * 6 + h) * E + e) * 96 + part * 32 + fq * 4;
;       if (part < 2) store8bf(qa + ((size_t)(b * 6 + h) * E + e) * 96 + part * 32 + fq * 8, v0 * sc, v1 * sc);
.LBB0_1121:
	s_andn2_saveexec_b64 s[0:1], s[18:19]
	s_cbranch_execz .LBB0_1123
	v_lshlrev_b32_e32 v64, 1, v144
	v_mov_b32_e32 v65, v1
	v_pk_mul_f32 v[52:53], v[52:53], v[58:59] op_sel_hi:[1,0]
	v_pk_mul_f32 v[50:51], v[50:51], v[58:59] op_sel_hi:[1,0]
	v_pk_mul_f32 v[56:57], v[56:57], v[58:59] op_sel_hi:[1,0]
	v_pk_mul_f32 v[54:55], v[54:55], v[58:59] op_sel_hi:[1,0]
	v_lshl_add_u64 v[60:61], v[60:61], 0, v[64:65]
	v_cvt_pk_bf16_f32 v50, v50, v51
	v_cvt_pk_bf16_f32 v51, v52, v53
	v_cvt_pk_bf16_f32 v52, v54, v55
	v_cvt_pk_bf16_f32 v53, v56, v57
	global_store_dwordx4 v[60:61], v[50:53], off sc0 sc1

; #define LAS __attribute__((address_space(3)))
; __device__ __forceinline__ void store4bf(bf16_t* p, f32x4 v) { u32x2 w; w.x = cvt_pk_bf16(v[0], v[1]); w.y = cvt_pk_bf16(v[2], v[3]); *(u32x2*)p = w; }
; __device__ __forceinline__ void store8bf(bf16_t* p, f32x4 v0, f32x4 v1) { u32x4 w; w.x = cvt_pk_bf16(v0[0], v0[1]); w.y = cvt_pk_bf16(v0[2], v0[3]); w.z = cvt_pk_bf16(v1[0], v1[1]); w.w = cvt_pk_bf16(v1[2], v1[3]); *(u32x4*)p = w; }
;   __device__ __forceinline__ void group(int row, int c32, int fq, f32x4 v0, f32x4 v1) const { e->group(row, c32 + sh, fq, v0, v1); }
;   __device__ __forceinline__ void group(int row, int c32, int fq, f32x4 v0, f32x4 v1) const {
;     int b, e; if (!row_be(row, b, e)) return;
;     const float rs = use_direct ? rs_direct : ((LAS const float*)(lds_raw + RS_OFF))[row - brow];
;     if (c32 < 768) {
;       if (c32 >= 576) return;
;       const int h = c32 / 96, part = (c32 - h * 96) >> 5; const float sc = rs * QSC_A;
;       bf16_t* p = qa + ((size_t)(b * 6 + h) * E + e) * 96 + part * 32 + fq * 4;
;       if (part < 2) store8bf(qa + ((size_t)(b * 6 + h) * E + e) * 96 + part * 32 + fq * 8, v0 * sc, v1 * sc);
;       else { const float2* rp = rope + pos_of_e(e) * 16 + fq * 4; f32x4 o0, o1;
; #pragma unroll
;         for (int j = 0; j < 4; ++j) { const float2 cs = rp[j]; o0[j] = (v0[j] * cs.x - v1[j] * cs.y) * sc; o1[j] = (v1[j] * cs.x + v0[j] * cs.y) * sc; }
;         store4bf(p, o0); store4bf(p + 16, o1); }
;     } else {
;       const int cc = c32 - 768, h = cc >> 7, part = (cc & 127) >> 5;
;       if (part < 2) store8bf(ka + ((size_t)(b * 6 + h) * E + e) * 96 + part * 32 + fq * 8, v0 * rs, v1 * rs);
.LBB0_1130:
	s_andn2_saveexec_b64 s[0:1], s[24:25]
	s_cbranch_execz .LBB0_1132
	v_lshlrev_b32_e32 v56, 1, v144
	v_mov_b32_e32 v57, v1
	v_pk_mul_f32 v[44:45], v[44:45], v[50:51] op_sel_hi:[1,0]
	v_pk_mul_f32 v[42:43], v[42:43], v[50:51] op_sel_hi:[1,0]
	v_pk_mul_f32 v[48:49], v[48:49], v[50:51] op_sel_hi:[1,0]
	v_pk_mul_f32 v[46:47], v[46:47], v[50:51] op_sel_hi:[1,0]
	v_lshl_add_u64 v[52:53], v[52:53], 0, v[56:57]
	v_cvt_pk_bf16_f32 v42, v42, v43
	v_cvt_pk_bf16_f32 v43, v44, v45
	v_cvt_pk_bf16_f32 v44, v46, v47
	v_cvt_pk_bf16_f32 v45, v48, v49
	global_store_dwordx4 v[52:53], v[42:45], off sc0 sc1

; #define LAS __attribute__((address_space(3)))
; __device__ __forceinline__ void store4bf(bf16_t* p, f32x4 v) { u32x2 w; w.x = cvt_pk_bf16(v[0], v[1]); w.y = cvt_pk_bf16(v[2], v[3]); *(u32x2*)p = w; }
; __device__ __forceinline__ void store8bf(bf16_t* p, f32x4 v0, f32x4 v1) { u32x4 w; w.x = cvt_pk_bf16(v0[0], v0[1]); w.y = cvt_pk_bf16(v0[2], v0[3]); w.z = cvt_pk_bf16(v1[0], v1[1]); w.w = cvt_pk_bf16(v1[2], v1[3]); *(u32x4*)p = w; }
;   __device__ __forceinline__ void group(int row, int c32, int fq, f32x4 v0, f32x4 v1) const { e->group(row, c32 + sh, fq, v0, v1); }
;   __device__ __forceinline__ void group(int row, int c32, int fq, f32x4 v0, f32x4 v1) const {
;     int b, e; if (!row_be(row, b, e)) return;
;     const float rs = use_direct ? rs_direct : ((LAS const float*)(lds_raw + RS_OFF))[row - brow];
;     if (c32 < 768) {
;       if (c32 >= 576) return;
;       const int h = c32 / 96, part = (c32 - h * 96) >> 5; const float sc = rs * QSC_A;
;       bf16_t* p = qa + ((size_t)(b * 6 + h) * E + e) * 96 + part * 32 + fq * 4;
;       if (part < 2) store8bf(qa + ((size_t)(b * 6 + h) * E + e) * 96 + part * 32 + fq * 8, v0 * sc, v1 * sc);
;       else { const float2* rp = rope + pos_of_e(e) * 16 + fq * 4; f32x4 o0, o1;
; #pragma unroll
;         for (int j = 0; j < 4; ++j) { const float2 cs = rp[j]; o0[j] = (v0[j] * cs.x - v1[j] * cs.y) * sc; o1[j] = (v1[j] * cs.x + v0[j] * cs.y) * sc; }
;         store4bf(p, o0); store4bf(p + 16, o1); }
;     } else {
;       const int cc = c32 - 768, h = cc >> 7, part = (cc & 127) >> 5;
;       if (part < 2) store8bf(ka + ((size_t)(b * 6 + h) * E + e) * 96 + part * 32 + fq * 8, v0 * rs, v1 * rs);
.LBB0_1139:
	s_andn2_saveexec_b64 s[0:1], s[8:9]
	s_cbranch_execz .LBB0_1141
	v_lshlrev_b32_e32 v48, 1, v144
	v_mov_b32_e32 v49, v1
	v_pk_mul_f32 v[36:37], v[36:37], v[42:43] op_sel_hi:[1,0]
	v_pk_mul_f32 v[34:35], v[34:35], v[42:43] op_sel_hi:[1,0]
	v_pk_mul_f32 v[40:41], v[40:41], v[42:43] op_sel_hi:[1,0]
	v_pk_mul_f32 v[38:39], v[38:39], v[42:43] op_sel_hi:[1,0]
	v_lshl_add_u64 v[44:45], v[44:45], 0, v[48:49]
	v_cvt_pk_bf16_f32 v34, v34, v35
	v_cvt_pk_bf16_f32 v35, v36, v37
	v_cvt_pk_bf16_f32 v36, v38, v39
	v_cvt_pk_bf16_f32 v37, v40, v41
	global_store_dwordx4 v[44:45], v[34:37], off sc0 sc1

; #define LAS __attribute__((address_space(3)))
; __device__ __forceinline__ void store4bf(bf16_t* p, f32x4 v) { u32x2 w; w.x = cvt_pk_bf16(v[0], v[1]); w.y = cvt_pk_bf16(v[2], v[3]); *(u32x2*)p = w; }
; __device__ __forceinline__ void store8bf(bf16_t* p, f32x4 v0, f32x4 v1) { u32x4 w; w.x = cvt_pk_bf16(v0[0], v0[1]); w.y = cvt_pk_bf16(v0[2], v0[3]); w.z = cvt_pk_bf16(v1[0], v1[1]); w.w = cvt_pk_bf16(v1[2], v1[3]); *(u32x4*)p = w; }
;   __device__ __forceinline__ void group(int row, int c32, int fq, f32x4 v0, f32x4 v1) const { e->group(row, c32 + sh, fq, v0, v1); }
;   __device__ __forceinline__ void group(int row, int c32, int fq, f32x4 v0, f32x4 v1) const {
;     int b, e; if (!row_be(row, b, e)) return;
;     const float rs = use_direct ? rs_direct : ((LAS const float*)(lds_raw + RS_OFF))[row - brow];
;     if (c32 < 768) {
;       if (c32 >= 576) return;
;       const int h = c32 / 96, part = (c32 - h * 96) >> 5; const float sc = rs * QSC_A;
;       bf16_t* p = qa + ((size_t)(b * 6 + h) * E + e) * 96 + part * 32 + fq * 4;
;       if (part < 2) store8bf(qa + ((size_t)(b * 6 + h) * E + e) * 96 + part * 32 + fq * 8, v0 * sc, v1 * sc);
;       else { const float2* rp = rope + pos_of_e(e) * 16 + fq * 4; f32x4 o0, o1;
; #pragma unroll
;         for (int j = 0; j < 4; ++j) { const float2 cs = rp[j]; o0[j] = (v0[j] * cs.x - v1[j] * cs.y) * sc; o1[j] = (v1[j] * cs.x + v0[j] * cs.y) * sc; }
;         store4bf(p, o0); store4bf(p + 16, o1); }
;     } else {
;       const int cc = c32 - 768, h = cc >> 7, part = (cc & 127) >> 5;
;       if (part < 2) store8bf(ka + ((size_t)(b * 6 + h) * E + e) * 96 + part * 32 + fq * 8, v0 * rs, v1 * rs);
.LBB0_1148:
	s_andn2_saveexec_b64 s[0:1], s[12:13]
	s_cbranch_execz .LBB0_1150
	v_lshlrev_b32_e32 v38, 1, v144
	v_mov_b32_e32 v39, v1
	v_pk_mul_f32 v[28:29], v[28:29], v[34:35] op_sel_hi:[1,0]
	v_pk_mul_f32 v[26:27], v[26:27], v[34:35] op_sel_hi:[1,0]
	v_pk_mul_f32 v[32:33], v[32:33], v[34:35] op_sel_hi:[1,0]
	v_pk_mul_f32 v[30:31], v[30:31], v[34:35] op_sel_hi:[1,0]
	v_lshl_add_u64 v[36:37], v[36:37], 0, v[38:39]
	v_cvt_pk_bf16_f32 v26, v26, v27
	v_cvt_pk_bf16_f32 v27, v28, v29
	v_cvt_pk_bf16_f32 v28, v30, v31
	v_cvt_pk_bf16_f32 v29, v32, v33
	global_store_dwordx4 v[36:37], v[26:29], off offset:256 sc0 sc1

; #define LAS __attribute__((address_space(3)))
; __device__ __forceinline__ void store4bf(bf16_t* p, f32x4 v) { u32x2 w; w.x = cvt_pk_bf16(v[0], v[1]); w.y = cvt_pk_bf16(v[2], v[3]); *(u32x2*)p = w; }
; __device__ __forceinline__ void store8bf(bf16_t* p, f32x4 v0, f32x4 v1) { u32x4 w; w.x = cvt_pk_bf16(v0[0], v0[1]); w.y = cvt_pk_bf16(v0[2], v0[3]); w.z = cvt_pk_bf16(v1[0], v1[1]); w.w = cvt_pk_bf16(v1[2], v1[3]); *(u32x4*)p = w; }
;   __device__ __forceinline__ void group(int row, int c32, int fq, f32x4 v0, f32x4 v1) const { e->group(row, c32 + sh, fq, v0, v1); }
; __device__ __forceinline__ bool row_be(int r, int& b, int& e) {
;   if (r < NREAL) { b = r >> 13; e = 64 + (r & 8191); return true; }
;   const int m = r - NREAL; b = (m >> 4) & 3; e = m & 15; return m < 64;
; }
;   __device__ __forceinline__ void group(int row, int c32, int fq, f32x4 v0, f32x4 v1) const {
;     int b, e; if (!row_be(row, b, e)) return;
;     const float rs = use_direct ? rs_direct : ((LAS const float*)(lds_raw + RS_OFF))[row - brow];
;     if (c32 < 768) {
;       if (c32 >= 576) return;
;       const int h = c32 / 96, part = (c32 - h * 96) >> 5; const float sc = rs * QSC_A;
;       bf16_t* p = qa + ((size_t)(b * 6 + h) * E + e) * 96 + part * 32 + fq * 4;
;       if (part < 2) store8bf(qa + ((size_t)(b * 6 + h) * E + e) * 96 + part * 32 + fq * 8, v0 * sc, v1 * sc);
;       else { const float2* rp = rope + pos_of_e(e) * 16 + fq * 4; f32x4 o0, o1;
; #pragma unroll
;         for (int j = 0; j < 4; ++j) { const float2 cs = rp[j]; o0[j] = (v0[j] * cs.x - v1[j] * cs.y) * sc; o1[j] = (v1[j] * cs.x + v0[j] * cs.y) * sc; }
;         store4bf(p, o0); store4bf(p + 16, o1); }
;     } else {
;       const int cc = c32 - 768, h = cc >> 7, part = (cc & 127) >> 5;
;       if (part < 2) store8bf(ka + ((size_t)(b * 6 + h) * E + e) * 96 + part * 32 + fq * 8, v0 * rs, v1 * rs);
.LBB0_1154:
	s_movk_i32 s1, 0x7fff
	v_cmp_lt_i32_e32 vcc, s1, v69
	s_and_saveexec_b64 s[6:7], vcc
	s_xor_b64 s[6:7], exec, s[6:7]
	v_cmp_gt_u32_e64 s[8:9], s49, v68
	s_or_saveexec_b64 s[6:7], s[6:7]
	v_mov_b32_e32 v35, 0
	v_mul_i32_i24_e32 v40, 6, v70
	v_mov_b32_e32 v38, v130
	s_xor_b64 exec, exec, s[6:7]
	v_and_b32_e32 v10, 0x1fcf, v69
	v_add_u32_e32 v38, 64, v10
	v_mul_i32_i24_e32 v35, 6, v70
	s_or_b64 s[8:9], s[8:9], exec
	s_or_b64 exec, exec, s[6:7]
	v_lshlrev_b32_e32 v36, 1, v0
	v_lshlrev_b32_e32 v34, 1, v131
	s_and_saveexec_b64 s[6:7], s[8:9]
	s_cbranch_execz .LBB0_1160
	v_add_u32_e32 v10, s0, v35
	v_mov_b32_e32 v39, v1
	s_movk_i32 s1, 0x2040
	v_mad_i64_i32 v[10:11], s[8:9], v10, s1, v[38:39]
	v_add_u32_e32 v0, 0x20000, v71
	v_readlane_b32 s8, v254, 4
	ds_read_b32 v0, v0
	v_readlane_b32 s9, v254, 5
	v_mov_b32_e32 v37, v1
	v_mov_b32_e32 v35, v1
	v_mov_b64_e32 v[12:13], s[8:9]
	v_mad_u64_u32 v[12:13], s[8:9], v10, s47, v[12:13]
	v_mad_i32_i24 v13, v11, s47, v13
	v_lshl_add_u64 v[10:11], v[12:13], 0, v[36:37]
	v_lshl_add_u64 v[38:39], v[10:11], 0, v[34:35]
	s_waitcnt lgkmcnt(0)
	v_pk_mul_f32 v[12:13], v[32:33], v[0:1] op_sel_hi:[1,0]
	v_pk_mul_f32 v[10:11], v[30:31], v[0:1] op_sel_hi:[1,0]
	v_pk_mul_f32 v[28:29], v[28:29], v[0:1] op_sel_hi:[1,0]
	v_pk_mul_f32 v[26:27], v[26:27], v[0:1] op_sel_hi:[1,0]
	v_cvt_pk_bf16_f32 v10, v10, v11
	v_cvt_pk_bf16_f32 v11, v12, v13
	v_cvt_pk_bf16_f32 v12, v26, v27
	v_cvt_pk_bf16_f32 v13, v28, v29
	global_store_dwordx4 v[38:39], v[10:13], off sc0 sc1

; #define LAS __attribute__((address_space(3)))
; __device__ __forceinline__ void store4bf(bf16_t* p, f32x4 v) { u32x2 w; w.x = cvt_pk_bf16(v[0], v[1]); w.y = cvt_pk_bf16(v[2], v[3]); *(u32x2*)p = w; }
; __device__ __forceinline__ void store8bf(bf16_t* p, f32x4 v0, f32x4 v1) { u32x4 w; w.x = cvt_pk_bf16(v0[0], v0[1]); w.y = cvt_pk_bf16(v0[2], v0[3]); w.z = cvt_pk_bf16(v1[0], v1[1]); w.w = cvt_pk_bf16(v1[2], v1[3]); *(u32x4*)p = w; }
;   __device__ __forceinline__ void group(int row, int c32, int fq, f32x4 v0, f32x4 v1) const { e->group(row, c32 + sh, fq, v0, v1); }
;   __device__ __forceinline__ void group(int row, int c32, int fq, f32x4 v0, f32x4 v1) const {
;     int b, e; if (!row_be(row, b, e)) return;
;     const float rs = use_direct ? rs_direct : ((LAS const float*)(lds_raw + RS_OFF))[row - brow];
;     if (c32 < 768) {
;       if (c32 >= 576) return;
;       const int h = c32 / 96, part = (c32 - h * 96) >> 5; const float sc = rs * QSC_A;
;       bf16_t* p = qa + ((size_t)(b * 6 + h) * E + e) * 96 + part * 32 + fq * 4;
;       if (part < 2) store8bf(qa + ((size_t)(b * 6 + h) * E + e) * 96 + part * 32 + fq * 8, v0 * sc, v1 * sc);
;       else { const float2* rp = rope + pos_of_e(e) * 16 + fq * 4; f32x4 o0, o1;
; #pragma unroll
;         for (int j = 0; j < 4; ++j) { const float2 cs = rp[j]; o0[j] = (v0[j] * cs.x - v1[j] * cs.y) * sc; o1[j] = (v1[j] * cs.x + v0[j] * cs.y) * sc; }
;         store4bf(p, o0); store4bf(p + 16, o1); }
;     } else {
;       const int cc = c32 - 768, h = cc >> 7, part = (cc & 127) >> 5;
;       if (part < 2) store8bf(ka + ((size_t)(b * 6 + h) * E + e) * 96 + part * 32 + fq * 8, v0 * rs, v1 * rs);
.LBB0_1163:
	v_subrev_u32_e32 v0, s20, v0
	v_mad_i32_i24 v10, v27, 6, s0
	v_mov_b32_e32 v27, v1
	s_movk_i32 s1, 0x2040
	v_lshl_add_u32 v0, v0, 2, 0
	v_mad_i64_i32 v[10:11], s[8:9], v10, s1, v[26:27]
	v_add_u32_e32 v0, 0x20000, v0
	v_readlane_b32 s8, v254, 4
	ds_read_b32 v0, v0
	v_readlane_b32 s9, v254, 5
	v_mov_b32_e32 v37, v1
	v_mov_b32_e32 v35, v1
	v_mov_b64_e32 v[12:13], s[8:9]
	v_mad_u64_u32 v[12:13], s[8:9], v10, s47, v[12:13]
	v_mad_i32_i24 v13, v11, s47, v13
	v_lshl_add_u64 v[10:11], v[12:13], 0, v[36:37]
	v_lshl_add_u64 v[26:27], v[10:11], 0, v[34:35]
	s_waitcnt lgkmcnt(0)
	v_pk_mul_f32 v[12:13], v[24:25], v[0:1] op_sel_hi:[1,0]
	v_pk_mul_f32 v[10:11], v[22:23], v[0:1] op_sel_hi:[1,0]
	v_pk_mul_f32 v[20:21], v[20:21], v[0:1] op_sel_hi:[1,0]
	v_pk_mul_f32 v[18:19], v[18:19], v[0:1] op_sel_hi:[1,0]
	v_cvt_pk_bf16_f32 v10, v10, v11
	v_cvt_pk_bf16_f32 v11, v12, v13
	v_cvt_pk_bf16_f32 v12, v18, v19
	v_cvt_pk_bf16_f32 v13, v20, v21
	global_store_dwordx4 v[26:27], v[10:13], off sc0 sc1

; #define LAS __attribute__((address_space(3)))
; __device__ __forceinline__ void store4bf(bf16_t* p, f32x4 v) { u32x2 w; w.x = cvt_pk_bf16(v[0], v[1]); w.y = cvt_pk_bf16(v[2], v[3]); *(u32x2*)p = w; }
; __device__ __forceinline__ void store8bf(bf16_t* p, f32x4 v0, f32x4 v1) { u32x4 w; w.x = cvt_pk_bf16(v0[0], v0[1]); w.y = cvt_pk_bf16(v0[2], v0[3]); w.z = cvt_pk_bf16(v1[0], v1[1]); w.w = cvt_pk_bf16(v1[2], v1[3]); *(u32x4*)p = w; }
;   __device__ __forceinline__ void group(int row, int c32, int fq, f32x4 v0, f32x4 v1) const { e->group(row, c32 + sh, fq, v0, v1); }
;   __device__ __forceinline__ void group(int row, int c32, int fq, f32x4 v0, f32x4 v1) const {
;     int b, e; if (!row_be(row, b, e)) return;
;     const float rs = use_direct ? rs_direct : ((LAS const float*)(lds_raw + RS_OFF))[row - brow];
;     if (c32 < 768) {
;       if (c32 >= 576) return;
;       const int h = c32 / 96, part = (c32 - h * 96) >> 5; const float sc = rs * QSC_A;
;       bf16_t* p = qa + ((size_t)(b * 6 + h) * E + e) * 96 + part * 32 + fq * 4;
;       if (part < 2) store8bf(qa + ((size_t)(b * 6 + h) * E + e) * 96 + part * 32 + fq * 8, v0 * sc, v1 * sc);
;       else { const float2* rp = rope + pos_of_e(e) * 16 + fq * 4; f32x4 o0, o1;
; #pragma unroll
;         for (int j = 0; j < 4; ++j) { const float2 cs = rp[j]; o0[j] = (v0[j] * cs.x - v1[j] * cs.y) * sc; o1[j] = (v1[j] * cs.x + v0[j] * cs.y) * sc; }
;         store4bf(p, o0); store4bf(p + 16, o1); }
;     } else {
;       const int cc = c32 - 768, h = cc >> 7, part = (cc & 127) >> 5;
;       if (part < 2) store8bf(ka + ((size_t)(b * 6 + h) * E + e) * 96 + part * 32 + fq * 8, v0 * rs, v1 * rs);
.LBB0_1167:
	v_subrev_u32_e32 v0, s20, v0
	v_mad_i32_i24 v10, v70, 6, s0
	v_mov_b32_e32 v19, v1
	s_movk_i32 s1, 0x2040
	v_lshl_add_u32 v0, v0, 2, 0
	v_mad_i64_i32 v[10:11], s[8:9], v10, s1, v[18:19]
	v_add_u32_e32 v0, 0x20000, v0
	v_readlane_b32 s8, v254, 4
	ds_read_b32 v0, v0
	v_readlane_b32 s9, v254, 5
	v_mov_b32_e32 v37, v1
	v_mov_b32_e32 v35, v1
	v_mov_b64_e32 v[12:13], s[8:9]
	v_mad_u64_u32 v[12:13], s[8:9], v10, s47, v[12:13]
	v_mad_i32_i24 v13, v11, s47, v13
	v_lshl_add_u64 v[10:11], v[12:13], 0, v[36:37]
	v_lshl_add_u64 v[18:19], v[10:11], 0, v[34:35]
	s_waitcnt lgkmcnt(0)
	v_pk_mul_f32 v[12:13], v[16:17], v[0:1] op_sel_hi:[1,0]
	v_pk_mul_f32 v[10:11], v[14:15], v[0:1] op_sel_hi:[1,0]
	v_pk_mul_f32 v[14:15], v[152:153], v[0:1] op_sel_hi:[1,0]
	v_pk_mul_f32 v[16:17], v[150:151], v[0:1] op_sel_hi:[1,0]
	v_cvt_pk_bf16_f32 v10, v10, v11
	v_cvt_pk_bf16_f32 v11, v12, v13
	v_cvt_pk_bf16_f32 v12, v16, v17
	v_cvt_pk_bf16_f32 v13, v14, v15
	global_store_dwordx4 v[18:19], v[10:13], off sc0 sc1

; #define LAS __attribute__((address_space(3)))
; __device__ __forceinline__ void store4bf(bf16_t* p, f32x4 v) { u32x2 w; w.x = cvt_pk_bf16(v[0], v[1]); w.y = cvt_pk_bf16(v[2], v[3]); *(u32x2*)p = w; }
; __device__ __forceinline__ void store8bf(bf16_t* p, f32x4 v0, f32x4 v1) { u32x4 w; w.x = cvt_pk_bf16(v0[0], v0[1]); w.y = cvt_pk_bf16(v0[2], v0[3]); w.z = cvt_pk_bf16(v1[0], v1[1]); w.w = cvt_pk_bf16(v1[2], v1[3]); *(u32x4*)p = w; }
;   __device__ __forceinline__ void group(int row, int c32, int fq, f32x4 v0, f32x4 v1) const { e->group(row, c32 + sh, fq, v0, v1); }
;   __device__ __forceinline__ void group(int row, int c32, int fq, f32x4 v0, f32x4 v1) const {
;     int b, e; if (!row_be(row, b, e)) return;
;     const float rs = use_direct ? rs_direct : ((LAS const float*)(lds_raw + RS_OFF))[row - brow];
;     if (c32 < 768) {
;       if (c32 >= 576) return;
;       const int h = c32 / 96, part = (c32 - h * 96) >> 5; const float sc = rs * QSC_A;
;       bf16_t* p = qa + ((size_t)(b * 6 + h) * E + e) * 96 + part * 32 + fq * 4;
;       if (part < 2) store8bf(qa + ((size_t)(b * 6 + h) * E + e) * 96 + part * 32 + fq * 8, v0 * sc, v1 * sc);
;       else { const float2* rp = rope + pos_of_e(e) * 16 + fq * 4; f32x4 o0, o1;
; #pragma unroll
;         for (int j = 0; j < 4; ++j) { const float2 cs = rp[j]; o0[j] = (v0[j] * cs.x - v1[j] * cs.y) * sc; o1[j] = (v1[j] * cs.x + v0[j] * cs.y) * sc; }
;         store4bf(p, o0); store4bf(p + 16, o1); }
;     } else {
;       const int cc = c32 - 768, h = cc >> 7, part = (cc & 127) >> 5;
;       if (part < 2) store8bf(ka + ((size_t)(b * 6 + h) * E + e) * 96 + part * 32 + fq * 8, v0 * rs, v1 * rs);
.LBB0_1171:
	v_subrev_u32_e32 v0, s20, v0
	v_lshl_add_u32 v0, v0, 2, 0
	v_add_u32_e32 v10, s0, v10
	v_mov_b32_e32 v131, v1
	s_movk_i32 s1, 0x2040
	v_add_u32_e32 v0, 0x20000, v0
	v_mad_i64_i32 v[10:11], s[8:9], v10, s1, v[130:131]
	ds_read_b32 v0, v0
	v_readlane_b32 s8, v254, 4
	v_readlane_b32 s9, v254, 5
	v_mov_b32_e32 v37, v1
	v_mov_b32_e32 v35, v1
	v_mov_b64_e32 v[12:13], s[8:9]
	v_mad_u64_u32 v[12:13], s[8:9], v10, s47, v[12:13]
	v_mad_i32_i24 v13, v11, s47, v13
	v_lshl_add_u64 v[10:11], v[12:13], 0, v[36:37]
	s_waitcnt lgkmcnt(0)
	v_pk_mul_f32 v[8:9], v[8:9], v[0:1] op_sel_hi:[1,0]
	v_pk_mul_f32 v[6:7], v[6:7], v[0:1] op_sel_hi:[1,0]
	v_pk_mul_f32 v[12:13], v[4:5], v[0:1] op_sel_hi:[1,0]
	v_pk_mul_f32 v[4:5], v[2:3], v[0:1] op_sel_hi:[1,0]
	v_lshl_add_u64 v[10:11], v[10:11], 0, v[34:35]
	v_cvt_pk_bf16_f32 v2, v6, v7
	v_cvt_pk_bf16_f32 v3, v8, v9
	v_cvt_pk_bf16_f32 v4, v4, v5
	v_cvt_pk_bf16_f32 v5, v12, v13
	global_store_dwordx4 v[10:11], v[2:5], off sc0 sc1

; #define LAS __attribute__((address_space(3)))
; __device__ __forceinline__ void store4bf(bf16_t* p, f32x4 v) { u32x2 w; w.x = cvt_pk_bf16(v[0], v[1]); w.y = cvt_pk_bf16(v[2], v[3]); *(u32x2*)p = w; }
; __device__ __forceinline__ void store8bf(bf16_t* p, f32x4 v0, f32x4 v1) { u32x4 w; w.x = cvt_pk_bf16(v0[0], v0[1]); w.y = cvt_pk_bf16(v0[2], v0[3]); w.z = cvt_pk_bf16(v1[0], v1[1]); w.w = cvt_pk_bf16(v1[2], v1[3]); *(u32x4*)p = w; }
;   __device__ __forceinline__ void group(int row, int c32, int fq, f32x4 v0, f32x4 v1) const { e->group(row, c32 + sh, fq, v0, v1); }
;   __device__ __forceinline__ void group(int row, int c32, int fq, f32x4 v0, f32x4 v1) const {
;     int b, e; if (!row_be(row, b, e)) return;
;     const float rs = use_direct ? rs_direct : ((LAS const float*)(lds_raw + RS_OFF))[row - brow];
;     if (c32 < 768) {
;       if (c32 >= 576) return;
;       const int h = c32 / 96, part = (c32 - h * 96) >> 5; const float sc = rs * QSC_A;
;       bf16_t* p = qa + ((size_t)(b * 6 + h) * E + e) * 96 + part * 32 + fq * 4;
;       if (part < 2) store8bf(qa + ((size_t)(b * 6 + h) * E + e) * 96 + part * 32 + fq * 8, v0 * sc, v1 * sc);
;       else { const float2* rp = rope + pos_of_e(e) * 16 + fq * 4; f32x4 o0, o1;
; #pragma unroll
;         for (int j = 0; j < 4; ++j) { const float2 cs = rp[j]; o0[j] = (v0[j] * cs.x - v1[j] * cs.y) * sc; o1[j] = (v1[j] * cs.x + v0[j] * cs.y) * sc; }
;         store4bf(p, o0); store4bf(p + 16, o1); }
;     } else {
;       const int cc = c32 - 768, h = cc >> 7, part = (cc & 127) >> 5;
;       if (part < 2) store8bf(ka + ((size_t)(b * 6 + h) * E + e) * 96 + part * 32 + fq * 8, v0 * rs, v1 * rs);
.LBB0_1177:
	s_andn2_saveexec_b64 s[0:1], s[10:11]
	s_cbranch_execz .LBB0_1179
	v_lshlrev_b32_e32 v30, 1, v144
	v_mov_b32_e32 v31, v1
	v_pk_mul_f32 v[20:21], v[20:21], v[26:27] op_sel_hi:[1,0]
	v_pk_mul_f32 v[18:19], v[18:19], v[26:27] op_sel_hi:[1,0]
	v_pk_mul_f32 v[24:25], v[24:25], v[26:27] op_sel_hi:[1,0]
	v_pk_mul_f32 v[22:23], v[22:23], v[26:27] op_sel_hi:[1,0]
	v_lshl_add_u64 v[28:29], v[28:29], 0, v[30:31]
	v_cvt_pk_bf16_f32 v18, v18, v19
	v_cvt_pk_bf16_f32 v19, v20, v21
	v_cvt_pk_bf16_f32 v20, v22, v23
	v_cvt_pk_bf16_f32 v21, v24, v25
	global_store_dwordx4 v[28:29], v[18:21], off offset:256 sc0 sc1

; #define LAS __attribute__((address_space(3)))
; __device__ __forceinline__ void store4bf(bf16_t* p, f32x4 v) { u32x2 w; w.x = cvt_pk_bf16(v[0], v[1]); w.y = cvt_pk_bf16(v[2], v[3]); *(u32x2*)p = w; }
; __device__ __forceinline__ void store8bf(bf16_t* p, f32x4 v0, f32x4 v1) { u32x4 w; w.x = cvt_pk_bf16(v0[0], v0[1]); w.y = cvt_pk_bf16(v0[2], v0[3]); w.z = cvt_pk_bf16(v1[0], v1[1]); w.w = cvt_pk_bf16(v1[2], v1[3]); *(u32x4*)p = w; }
;   __device__ __forceinline__ void group(int row, int c32, int fq, f32x4 v0, f32x4 v1) const { e->group(row, c32 + sh, fq, v0, v1); }
;   __device__ __forceinline__ void group(int row, int c32, int fq, f32x4 v0, f32x4 v1) const {
;     int b, e; if (!row_be(row, b, e)) return;
;     const float rs = use_direct ? rs_direct : ((LAS const float*)(lds_raw + RS_OFF))[row - brow];
;     if (c32 < 768) {
;       if (c32 >= 576) return;
;       const int h = c32 / 96, part = (c32 - h * 96) >> 5; const float sc = rs * QSC_A;
;       bf16_t* p = qa + ((size_t)(b * 6 + h) * E + e) * 96 + part * 32 + fq * 4;
;       if (part < 2) store8bf(qa + ((size_t)(b * 6 + h) * E + e) * 96 + part * 32 + fq * 8, v0 * sc, v1 * sc);
;       else { const float2* rp = rope + pos_of_e(e) * 16 + fq * 4; f32x4 o0, o1;
; #pragma unroll
;         for (int j = 0; j < 4; ++j) { const float2 cs = rp[j]; o0[j] = (v0[j] * cs.x - v1[j] * cs.y) * sc; o1[j] = (v1[j] * cs.x + v0[j] * cs.y) * sc; }
;         store4bf(p, o0); store4bf(p + 16, o1); }
;     } else {
;       const int cc = c32 - 768, h = cc >> 7, part = (cc & 127) >> 5;
;       if (part < 2) store8bf(ka + ((size_t)(b * 6 + h) * E + e) * 96 + part * 32 + fq * 8, v0 * rs, v1 * rs);
.LBB0_1186:
	s_andn2_saveexec_b64 s[0:1], s[10:11]
	s_cbranch_execz .LBB0_1188
	v_lshlrev_b32_e32 v22, 1, v144
	v_mov_b32_e32 v23, v1
	v_pk_mul_f32 v[12:13], v[12:13], v[18:19] op_sel_hi:[1,0]
	v_pk_mul_f32 v[10:11], v[10:11], v[18:19] op_sel_hi:[1,0]
	v_pk_mul_f32 v[16:17], v[16:17], v[18:19] op_sel_hi:[1,0]
	v_pk_mul_f32 v[14:15], v[14:15], v[18:19] op_sel_hi:[1,0]
	v_lshl_add_u64 v[20:21], v[20:21], 0, v[22:23]
	v_cvt_pk_bf16_f32 v10, v10, v11
	v_cvt_pk_bf16_f32 v11, v12, v13
	v_cvt_pk_bf16_f32 v12, v14, v15
	v_cvt_pk_bf16_f32 v13, v16, v17
	global_store_dwordx4 v[20:21], v[10:13], off offset:256 sc0 sc1

; #define LAS __attribute__((address_space(3)))
; __device__ __forceinline__ void store4bf(bf16_t* p, f32x4 v) { u32x2 w; w.x = cvt_pk_bf16(v[0], v[1]); w.y = cvt_pk_bf16(v[2], v[3]); *(u32x2*)p = w; }
; __device__ __forceinline__ void store8bf(bf16_t* p, f32x4 v0, f32x4 v1) { u32x4 w; w.x = cvt_pk_bf16(v0[0], v0[1]); w.y = cvt_pk_bf16(v0[2], v0[3]); w.z = cvt_pk_bf16(v1[0], v1[1]); w.w = cvt_pk_bf16(v1[2], v1[3]); *(u32x4*)p = w; }
;   __device__ __forceinline__ void group(int row, int c32, int fq, f32x4 v0, f32x4 v1) const { e->group(row, c32 + sh, fq, v0, v1); }
;   __device__ __forceinline__ void group(int row, int c32, int fq, f32x4 v0, f32x4 v1) const {
;     int b, e; if (!row_be(row, b, e)) return;
;     const float rs = use_direct ? rs_direct : ((LAS const float*)(lds_raw + RS_OFF))[row - brow];
;     if (c32 < 768) {
;       if (c32 >= 576) return;
;       const int h = c32 / 96, part = (c32 - h * 96) >> 5; const float sc = rs * QSC_A;
;       bf16_t* p = qa + ((size_t)(b * 6 + h) * E + e) * 96 + part * 32 + fq * 4;
;       if (part < 2) store8bf(qa + ((size_t)(b * 6 + h) * E + e) * 96 + part * 32 + fq * 8, v0 * sc, v1 * sc);
;       else { const float2* rp = rope + pos_of_e(e) * 16 + fq * 4; f32x4 o0, o1;
; #pragma unroll
;         for (int j = 0; j < 4; ++j) { const float2 cs = rp[j]; o0[j] = (v0[j] * cs.x - v1[j] * cs.y) * sc; o1[j] = (v1[j] * cs.x + v0[j] * cs.y) * sc; }
;         store4bf(p, o0); store4bf(p + 16, o1); }
;     } else {
;       const int cc = c32 - 768, h = cc >> 7, part = (cc & 127) >> 5;
;       if (part < 2) store8bf(ka + ((size_t)(b * 6 + h) * E + e) * 96 + part * 32 + fq * 8, v0 * rs, v1 * rs);
.LBB0_1195:
	s_andn2_saveexec_b64 s[0:1], s[6:7]
	s_cbranch_execz .LBB0_836
	v_lshlrev_b32_e32 v12, 1, v144
	v_mov_b32_e32 v13, v1
	v_pk_mul_f32 v[4:5], v[4:5], v[0:1] op_sel_hi:[1,0]
	v_pk_mul_f32 v[2:3], v[2:3], v[0:1] op_sel_hi:[1,0]
	v_pk_mul_f32 v[8:9], v[8:9], v[0:1] op_sel_hi:[1,0]
	v_pk_mul_f32 v[6:7], v[6:7], v[0:1] op_sel_hi:[1,0]
	v_lshl_add_u64 v[10:11], v[10:11], 0, v[12:13]
	v_cvt_pk_bf16_f32 v2, v2, v3
	v_cvt_pk_bf16_f32 v3, v4, v5
	v_cvt_pk_bf16_f32 v4, v6, v7
	v_cvt_pk_bf16_f32 v5, v8, v9
	global_store_dwordx4 v[10:11], v[2:5], off offset:256 sc0 sc1
	s_branch .LBB0_836

; __global__ void __launch_bounds__(512) mega(Params P) {
;     ...
;     grid.sync();
.LBB0_1207:
	s_barrier
	s_mov_b64 s[2:3], exec
	v_readlane_b32 s0, v253, 57
	v_readlane_b32 s1, v253, 58
	s_and_b64 s[0:1], s[2:3], s[0:1]
	s_mov_b64 exec, s[0:1]
	s_cbranch_execz .LBB0_1217
	buffer_wbl2 sc1
	s_load_dwordx2 s[4:5], s[56:57], -0x8
	s_load_dword s0, s[56:57], 0x0
	v_readlane_b32 s1, v253, 55
	s_waitcnt lgkmcnt(0)
	s_and_b32 s1, s1, 7
	s_add_i32 s6, s0, 7
	s_sub_i32 s6, s6, s1
	s_lshr_b32 s6, s6, 3
	s_min_u32 s7, s0, 8
	s_lshl_b32 s1, s1, 2
	s_addk_i32 s1, 0x88
	v_mov_b32_e32 v2, s1
	global_load_dword v0, v1, s[4:5] sc1
	v_mov_b32_e32 v3, 1
	s_waitcnt vmcnt(0)
	v_and_b32_e32 v0, 0xffff0000, v0
	global_atomic_add v3, v2, v3, s[4:5] sc0
	s_waitcnt vmcnt(0)
	v_and_b32_e32 v3, 0xffff, v3
	s_nop 0
	v_readfirstlane_b32 s1, v3
	s_nop 3
	s_add_i32 s0, s6, -1
	s_cmp_lg_u32 s1, s0
	s_cbranch_scc1 .Lgb_poll_2
	s_sub_i32 s1, 0x10000, s6
	v_mov_b32_e32 v3, s1
	global_atomic_add v3, v2, v3, s[4:5] sc0
	s_waitcnt vmcnt(0)
	v_mov_b32_e32 v3, 1
	global_atomic_add v3, v1, v3, s[4:5] sc0
	s_waitcnt vmcnt(0)
	v_and_b32_e32 v3, 0xffff, v3
	s_nop 0
	v_readfirstlane_b32 s1, v3
	s_nop 3
	s_add_i32 s0, s7, -1
	s_cmp_lg_u32 s1, s0
	s_cbranch_scc1 .Lgb_poll_2
	s_sub_i32 s1, 0x10000, s7
	v_mov_b32_e32 v3, s1
	global_atomic_add v1, v3, s[4:5]

; __global__ void __launch_bounds__(512) mega(Params P) {
;     ...
;     grid.sync();
.LBB0_1432:
	s_waitcnt lgkmcnt(0)
	s_barrier
	s_mov_b64 s[2:3], exec
	v_readlane_b32 s0, v253, 57
	v_readlane_b32 s1, v253, 58
	v_readlane_b32 s56, v254, 50
	s_and_b64 s[0:1], s[2:3], s[0:1]
	v_readlane_b32 s52, v254, 52
	v_readlane_b32 s57, v254, 51
	v_readlane_b32 s53, v254, 53
	s_mov_b64 exec, s[0:1]
	s_cbranch_execz .LBB0_1442
	buffer_wbl2 sc1
	s_load_dwordx2 s[4:5], s[56:57], -0x8
	s_load_dword s0, s[56:57], 0x0
	v_readlane_b32 s1, v253, 55
	s_waitcnt lgkmcnt(0)
	s_and_b32 s1, s1, 7
	s_add_i32 s6, s0, 7
	s_sub_i32 s6, s6, s1
	s_lshr_b32 s6, s6, 3
	s_min_u32 s7, s0, 8
	s_lshl_b32 s1, s1, 2
	s_addk_i32 s1, 0x88
	v_mov_b32_e32 v2, s1
	global_load_dword v0, v1, s[4:5] sc1
	v_mov_b32_e32 v3, 1
	s_waitcnt vmcnt(0)
	v_and_b32_e32 v0, 0xffff0000, v0
	global_atomic_add v3, v2, v3, s[4:5] sc0
	s_waitcnt vmcnt(0)
	v_and_b32_e32 v3, 0xffff, v3
	s_nop 0
	v_readfirstlane_b32 s1, v3
	s_nop 3
	s_add_i32 s0, s6, -1
	s_cmp_lg_u32 s1, s0
	s_cbranch_scc1 .Lgb_poll_3
	s_sub_i32 s1, 0x10000, s6
	v_mov_b32_e32 v3, s1
	global_atomic_add v3, v2, v3, s[4:5] sc0
	s_waitcnt vmcnt(0)
	v_mov_b32_e32 v3, 1
	global_atomic_add v3, v1, v3, s[4:5] sc0
	s_waitcnt vmcnt(0)
	v_and_b32_e32 v3, 0xffff, v3
	s_nop 0
	v_readfirstlane_b32 s1, v3
	s_nop 3
	s_add_i32 s0, s7, -1
	s_cmp_lg_u32 s1, s0
	s_cbranch_scc1 .Lgb_poll_3
	s_sub_i32 s1, 0x10000, s7
	v_mov_b32_e32 v3, s1
	global_atomic_add v1, v3, s[4:5]

; template <class Epi, class Pre>
; __device__ __forceinline__ void meta_gemm(const bf16_t* __restrict__ A, int lda, const bf16_t* __restrict__ Bt, int ldb, int N, int K, Epi& epi, Pre pre) {
;     ...
;     const bf16_t* ap = A + (size_t)(NREAL + fr) * lda + wid * ks + fq * 8;
;     const bf16_t* bp = Bt + (size_t)(cb + fr) * ldb + wid * ks + fq * 8;
; #pragma unroll 4
;     for (int k0 = 0; k0 < ks; k0 += 32) {
;       const bf16x8 a = *(const bf16x8*)(ap + k0);
; #pragma unroll
;       for (int bj = 0; bj < 2; ++bj)
; #pragma unroll
;         for (int n = 0; n < 2; ++n) { const bf16x8 b = *(const bf16x8*)(bp + (size_t)(bj * 128 + n * 16) * ldb + k0); acc[bj][n] = __builtin_amdgcn_mfma_f32_16x16x32_bf16(b, a, acc[bj][n], 0, 0, 0); }
;     }
; #pragma unroll
;     for (int bj = 0; bj < 2; ++bj)
; #pragma unroll
;       for (int n = 0; n < 2; ++n)
; #pragma unroll
;         for (int j = 0; j < 4; ++j) part[(wid * 16 + (bj * 2 + n) * 4 + j) * 64 + lane] = acc[bj][n][j];
;     __syncthreads();
;     if (wid < 4) {
;       f32x4 v[2][2];
; #pragma unroll
;       for (int bj = 0; bj < 2; ++bj)
; #pragma unroll
;         for (int n = 0; n < 2; ++n)
; #pragma unroll
;           for (int j = 0; j < 4; ++j) { float s = 0.f;
; #pragma unroll
;             for (int w = 0; w < 8; ++w) s += part[(w * 16 + (bj * 2 + n) * 4 + j) * 64 + lane];
.LBB0_1446:
	s_and_b32 s10, s1, 0x60
	s_and_b32 s11, s0, 0xffffff00
	s_or_b32 s12, s11, s10
	v_or_b32_e32 v2, s12, v0
	v_ashrrev_i32_e32 v3, 31, v2
	v_lshlrev_b64 v[2:3], 11, v[2:3]
	v_lshl_add_u64 v[32:33], v[20:21], 0, v[2:3]
	s_mov_b32 s10, 0x8000
	v_add_co_u32_e32 v34, vcc, s10, v32
	s_mov_b32 s10, 0x40000
	s_nop 0
	v_addc_co_u32_e32 v35, vcc, 0, v33, vcc
	v_add_co_u32_e32 v36, vcc, s10, v32
	s_mov_b32 s10, 0x48000
	s_nop 0
	v_addc_co_u32_e32 v37, vcc, 0, v33, vcc
	v_add_co_u32_e32 v38, vcc, s10, v32
	global_load_dwordx4 v[2:5], v[18:19], off
	global_load_dwordx4 v[6:9], v[32:33], off
	v_addc_co_u32_e32 v39, vcc, 0, v33, vcc
	global_load_dwordx4 v[10:13], v[34:35], off
	global_load_dwordx4 v[14:17], v[36:37], off
	global_load_dwordx4 v[24:27], v[38:39], off
	s_waitcnt vmcnt(3)
	v_mfma_f32_16x16x32_bf16 v[6:9], v[6:9], v[2:5], 0
	s_waitcnt vmcnt(2)
	v_mfma_f32_16x16x32_bf16 v[10:13], v[10:13], v[2:5], 0
	s_waitcnt vmcnt(1)
	v_mfma_f32_16x16x32_bf16 v[14:17], v[14:17], v[2:5], 0
	s_waitcnt vmcnt(0)
	v_mfma_f32_16x16x32_bf16 v[2:5], v[24:27], v[2:5], 0
	global_load_dwordx4 v[24:27], v[18:19], off offset:64
	global_load_dwordx4 v[28:31], v[32:33], off offset:64
	s_waitcnt vmcnt(0)
	v_mfma_f32_16x16x32_bf16 v[6:9], v[28:31], v[24:27], v[6:9]
	global_load_dwordx4 v[28:31], v[34:35], off offset:64
	s_waitcnt vmcnt(0)
	v_mfma_f32_16x16x32_bf16 v[10:13], v[28:31], v[24:27], v[10:13]
	global_load_dwordx4 v[28:31], v[36:37], off offset:64
	s_waitcnt vmcnt(0)
	v_mfma_f32_16x16x32_bf16 v[14:17], v[28:31], v[24:27], v[14:17]
	global_load_dwordx4 v[28:31], v[38:39], off offset:64
	s_waitcnt vmcnt(0)
	v_mfma_f32_16x16x32_bf16 v[2:5], v[28:31], v[24:27], v[2:5]
	global_load_dwordx4 v[24:27], v[18:19], off offset:128
	global_load_dwordx4 v[28:31], v[32:33], off offset:128
	s_waitcnt vmcnt(0)
	v_mfma_f32_16x16x32_bf16 v[6:9], v[28:31], v[24:27], v[6:9]
	global_load_dwordx4 v[28:31], v[34:35], off offset:128
	s_waitcnt vmcnt(0)
	v_mfma_f32_16x16x32_bf16 v[10:13], v[28:31], v[24:27], v[10:13]
	global_load_dwordx4 v[28:31], v[36:37], off offset:128
	s_waitcnt vmcnt(0)
	v_mfma_f32_16x16x32_bf16 v[14:17], v[28:31], v[24:27], v[14:17]
	global_load_dwordx4 v[28:31], v[38:39], off offset:128
	s_waitcnt vmcnt(0)
	v_mfma_f32_16x16x32_bf16 v[2:5], v[28:31], v[24:27], v[2:5]
	global_load_dwordx4 v[24:27], v[18:19], off offset:192
	global_load_dwordx4 v[28:31], v[32:33], off offset:192
	s_waitcnt vmcnt(0)
	v_mfma_f32_16x16x32_bf16 v[6:9], v[28:31], v[24:27], v[6:9]
	global_load_dwordx4 v[28:31], v[34:35], off offset:192
	s_waitcnt vmcnt(0)
	v_mfma_f32_16x16x32_bf16 v[10:13], v[28:31], v[24:27], v[10:13]
	global_load_dwordx4 v[28:31], v[36:37], off offset:192
	s_waitcnt vmcnt(0)
	v_mfma_f32_16x16x32_bf16 v[14:17], v[28:31], v[24:27], v[14:17]
	global_load_dwordx4 v[28:31], v[38:39], off offset:192
	s_waitcnt vmcnt(0)
	v_mfma_f32_16x16x32_bf16 v[2:5], v[28:31], v[24:27], v[2:5]
	ds_write2st64_b32 v43, v6, v7 offset1:1
	ds_write2st64_b32 v43, v8, v9 offset0:2 offset1:3
	ds_write2st64_b32 v43, v10, v11 offset0:4 offset1:5
	ds_write2st64_b32 v43, v12, v13 offset0:6 offset1:7
	s_nop 0
	ds_write2st64_b32 v43, v14, v15 offset0:8 offset1:9
	ds_write2st64_b32 v43, v16, v17 offset0:10 offset1:11
	s_nop 0
	ds_write2st64_b32 v43, v2, v3 offset0:12 offset1:13
	ds_write2st64_b32 v43, v4, v5 offset0:14 offset1:15
	s_waitcnt lgkmcnt(0)
	s_barrier
	s_and_saveexec_b64 s[10:11], s[4:5]
	s_cbranch_execz .LBB0_1445
	ds_read2st64_b32 v[2:3], v42 offset1:1
	ds_read2st64_b32 v[4:5], v42 offset0:16 offset1:17
	ds_read2st64_b32 v[6:7], v42 offset0:32 offset1:33
	ds_read2st64_b32 v[8:9], v42 offset0:48 offset1:49
	ds_read2st64_b32 v[10:11], v42 offset0:64 offset1:65
	ds_read2st64_b32 v[12:13], v42 offset0:80 offset1:81
	ds_read2st64_b32 v[14:15], v42 offset0:96 offset1:97
	ds_read2st64_b32 v[16:17], v42 offset0:112 offset1:113
	ds_read2st64_b32 v[24:25], v42 offset0:2 offset1:3
	ds_read2st64_b32 v[26:27], v42 offset0:18 offset1:19
	ds_read2st64_b32 v[28:29], v42 offset0:34 offset1:35
	ds_read2st64_b32 v[30:31], v42 offset0:50 offset1:51
	ds_read2st64_b32 v[32:33], v42 offset0:66 offset1:67
	ds_read2st64_b32 v[34:35], v42 offset0:82 offset1:83
	ds_read2st64_b32 v[36:37], v42 offset0:98 offset1:99
	ds_read2st64_b32 v[38:39], v42 offset0:114 offset1:115
	s_waitcnt lgkmcnt(7)
	v_pk_add_f32 v[24:25], v[24:25], 0 op_sel_hi:[1,0]
	v_pk_add_f32 v[2:3], v[2:3], 0 op_sel_hi:[1,0]
	s_ashr_i32 s13, s12, 31
	v_pk_add_f32 v[2:3], v[2:3], v[4:5]
	s_waitcnt lgkmcnt(6)
	v_pk_add_f32 v[4:5], v[24:25], v[26:27]
	v_pk_add_f32 v[2:3], v[2:3], v[6:7]
	s_waitcnt lgkmcnt(5)
	v_pk_add_f32 v[4:5], v[4:5], v[28:29]
	v_pk_add_f32 v[2:3], v[2:3], v[8:9]
	s_waitcnt lgkmcnt(4)
	v_pk_add_f32 v[4:5], v[4:5], v[30:31]
	v_pk_add_f32 v[2:3], v[2:3], v[10:11]
	s_waitcnt lgkmcnt(3)
	v_pk_add_f32 v[4:5], v[4:5], v[32:33]
	v_pk_add_f32 v[2:3], v[2:3], v[12:13]
	s_waitcnt lgkmcnt(2)
	v_pk_add_f32 v[4:5], v[4:5], v[34:35]
	v_pk_add_f32 v[2:3], v[2:3], v[14:15]
	s_waitcnt lgkmcnt(1)
	v_pk_add_f32 v[4:5], v[4:5], v[36:37]
	v_pk_add_f32 v[24:25], v[2:3], v[16:17]
	s_waitcnt lgkmcnt(0)
	v_pk_add_f32 v[26:27], v[4:5], v[38:39]
	ds_read2st64_b32 v[2:3], v42 offset0:4 offset1:5
	ds_read2st64_b32 v[4:5], v42 offset0:20 offset1:21
	ds_read2st64_b32 v[6:7], v42 offset0:36 offset1:37
	ds_read2st64_b32 v[8:9], v42 offset0:52 offset1:53
	ds_read2st64_b32 v[10:11], v42 offset0:68 offset1:69
	ds_read2st64_b32 v[12:13], v42 offset0:84 offset1:85
	ds_read2st64_b32 v[14:15], v42 offset0:100 offset1:101
	ds_read2st64_b32 v[16:17], v42 offset0:116 offset1:117
	ds_read2st64_b32 v[28:29], v42 offset0:6 offset1:7
	ds_read2st64_b32 v[30:31], v42 offset0:22 offset1:23
	ds_read2st64_b32 v[32:33], v42 offset0:38 offset1:39
	ds_read2st64_b32 v[34:35], v42 offset0:54 offset1:55
	ds_read2st64_b32 v[36:37], v42 offset0:70 offset1:71
	ds_read2st64_b32 v[38:39], v42 offset0:86 offset1:87
	ds_read2st64_b32 v[40:41], v42 offset0:102 offset1:103
	ds_read2st64_b32 v[44:45], v42 offset0:118 offset1:119
	s_waitcnt lgkmcnt(7)
; template <class Epi, class Pre>
; __device__ __forceinline__ void meta_gemm(const bf16_t* __restrict__ A, int lda, const bf16_t* __restrict__ Bt, int ldb, int N, int K, Epi& epi, Pre pre) {
;     ...
;           for (int j = 0; j < 4; ++j) { float s = 0.f;
; #pragma unroll
;             for (int w = 0; w < 8; ++w) s += part[(w * 16 + (bj * 2 + n) * 4 + j) * 64 + lane];
;             v[bj][n][j] = s; }
;       pre(fr, fq);
;       epi(NREAL + 16 * wid + fr, cb, fq, v[0][0], v[0][1], v[1][0], v[1][1]);
	v_pk_add_f32 v[28:29], v[28:29], 0 op_sel_hi:[1,0]
	v_pk_add_f32 v[2:3], v[2:3], 0 op_sel_hi:[1,0]
	s_nop 0
	v_pk_add_f32 v[2:3], v[2:3], v[4:5]
	s_waitcnt lgkmcnt(6)
	v_pk_add_f32 v[4:5], v[28:29], v[30:31]
	v_pk_add_f32 v[2:3], v[2:3], v[6:7]
	s_waitcnt lgkmcnt(5)
	v_pk_add_f32 v[4:5], v[4:5], v[32:33]
	v_pk_add_f32 v[2:3], v[2:3], v[8:9]
	s_waitcnt lgkmcnt(4)
	v_pk_add_f32 v[4:5], v[4:5], v[34:35]
	v_pk_add_f32 v[2:3], v[2:3], v[10:11]
	s_waitcnt lgkmcnt(3)
	v_pk_add_f32 v[4:5], v[4:5], v[36:37]
	v_pk_add_f32 v[2:3], v[2:3], v[12:13]
	s_waitcnt lgkmcnt(2)
	v_pk_add_f32 v[4:5], v[4:5], v[38:39]
	v_pk_add_f32 v[2:3], v[2:3], v[14:15]
	s_waitcnt lgkmcnt(1)
	v_pk_add_f32 v[4:5], v[4:5], v[40:41]
	v_pk_add_f32 v[28:29], v[2:3], v[16:17]
	s_waitcnt lgkmcnt(0)
	v_pk_add_f32 v[30:31], v[4:5], v[44:45]
	ds_read2st64_b32 v[2:3], v42 offset0:8 offset1:9
	ds_read2st64_b32 v[4:5], v42 offset0:24 offset1:25
	ds_read2st64_b32 v[6:7], v42 offset0:40 offset1:41
	ds_read2st64_b32 v[8:9], v42 offset0:56 offset1:57
	ds_read2st64_b32 v[10:11], v42 offset0:72 offset1:73
	ds_read2st64_b32 v[12:13], v42 offset0:88 offset1:89
	ds_read2st64_b32 v[14:15], v42 offset0:104 offset1:105
	ds_read2st64_b32 v[16:17], v42 offset0:120 offset1:121
	ds_read2st64_b32 v[32:33], v42 offset0:10 offset1:11
	ds_read2st64_b32 v[34:35], v42 offset0:26 offset1:27
	ds_read2st64_b32 v[36:37], v42 offset0:42 offset1:43
	ds_read2st64_b32 v[38:39], v42 offset0:58 offset1:59
	ds_read2st64_b32 v[40:41], v42 offset0:74 offset1:75
	ds_read2st64_b32 v[44:45], v42 offset0:90 offset1:91
	ds_read2st64_b32 v[46:47], v42 offset0:106 offset1:107
	ds_read2st64_b32 v[48:49], v42 offset0:122 offset1:123
	s_waitcnt lgkmcnt(7)
	v_pk_add_f32 v[32:33], v[32:33], 0 op_sel_hi:[1,0]
	v_pk_add_f32 v[2:3], v[2:3], 0 op_sel_hi:[1,0]
	s_nop 0
	v_pk_add_f32 v[2:3], v[2:3], v[4:5]
	s_waitcnt lgkmcnt(6)
	v_pk_add_f32 v[4:5], v[32:33], v[34:35]
	v_pk_add_f32 v[2:3], v[2:3], v[6:7]
	s_waitcnt lgkmcnt(5)
	v_pk_add_f32 v[4:5], v[4:5], v[36:37]
	v_pk_add_f32 v[2:3], v[2:3], v[8:9]
	s_waitcnt lgkmcnt(4)
	v_pk_add_f32 v[4:5], v[4:5], v[38:39]
	v_pk_add_f32 v[2:3], v[2:3], v[10:11]
	s_waitcnt lgkmcnt(3)
	v_pk_add_f32 v[4:5], v[4:5], v[40:41]
	v_pk_add_f32 v[2:3], v[2:3], v[12:13]
	s_waitcnt lgkmcnt(2)
	v_pk_add_f32 v[4:5], v[4:5], v[44:45]
	v_pk_add_f32 v[2:3], v[2:3], v[14:15]
	s_waitcnt lgkmcnt(1)
	v_pk_add_f32 v[4:5], v[4:5], v[46:47]
	v_pk_add_f32 v[32:33], v[2:3], v[16:17]
	s_waitcnt lgkmcnt(0)
	v_pk_add_f32 v[34:35], v[4:5], v[48:49]
	ds_read2st64_b32 v[2:3], v42 offset0:12 offset1:13
	ds_read2st64_b32 v[4:5], v42 offset0:28 offset1:29
	ds_read2st64_b32 v[6:7], v42 offset0:44 offset1:45
	ds_read2st64_b32 v[8:9], v42 offset0:60 offset1:61
	ds_read2st64_b32 v[10:11], v42 offset0:76 offset1:77
	ds_read2st64_b32 v[12:13], v42 offset0:92 offset1:93
	ds_read2st64_b32 v[14:15], v42 offset0:108 offset1:109
	ds_read2st64_b32 v[16:17], v42 offset0:124 offset1:125
	ds_read2st64_b32 v[36:37], v42 offset0:14 offset1:15
	ds_read2st64_b32 v[38:39], v42 offset0:30 offset1:31
	ds_read2st64_b32 v[40:41], v42 offset0:46 offset1:47
	ds_read2st64_b32 v[44:45], v42 offset0:62 offset1:63
	ds_read2st64_b32 v[46:47], v42 offset0:78 offset1:79
	ds_read2st64_b32 v[48:49], v42 offset0:94 offset1:95
	ds_read2st64_b32 v[50:51], v42 offset0:110 offset1:111
	ds_read2st64_b32 v[52:53], v42 offset0:126 offset1:127
	s_waitcnt lgkmcnt(7)
	v_pk_add_f32 v[36:37], v[36:37], 0 op_sel_hi:[1,0]
	v_pk_add_f32 v[2:3], v[2:3], 0 op_sel_hi:[1,0]
	s_nop 0
	v_pk_add_f32 v[2:3], v[2:3], v[4:5]
	s_waitcnt lgkmcnt(6)
	v_pk_add_f32 v[4:5], v[36:37], v[38:39]
	v_pk_add_f32 v[2:3], v[2:3], v[6:7]
	s_waitcnt lgkmcnt(5)
	v_pk_add_f32 v[4:5], v[4:5], v[40:41]
	v_pk_add_f32 v[2:3], v[2:3], v[8:9]
	s_waitcnt lgkmcnt(4)
	v_pk_add_f32 v[4:5], v[4:5], v[44:45]
	v_pk_add_f32 v[2:3], v[2:3], v[10:11]
	s_waitcnt lgkmcnt(3)
	v_pk_add_f32 v[4:5], v[4:5], v[46:47]
	v_pk_add_f32 v[2:3], v[2:3], v[12:13]
	s_waitcnt lgkmcnt(2)
	v_pk_add_f32 v[4:5], v[4:5], v[48:49]
	v_pk_add_f32 v[2:3], v[2:3], v[14:15]
	s_waitcnt lgkmcnt(1)
	v_pk_add_f32 v[4:5], v[4:5], v[50:51]
	v_lshl_add_u64 v[40:41], s[12:13], 2, v[22:23]
	v_pk_add_f32 v[36:37], v[2:3], v[16:17]
	s_waitcnt lgkmcnt(0)
	v_pk_add_f32 v[38:39], v[4:5], v[52:53]
	global_load_dwordx4 v[2:5], v[40:41], off
	global_load_dwordx4 v[6:9], v[40:41], off offset:64
	global_load_dwordx4 v[10:13], v[40:41], off offset:512
	global_load_dwordx4 v[14:17], v[40:41], off offset:576
	s_waitcnt vmcnt(3)
	v_pk_add_f32 v[4:5], v[26:27], v[4:5]
	v_pk_add_f32 v[2:3], v[24:25], v[2:3]
	global_store_dwordx4 v[40:41], v[2:5], off sc0 sc1
	s_waitcnt vmcnt(3)
	s_nop 0
	v_pk_add_f32 v[4:5], v[30:31], v[8:9]
	v_pk_add_f32 v[2:3], v[28:29], v[6:7]
	global_store_dwordx4 v[40:41], v[2:5], off offset:64 sc0 sc1
	s_waitcnt vmcnt(3)
	s_nop 0
	v_pk_add_f32 v[4:5], v[34:35], v[12:13]
	v_pk_add_f32 v[2:3], v[32:33], v[10:11]
	global_store_dwordx4 v[40:41], v[2:5], off offset:512 sc0 sc1
	s_waitcnt vmcnt(3)
	s_nop 0
	v_pk_add_f32 v[4:5], v[38:39], v[16:17]
	v_pk_add_f32 v[2:3], v[36:37], v[14:15]
	global_store_dwordx4 v[40:41], v[2:5], off offset:576 sc0 sc1
	s_branch .LBB0_1445

;     ...
; #pragma unroll
;     for (int ai = 0; ai < 2; ++ai)
; #pragma unroll
;       for (int m = 0; m < 4; ++m)
;         epi(brow + ai * HALF + wr * 64 + m * 16 + fr, bcol + wc * 32, fq, acc[ai][0][m][0], acc[ai][0][m][1], acc[ai][1][m][0], acc[ai][1][m][1]);
;   }
.LBB0_1463:
	v_or_b32_e32 v0, s10, v218
	v_add_u32_e32 v136, v0, v215
	v_ashrrev_i32_e32 v137, 31, v136
	v_readlane_b32 s6, v253, 60
	v_lshl_or_b32 v0, v139, 5, s90
	v_lshlrev_b64 v[132:133], 12, v[136:137]
	v_readlane_b32 s7, v253, 61
	v_lshlrev_b64 v[134:135], 2, v[0:1]
	v_mov_b32_e32 v131, v1
	v_lshl_add_u64 v[132:133], s[6:7], 0, v[132:133]
	v_lshl_add_u64 v[132:133], v[132:133], 0, v[134:135]
	v_lshl_add_u64 v[132:133], v[132:133], 0, v[130:131]
	global_load_dwordx4 v[138:141], v[132:133], off
	global_load_dwordx4 v[142:145], v[132:133], off offset:64
	global_load_dwordx4 v[146:149], v[132:133], off offset:512
	global_load_dwordx4 v[150:153], v[132:133], off offset:576
	v_cndmask_b32_e64 v0, 0, 1, s[4:5]
	s_waitcnt vmcnt(0)
	v_pk_add_f32 v[120:121], v[120:121], v[140:141]
	v_pk_add_f32 v[116:117], v[116:117], v[144:145]
	v_pk_add_f32 v[114:115], v[114:115], v[142:143]
	global_store_dwordx4 v[132:133], v[114:117], off offset:64 sc0 sc1
	v_pk_add_f32 v[118:119], v[118:119], v[138:139]
	global_store_dwordx4 v[132:133], v[118:121], off sc0 sc1
	v_pk_add_f32 v[116:117], v[128:129], v[148:149]
	v_pk_add_f32 v[114:115], v[126:127], v[146:147]
	global_store_dwordx4 v[132:133], v[114:117], off offset:512 sc0 sc1
	s_nop 1
	v_pk_add_f32 v[116:117], v[124:125], v[152:153]
	v_pk_add_f32 v[114:115], v[122:123], v[150:151]
	global_store_dwordx4 v[132:133], v[114:117], off offset:576 sc0 sc1
	s_nop 1
	v_or_b32_e32 v114, 16, v136
	v_ashrrev_i32_e32 v115, 31, v114
	v_lshlrev_b64 v[114:115], 12, v[114:115]
	v_lshl_add_u64 v[114:115], s[6:7], 0, v[114:115]
	v_lshl_add_u64 v[114:115], v[114:115], 0, v[134:135]
	v_lshl_add_u64 v[138:139], v[114:115], 0, v[130:131]
	global_load_dwordx4 v[114:117], v[138:139], off
	global_load_dwordx4 v[118:121], v[138:139], off offset:64
	global_load_dwordx4 v[122:125], v[138:139], off offset:512
	global_load_dwordx4 v[126:129], v[138:139], off offset:576
	s_waitcnt vmcnt(0)
	v_pk_add_f32 v[104:105], v[104:105], v[116:117]
	v_pk_add_f32 v[100:101], v[100:101], v[120:121]
	v_pk_add_f32 v[98:99], v[98:99], v[118:119]
	global_store_dwordx4 v[138:139], v[98:101], off offset:64 sc0 sc1
	v_pk_add_f32 v[102:103], v[102:103], v[114:115]
	global_store_dwordx4 v[138:139], v[102:105], off sc0 sc1
	v_pk_add_f32 v[100:101], v[112:113], v[124:125]
	v_pk_add_f32 v[98:99], v[110:111], v[122:123]
	global_store_dwordx4 v[138:139], v[98:101], off offset:512 sc0 sc1
	s_nop 1
	v_pk_add_f32 v[100:101], v[108:109], v[128:129]
	v_pk_add_f32 v[98:99], v[106:107], v[126:127]
	global_store_dwordx4 v[138:139], v[98:101], off offset:576 sc0 sc1
	s_nop 1
	v_or_b32_e32 v98, 32, v136
	v_ashrrev_i32_e32 v99, 31, v98
	v_lshlrev_b64 v[98:99], 12, v[98:99]
	v_lshl_add_u64 v[98:99], s[6:7], 0, v[98:99]
	v_lshl_add_u64 v[98:99], v[98:99], 0, v[134:135]
	v_lshl_add_u64 v[114:115], v[98:99], 0, v[130:131]
	global_load_dwordx4 v[98:101], v[114:115], off
	global_load_dwordx4 v[102:105], v[114:115], off offset:64
	global_load_dwordx4 v[106:109], v[114:115], off offset:512
	global_load_dwordx4 v[110:113], v[114:115], off offset:576
	s_waitcnt vmcnt(0)
	v_pk_add_f32 v[88:89], v[88:89], v[100:101]
	v_pk_add_f32 v[84:85], v[84:85], v[104:105]
	v_pk_add_f32 v[82:83], v[82:83], v[102:103]
	global_store_dwordx4 v[114:115], v[82:85], off offset:64 sc0 sc1
	v_pk_add_f32 v[86:87], v[86:87], v[98:99]
	global_store_dwordx4 v[114:115], v[86:89], off sc0 sc1
	v_pk_add_f32 v[84:85], v[96:97], v[108:109]
	v_pk_add_f32 v[82:83], v[94:95], v[106:107]
	global_store_dwordx4 v[114:115], v[82:85], off offset:512 sc0 sc1
	s_nop 1
	v_pk_add_f32 v[84:85], v[92:93], v[112:113]
	v_pk_add_f32 v[82:83], v[90:91], v[110:111]
	global_store_dwordx4 v[114:115], v[82:85], off offset:576 sc0 sc1
	s_nop 1
	v_or_b32_e32 v82, 48, v136
	v_ashrrev_i32_e32 v83, 31, v82
	v_lshlrev_b64 v[82:83], 12, v[82:83]
	v_lshl_add_u64 v[82:83], s[6:7], 0, v[82:83]
	v_lshl_add_u64 v[82:83], v[82:83], 0, v[134:135]
	v_lshl_add_u64 v[98:99], v[82:83], 0, v[130:131]
	global_load_dwordx4 v[82:85], v[98:99], off
	global_load_dwordx4 v[86:89], v[98:99], off offset:64
	global_load_dwordx4 v[90:93], v[98:99], off offset:512
	global_load_dwordx4 v[94:97], v[98:99], off offset:576
	s_mov_b64 s[6:7], 0x80000
	s_waitcnt vmcnt(0)
; #define WAIT_V(n) asm volatile("s_waitcnt vmcnt(" #n ")" ::: "memory")
;     ...
; #pragma unroll
;     for (int ai = 0; ai < 2; ++ai)
; #pragma unroll
;       for (int m = 0; m < 4; ++m)
;         epi(brow + ai * HALF + wr * 64 + m * 16 + fr, bcol + wc * 32, fq, acc[ai][0][m][0], acc[ai][0][m][1], acc[ai][1][m][0], acc[ai][1][m][1]);
;   }
;   if (!have_next) { WAIT_V(0); __syncthreads(); }
	v_pk_add_f32 v[70:71], v[70:71], v[82:83]
	v_pk_add_f32 v[68:69], v[68:69], v[88:89]
	v_pk_add_f32 v[66:67], v[66:67], v[86:87]
	global_store_dwordx4 v[98:99], v[66:69], off offset:64 sc0 sc1
	v_lshl_add_u64 v[82:83], v[132:133], 0, s[6:7]
	s_mov_b32 s6, 0x80000
	v_pk_add_f32 v[68:69], v[80:81], v[92:93]
	v_pk_add_f32 v[66:67], v[78:79], v[90:91]
	v_pk_add_f32 v[72:73], v[72:73], v[84:85]
	global_store_dwordx4 v[98:99], v[66:69], off offset:512 sc0 sc1
	v_add_co_u32_e32 v84, vcc, s6, v132
	s_nop 0
	v_pk_add_f32 v[68:69], v[76:77], v[96:97]
	v_pk_add_f32 v[66:67], v[74:75], v[94:95]
	global_store_dwordx4 v[98:99], v[70:73], off sc0 sc1
	global_store_dwordx4 v[98:99], v[66:69], off offset:576 sc0 sc1
	v_addc_co_u32_e32 v85, vcc, 0, v133, vcc
	global_load_dwordx4 v[66:69], v[84:85], off
	global_load_dwordx4 v[70:73], v[82:83], off offset:64
	global_load_dwordx4 v[74:77], v[82:83], off offset:512
	global_load_dwordx4 v[78:81], v[82:83], off offset:576
	s_mov_b64 s[6:7], 0x90000
	s_waitcnt vmcnt(0)
	v_pk_add_f32 v[54:55], v[54:55], v[66:67]
	v_pk_add_f32 v[52:53], v[52:53], v[72:73]
	v_pk_add_f32 v[50:51], v[50:51], v[70:71]
	global_store_dwordx4 v[82:83], v[50:53], off offset:64 sc0 sc1
	v_lshl_add_u64 v[66:67], v[132:133], 0, s[6:7]
	s_mov_b32 s6, 0x90000
	v_pk_add_f32 v[52:53], v[64:65], v[76:77]
	v_pk_add_f32 v[50:51], v[62:63], v[74:75]
	v_pk_add_f32 v[56:57], v[56:57], v[68:69]
	global_store_dwordx4 v[82:83], v[50:53], off offset:512 sc0 sc1
	v_add_co_u32_e32 v68, vcc, s6, v132
	s_nop 0
	v_pk_add_f32 v[52:53], v[60:61], v[80:81]
	v_pk_add_f32 v[50:51], v[58:59], v[78:79]
	global_store_dwordx4 v[84:85], v[54:57], off sc0 sc1
	global_store_dwordx4 v[82:83], v[50:53], off offset:576 sc0 sc1
	v_addc_co_u32_e32 v69, vcc, 0, v133, vcc
	global_load_dwordx4 v[50:53], v[68:69], off
	global_load_dwordx4 v[54:57], v[66:67], off offset:64
	global_load_dwordx4 v[58:61], v[66:67], off offset:512
	global_load_dwordx4 v[62:65], v[66:67], off offset:576
	s_mov_b64 s[6:7], 0xa0000
	s_waitcnt vmcnt(0)
	v_pk_add_f32 v[38:39], v[38:39], v[50:51]
	v_pk_add_f32 v[36:37], v[36:37], v[56:57]
	v_pk_add_f32 v[34:35], v[34:35], v[54:55]
	global_store_dwordx4 v[66:67], v[34:37], off offset:64 sc0 sc1
	v_lshl_add_u64 v[50:51], v[132:133], 0, s[6:7]
	s_mov_b32 s6, 0xa0000
	v_pk_add_f32 v[36:37], v[48:49], v[60:61]
	v_pk_add_f32 v[34:35], v[46:47], v[58:59]
	v_pk_add_f32 v[40:41], v[40:41], v[52:53]
	global_store_dwordx4 v[66:67], v[34:37], off offset:512 sc0 sc1
	v_add_co_u32_e32 v52, vcc, s6, v132
	s_nop 0
	v_pk_add_f32 v[36:37], v[44:45], v[64:65]
	v_pk_add_f32 v[34:35], v[42:43], v[62:63]
	global_store_dwordx4 v[68:69], v[38:41], off sc0 sc1
	global_store_dwordx4 v[66:67], v[34:37], off offset:576 sc0 sc1
	v_addc_co_u32_e32 v53, vcc, 0, v133, vcc
	global_load_dwordx4 v[34:37], v[52:53], off
	global_load_dwordx4 v[38:41], v[50:51], off offset:64
	global_load_dwordx4 v[42:45], v[50:51], off offset:512
	global_load_dwordx4 v[46:49], v[50:51], off offset:576
	s_mov_b64 s[6:7], 0xb0000
	s_waitcnt vmcnt(0)
	v_pk_add_f32 v[22:23], v[22:23], v[34:35]
	v_pk_add_f32 v[20:21], v[20:21], v[40:41]
	v_pk_add_f32 v[18:19], v[18:19], v[38:39]
	global_store_dwordx4 v[50:51], v[18:21], off offset:64 sc0 sc1
	v_lshl_add_u64 v[34:35], v[132:133], 0, s[6:7]
	s_mov_b32 s6, 0xb0000
	v_pk_add_f32 v[20:21], v[32:33], v[44:45]
	v_pk_add_f32 v[18:19], v[30:31], v[42:43]
	v_pk_add_f32 v[24:25], v[24:25], v[36:37]
	global_store_dwordx4 v[50:51], v[18:21], off offset:512 sc0 sc1
	v_add_co_u32_e32 v36, vcc, s6, v132
	s_nop 0
	v_pk_add_f32 v[20:21], v[28:29], v[48:49]
	v_pk_add_f32 v[18:19], v[26:27], v[46:47]
	global_store_dwordx4 v[52:53], v[22:25], off sc0 sc1
	global_store_dwordx4 v[50:51], v[18:21], off offset:576 sc0 sc1
	v_addc_co_u32_e32 v37, vcc, 0, v133, vcc
	global_load_dwordx4 v[30:33], v[36:37], off
	global_load_dwordx4 v[26:29], v[34:35], off offset:64
	global_load_dwordx4 v[22:25], v[34:35], off offset:512
	global_load_dwordx4 v[18:21], v[34:35], off offset:576
	v_cmp_ne_u32_e64 s[6:7], 1, v0
	s_andn2_b64 vcc, exec, s[4:5]
	s_waitcnt vmcnt(0)
	v_pk_add_f32 v[16:17], v[16:17], v[32:33]
	v_pk_add_f32 v[8:9], v[8:9], v[28:29]
	v_pk_add_f32 v[6:7], v[6:7], v[26:27]
	v_pk_add_f32 v[14:15], v[14:15], v[30:31]
	global_store_dwordx4 v[34:35], v[6:9], off offset:64 sc0 sc1
	v_pk_add_f32 v[4:5], v[4:5], v[20:21]
	v_pk_add_f32 v[2:3], v[2:3], v[18:19]
	v_pk_add_f32 v[8:9], v[12:13], v[24:25]
	v_pk_add_f32 v[6:7], v[10:11], v[22:23]
	global_store_dwordx4 v[36:37], v[14:17], off sc0 sc1
	global_store_dwordx4 v[34:35], v[6:9], off offset:512 sc0 sc1
	global_store_dwordx4 v[34:35], v[2:5], off offset:576 sc0 sc1
	s_cbranch_vccnz .LBB0_1450
	s_waitcnt vmcnt(0)
	s_waitcnt lgkmcnt(0)
	s_barrier
	s_branch .LBB0_1450

; template <class Epi, class Pre>
; __device__ __forceinline__ void meta_gemm(const bf16_t* __restrict__ A, int lda, const bf16_t* __restrict__ Bt, int ldb, int N, int K, Epi& epi, Pre pre) {
;     ...
;     const bf16_t* ap = A + (size_t)(NREAL + fr) * lda + wid * ks + fq * 8;
;     const bf16_t* bp = Bt + (size_t)(cb + fr) * ldb + wid * ks + fq * 8;
; #pragma unroll 4
;     for (int k0 = 0; k0 < ks; k0 += 32) {
;       const bf16x8 a = *(const bf16x8*)(ap + k0);
; #pragma unroll
;       for (int bj = 0; bj < 2; ++bj)
; #pragma unroll
;         for (int n = 0; n < 2; ++n) { const bf16x8 b = *(const bf16x8*)(bp + (size_t)(bj * 128 + n * 16) * ldb + k0); acc[bj][n] = __builtin_amdgcn_mfma_f32_16x16x32_bf16(b, a, acc[bj][n], 0, 0, 0); }
;     }
; #pragma unroll
;     for (int bj = 0; bj < 2; ++bj)
; #pragma unroll
;       for (int n = 0; n < 2; ++n)
; #pragma unroll
;         for (int j = 0; j < 4; ++j) part[(wid * 16 + (bj * 2 + n) * 4 + j) * 64 + lane] = acc[bj][n][j];
;     __syncthreads();
;     if (wid < 4) {
;       f32x4 v[2][2];
; #pragma unroll
;       for (int bj = 0; bj < 2; ++bj)
; #pragma unroll
;         for (int n = 0; n < 2; ++n)
; #pragma unroll
;           for (int j = 0; j < 4; ++j) { float s = 0.f;
; #pragma unroll
;             for (int w = 0; w < 8; ++w) s += part[(w * 16 + (bj * 2 + n) * 4 + j) * 64 + lane];
.LBB0_1470:
	s_and_b32 s6, s1, 0x60
	s_and_b32 s7, s0, 0xffffff00
	s_or_b32 s8, s7, s6
	v_or_b32_e32 v18, s8, v0
	v_ashrrev_i32_e32 v19, 31, v18
	v_lshlrev_b64 v[18:19], 11, v[18:19]
	v_lshl_add_u64 v[44:45], v[34:35], 0, v[18:19]
	global_load_dwordx4 v[18:21], v[44:45], off
	global_load_dwordx4 v[40:43], v[44:45], off offset:64
	v_add_co_u32_e32 v46, vcc, 0x8000, v44
	s_waitcnt vmcnt(0)
	v_mfma_f32_16x16x32_bf16 v[18:21], v[18:21], v[10:13], 0
	v_addc_co_u32_e32 v47, vcc, 0, v45, vcc
	global_load_dwordx4 v[22:25], v[46:47], off
	v_mfma_f32_16x16x32_bf16 v[18:21], v[40:43], v[2:5], v[18:21]
	global_load_dwordx4 v[40:43], v[46:47], off offset:64
	v_add_co_u32_e32 v48, vcc, 0x40000, v44
	s_waitcnt vmcnt(0)
	v_mfma_f32_16x16x32_bf16 v[22:25], v[22:25], v[10:13], 0
	v_addc_co_u32_e32 v49, vcc, 0, v45, vcc
	global_load_dwordx4 v[26:29], v[48:49], off
	v_mfma_f32_16x16x32_bf16 v[22:25], v[40:43], v[2:5], v[22:25]
	global_load_dwordx4 v[40:43], v[48:49], off offset:64
	v_add_co_u32_e32 v50, vcc, 0x48000, v44
	s_waitcnt vmcnt(0)
	v_mfma_f32_16x16x32_bf16 v[26:29], v[26:29], v[10:13], 0
	v_addc_co_u32_e32 v51, vcc, 0, v45, vcc
	global_load_dwordx4 v[30:33], v[50:51], off
	v_mfma_f32_16x16x32_bf16 v[26:29], v[40:43], v[2:5], v[26:29]
	global_load_dwordx4 v[40:43], v[50:51], off offset:64
	s_waitcnt vmcnt(0)
	v_mfma_f32_16x16x32_bf16 v[30:33], v[30:33], v[10:13], 0
	v_mfma_f32_16x16x32_bf16 v[30:33], v[40:43], v[2:5], v[30:33]
	global_load_dwordx4 v[40:43], v[44:45], off offset:128
	s_waitcnt vmcnt(0)
	v_mfma_f32_16x16x32_bf16 v[18:21], v[40:43], v[6:9], v[18:21]
	global_load_dwordx4 v[40:43], v[46:47], off offset:128
	s_waitcnt vmcnt(0)
	v_mfma_f32_16x16x32_bf16 v[22:25], v[40:43], v[6:9], v[22:25]
	global_load_dwordx4 v[40:43], v[48:49], off offset:128
	s_waitcnt vmcnt(0)
	v_mfma_f32_16x16x32_bf16 v[26:29], v[40:43], v[6:9], v[26:29]
	global_load_dwordx4 v[40:43], v[50:51], off offset:128
	s_waitcnt vmcnt(0)
	v_mfma_f32_16x16x32_bf16 v[30:33], v[40:43], v[6:9], v[30:33]
	global_load_dwordx4 v[40:43], v[44:45], off offset:192
	s_waitcnt vmcnt(0)
	v_mfma_f32_16x16x32_bf16 v[18:21], v[40:43], v[14:17], v[18:21]
	global_load_dwordx4 v[40:43], v[46:47], off offset:192
	s_waitcnt vmcnt(0)
	v_mfma_f32_16x16x32_bf16 v[22:25], v[40:43], v[14:17], v[22:25]
	global_load_dwordx4 v[40:43], v[48:49], off offset:192
	s_waitcnt vmcnt(0)
	v_mfma_f32_16x16x32_bf16 v[26:29], v[40:43], v[14:17], v[26:29]
	global_load_dwordx4 v[40:43], v[50:51], off offset:192
	s_waitcnt vmcnt(0)
	v_mfma_f32_16x16x32_bf16 v[30:33], v[40:43], v[14:17], v[30:33]
	ds_write2st64_b32 v59, v18, v19 offset1:1
	ds_write2st64_b32 v59, v20, v21 offset0:2 offset1:3
	ds_write2st64_b32 v59, v22, v23 offset0:4 offset1:5
	ds_write2st64_b32 v59, v24, v25 offset0:6 offset1:7
	s_nop 0
	ds_write2st64_b32 v59, v26, v27 offset0:8 offset1:9
	ds_write2st64_b32 v59, v28, v29 offset0:10 offset1:11
	s_nop 0
	ds_write2st64_b32 v59, v30, v31 offset0:12 offset1:13
	ds_write2st64_b32 v59, v32, v33 offset0:14 offset1:15
	s_waitcnt lgkmcnt(0)
	s_barrier
	s_and_saveexec_b64 s[6:7], s[4:5]
	s_cbranch_execz .LBB0_1469
	ds_read2st64_b32 v[18:19], v58 offset1:1
	ds_read2st64_b32 v[20:21], v58 offset0:16 offset1:17
	ds_read2st64_b32 v[22:23], v58 offset0:32 offset1:33
	ds_read2st64_b32 v[24:25], v58 offset0:48 offset1:49
	ds_read2st64_b32 v[26:27], v58 offset0:64 offset1:65
	ds_read2st64_b32 v[28:29], v58 offset0:80 offset1:81
	ds_read2st64_b32 v[30:31], v58 offset0:96 offset1:97
	ds_read2st64_b32 v[32:33], v58 offset0:112 offset1:113
	ds_read2st64_b32 v[40:41], v58 offset0:2 offset1:3
	ds_read2st64_b32 v[42:43], v58 offset0:18 offset1:19
	ds_read2st64_b32 v[44:45], v58 offset0:34 offset1:35
	ds_read2st64_b32 v[46:47], v58 offset0:50 offset1:51
	ds_read2st64_b32 v[48:49], v58 offset0:66 offset1:67
	ds_read2st64_b32 v[50:51], v58 offset0:82 offset1:83
	ds_read2st64_b32 v[52:53], v58 offset0:98 offset1:99
	ds_read2st64_b32 v[54:55], v58 offset0:114 offset1:115
	s_waitcnt lgkmcnt(7)
	v_pk_add_f32 v[40:41], v[40:41], 0 op_sel_hi:[1,0]
	v_pk_add_f32 v[18:19], v[18:19], 0 op_sel_hi:[1,0]
	s_ashr_i32 s9, s8, 31
	v_pk_add_f32 v[18:19], v[18:19], v[20:21]
	s_waitcnt lgkmcnt(6)
	v_pk_add_f32 v[20:21], v[40:41], v[42:43]
	v_pk_add_f32 v[18:19], v[18:19], v[22:23]
	s_waitcnt lgkmcnt(5)
	v_pk_add_f32 v[20:21], v[20:21], v[44:45]
	v_pk_add_f32 v[18:19], v[18:19], v[24:25]
	s_waitcnt lgkmcnt(4)
	v_pk_add_f32 v[20:21], v[20:21], v[46:47]
	v_pk_add_f32 v[18:19], v[18:19], v[26:27]
	s_waitcnt lgkmcnt(3)
	v_pk_add_f32 v[20:21], v[20:21], v[48:49]
	v_pk_add_f32 v[18:19], v[18:19], v[28:29]
	s_waitcnt lgkmcnt(2)
	v_pk_add_f32 v[20:21], v[20:21], v[50:51]
	v_pk_add_f32 v[18:19], v[18:19], v[30:31]
	s_waitcnt lgkmcnt(1)
	v_pk_add_f32 v[20:21], v[20:21], v[52:53]
	v_pk_add_f32 v[40:41], v[18:19], v[32:33]
	s_waitcnt lgkmcnt(0)
	v_pk_add_f32 v[42:43], v[20:21], v[54:55]
	ds_read2st64_b32 v[18:19], v58 offset0:4 offset1:5
	ds_read2st64_b32 v[20:21], v58 offset0:20 offset1:21
	ds_read2st64_b32 v[22:23], v58 offset0:36 offset1:37
	ds_read2st64_b32 v[24:25], v58 offset0:52 offset1:53
	ds_read2st64_b32 v[26:27], v58 offset0:68 offset1:69
	ds_read2st64_b32 v[28:29], v58 offset0:84 offset1:85
	ds_read2st64_b32 v[30:31], v58 offset0:100 offset1:101
	ds_read2st64_b32 v[32:33], v58 offset0:116 offset1:117
	ds_read2st64_b32 v[44:45], v58 offset0:6 offset1:7
	ds_read2st64_b32 v[46:47], v58 offset0:22 offset1:23
	ds_read2st64_b32 v[48:49], v58 offset0:38 offset1:39
	ds_read2st64_b32 v[50:51], v58 offset0:54 offset1:55
	ds_read2st64_b32 v[52:53], v58 offset0:70 offset1:71
	ds_read2st64_b32 v[54:55], v58 offset0:86 offset1:87
	ds_read2st64_b32 v[56:57], v58 offset0:102 offset1:103
	ds_read2st64_b32 v[60:61], v58 offset0:118 offset1:119
	s_waitcnt lgkmcnt(7)
; template <class Epi, class Pre>
; __device__ __forceinline__ void meta_gemm(const bf16_t* __restrict__ A, int lda, const bf16_t* __restrict__ Bt, int ldb, int N, int K, Epi& epi, Pre pre) {
;     ...
;           for (int j = 0; j < 4; ++j) { float s = 0.f;
; #pragma unroll
;             for (int w = 0; w < 8; ++w) s += part[(w * 16 + (bj * 2 + n) * 4 + j) * 64 + lane];
;             v[bj][n][j] = s; }
;       pre(fr, fq);
;       epi(NREAL + 16 * wid + fr, cb, fq, v[0][0], v[0][1], v[1][0], v[1][1]);
	v_pk_add_f32 v[44:45], v[44:45], 0 op_sel_hi:[1,0]
	v_pk_add_f32 v[18:19], v[18:19], 0 op_sel_hi:[1,0]
	s_lshl_b64 s[8:9], s[8:9], 2
	v_pk_add_f32 v[18:19], v[18:19], v[20:21]
	s_waitcnt lgkmcnt(6)
	v_pk_add_f32 v[20:21], v[44:45], v[46:47]
	v_pk_add_f32 v[18:19], v[18:19], v[22:23]
	s_waitcnt lgkmcnt(5)
	v_pk_add_f32 v[20:21], v[20:21], v[48:49]
	v_pk_add_f32 v[18:19], v[18:19], v[24:25]
	s_waitcnt lgkmcnt(4)
	v_pk_add_f32 v[20:21], v[20:21], v[50:51]
	v_pk_add_f32 v[18:19], v[18:19], v[26:27]
	s_waitcnt lgkmcnt(3)
	v_pk_add_f32 v[20:21], v[20:21], v[52:53]
	v_pk_add_f32 v[18:19], v[18:19], v[28:29]
	s_waitcnt lgkmcnt(2)
	v_pk_add_f32 v[20:21], v[20:21], v[54:55]
	v_pk_add_f32 v[18:19], v[18:19], v[30:31]
	s_waitcnt lgkmcnt(1)
	v_pk_add_f32 v[20:21], v[20:21], v[56:57]
	v_pk_add_f32 v[44:45], v[18:19], v[32:33]
	s_waitcnt lgkmcnt(0)
	v_pk_add_f32 v[46:47], v[20:21], v[60:61]
	ds_read2st64_b32 v[18:19], v58 offset0:8 offset1:9
	ds_read2st64_b32 v[20:21], v58 offset0:24 offset1:25
	ds_read2st64_b32 v[22:23], v58 offset0:40 offset1:41
	ds_read2st64_b32 v[24:25], v58 offset0:56 offset1:57
	ds_read2st64_b32 v[26:27], v58 offset0:72 offset1:73
	ds_read2st64_b32 v[28:29], v58 offset0:88 offset1:89
	ds_read2st64_b32 v[30:31], v58 offset0:104 offset1:105
	ds_read2st64_b32 v[32:33], v58 offset0:120 offset1:121
	ds_read2st64_b32 v[48:49], v58 offset0:10 offset1:11
	ds_read2st64_b32 v[50:51], v58 offset0:26 offset1:27
	ds_read2st64_b32 v[52:53], v58 offset0:42 offset1:43
	ds_read2st64_b32 v[54:55], v58 offset0:58 offset1:59
	ds_read2st64_b32 v[56:57], v58 offset0:74 offset1:75
	ds_read2st64_b32 v[60:61], v58 offset0:90 offset1:91
	ds_read2st64_b32 v[62:63], v58 offset0:106 offset1:107
	ds_read2st64_b32 v[64:65], v58 offset0:122 offset1:123
	s_waitcnt lgkmcnt(7)
	v_pk_add_f32 v[48:49], v[48:49], 0 op_sel_hi:[1,0]
	v_pk_add_f32 v[18:19], v[18:19], 0 op_sel_hi:[1,0]
	s_nop 0
	v_pk_add_f32 v[18:19], v[18:19], v[20:21]
	s_waitcnt lgkmcnt(6)
	v_pk_add_f32 v[20:21], v[48:49], v[50:51]
	v_pk_add_f32 v[18:19], v[18:19], v[22:23]
	s_waitcnt lgkmcnt(5)
	v_pk_add_f32 v[20:21], v[20:21], v[52:53]
	v_pk_add_f32 v[18:19], v[18:19], v[24:25]
	s_waitcnt lgkmcnt(4)
	v_pk_add_f32 v[20:21], v[20:21], v[54:55]
	v_pk_add_f32 v[18:19], v[18:19], v[26:27]
	s_waitcnt lgkmcnt(3)
	v_pk_add_f32 v[20:21], v[20:21], v[56:57]
	v_pk_add_f32 v[18:19], v[18:19], v[28:29]
	s_waitcnt lgkmcnt(2)
	v_pk_add_f32 v[20:21], v[20:21], v[60:61]
	v_pk_add_f32 v[18:19], v[18:19], v[30:31]
	s_waitcnt lgkmcnt(1)
	v_pk_add_f32 v[20:21], v[20:21], v[62:63]
	v_pk_add_f32 v[48:49], v[18:19], v[32:33]
	s_waitcnt lgkmcnt(0)
	v_pk_add_f32 v[50:51], v[20:21], v[64:65]
	ds_read2st64_b32 v[18:19], v58 offset0:12 offset1:13
	ds_read2st64_b32 v[20:21], v58 offset0:28 offset1:29
	ds_read2st64_b32 v[22:23], v58 offset0:44 offset1:45
	ds_read2st64_b32 v[24:25], v58 offset0:60 offset1:61
	ds_read2st64_b32 v[26:27], v58 offset0:76 offset1:77
	ds_read2st64_b32 v[28:29], v58 offset0:92 offset1:93
	ds_read2st64_b32 v[30:31], v58 offset0:108 offset1:109
	ds_read2st64_b32 v[32:33], v58 offset0:124 offset1:125
	ds_read2st64_b32 v[52:53], v58 offset0:14 offset1:15
	ds_read2st64_b32 v[54:55], v58 offset0:30 offset1:31
	ds_read2st64_b32 v[56:57], v58 offset0:46 offset1:47
	ds_read2st64_b32 v[60:61], v58 offset0:62 offset1:63
	ds_read2st64_b32 v[62:63], v58 offset0:78 offset1:79
	ds_read2st64_b32 v[64:65], v58 offset0:94 offset1:95
	ds_read2st64_b32 v[66:67], v58 offset0:110 offset1:111
	ds_read2st64_b32 v[68:69], v58 offset0:126 offset1:127
	s_waitcnt lgkmcnt(7)
	v_pk_add_f32 v[52:53], v[52:53], 0 op_sel_hi:[1,0]
	v_pk_add_f32 v[18:19], v[18:19], 0 op_sel_hi:[1,0]
	s_nop 0
	v_pk_add_f32 v[18:19], v[18:19], v[20:21]
	s_waitcnt lgkmcnt(6)
	v_pk_add_f32 v[20:21], v[52:53], v[54:55]
	v_pk_add_f32 v[18:19], v[18:19], v[22:23]
	s_waitcnt lgkmcnt(5)
	v_pk_add_f32 v[20:21], v[20:21], v[56:57]
	v_pk_add_f32 v[18:19], v[18:19], v[24:25]
	s_waitcnt lgkmcnt(4)
	v_pk_add_f32 v[20:21], v[20:21], v[60:61]
	v_pk_add_f32 v[18:19], v[18:19], v[26:27]
	s_waitcnt lgkmcnt(3)
	v_pk_add_f32 v[20:21], v[20:21], v[62:63]
	v_pk_add_f32 v[18:19], v[18:19], v[28:29]
	s_waitcnt lgkmcnt(2)
	v_pk_add_f32 v[20:21], v[20:21], v[64:65]
	v_pk_add_f32 v[18:19], v[18:19], v[30:31]
	s_waitcnt lgkmcnt(1)
	v_pk_add_f32 v[20:21], v[20:21], v[66:67]
	v_lshl_add_u64 v[30:31], v[38:39], 0, s[8:9]
	v_pk_add_f32 v[52:53], v[18:19], v[32:33]
	s_waitcnt lgkmcnt(0)
	v_pk_add_f32 v[54:55], v[20:21], v[68:69]
	global_load_dwordx4 v[18:21], v[30:31], off
	global_load_dwordx4 v[22:25], v[30:31], off offset:64
	global_load_dwordx4 v[26:29], v[30:31], off offset:512
	s_nop 0
	global_load_dwordx4 v[30:33], v[30:31], off offset:576
	v_lshl_add_u64 v[56:57], v[36:37], 0, s[8:9]
	s_waitcnt vmcnt(3)
	v_pk_add_f32 v[20:21], v[42:43], v[20:21]
	v_pk_add_f32 v[18:19], v[40:41], v[18:19]
	global_store_dwordx4 v[56:57], v[18:21], off sc0 sc1
	s_waitcnt vmcnt(3)
	s_nop 0
	v_pk_add_f32 v[20:21], v[46:47], v[24:25]
	v_pk_add_f32 v[18:19], v[44:45], v[22:23]
	global_store_dwordx4 v[56:57], v[18:21], off offset:64 sc0 sc1
	s_waitcnt vmcnt(3)
	s_nop 0
	v_pk_add_f32 v[20:21], v[50:51], v[28:29]
	v_pk_add_f32 v[18:19], v[48:49], v[26:27]
	global_store_dwordx4 v[56:57], v[18:21], off offset:512 sc0 sc1
	s_waitcnt vmcnt(3)
	s_nop 0
	v_pk_add_f32 v[20:21], v[54:55], v[32:33]
	v_pk_add_f32 v[18:19], v[52:53], v[30:31]
	global_store_dwordx4 v[56:57], v[18:21], off offset:576 sc0 sc1
	s_branch .LBB0_1469

;     ...
; #pragma unroll
;     for (int ai = 0; ai < 2; ++ai)
; #pragma unroll
;       for (int m = 0; m < 4; ++m)
;         epi(brow + ai * HALF + wr * 64 + m * 16 + fr, bcol + wc * 32, fq, acc[ai][0][m][0], acc[ai][0][m][1], acc[ai][1][m][0], acc[ai][1][m][1]);
;   }
.LBB0_1487:
	v_or_b32_e32 v0, s8, v140
	v_readlane_b32 s16, v253, 24
	v_add_u32_e32 v136, v0, v141
	v_readlane_b32 s17, v253, 25
	v_ashrrev_i32_e32 v137, 31, v136
	v_readlane_b32 s18, v253, 26
	v_readlane_b32 s19, v253, 27
	v_readlane_b32 s20, v253, 28
	v_readlane_b32 s21, v253, 29
	s_mov_b64 s[8:9], s[16:17]
	v_lshl_or_b32 v0, v139, 5, s90
	s_mov_b32 s6, 0x8000
	v_lshlrev_b64 v[138:139], 12, v[136:137]
	s_mov_b64 s[10:11], s[18:19]
	v_lshlrev_b32_e32 v20, 12, v140
	v_mov_b32_e32 v21, v1
	v_cmp_gt_i32_e32 vcc, s6, v136
	v_lshl_add_u64 v[18:19], s[8:9], 0, v[138:139]
	v_lshl_add_u64 v[134:135], s[10:11], 0, v[20:21]
	v_readlane_b32 s10, v253, 60
	v_cndmask_b32_e32 v19, v135, v19, vcc
	v_cndmask_b32_e32 v18, v134, v18, vcc
	v_readlane_b32 s11, v253, 61
	v_lshlrev_b64 v[132:133], 2, v[0:1]
	v_mov_b32_e32 v131, v1
	v_lshl_add_u64 v[20:21], s[10:11], 0, v[138:139]
	v_lshl_add_u64 v[18:19], v[18:19], 0, v[132:133]
	v_lshl_add_u64 v[20:21], v[20:21], 0, v[132:133]
	v_lshl_add_u64 v[148:149], v[18:19], 0, v[130:131]
	v_lshl_add_u64 v[152:153], v[20:21], 0, v[130:131]
	global_load_dwordx4 v[18:21], v[148:149], off
	global_load_dwordx4 v[140:143], v[148:149], off offset:64
	global_load_dwordx4 v[144:147], v[148:149], off offset:512
	s_nop 0
	global_load_dwordx4 v[148:151], v[148:149], off offset:576
	v_readlane_b32 s22, v253, 30
	v_readlane_b32 s23, v253, 31
	v_readlane_b32 s24, v253, 32
	v_readlane_b32 s25, v253, 33
	v_readlane_b32 s26, v253, 34
	v_readlane_b32 s27, v253, 35
	v_readlane_b32 s28, v253, 36
	v_readlane_b32 s29, v253, 37
	v_readlane_b32 s30, v253, 38
	v_readlane_b32 s31, v253, 39
	s_mov_b64 s[12:13], s[20:21]
	s_waitcnt vmcnt(0)
	v_pk_add_f32 v[20:21], v[120:121], v[20:21]
	v_pk_add_f32 v[18:19], v[118:119], v[18:19]
	global_store_dwordx4 v[152:153], v[18:21], off sc0 sc1
	s_nop 1
	v_pk_add_f32 v[20:21], v[116:117], v[142:143]
	v_pk_add_f32 v[18:19], v[114:115], v[140:141]
	global_store_dwordx4 v[152:153], v[18:21], off offset:64 sc0 sc1
	s_nop 1
	v_pk_add_f32 v[20:21], v[128:129], v[146:147]
	v_pk_add_f32 v[18:19], v[126:127], v[144:145]
	global_store_dwordx4 v[152:153], v[18:21], off offset:512 sc0 sc1
	s_nop 1
	v_pk_add_f32 v[20:21], v[124:125], v[150:151]
	v_pk_add_f32 v[18:19], v[122:123], v[148:149]
	global_store_dwordx4 v[152:153], v[18:21], off offset:576 sc0 sc1
	s_nop 1
	v_or_b32_e32 v18, 16, v136
	v_ashrrev_i32_e32 v19, 31, v18
	v_cmp_gt_i32_e32 vcc, s6, v18
	v_lshlrev_b64 v[18:19], 12, v[18:19]
	v_lshl_add_u64 v[20:21], s[8:9], 0, v[18:19]
	v_lshl_add_u64 v[18:19], s[10:11], 0, v[18:19]
	v_cndmask_b32_e32 v21, v135, v21, vcc
	v_cndmask_b32_e32 v20, v134, v20, vcc
	v_lshl_add_u64 v[18:19], v[18:19], 0, v[132:133]
	v_lshl_add_u64 v[126:127], v[18:19], 0, v[130:131]
	v_lshl_add_u64 v[18:19], v[20:21], 0, v[132:133]
	v_lshl_add_u64 v[122:123], v[18:19], 0, v[130:131]
	global_load_dwordx4 v[18:21], v[122:123], off
	global_load_dwordx4 v[114:117], v[122:123], off offset:64
	global_load_dwordx4 v[118:121], v[122:123], off offset:512
	s_nop 0
	global_load_dwordx4 v[122:125], v[122:123], off offset:576
	s_waitcnt vmcnt(0)
	v_pk_add_f32 v[20:21], v[104:105], v[20:21]
	v_pk_add_f32 v[18:19], v[102:103], v[18:19]
	global_store_dwordx4 v[126:127], v[18:21], off sc0 sc1
	s_nop 1
	v_pk_add_f32 v[20:21], v[100:101], v[116:117]
	v_pk_add_f32 v[18:19], v[98:99], v[114:115]
	global_store_dwordx4 v[126:127], v[18:21], off offset:64 sc0 sc1
	s_nop 1
	v_pk_add_f32 v[20:21], v[112:113], v[120:121]
	v_pk_add_f32 v[18:19], v[110:111], v[118:119]
	global_store_dwordx4 v[126:127], v[18:21], off offset:512 sc0 sc1
	s_nop 1
	v_pk_add_f32 v[20:21], v[108:109], v[124:125]
	v_pk_add_f32 v[18:19], v[106:107], v[122:123]
	global_store_dwordx4 v[126:127], v[18:21], off offset:576 sc0 sc1
	s_nop 1
	v_or_b32_e32 v18, 32, v136
	v_ashrrev_i32_e32 v19, 31, v18
	v_cmp_gt_i32_e32 vcc, s6, v18
	v_lshlrev_b64 v[18:19], 12, v[18:19]
	v_lshl_add_u64 v[20:21], s[8:9], 0, v[18:19]
	v_lshl_add_u64 v[18:19], s[10:11], 0, v[18:19]
	v_cndmask_b32_e32 v21, v135, v21, vcc
	v_cndmask_b32_e32 v20, v134, v20, vcc
	v_lshl_add_u64 v[18:19], v[18:19], 0, v[132:133]
	v_lshl_add_u64 v[110:111], v[18:19], 0, v[130:131]
	v_lshl_add_u64 v[18:19], v[20:21], 0, v[132:133]
	v_lshl_add_u64 v[106:107], v[18:19], 0, v[130:131]
	global_load_dwordx4 v[18:21], v[106:107], off
	global_load_dwordx4 v[98:101], v[106:107], off offset:64
	global_load_dwordx4 v[102:105], v[106:107], off offset:512
	s_nop 0
	global_load_dwordx4 v[106:109], v[106:107], off offset:576
	s_waitcnt vmcnt(0)
	v_pk_add_f32 v[20:21], v[88:89], v[20:21]
	v_pk_add_f32 v[18:19], v[86:87], v[18:19]
	global_store_dwordx4 v[110:111], v[18:21], off sc0 sc1
	s_nop 1
	v_pk_add_f32 v[20:21], v[84:85], v[100:101]
	v_pk_add_f32 v[18:19], v[82:83], v[98:99]
	global_store_dwordx4 v[110:111], v[18:21], off offset:64 sc0 sc1
	s_nop 1
	v_pk_add_f32 v[20:21], v[96:97], v[104:105]
	v_pk_add_f32 v[18:19], v[94:95], v[102:103]
	global_store_dwordx4 v[110:111], v[18:21], off offset:512 sc0 sc1
	s_nop 1
	v_pk_add_f32 v[20:21], v[92:93], v[108:109]
	v_pk_add_f32 v[18:19], v[90:91], v[106:107]
	global_store_dwordx4 v[110:111], v[18:21], off offset:576 sc0 sc1
	s_nop 1
	v_or_b32_e32 v18, 48, v136
	v_ashrrev_i32_e32 v19, 31, v18
	v_cmp_gt_i32_e32 vcc, s6, v18
	v_lshlrev_b64 v[18:19], 12, v[18:19]
	v_lshl_add_u64 v[20:21], s[8:9], 0, v[18:19]
	v_lshl_add_u64 v[18:19], s[10:11], 0, v[18:19]
	v_cndmask_b32_e32 v21, v135, v21, vcc
	v_cndmask_b32_e32 v20, v134, v20, vcc
	v_lshl_add_u64 v[18:19], v[18:19], 0, v[132:133]
	v_lshl_add_u64 v[94:95], v[18:19], 0, v[130:131]
	v_lshl_add_u64 v[18:19], v[20:21], 0, v[132:133]
	v_lshl_add_u64 v[90:91], v[18:19], 0, v[130:131]
	global_load_dwordx4 v[18:21], v[90:91], off
	global_load_dwordx4 v[82:85], v[90:91], off offset:64
	global_load_dwordx4 v[86:89], v[90:91], off offset:512
	s_nop 0
	global_load_dwordx4 v[90:93], v[90:91], off offset:576
	s_mov_b64 s[6:7], 0x80000
	s_waitcnt vmcnt(0)
; #define WAIT_V(n) asm volatile("s_waitcnt vmcnt(" #n ")" ::: "memory")
;     ...
; #pragma unroll
;     for (int ai = 0; ai < 2; ++ai)
; #pragma unroll
;       for (int m = 0; m < 4; ++m)
;         epi(brow + ai * HALF + wr * 64 + m * 16 + fr, bcol + wc * 32, fq, acc[ai][0][m][0], acc[ai][0][m][1], acc[ai][1][m][0], acc[ai][1][m][1]);
;   }
;   if (!have_next) { WAIT_V(0); __syncthreads(); }
	v_pk_add_f32 v[20:21], v[72:73], v[20:21]
	v_pk_add_f32 v[18:19], v[70:71], v[18:19]
	global_store_dwordx4 v[94:95], v[18:21], off sc0 sc1
	s_nop 1
	v_pk_add_f32 v[20:21], v[68:69], v[84:85]
	v_pk_add_f32 v[18:19], v[66:67], v[82:83]
	global_store_dwordx4 v[94:95], v[18:21], off offset:64 sc0 sc1
	s_nop 1
	v_pk_add_f32 v[20:21], v[80:81], v[88:89]
	v_pk_add_f32 v[18:19], v[78:79], v[86:87]
	global_store_dwordx4 v[94:95], v[18:21], off offset:512 sc0 sc1
	s_nop 1
	v_pk_add_f32 v[20:21], v[76:77], v[92:93]
	v_pk_add_f32 v[18:19], v[74:75], v[90:91]
	global_store_dwordx4 v[94:95], v[18:21], off offset:576 sc0 sc1
	s_nop 1
	v_lshl_add_u64 v[18:19], v[138:139], 0, s[6:7]
	s_movk_i32 s6, 0x7f80
	v_cmp_gt_i32_e32 vcc, s6, v136
	v_lshl_add_u64 v[20:21], s[8:9], 0, v[18:19]
	v_lshl_add_u64 v[18:19], s[10:11], 0, v[18:19]
	v_cndmask_b32_e32 v21, v135, v21, vcc
	v_cndmask_b32_e32 v20, v134, v20, vcc
	v_lshl_add_u64 v[18:19], v[18:19], 0, v[132:133]
	v_lshl_add_u64 v[78:79], v[18:19], 0, v[130:131]
	v_lshl_add_u64 v[18:19], v[20:21], 0, v[132:133]
	v_lshl_add_u64 v[74:75], v[18:19], 0, v[130:131]
	global_load_dwordx4 v[18:21], v[74:75], off
	global_load_dwordx4 v[66:69], v[74:75], off offset:64
	global_load_dwordx4 v[70:73], v[74:75], off offset:512
	s_nop 0
	global_load_dwordx4 v[74:77], v[74:75], off offset:576
	s_mov_b64 s[6:7], 0x90000
	s_waitcnt vmcnt(0)
	v_pk_add_f32 v[20:21], v[56:57], v[20:21]
	v_pk_add_f32 v[18:19], v[54:55], v[18:19]
	global_store_dwordx4 v[78:79], v[18:21], off sc0 sc1
	s_nop 1
	v_pk_add_f32 v[20:21], v[52:53], v[68:69]
	v_pk_add_f32 v[18:19], v[50:51], v[66:67]
	global_store_dwordx4 v[78:79], v[18:21], off offset:64 sc0 sc1
	s_nop 1
	v_pk_add_f32 v[20:21], v[64:65], v[72:73]
	v_pk_add_f32 v[18:19], v[62:63], v[70:71]
	global_store_dwordx4 v[78:79], v[18:21], off offset:512 sc0 sc1
	s_nop 1
	v_pk_add_f32 v[20:21], v[60:61], v[76:77]
	v_pk_add_f32 v[18:19], v[58:59], v[74:75]
	global_store_dwordx4 v[78:79], v[18:21], off offset:576 sc0 sc1
	s_nop 1
	v_lshl_add_u64 v[18:19], v[138:139], 0, s[6:7]
	s_movk_i32 s6, 0x7f70
	v_cmp_gt_i32_e32 vcc, s6, v136
	v_lshl_add_u64 v[20:21], s[8:9], 0, v[18:19]
	v_lshl_add_u64 v[18:19], s[10:11], 0, v[18:19]
	v_cndmask_b32_e32 v21, v135, v21, vcc
	v_cndmask_b32_e32 v20, v134, v20, vcc
	v_lshl_add_u64 v[18:19], v[18:19], 0, v[132:133]
	v_lshl_add_u64 v[62:63], v[18:19], 0, v[130:131]
	v_lshl_add_u64 v[18:19], v[20:21], 0, v[132:133]
	v_lshl_add_u64 v[58:59], v[18:19], 0, v[130:131]
	global_load_dwordx4 v[18:21], v[58:59], off
	global_load_dwordx4 v[50:53], v[58:59], off offset:64
	global_load_dwordx4 v[54:57], v[58:59], off offset:512
	s_nop 0
	global_load_dwordx4 v[58:61], v[58:59], off offset:576
	s_mov_b64 s[6:7], 0xa0000
	s_waitcnt vmcnt(0)
	v_pk_add_f32 v[20:21], v[40:41], v[20:21]
	v_pk_add_f32 v[18:19], v[38:39], v[18:19]
	global_store_dwordx4 v[62:63], v[18:21], off sc0 sc1
	s_nop 1
	v_pk_add_f32 v[20:21], v[36:37], v[52:53]
	v_pk_add_f32 v[18:19], v[34:35], v[50:51]
	global_store_dwordx4 v[62:63], v[18:21], off offset:64 sc0 sc1
	s_nop 1
	v_pk_add_f32 v[20:21], v[48:49], v[56:57]
	v_pk_add_f32 v[18:19], v[46:47], v[54:55]
	global_store_dwordx4 v[62:63], v[18:21], off offset:512 sc0 sc1
	s_nop 1
	v_pk_add_f32 v[20:21], v[44:45], v[60:61]
	v_pk_add_f32 v[18:19], v[42:43], v[58:59]
	global_store_dwordx4 v[62:63], v[18:21], off offset:576 sc0 sc1
	s_nop 1
	v_lshl_add_u64 v[18:19], v[138:139], 0, s[6:7]
	s_movk_i32 s6, 0x7f60
	v_cmp_gt_i32_e32 vcc, s6, v136
	v_lshl_add_u64 v[20:21], s[8:9], 0, v[18:19]
	v_lshl_add_u64 v[18:19], s[10:11], 0, v[18:19]
	v_cndmask_b32_e32 v21, v135, v21, vcc
	v_cndmask_b32_e32 v20, v134, v20, vcc
	v_lshl_add_u64 v[18:19], v[18:19], 0, v[132:133]
	v_lshl_add_u64 v[46:47], v[18:19], 0, v[130:131]
	v_lshl_add_u64 v[18:19], v[20:21], 0, v[132:133]
	v_lshl_add_u64 v[42:43], v[18:19], 0, v[130:131]
	global_load_dwordx4 v[18:21], v[42:43], off
	global_load_dwordx4 v[34:37], v[42:43], off offset:64
	global_load_dwordx4 v[38:41], v[42:43], off offset:512
	s_nop 0
	global_load_dwordx4 v[42:45], v[42:43], off offset:576
	s_mov_b64 s[6:7], 0xb0000
	s_waitcnt vmcnt(0)
	v_pk_add_f32 v[20:21], v[24:25], v[20:21]
	v_pk_add_f32 v[18:19], v[22:23], v[18:19]
	global_store_dwordx4 v[46:47], v[18:21], off sc0 sc1
	s_nop 1
	v_pk_add_f32 v[20:21], v[222:223], v[36:37]
	v_pk_add_f32 v[18:19], v[220:221], v[34:35]
	global_store_dwordx4 v[46:47], v[18:21], off offset:64 sc0 sc1
	s_nop 1
	v_pk_add_f32 v[20:21], v[32:33], v[40:41]
	v_pk_add_f32 v[18:19], v[30:31], v[38:39]
	global_store_dwordx4 v[46:47], v[18:21], off offset:512 sc0 sc1
	s_nop 1
	v_pk_add_f32 v[20:21], v[28:29], v[44:45]
	v_pk_add_f32 v[18:19], v[26:27], v[42:43]
	global_store_dwordx4 v[46:47], v[18:21], off offset:576 sc0 sc1
	s_nop 1
	v_lshl_add_u64 v[18:19], v[138:139], 0, s[6:7]
	s_movk_i32 s6, 0x7f50
	v_cmp_gt_i32_e32 vcc, s6, v136
	v_lshl_add_u64 v[20:21], s[8:9], 0, v[18:19]
	v_lshl_add_u64 v[18:19], s[10:11], 0, v[18:19]
	v_cndmask_b32_e32 v21, v135, v21, vcc
	v_cndmask_b32_e32 v20, v134, v20, vcc
	v_lshl_add_u64 v[18:19], v[18:19], 0, v[132:133]
	v_lshl_add_u64 v[34:35], v[18:19], 0, v[130:131]
	v_lshl_add_u64 v[18:19], v[20:21], 0, v[132:133]
	v_lshl_add_u64 v[30:31], v[18:19], 0, v[130:131]
	global_load_dwordx4 v[18:21], v[30:31], off
	global_load_dwordx4 v[22:25], v[30:31], off offset:64
	global_load_dwordx4 v[26:29], v[30:31], off offset:512
	s_nop 0
	global_load_dwordx4 v[30:33], v[30:31], off offset:576
	s_andn2_b64 vcc, exec, s[4:5]
	s_waitcnt vmcnt(0)
	v_pk_add_f32 v[8:9], v[8:9], v[20:21]
	v_pk_add_f32 v[4:5], v[4:5], v[24:25]
	v_pk_add_f32 v[2:3], v[2:3], v[22:23]
	global_store_dwordx4 v[34:35], v[2:5], off offset:64 sc0 sc1
	v_pk_add_f32 v[6:7], v[6:7], v[18:19]
	global_store_dwordx4 v[34:35], v[6:9], off sc0 sc1
	v_pk_add_f32 v[4:5], v[16:17], v[28:29]
	v_pk_add_f32 v[2:3], v[14:15], v[26:27]
	global_store_dwordx4 v[34:35], v[2:5], off offset:512 sc0 sc1
	s_nop 1
	v_pk_add_f32 v[4:5], v[12:13], v[32:33]
	v_pk_add_f32 v[2:3], v[10:11], v[30:31]
	global_store_dwordx4 v[34:35], v[2:5], off offset:576 sc0 sc1
	s_cbranch_vccnz .LBB0_1474
	s_waitcnt vmcnt(0)
	s_waitcnt lgkmcnt(0)
	s_barrier
	s_branch .LBB0_1474
; __global__ void __launch_bounds__(512) mega(Params P) {
;     ...
;     grid.sync();
.LBB0_1489:
	s_waitcnt lgkmcnt(0)
	s_barrier
	s_mov_b64 s[4:5], exec
	v_readlane_b32 s0, v253, 57
	v_readlane_b32 s1, v253, 58
	s_and_b64 s[0:1], s[4:5], s[0:1]
	s_mov_b64 exec, s[0:1]
	s_cbranch_execz .LBB0_1499
	buffer_wbl2 sc1
	s_load_dwordx2 s[6:7], s[56:57], -0x8
	s_load_dword s0, s[56:57], 0x0
	v_readlane_b32 s1, v253, 55
	s_waitcnt lgkmcnt(0)
	s_and_b32 s1, s1, 7
	s_add_i32 s8, s0, 7
	s_sub_i32 s8, s8, s1
	s_lshr_b32 s8, s8, 3
	s_min_u32 s9, s0, 8
	s_lshl_b32 s1, s1, 2
	s_addk_i32 s1, 0x88
	v_mov_b32_e32 v2, s1
	global_load_dword v0, v1, s[6:7] sc1
	v_mov_b32_e32 v3, 1
	s_waitcnt vmcnt(0)
	v_and_b32_e32 v0, 0xffff0000, v0
	global_atomic_add v3, v2, v3, s[6:7] sc0
	s_waitcnt vmcnt(0)
	v_and_b32_e32 v3, 0xffff, v3
	s_nop 0
	v_readfirstlane_b32 s1, v3
	s_nop 3
	s_add_i32 s0, s8, -1
	s_cmp_lg_u32 s1, s0
	s_cbranch_scc1 .Lgb_poll_4
	s_sub_i32 s1, 0x10000, s8
	v_mov_b32_e32 v3, s1
	global_atomic_add v3, v2, v3, s[6:7] sc0
	s_waitcnt vmcnt(0)
	v_mov_b32_e32 v3, 1
	global_atomic_add v3, v1, v3, s[6:7] sc0
	s_waitcnt vmcnt(0)
	v_and_b32_e32 v3, 0xffff, v3
	s_nop 0
	v_readfirstlane_b32 s1, v3
	s_nop 3
	s_add_i32 s0, s9, -1
	s_cmp_lg_u32 s1, s0
	s_cbranch_scc1 .Lgb_poll_4
	s_sub_i32 s1, 0x10000, s9
	v_mov_b32_e32 v3, s1
	global_atomic_add v1, v3, s[6:7]

; __device__ __forceinline__ void norm_phase(const float* H, const float* g, bf16_t* HN) {
;     ...
;   for (int row = gw; row < NREAL + 64; row += 2 * nw) {
;     const int row2 = row + nw < NREAL + 64 ? row + nw : row;
;     const float* p = H + (size_t)row * DM + lane * 8; const float* p2 = H + (size_t)row2 * DM + lane * 8; f32x4 v[4], u[4]; float ss = 0.f, ss2 = 0.f;
; #pragma unroll
;     for (int i = 0; i < 4; ++i) { v[i] = *(const f32x4*)(p + 512 * (i >> 1) + 4 * (i & 1)); u[i] = *(const f32x4*)(p2 + 512 * (i >> 1) + 4 * (i & 1)); }
; #pragma unroll
;     for (int i = 0; i < 4; ++i) { ss += v[i][0] * v[i][0] + v[i][1] * v[i][1] + v[i][2] * v[i][2] + v[i][3] * v[i][3]; ss2 += u[i][0] * u[i][0] + u[i][1] * u[i][1] + u[i][2] * u[i][2] + u[i][3] * u[i][3]; }
;     ss = wave_sum(ss); ss2 = wave_sum(ss2); const float rs = rsqrtf(ss * (1.0f / 1024.0f) + 1e-6f), rs2 = rsqrtf(ss2 * (1.0f / 1024.0f) + 1e-6f);
.LBB0_1501:
	v_add_u32_e32 v0, s24, v54
	v_cmp_gt_i32_e32 vcc, s49, v0
	v_ashrrev_i32_e32 v55, 31, v54
	v_lshlrev_b64 v[18:19], 12, v[54:55]
	v_cndmask_b32_e32 v56, v54, v0, vcc
	v_ashrrev_i32_e32 v57, 31, v56
	v_lshlrev_b64 v[20:21], 12, v[56:57]
	v_lshl_add_u64 v[18:19], v[50:51], 0, v[18:19]
	v_lshl_add_u64 v[20:21], v[50:51], 0, v[20:21]
	global_load_dwordx4 v[46:49], v[18:19], off
	global_load_dwordx4 v[42:45], v[18:19], off offset:16
	global_load_dwordx4 v[38:41], v[20:21], off
	global_load_dwordx4 v[34:37], v[20:21], off offset:16
	global_load_dwordx4 v[30:33], v[18:19], off offset:2048
	global_load_dwordx4 v[26:29], v[18:19], off offset:2064
	global_load_dwordx4 v[22:25], v[20:21], off offset:2048
	s_nop 0
	global_load_dwordx4 v[18:21], v[20:21], off offset:2064
	v_lshlrev_b64 v[54:55], 11, v[54:55]
	v_lshl_add_u64 v[54:55], v[52:53], 0, v[54:55]
	v_lshlrev_b64 v[56:57], 11, v[56:57]
	v_lshl_add_u64 v[56:57], v[52:53], 0, v[56:57]
	s_waitcnt vmcnt(7)
	v_mov_b32_e32 v60, v47
	s_waitcnt vmcnt(6)
	v_mov_b32_e32 v61, v43
	v_mov_b32_e32 v58, v46
	v_mov_b32_e32 v59, v42
	v_pk_mul_f32 v[60:61], v[60:61], v[60:61]
	s_waitcnt vmcnt(5)
	v_mov_b32_e32 v62, v39
	v_pk_fma_f32 v[58:59], v[58:59], v[58:59], v[60:61]
	v_mov_b32_e32 v60, v48
	v_mov_b32_e32 v61, v44
	v_pk_fma_f32 v[58:59], v[60:61], v[60:61], v[58:59]
	v_mov_b32_e32 v60, v49
	v_mov_b32_e32 v61, v45
	s_waitcnt vmcnt(4)
	v_mov_b32_e32 v63, v35
	v_pk_fma_f32 v[58:59], v[60:61], v[60:61], v[58:59]
	v_mov_b32_e32 v60, v38
	v_mov_b32_e32 v61, v34
	v_pk_mul_f32 v[62:63], v[62:63], v[62:63]
	s_waitcnt vmcnt(3)
	v_mov_b32_e32 v64, v31
	v_pk_fma_f32 v[60:61], v[60:61], v[60:61], v[62:63]
	v_mov_b32_e32 v62, v40
	v_mov_b32_e32 v63, v36
	v_pk_fma_f32 v[60:61], v[62:63], v[62:63], v[60:61]
	v_mov_b32_e32 v62, v41
	v_mov_b32_e32 v63, v37
	s_waitcnt vmcnt(2)
	v_mov_b32_e32 v65, v27
	v_pk_fma_f32 v[60:61], v[62:63], v[62:63], v[60:61]
	v_mov_b32_e32 v62, v30
	v_mov_b32_e32 v63, v26
	v_pk_mul_f32 v[64:65], v[64:65], v[64:65]
	s_waitcnt vmcnt(1)
	v_mov_b32_e32 v66, v23
	v_pk_fma_f32 v[62:63], v[62:63], v[62:63], v[64:65]
	v_mov_b32_e32 v64, v32
	v_mov_b32_e32 v65, v28
	v_pk_fma_f32 v[62:63], v[64:65], v[64:65], v[62:63]
	v_mov_b32_e32 v64, v33
	v_mov_b32_e32 v65, v29
	s_waitcnt vmcnt(0)
	v_mov_b32_e32 v67, v19
	v_pk_fma_f32 v[62:63], v[64:65], v[64:65], v[62:63]
	v_mov_b32_e32 v64, v22
	v_mov_b32_e32 v65, v18
	v_pk_mul_f32 v[66:67], v[66:67], v[66:67]
	s_nop 0
	v_pk_fma_f32 v[64:65], v[64:65], v[64:65], v[66:67]
	v_mov_b32_e32 v66, v24
	v_mov_b32_e32 v67, v20
	v_pk_fma_f32 v[64:65], v[66:67], v[66:67], v[64:65]
	v_mov_b32_e32 v66, v25
	v_mov_b32_e32 v67, v21
	v_pk_fma_f32 v[64:65], v[66:67], v[66:67], v[64:65]
	v_mov_b32_e32 v66, v210
	v_mov_b32_e32 v67, v58
	v_lshlrev_b32_e32 v66, 2, v66
	v_xor_b32_e32 v68, 0x80, v66
	v_mov_b32_e32 v66, v210
	v_mov_b32_e32 v58, v61
	v_lshlrev_b32_e32 v66, 2, v66
	v_xor_b32_e32 v69, 0x80, v66
	v_mov_b32_e32 v66, v60
	v_pk_add_f32 v[58:59], v[66:67], v[58:59]
	v_mov_b32_e32 v60, v64
	v_mov_b32_e32 v61, v62
	v_pk_add_f32 v[58:59], v[58:59], v[60:61]
	v_mov_b32_e32 v62, v65
	v_pk_add_f32 v[58:59], v[58:59], v[62:63]
	ds_swizzle_b32 v61, v59 offset:swizzle(SWAP,16)
	ds_swizzle_b32 v60, v58 offset:swizzle(SWAP,16)
	s_waitcnt lgkmcnt(0)
	v_pk_add_f32 v[58:59], v[58:59], v[60:61]
	ds_swizzle_b32 v61, v59 offset:swizzle(SWAP,8)
	ds_swizzle_b32 v60, v58 offset:swizzle(SWAP,8)
	s_waitcnt lgkmcnt(0)
	v_pk_add_f32 v[58:59], v[58:59], v[60:61]
	ds_swizzle_b32 v61, v59 offset:swizzle(SWAP,4)
	ds_swizzle_b32 v60, v58 offset:swizzle(SWAP,4)
	s_waitcnt lgkmcnt(0)
	v_pk_add_f32 v[58:59], v[58:59], v[60:61]
	ds_swizzle_b32 v61, v59 offset:swizzle(SWAP,2)
	ds_swizzle_b32 v60, v58 offset:swizzle(SWAP,2)
	s_waitcnt lgkmcnt(0)
	v_pk_add_f32 v[58:59], v[58:59], v[60:61]
	ds_swizzle_b32 v61, v59 offset:swizzle(SWAP,1)
	ds_swizzle_b32 v60, v58 offset:swizzle(SWAP,1)
	s_waitcnt lgkmcnt(0)
	v_pk_add_f32 v[58:59], v[58:59], v[60:61]
	ds_bpermute_b32 v61, v68, v59
	ds_bpermute_b32 v60, v69, v58
	s_waitcnt lgkmcnt(0)
; __device__ __forceinline__ void store8bf(bf16_t* p, f32x4 v0, f32x4 v1) { u32x4 w; w.x = cvt_pk_bf16(v0[0], v0[1]); w.y = cvt_pk_bf16(v0[2], v0[3]); w.z = cvt_pk_bf16(v1[0], v1[1]); w.w = cvt_pk_bf16(v1[2], v1[3]); *(u32x4*)p = w; }
; __device__ __forceinline__ void norm_phase(const float* H, const float* g, bf16_t* HN) {
;     ...
;     ss = wave_sum(ss); ss2 = wave_sum(ss2); const float rs = rsqrtf(ss * (1.0f / 1024.0f) + 1e-6f), rs2 = rsqrtf(ss2 * (1.0f / 1024.0f) + 1e-6f);
;     bf16_t* q = HN + (size_t)row * DM + lane * 8; bf16_t* q2 = HN + (size_t)row2 * DM + lane * 8;
; #pragma unroll
;     for (int i = 0; i < 2; ++i) { store8bf(q + 512 * i, v[2 * i] * rs * gv[2 * i], v[2 * i + 1] * rs * gv[2 * i + 1]); store8bf(q2 + 512 * i, u[2 * i] * rs2 * gv[2 * i], u[2 * i + 1] * rs2 * gv[2 * i + 1]); }
; __global__ void __launch_bounds__(512) mega(Params P) {
;     ...
;     grid.sync();
	v_pk_add_f32 v[58:59], v[58:59], v[60:61]
	s_nop 0
	v_pk_fma_f32 v[58:59], v[58:59], s[58:59], v[154:155] op_sel_hi:[1,0,0]
	s_nop 0
	v_mul_f32_e32 v60, 0x4b800000, v59
	v_cmp_gt_f32_e64 s[4:5], s46, v59
	v_cmp_gt_f32_e32 vcc, s46, v58
	s_nop 0
	v_cndmask_b32_e64 v59, v59, v60, s[4:5]
	v_rsq_f32_e32 v59, v59
	s_nop 0
	v_mul_f32_e32 v60, 0x45800000, v59
	v_cndmask_b32_e64 v60, v59, v60, s[4:5]
	v_mul_f32_e32 v59, 0x4b800000, v58
	v_cndmask_b32_e32 v58, v58, v59, vcc
	v_rsq_f32_e32 v58, v58
	v_pk_mul_f32 v[46:47], v[46:47], v[60:61] op_sel_hi:[1,0]
	v_pk_mul_f32 v[48:49], v[48:49], v[60:61] op_sel_hi:[1,0]
	v_pk_mul_f32 v[42:43], v[42:43], v[60:61] op_sel_hi:[1,0]
	v_mul_f32_e32 v59, 0x45800000, v58
	v_pk_mul_f32 v[44:45], v[44:45], v[60:61] op_sel_hi:[1,0]
	v_cndmask_b32_e32 v58, v58, v59, vcc
	v_pk_mul_f32 v[48:49], v[8:9], v[48:49]
	v_pk_mul_f32 v[46:47], v[6:7], v[46:47]
	v_pk_mul_f32 v[62:63], v[4:5], v[44:45]
	v_pk_mul_f32 v[44:45], v[2:3], v[42:43]
	v_cvt_pk_bf16_f32 v42, v46, v47
	v_cvt_pk_bf16_f32 v43, v48, v49
	v_cvt_pk_bf16_f32 v44, v44, v45
	v_cvt_pk_bf16_f32 v45, v62, v63
	v_pk_mul_f32 v[38:39], v[38:39], v[58:59] op_sel_hi:[1,0]
	v_pk_mul_f32 v[40:41], v[40:41], v[58:59] op_sel_hi:[1,0]
	v_pk_mul_f32 v[34:35], v[34:35], v[58:59] op_sel_hi:[1,0]
	v_pk_mul_f32 v[36:37], v[36:37], v[58:59] op_sel_hi:[1,0]
	global_store_dwordx4 v[54:55], v[42:45], off sc0 sc1
	v_pk_mul_f32 v[40:41], v[8:9], v[40:41]
	v_pk_mul_f32 v[38:39], v[6:7], v[38:39]
	v_pk_mul_f32 v[42:43], v[4:5], v[36:37]
	v_pk_mul_f32 v[36:37], v[2:3], v[34:35]
	v_cvt_pk_bf16_f32 v34, v38, v39
	v_cvt_pk_bf16_f32 v35, v40, v41
	v_cvt_pk_bf16_f32 v36, v36, v37
	v_cvt_pk_bf16_f32 v37, v42, v43
	v_pk_mul_f32 v[30:31], v[30:31], v[60:61] op_sel_hi:[1,0]
	v_pk_mul_f32 v[32:33], v[32:33], v[60:61] op_sel_hi:[1,0]
	v_pk_mul_f32 v[26:27], v[26:27], v[60:61] op_sel_hi:[1,0]
	v_pk_mul_f32 v[28:29], v[28:29], v[60:61] op_sel_hi:[1,0]
	global_store_dwordx4 v[56:57], v[34:37], off sc0 sc1
	v_pk_mul_f32 v[32:33], v[16:17], v[32:33]
	v_pk_mul_f32 v[30:31], v[14:15], v[30:31]
	v_pk_mul_f32 v[34:35], v[12:13], v[28:29]
	v_pk_mul_f32 v[28:29], v[10:11], v[26:27]
	v_cvt_pk_bf16_f32 v26, v30, v31
	v_cvt_pk_bf16_f32 v27, v32, v33
	v_cvt_pk_bf16_f32 v28, v28, v29
	v_cvt_pk_bf16_f32 v29, v34, v35
	global_store_dwordx4 v[54:55], v[26:29], off offset:1024 sc0 sc1
	v_pk_mul_f32 v[22:23], v[22:23], v[58:59] op_sel_hi:[1,0]
	v_pk_mul_f32 v[24:25], v[24:25], v[58:59] op_sel_hi:[1,0]
	v_pk_mul_f32 v[18:19], v[18:19], v[58:59] op_sel_hi:[1,0]
	v_pk_mul_f32 v[20:21], v[20:21], v[58:59] op_sel_hi:[1,0]
	v_add_u32_e32 v54, s24, v0
	v_pk_mul_f32 v[24:25], v[16:17], v[24:25]
	v_pk_mul_f32 v[22:23], v[14:15], v[22:23]
	v_pk_mul_f32 v[26:27], v[12:13], v[20:21]
	v_pk_mul_f32 v[20:21], v[10:11], v[18:19]
	v_cmp_lt_i32_e32 vcc, s50, v54
	v_cvt_pk_bf16_f32 v18, v22, v23
	v_cvt_pk_bf16_f32 v19, v24, v25
	v_cvt_pk_bf16_f32 v20, v20, v21
	v_cvt_pk_bf16_f32 v21, v26, v27
	s_or_b64 s[8:9], vcc, s[8:9]
	global_store_dwordx4 v[56:57], v[18:21], off offset:1024 sc0 sc1
	s_andn2_b64 exec, exec, s[8:9]
	s_cbranch_execnz .LBB0_1501
.LBB0_1502:
	s_or_b64 exec, exec, s[6:7]
	s_barrier
	s_mov_b64 s[4:5], exec
	v_readlane_b32 s0, v253, 57
	v_readlane_b32 s1, v253, 58
	s_and_b64 s[0:1], s[4:5], s[0:1]
	s_mov_b64 exec, s[0:1]
	s_cbranch_execz .LBB0_1512
	buffer_wbl2 sc1
	s_load_dwordx2 s[6:7], s[56:57], -0x8
	s_load_dword s0, s[56:57], 0x0
	v_readlane_b32 s1, v253, 55
	s_waitcnt lgkmcnt(0)
	s_and_b32 s1, s1, 7
	s_add_i32 s8, s0, 7
	s_sub_i32 s8, s8, s1
	s_lshr_b32 s8, s8, 3
	s_min_u32 s9, s0, 8
	s_lshl_b32 s1, s1, 2
	s_addk_i32 s1, 0x88
	v_mov_b32_e32 v2, s1
	global_load_dword v0, v1, s[6:7] sc1
	v_mov_b32_e32 v3, 1
	s_waitcnt vmcnt(0)
	v_and_b32_e32 v0, 0xffff0000, v0
	global_atomic_add v3, v2, v3, s[6:7] sc0
	s_waitcnt vmcnt(0)
	v_and_b32_e32 v3, 0xffff, v3
	s_nop 0
	v_readfirstlane_b32 s1, v3
	s_nop 3
	s_add_i32 s0, s8, -1
	s_cmp_lg_u32 s1, s0
	s_cbranch_scc1 .Lgb_poll_5
	s_sub_i32 s1, 0x10000, s8
	v_mov_b32_e32 v3, s1
	global_atomic_add v3, v2, v3, s[6:7] sc0
	s_waitcnt vmcnt(0)
	v_mov_b32_e32 v3, 1
	global_atomic_add v3, v1, v3, s[6:7] sc0
	s_waitcnt vmcnt(0)
	v_and_b32_e32 v3, 0xffff, v3
	s_nop 0
	v_readfirstlane_b32 s1, v3
	s_nop 3
	s_add_i32 s0, s9, -1
	s_cmp_lg_u32 s1, s0
	s_cbranch_scc1 .Lgb_poll_5
	s_sub_i32 s1, 0x10000, s9
	v_mov_b32_e32 v3, s1
	global_atomic_add v1, v3, s[6:7]

; template <class Epi, class Pre>
; __device__ __forceinline__ void meta_gemm(const bf16_t* __restrict__ A, int lda, const bf16_t* __restrict__ Bt, int ldb, int N, int K, Epi& epi, Pre pre) {
;     ...
;     const bf16_t* ap = A + (size_t)(NREAL + fr) * lda + wid * ks + fq * 8;
;     const bf16_t* bp = Bt + (size_t)(cb + fr) * ldb + wid * ks + fq * 8;
; #pragma unroll 4
;     for (int k0 = 0; k0 < ks; k0 += 32) {
;       const bf16x8 a = *(const bf16x8*)(ap + k0);
; #pragma unroll
;       for (int bj = 0; bj < 2; ++bj)
; #pragma unroll
;         for (int n = 0; n < 2; ++n) { const bf16x8 b = *(const bf16x8*)(bp + (size_t)(bj * 128 + n * 16) * ldb + k0); acc[bj][n] = __builtin_amdgcn_mfma_f32_16x16x32_bf16(b, a, acc[bj][n], 0, 0, 0); }
;     }
; #pragma unroll
;     for (int bj = 0; bj < 2; ++bj)
; #pragma unroll
;       for (int n = 0; n < 2; ++n)
; #pragma unroll
;         for (int j = 0; j < 4; ++j) part[(wid * 16 + (bj * 2 + n) * 4 + j) * 64 + lane] = acc[bj][n][j];
;     __syncthreads();
;     if (wid < 4) {
;       f32x4 v[2][2];
; #pragma unroll
;       for (int bj = 0; bj < 2; ++bj)
; #pragma unroll
;         for (int n = 0; n < 2; ++n)
; #pragma unroll
;           for (int j = 0; j < 4; ++j) { float s = 0.f;
; #pragma unroll
;             for (int w = 0; w < 8; ++w) s += part[(w * 16 + (bj * 2 + n) * 4 + j) * 64 + lane];
.LBB0_1515:
	s_and_b32 s6, s1, 0xffffff00
	s_and_b32 s12, s10, 0x60
	v_or_b32_e32 v23, s6, v0
	v_or_b32_e32 v24, s12, v23
	v_ashrrev_i32_e32 v25, 31, v24
	v_lshlrev_b64 v[24:25], 11, v[24:25]
	v_lshl_add_u64 v[44:45], v[18:19], 0, v[24:25]
	global_load_dwordx4 v[24:27], v[44:45], off
	global_load_dwordx4 v[40:43], v[44:45], off offset:64
	v_add_co_u32_e32 v46, vcc, 0x8000, v44
	s_waitcnt vmcnt(1)
	v_mfma_f32_16x16x32_bf16 v[24:27], v[24:27], v[10:13], 0
	v_addc_co_u32_e32 v47, vcc, 0, v45, vcc
	global_load_dwordx4 v[28:31], v[46:47], off
	s_waitcnt vmcnt(1)
	v_mfma_f32_16x16x32_bf16 v[24:27], v[40:43], v[2:5], v[24:27]
	global_load_dwordx4 v[40:43], v[46:47], off offset:64
	v_add_co_u32_e32 v48, vcc, 0x40000, v44
	s_waitcnt vmcnt(1)
	v_mfma_f32_16x16x32_bf16 v[28:31], v[28:31], v[10:13], 0
	v_addc_co_u32_e32 v49, vcc, 0, v45, vcc
	global_load_dwordx4 v[32:35], v[48:49], off
	s_waitcnt vmcnt(1)
	v_mfma_f32_16x16x32_bf16 v[28:31], v[40:43], v[2:5], v[28:31]
	global_load_dwordx4 v[40:43], v[48:49], off offset:64
	v_add_co_u32_e32 v50, vcc, 0x48000, v44
	s_waitcnt vmcnt(1)
	v_mfma_f32_16x16x32_bf16 v[32:35], v[32:35], v[10:13], 0
	v_addc_co_u32_e32 v51, vcc, 0, v45, vcc
	global_load_dwordx4 v[36:39], v[50:51], off
	s_waitcnt vmcnt(1)
	v_mfma_f32_16x16x32_bf16 v[32:35], v[40:43], v[2:5], v[32:35]
	global_load_dwordx4 v[40:43], v[50:51], off offset:64
	s_waitcnt vmcnt(1)
	v_mfma_f32_16x16x32_bf16 v[36:39], v[36:39], v[10:13], 0
	s_waitcnt vmcnt(0)
	v_mfma_f32_16x16x32_bf16 v[36:39], v[40:43], v[2:5], v[36:39]
	global_load_dwordx4 v[40:43], v[44:45], off offset:128
	s_waitcnt vmcnt(0)
	v_mfma_f32_16x16x32_bf16 v[24:27], v[40:43], v[6:9], v[24:27]
	global_load_dwordx4 v[40:43], v[46:47], off offset:128
	s_waitcnt vmcnt(0)
	v_mfma_f32_16x16x32_bf16 v[28:31], v[40:43], v[6:9], v[28:31]
	global_load_dwordx4 v[40:43], v[48:49], off offset:128
	s_waitcnt vmcnt(0)
	v_mfma_f32_16x16x32_bf16 v[32:35], v[40:43], v[6:9], v[32:35]
	global_load_dwordx4 v[40:43], v[50:51], off offset:128
	s_waitcnt vmcnt(0)
	v_mfma_f32_16x16x32_bf16 v[36:39], v[40:43], v[6:9], v[36:39]
	global_load_dwordx4 v[40:43], v[44:45], off offset:192
	s_waitcnt vmcnt(0)
	v_mfma_f32_16x16x32_bf16 v[24:27], v[40:43], v[14:17], v[24:27]
	global_load_dwordx4 v[40:43], v[46:47], off offset:192
	s_waitcnt vmcnt(0)
	v_mfma_f32_16x16x32_bf16 v[28:31], v[40:43], v[14:17], v[28:31]
	global_load_dwordx4 v[40:43], v[48:49], off offset:192
	s_waitcnt vmcnt(0)
	v_mfma_f32_16x16x32_bf16 v[32:35], v[40:43], v[14:17], v[32:35]
	global_load_dwordx4 v[40:43], v[50:51], off offset:192
	s_waitcnt vmcnt(0)
	v_mfma_f32_16x16x32_bf16 v[36:39], v[40:43], v[14:17], v[36:39]
	ds_write2st64_b32 v75, v24, v25 offset1:1
	ds_write2st64_b32 v75, v26, v27 offset0:2 offset1:3
	ds_write2st64_b32 v75, v28, v29 offset0:4 offset1:5
	ds_write2st64_b32 v75, v30, v31 offset0:6 offset1:7
	s_nop 0
	ds_write2st64_b32 v75, v32, v33 offset0:8 offset1:9
	ds_write2st64_b32 v75, v34, v35 offset0:10 offset1:11
	s_nop 0
	ds_write2st64_b32 v75, v36, v37 offset0:12 offset1:13
	ds_write2st64_b32 v75, v38, v39 offset0:14 offset1:15
	s_waitcnt lgkmcnt(0)
	s_barrier
	s_and_saveexec_b64 s[6:7], s[4:5]
	s_cbranch_execz .LBB0_1514
	ds_read2st64_b32 v[76:77], v74 offset1:1
	ds_read2st64_b32 v[38:39], v74 offset0:2 offset1:3
	ds_read2st64_b32 v[72:73], v74 offset0:4 offset1:5
	ds_read2st64_b32 v[24:25], v74 offset0:6 offset1:7
	ds_read2st64_b32 v[78:79], v74 offset0:16 offset1:17
	ds_read2st64_b32 v[42:43], v74 offset0:18 offset1:19
	ds_read2st64_b32 v[80:81], v74 offset0:20 offset1:21
	ds_read2st64_b32 v[26:27], v74 offset0:22 offset1:23
	ds_read2st64_b32 v[82:83], v74 offset0:32 offset1:33
	ds_read2st64_b32 v[44:45], v74 offset0:34 offset1:35
	ds_read2st64_b32 v[84:85], v74 offset0:36 offset1:37
	ds_read2st64_b32 v[28:29], v74 offset0:38 offset1:39
	ds_read2st64_b32 v[86:87], v74 offset0:48 offset1:49
	ds_read2st64_b32 v[46:47], v74 offset0:50 offset1:51
	ds_read2st64_b32 v[88:89], v74 offset0:52 offset1:53
	ds_read2st64_b32 v[30:31], v74 offset0:54 offset1:55
	ds_read2st64_b32 v[90:91], v74 offset0:64 offset1:65
	ds_read2st64_b32 v[48:49], v74 offset0:66 offset1:67
	ds_read2st64_b32 v[92:93], v74 offset0:68 offset1:69
	ds_read2st64_b32 v[32:33], v74 offset0:70 offset1:71
	ds_read2st64_b32 v[94:95], v74 offset0:80 offset1:81
	ds_read2st64_b32 v[50:51], v74 offset0:82 offset1:83
	ds_read2st64_b32 v[96:97], v74 offset0:84 offset1:85
	ds_read2st64_b32 v[34:35], v74 offset0:86 offset1:87
	ds_read2st64_b32 v[98:99], v74 offset0:96 offset1:97
	ds_read2st64_b32 v[52:53], v74 offset0:98 offset1:99
	ds_read2st64_b32 v[100:101], v74 offset0:100 offset1:101
	ds_read2st64_b32 v[36:37], v74 offset0:102 offset1:103
	ds_read2st64_b32 v[102:103], v74 offset0:112 offset1:113
	ds_read2st64_b32 v[54:55], v74 offset0:114 offset1:115
	ds_read2st64_b32 v[104:105], v74 offset0:116 offset1:117
	ds_read2st64_b32 v[40:41], v74 offset0:118 offset1:119
	ds_read2st64_b32 v[106:107], v74 offset0:8 offset1:9
	ds_read2st64_b32 v[108:109], v74 offset0:10 offset1:11
	ds_read2st64_b32 v[110:111], v74 offset0:12 offset1:13
	ds_read2st64_b32 v[60:61], v74 offset0:14 offset1:15
	ds_read2st64_b32 v[112:113], v74 offset0:24 offset1:25
	ds_read2st64_b32 v[114:115], v74 offset0:26 offset1:27
	ds_read2st64_b32 v[116:117], v74 offset0:28 offset1:29
	ds_read2st64_b32 v[64:65], v74 offset0:30 offset1:31
	ds_read2st64_b32 v[118:119], v74 offset0:40 offset1:41
	ds_read2st64_b32 v[120:121], v74 offset0:42 offset1:43
	ds_read2st64_b32 v[122:123], v74 offset0:44 offset1:45
	ds_read2st64_b32 v[66:67], v74 offset0:46 offset1:47
	ds_read2st64_b32 v[124:125], v74 offset0:56 offset1:57
	ds_read2st64_b32 v[126:127], v74 offset0:58 offset1:59
	ds_read2st64_b32 v[128:129], v74 offset0:60 offset1:61
	ds_read2st64_b32 v[70:71], v74 offset0:62 offset1:63
	ds_read2st64_b32 v[130:131], v74 offset0:72 offset1:73
	ds_read2st64_b32 v[132:133], v74 offset0:74 offset1:75
	ds_read2st64_b32 v[134:135], v74 offset0:76 offset1:77
	ds_read2st64_b32 v[56:57], v74 offset0:78 offset1:79
	ds_read2st64_b32 v[136:137], v74 offset0:88 offset1:89
	ds_read2st64_b32 v[138:139], v74 offset0:90 offset1:91
	ds_read2st64_b32 v[140:141], v74 offset0:92 offset1:93
	ds_read2st64_b32 v[58:59], v74 offset0:94 offset1:95
	ds_read2st64_b32 v[142:143], v74 offset0:104 offset1:105
	ds_read2st64_b32 v[144:145], v74 offset0:106 offset1:107
	ds_read2st64_b32 v[146:147], v74 offset0:108 offset1:109
	ds_read2st64_b32 v[62:63], v74 offset0:110 offset1:111
	ds_read2st64_b32 v[148:149], v74 offset0:120 offset1:121
	ds_read2st64_b32 v[150:151], v74 offset0:122 offset1:123
	ds_read2st64_b32 v[152:153], v74 offset0:124 offset1:125
	ds_read2st64_b32 v[68:69], v74 offset0:126 offset1:127
	s_waitcnt lgkmcnt(14)
; __device__ __forceinline__ unsigned cvt_pk_bf16(float lo, float hi) { const f32x2 v = {lo, hi}; return __builtin_bit_cast(unsigned, __builtin_convertvector(v, bf16v2)); }
;   __device__ __forceinline__ void operator()(int row, int cb, int fq, f32x4 a, f32x4 b, f32x4 c, f32x4 d) const { group(row, cb, fq, a, b); group(row, cb + 128, fq, c, d); }
;   __device__ __forceinline__ void operator()(int row, int cb, int fq, f32x4 a, f32x4 b, f32x4 c, f32x4 d) const { group(row, cb, fq, a, b); group(row, cb + 128, fq, c, d); }
; __device__ __forceinline__ float silu_mul(float g, float u) { return g * __builtin_amdgcn_rcpf(1.0f + __builtin_amdgcn_exp2f(-g * LOG2E)) * u; }
;   __device__ __forceinline__ void operator()(int row, int cb, int fq, f32x4 g0, f32x4 g1, f32x4 u0, f32x4 u1) const {
;     bf16_t* p = act + (size_t)row * DFF + (cb >> 8) * 128 + (cb & 255) + fq * 8; f32x4 o0, o1;
; #pragma unroll
;     for (int j = 0; j < 4; ++j) { o0[j] = silu_mul(g0[j], u0[j]); o1[j] = silu_mul(g1[j], u1[j]); }
;     u32x4 w; w.x = cvt_pk_bf16(o0[0], o0[1]); w.y = cvt_pk_bf16(o0[2], o0[3]); w.z = cvt_pk_bf16(o1[0], o1[1]); w.w = cvt_pk_bf16(o1[2], o1[3]);
;     *(u32x4*)p = w;
;   }
; template <class Epi, class Pre>
; __device__ __forceinline__ void meta_gemm(const bf16_t* __restrict__ A, int lda, const bf16_t* __restrict__ Bt, int ldb, int N, int K, Epi& epi, Pre pre) {
;     ...
;           for (int j = 0; j < 4; ++j) { float s = 0.f;
; #pragma unroll
;             for (int w = 0; w < 8; ++w) s += part[(w * 16 + (bj * 2 + n) * 4 + j) * 64 + lane];
;             v[bj][n][j] = s; }
;       pre(fr, fq);
;       epi(NREAL + 16 * wid + fr, cb, fq, v[0][0], v[0][1], v[1][0], v[1][1]);
	v_pk_add_f32 v[76:77], v[76:77], 0 op_sel_hi:[1,0]
	v_pk_add_f32 v[72:73], v[72:73], 0 op_sel_hi:[1,0]
	v_pk_add_f32 v[76:77], v[76:77], v[78:79]
	v_pk_add_f32 v[72:73], v[72:73], v[80:81]
	v_pk_add_f32 v[76:77], v[76:77], v[82:83]
	v_pk_add_f32 v[72:73], v[72:73], v[84:85]
	v_pk_add_f32 v[76:77], v[76:77], v[86:87]
	v_pk_add_f32 v[72:73], v[72:73], v[88:89]
	v_pk_add_f32 v[76:77], v[76:77], v[90:91]
	v_pk_add_f32 v[72:73], v[72:73], v[92:93]
	v_pk_add_f32 v[76:77], v[76:77], v[94:95]
	v_pk_add_f32 v[72:73], v[72:73], v[96:97]
	v_pk_add_f32 v[76:77], v[76:77], v[98:99]
	v_pk_add_f32 v[72:73], v[72:73], v[100:101]
	v_pk_add_f32 v[76:77], v[76:77], v[102:103]
	v_pk_add_f32 v[72:73], v[72:73], v[104:105]
	v_mul_f32_e32 v23, 0xbfb8aa3b, v76
	v_exp_f32_e32 v23, v23
	v_mul_f32_e32 v82, 0xbfb8aa3b, v77
	v_exp_f32_e32 v83, v82
	v_pk_add_f32 v[38:39], v[38:39], 0 op_sel_hi:[1,0]
	v_add_f32_e32 v23, 1.0, v23
	v_rcp_f32_e32 v82, v23
	v_add_f32_e32 v23, 1.0, v83
	v_rcp_f32_e32 v83, v23
	v_mul_f32_e32 v23, 0xbfb8aa3b, v72
	v_pk_add_f32 v[38:39], v[38:39], v[42:43]
	v_exp_f32_e32 v23, v23
	v_mul_f32_e32 v80, 0xbfb8aa3b, v73
	v_pk_add_f32 v[38:39], v[38:39], v[44:45]
	v_exp_f32_e32 v81, v80
	v_pk_add_f32 v[38:39], v[38:39], v[46:47]
	v_add_f32_e32 v23, 1.0, v23
	v_pk_add_f32 v[38:39], v[38:39], v[48:49]
	v_rcp_f32_e32 v80, v23
	v_pk_add_f32 v[38:39], v[38:39], v[50:51]
	v_add_f32_e32 v23, 1.0, v81
	v_pk_add_f32 v[38:39], v[38:39], v[52:53]
	v_pk_add_f32 v[24:25], v[24:25], 0 op_sel_hi:[1,0]
	v_pk_add_f32 v[38:39], v[38:39], v[54:55]
	v_rcp_f32_e32 v81, v23
	v_mul_f32_e32 v23, 0xbfb8aa3b, v38
	v_pk_add_f32 v[24:25], v[24:25], v[26:27]
	v_exp_f32_e32 v23, v23
	v_mul_f32_e32 v44, 0xbfb8aa3b, v39
	v_pk_add_f32 v[24:25], v[24:25], v[28:29]
	v_exp_f32_e32 v45, v44
	v_pk_add_f32 v[24:25], v[24:25], v[30:31]
	v_pk_add_f32 v[78:79], v[106:107], 0 op_sel_hi:[1,0]
	v_pk_add_f32 v[24:25], v[24:25], v[32:33]
	v_pk_add_f32 v[78:79], v[78:79], v[112:113]
	v_pk_add_f32 v[24:25], v[24:25], v[34:35]
	v_add_f32_e32 v23, 1.0, v23
	v_pk_add_f32 v[24:25], v[24:25], v[36:37]
	v_pk_add_f32 v[78:79], v[78:79], v[118:119]
	v_rcp_f32_e32 v44, v23
	v_add_f32_e32 v23, 1.0, v45
	v_pk_add_f32 v[24:25], v[24:25], v[40:41]
	v_pk_add_f32 v[78:79], v[78:79], v[124:125]
	v_rcp_f32_e32 v45, v23
	v_mul_f32_e32 v23, 0xbfb8aa3b, v24
	v_pk_add_f32 v[78:79], v[78:79], v[130:131]
	v_exp_f32_e32 v23, v23
	v_mul_f32_e32 v28, 0xbfb8aa3b, v25
	s_waitcnt lgkmcnt(11)
	v_pk_add_f32 v[78:79], v[78:79], v[136:137]
	v_exp_f32_e32 v29, v28
	s_waitcnt lgkmcnt(7)
	v_pk_add_f32 v[78:79], v[78:79], v[142:143]
	v_pk_mul_f32 v[76:77], v[76:77], v[82:83]
	s_waitcnt lgkmcnt(3)
	v_pk_add_f32 v[78:79], v[78:79], v[148:149]
	v_pk_add_f32 v[26:27], v[60:61], 0 op_sel_hi:[1,0]
	v_pk_mul_f32 v[76:77], v[76:77], v[78:79]
	v_pk_add_f32 v[78:79], v[110:111], 0 op_sel_hi:[1,0]
	v_pk_add_f32 v[42:43], v[108:109], 0 op_sel_hi:[1,0]
	v_pk_add_f32 v[26:27], v[26:27], v[64:65]
	v_add_f32_e32 v23, 1.0, v23
	v_pk_add_f32 v[78:79], v[78:79], v[116:117]
	v_pk_add_f32 v[42:43], v[42:43], v[114:115]
	v_pk_add_f32 v[26:27], v[26:27], v[66:67]
	v_rcp_f32_e32 v28, v23
	v_add_f32_e32 v23, 1.0, v29
	v_pk_add_f32 v[78:79], v[78:79], v[122:123]
	v_pk_add_f32 v[42:43], v[42:43], v[120:121]
	v_pk_add_f32 v[26:27], v[26:27], v[70:71]
	v_rcp_f32_e32 v29, v23
	v_pk_add_f32 v[78:79], v[78:79], v[128:129]
	v_pk_add_f32 v[42:43], v[42:43], v[126:127]
	v_pk_add_f32 v[26:27], v[26:27], v[56:57]
	v_pk_add_f32 v[78:79], v[78:79], v[134:135]
	v_pk_add_f32 v[42:43], v[42:43], v[132:133]
	v_pk_add_f32 v[26:27], v[26:27], v[58:59]
	v_pk_add_f32 v[78:79], v[78:79], v[140:141]
	v_pk_add_f32 v[42:43], v[42:43], v[138:139]
	v_pk_add_f32 v[26:27], v[26:27], v[62:63]
	s_and_b32 s14, s10, 0xffffff80
	v_pk_add_f32 v[78:79], v[78:79], v[146:147]
	v_pk_add_f32 v[42:43], v[42:43], v[144:145]
	s_waitcnt lgkmcnt(0)
	v_pk_add_f32 v[26:27], v[26:27], v[68:69]
	v_pk_mul_f32 v[24:25], v[24:25], v[28:29]
	s_ashr_i32 s15, s14, 31
	v_pk_add_f32 v[78:79], v[78:79], v[152:153]
	v_pk_mul_f32 v[72:73], v[72:73], v[80:81]
	v_pk_add_f32 v[42:43], v[42:43], v[150:151]
	v_pk_mul_f32 v[38:39], v[38:39], v[44:45]
	v_pk_mul_f32 v[28:29], v[24:25], v[26:27]
	v_lshl_add_u64 v[24:25], s[14:15], 1, v[20:21]
	s_lshl_b32 s90, s12, 1
	v_pk_mul_f32 v[72:73], v[72:73], v[78:79]
	v_pk_mul_f32 v[38:39], v[38:39], v[42:43]
	v_lshl_add_u64 v[24:25], v[24:25], 0, s[90:91]
	v_mov_b32_e32 v23, v1
	v_lshl_add_u64 v[30:31], v[24:25], 0, v[22:23]
	v_cvt_pk_bf16_f32 v24, v76, v77
	v_cvt_pk_bf16_f32 v25, v38, v39
	v_cvt_pk_bf16_f32 v26, v72, v73
	v_cvt_pk_bf16_f32 v27, v28, v29
	global_store_dwordx4 v[30:31], v[24:27], off sc0 sc1
	s_branch .LBB0_1514

; __device__ __forceinline__ unsigned cvt_pk_bf16(float lo, float hi) { const f32x2 v = {lo, hi}; return __builtin_bit_cast(unsigned, __builtin_convertvector(v, bf16v2)); }
;   __device__ __forceinline__ void operator()(int row, int cb, int fq, f32x4 a, f32x4 b, f32x4 c, f32x4 d) const { group(row, cb, fq, a, b); group(row, cb + 128, fq, c, d); }
;   __device__ __forceinline__ void operator()(int row, int cb, int fq, f32x4 a, f32x4 b, f32x4 c, f32x4 d) const { group(row, cb, fq, a, b); group(row, cb + 128, fq, c, d); }
; __device__ __forceinline__ float silu_mul(float g, float u) { return g * __builtin_amdgcn_rcpf(1.0f + __builtin_amdgcn_exp2f(-g * LOG2E)) * u; }
;     ...
; #pragma unroll
;     for (int ai = 0; ai < 2; ++ai)
; #pragma unroll
;       for (int m = 0; m < 4; ++m)
;         epi(brow + ai * HALF + wr * 64 + m * 16 + fr, bcol + wc * 32, fq, acc[ai][0][m][0], acc[ai][0][m][1], acc[ai][1][m][0], acc[ai][1][m][1]);
;   }
;   __device__ __forceinline__ void operator()(int row, int cb, int fq, f32x4 g0, f32x4 g1, f32x4 u0, f32x4 u1) const {
;     bf16_t* p = act + (size_t)row * DFF + (cb >> 8) * 128 + (cb & 255) + fq * 8; f32x4 o0, o1;
; #pragma unroll
;     for (int j = 0; j < 4; ++j) { o0[j] = silu_mul(g0[j], u0[j]); o1[j] = silu_mul(g1[j], u1[j]); }
;     u32x4 w; w.x = cvt_pk_bf16(o0[0], o0[1]); w.y = cvt_pk_bf16(o0[2], o0[3]); w.z = cvt_pk_bf16(o1[0], o1[1]); w.w = cvt_pk_bf16(o1[2], o1[3]);
;     *(u32x4*)p = w;
.LBB0_1532:
	v_or_b32_e32 v0, s10, v140
	v_add_u32_e32 v132, v0, v141
	v_mul_f32_e32 v0, 0xbfb8aa3b, v122
	v_exp_f32_e32 v0, v0
	v_readlane_b32 s6, v254, 24
	v_readlane_b32 s7, v254, 25
	s_movk_i32 s10, 0x1600
	v_add_f32_e32 v0, 1.0, v0
	v_rcp_f32_e32 v134, v0
	v_mul_f32_e32 v0, 0xbfb8aa3b, v114
	v_exp_f32_e32 v0, v0
	s_andn2_b64 vcc, exec, s[4:5]
	v_add_f32_e32 v0, 1.0, v0
	v_rcp_f32_e32 v136, v0
	v_mul_f32_e32 v0, 0xbfb8aa3b, v123
	v_exp_f32_e32 v0, v0
	s_nop 0
	v_add_f32_e32 v0, 1.0, v0
	v_rcp_f32_e32 v135, v0
	v_mul_f32_e32 v0, 0xbfb8aa3b, v115
	v_exp_f32_e32 v0, v0
	v_pk_mul_f32 v[122:123], v[122:123], v[134:135]
	s_nop 0
	v_pk_mul_f32 v[122:123], v[122:123], v[126:127]
	v_add_f32_e32 v0, 1.0, v0
	v_rcp_f32_e32 v137, v0
	v_mul_f32_e32 v0, 0xbfb8aa3b, v124
	v_exp_f32_e32 v0, v0
	v_pk_mul_f32 v[114:115], v[114:115], v[136:137]
	s_nop 0
	v_pk_mul_f32 v[118:119], v[114:115], v[118:119]
	v_add_f32_e32 v0, 1.0, v0
	v_rcp_f32_e32 v114, v0
	v_mul_f32_e32 v0, 0xbfb8aa3b, v116
	v_exp_f32_e32 v0, v0
	v_cvt_pk_bf16_f32 v118, v118, v119
	v_add_f32_e32 v0, 1.0, v0
	v_rcp_f32_e32 v126, v0
	v_mul_f32_e32 v0, 0xbfb8aa3b, v125
	v_exp_f32_e32 v0, v0
	s_nop 0
	v_add_f32_e32 v0, 1.0, v0
	v_rcp_f32_e32 v115, v0
	v_mul_f32_e32 v0, 0xbfb8aa3b, v117
	v_exp_f32_e32 v0, v0
	v_pk_mul_f32 v[114:115], v[124:125], v[114:115]
	s_nop 0
	v_pk_mul_f32 v[124:125], v[114:115], v[128:129]
	v_add_f32_e32 v0, 1.0, v0
	v_rcp_f32_e32 v127, v0
	v_lshlrev_b32_e32 v0, 6, v131
	v_mov_b32_e32 v131, v1
	v_pk_mul_f32 v[114:115], v[116:117], v[126:127]
	s_nop 0
	v_pk_mul_f32 v[120:121], v[114:115], v[120:121]
	v_mov_b64_e32 v[114:115], s[6:7]
	v_mad_i64_i32 v[116:117], s[6:7], v132, s10, v[114:115]
	v_lshl_add_u64 v[116:117], v[116:117], 0, s[90:91]
	v_lshl_add_u64 v[116:117], v[116:117], 0, v[0:1]
	v_lshl_add_u64 v[126:127], v[116:117], 0, v[130:131]
	v_cvt_pk_bf16_f32 v116, v122, v123
	v_cvt_pk_bf16_f32 v117, v124, v125
	v_cvt_pk_bf16_f32 v119, v120, v121
	global_store_dwordx4 v[126:127], v[116:119], off sc0 sc1
	v_or_b32_e32 v120, 16, v132
	s_nop 0
	v_mul_f32_e32 v117, 0xbfb8aa3b, v98
	v_exp_f32_e32 v117, v117
	v_mul_f32_e32 v116, 0xbfb8aa3b, v106
	v_exp_f32_e32 v116, v116
	v_add_f32_e32 v117, 1.0, v117
	v_rcp_f32_e32 v118, v117
	v_mul_f32_e32 v117, 0xbfb8aa3b, v107
	v_exp_f32_e32 v117, v117
	v_add_f32_e32 v116, 1.0, v116
	v_rcp_f32_e32 v116, v116
	v_add_f32_e32 v117, 1.0, v117
	v_rcp_f32_e32 v117, v117
	s_nop 0
	v_pk_mul_f32 v[106:107], v[106:107], v[116:117]
	s_nop 0
	v_pk_mul_f32 v[106:107], v[106:107], v[110:111]
	v_mul_f32_e32 v110, 0xbfb8aa3b, v99
	v_exp_f32_e32 v110, v110
	s_nop 0
	v_add_f32_e32 v110, 1.0, v110
	v_rcp_f32_e32 v119, v110
	s_nop 0
	v_pk_mul_f32 v[98:99], v[98:99], v[118:119]
	s_nop 0
	v_pk_mul_f32 v[102:103], v[98:99], v[102:103]
	v_mul_f32_e32 v99, 0xbfb8aa3b, v100
	v_exp_f32_e32 v99, v99
	v_mul_f32_e32 v98, 0xbfb8aa3b, v108
	v_exp_f32_e32 v98, v98
	v_add_f32_e32 v99, 1.0, v99
	v_rcp_f32_e32 v110, v99
	v_mul_f32_e32 v99, 0xbfb8aa3b, v109
	v_exp_f32_e32 v99, v99
	v_add_f32_e32 v98, 1.0, v98
	v_rcp_f32_e32 v98, v98
	v_add_f32_e32 v99, 1.0, v99
	v_rcp_f32_e32 v99, v99
	s_nop 0
	v_pk_mul_f32 v[98:99], v[108:109], v[98:99]
	s_nop 0
	v_pk_mul_f32 v[108:109], v[98:99], v[112:113]
	v_mul_f32_e32 v98, 0xbfb8aa3b, v101
	v_exp_f32_e32 v98, v98
	s_nop 0
	v_add_f32_e32 v98, 1.0, v98
	v_rcp_f32_e32 v111, v98
	s_nop 0
	v_pk_mul_f32 v[98:99], v[100:101], v[110:111]
	s_nop 0
	v_pk_mul_f32 v[104:105], v[98:99], v[104:105]
	v_mad_i64_i32 v[98:99], s[6:7], v120, s10, v[114:115]
	v_lshl_add_u64 v[98:99], v[98:99], 0, s[90:91]
	v_lshl_add_u64 v[98:99], v[98:99], 0, v[0:1]
	v_lshl_add_u64 v[110:111], v[98:99], 0, v[130:131]
	v_cvt_pk_bf16_f32 v98, v106, v107
	v_cvt_pk_bf16_f32 v99, v108, v109
	v_cvt_pk_bf16_f32 v100, v102, v103
	v_cvt_pk_bf16_f32 v101, v104, v105
	global_store_dwordx4 v[110:111], v[98:101], off sc0 sc1
	v_or_b32_e32 v102, 32, v132
	s_nop 0
	v_mul_f32_e32 v99, 0xbfb8aa3b, v82
	v_exp_f32_e32 v99, v99
	v_mul_f32_e32 v98, 0xbfb8aa3b, v90
	v_exp_f32_e32 v98, v98
	v_add_f32_e32 v99, 1.0, v99
	v_rcp_f32_e32 v100, v99
	v_mul_f32_e32 v99, 0xbfb8aa3b, v91
	v_exp_f32_e32 v99, v99
	v_add_f32_e32 v98, 1.0, v98
	v_rcp_f32_e32 v98, v98
	v_add_f32_e32 v99, 1.0, v99
	v_rcp_f32_e32 v99, v99
	s_nop 0
	v_pk_mul_f32 v[90:91], v[90:91], v[98:99]
	s_nop 0
	v_pk_mul_f32 v[90:91], v[90:91], v[94:95]
	v_mul_f32_e32 v94, 0xbfb8aa3b, v83
	v_exp_f32_e32 v94, v94
	s_nop 0
	v_add_f32_e32 v94, 1.0, v94
	v_rcp_f32_e32 v101, v94
	s_nop 0
	v_pk_mul_f32 v[82:83], v[82:83], v[100:101]
	s_nop 0
	v_pk_mul_f32 v[86:87], v[82:83], v[86:87]
	v_mul_f32_e32 v83, 0xbfb8aa3b, v84
	v_exp_f32_e32 v83, v83
	v_mul_f32_e32 v82, 0xbfb8aa3b, v92
	v_exp_f32_e32 v82, v82
	v_add_f32_e32 v83, 1.0, v83
	v_rcp_f32_e32 v94, v83
	v_mul_f32_e32 v83, 0xbfb8aa3b, v93
	v_exp_f32_e32 v83, v83
	v_add_f32_e32 v82, 1.0, v82
	v_rcp_f32_e32 v82, v82
	v_add_f32_e32 v83, 1.0, v83
	v_rcp_f32_e32 v83, v83
	s_nop 0
	v_pk_mul_f32 v[82:83], v[92:93], v[82:83]
	s_nop 0
	v_pk_mul_f32 v[92:93], v[82:83], v[96:97]
	v_mul_f32_e32 v82, 0xbfb8aa3b, v85
	v_exp_f32_e32 v82, v82
	s_nop 0
	v_add_f32_e32 v82, 1.0, v82
	v_rcp_f32_e32 v95, v82
	s_nop 0
	v_pk_mul_f32 v[82:83], v[84:85], v[94:95]
	s_nop 0
	v_pk_mul_f32 v[88:89], v[82:83], v[88:89]
	v_mad_i64_i32 v[82:83], s[6:7], v102, s10, v[114:115]
	v_lshl_add_u64 v[82:83], v[82:83], 0, s[90:91]
	v_lshl_add_u64 v[82:83], v[82:83], 0, v[0:1]
	v_lshl_add_u64 v[94:95], v[82:83], 0, v[130:131]
	v_cvt_pk_bf16_f32 v82, v90, v91
	v_cvt_pk_bf16_f32 v83, v92, v93
	v_cvt_pk_bf16_f32 v84, v86, v87
	v_cvt_pk_bf16_f32 v85, v88, v89
	global_store_dwordx4 v[94:95], v[82:85], off sc0 sc1
	v_or_b32_e32 v86, 48, v132
; __device__ __forceinline__ unsigned cvt_pk_bf16(float lo, float hi) { const f32x2 v = {lo, hi}; return __builtin_bit_cast(unsigned, __builtin_convertvector(v, bf16v2)); }
;   __device__ __forceinline__ void operator()(int row, int cb, int fq, f32x4 a, f32x4 b, f32x4 c, f32x4 d) const { group(row, cb, fq, a, b); group(row, cb + 128, fq, c, d); }
;   __device__ __forceinline__ void operator()(int row, int cb, int fq, f32x4 a, f32x4 b, f32x4 c, f32x4 d) const { group(row, cb, fq, a, b); group(row, cb + 128, fq, c, d); }
; __device__ __forceinline__ float silu_mul(float g, float u) { return g * __builtin_amdgcn_rcpf(1.0f + __builtin_amdgcn_exp2f(-g * LOG2E)) * u; }
;     ...
; #pragma unroll
;     for (int ai = 0; ai < 2; ++ai)
; #pragma unroll
;       for (int m = 0; m < 4; ++m)
;         epi(brow + ai * HALF + wr * 64 + m * 16 + fr, bcol + wc * 32, fq, acc[ai][0][m][0], acc[ai][0][m][1], acc[ai][1][m][0], acc[ai][1][m][1]);
;   }
;   __device__ __forceinline__ void operator()(int row, int cb, int fq, f32x4 g0, f32x4 g1, f32x4 u0, f32x4 u1) const {
;     bf16_t* p = act + (size_t)row * DFF + (cb >> 8) * 128 + (cb & 255) + fq * 8; f32x4 o0, o1;
; #pragma unroll
;     for (int j = 0; j < 4; ++j) { o0[j] = silu_mul(g0[j], u0[j]); o1[j] = silu_mul(g1[j], u1[j]); }
;     u32x4 w; w.x = cvt_pk_bf16(o0[0], o0[1]); w.y = cvt_pk_bf16(o0[2], o0[3]); w.z = cvt_pk_bf16(o1[0], o1[1]); w.w = cvt_pk_bf16(o1[2], o1[3]);
;     *(u32x4*)p = w;
	s_nop 0
	v_mul_f32_e32 v83, 0xbfb8aa3b, v66
	v_exp_f32_e32 v83, v83
	v_mul_f32_e32 v82, 0xbfb8aa3b, v74
	v_exp_f32_e32 v82, v82
	v_add_f32_e32 v83, 1.0, v83
	v_rcp_f32_e32 v84, v83
	v_mul_f32_e32 v83, 0xbfb8aa3b, v75
	v_exp_f32_e32 v83, v83
	v_add_f32_e32 v82, 1.0, v82
	v_rcp_f32_e32 v82, v82
	v_add_f32_e32 v83, 1.0, v83
	v_rcp_f32_e32 v83, v83
	s_nop 0
	v_pk_mul_f32 v[74:75], v[74:75], v[82:83]
	s_nop 0
	v_pk_mul_f32 v[74:75], v[74:75], v[78:79]
	v_mul_f32_e32 v78, 0xbfb8aa3b, v67
	v_exp_f32_e32 v78, v78
	s_nop 0
	v_add_f32_e32 v78, 1.0, v78
	v_rcp_f32_e32 v85, v78
	s_nop 0
	v_pk_mul_f32 v[66:67], v[66:67], v[84:85]
	s_nop 0
	v_pk_mul_f32 v[70:71], v[66:67], v[70:71]
	v_mul_f32_e32 v67, 0xbfb8aa3b, v68
	v_exp_f32_e32 v67, v67
	v_mul_f32_e32 v66, 0xbfb8aa3b, v76
	v_exp_f32_e32 v66, v66
	v_add_f32_e32 v67, 1.0, v67
	v_rcp_f32_e32 v78, v67
	v_mul_f32_e32 v67, 0xbfb8aa3b, v77
	v_exp_f32_e32 v67, v67
	v_add_f32_e32 v66, 1.0, v66
	v_rcp_f32_e32 v66, v66
	v_add_f32_e32 v67, 1.0, v67
	v_rcp_f32_e32 v67, v67
	s_nop 0
	v_pk_mul_f32 v[66:67], v[76:77], v[66:67]
	s_nop 0
	v_pk_mul_f32 v[76:77], v[66:67], v[80:81]
	v_mul_f32_e32 v66, 0xbfb8aa3b, v69
	v_exp_f32_e32 v66, v66
	s_nop 0
	v_add_f32_e32 v66, 1.0, v66
	v_rcp_f32_e32 v79, v66
	s_nop 0
	v_pk_mul_f32 v[66:67], v[68:69], v[78:79]
	s_nop 0
	v_pk_mul_f32 v[72:73], v[66:67], v[72:73]
	v_mad_i64_i32 v[66:67], s[6:7], v86, s10, v[114:115]
	v_lshl_add_u64 v[66:67], v[66:67], 0, s[90:91]
	v_lshl_add_u64 v[66:67], v[66:67], 0, v[0:1]
	v_lshl_add_u64 v[78:79], v[66:67], 0, v[130:131]
	v_cvt_pk_bf16_f32 v66, v74, v75
	v_cvt_pk_bf16_f32 v67, v76, v77
	v_cvt_pk_bf16_f32 v68, v70, v71
	v_cvt_pk_bf16_f32 v69, v72, v73
	global_store_dwordx4 v[78:79], v[66:69], off sc0 sc1
	v_add_u32_e32 v70, 0x80, v132
	s_nop 0
	v_mul_f32_e32 v67, 0xbfb8aa3b, v50
	v_exp_f32_e32 v67, v67
	v_mul_f32_e32 v66, 0xbfb8aa3b, v58
	v_exp_f32_e32 v66, v66
	v_add_f32_e32 v67, 1.0, v67
	v_rcp_f32_e32 v68, v67
	v_mul_f32_e32 v67, 0xbfb8aa3b, v59
	v_exp_f32_e32 v67, v67
	v_add_f32_e32 v66, 1.0, v66
	v_rcp_f32_e32 v66, v66
	v_add_f32_e32 v67, 1.0, v67
	v_rcp_f32_e32 v67, v67
	s_nop 0
	v_pk_mul_f32 v[58:59], v[58:59], v[66:67]
	s_nop 0
	v_pk_mul_f32 v[58:59], v[58:59], v[62:63]
	v_mul_f32_e32 v62, 0xbfb8aa3b, v51
	v_exp_f32_e32 v62, v62
	s_nop 0
	v_add_f32_e32 v62, 1.0, v62
	v_rcp_f32_e32 v69, v62
	s_nop 0
	v_pk_mul_f32 v[50:51], v[50:51], v[68:69]
	s_nop 0
	v_pk_mul_f32 v[54:55], v[50:51], v[54:55]
	v_mul_f32_e32 v51, 0xbfb8aa3b, v52
	v_exp_f32_e32 v51, v51
	v_mul_f32_e32 v50, 0xbfb8aa3b, v60
	v_exp_f32_e32 v50, v50
	v_add_f32_e32 v51, 1.0, v51
	v_rcp_f32_e32 v62, v51
	v_mul_f32_e32 v51, 0xbfb8aa3b, v61
	v_exp_f32_e32 v51, v51
	v_add_f32_e32 v50, 1.0, v50
	v_rcp_f32_e32 v50, v50
	v_add_f32_e32 v51, 1.0, v51
	v_rcp_f32_e32 v51, v51
	s_nop 0
	v_pk_mul_f32 v[50:51], v[60:61], v[50:51]
	s_nop 0
	v_pk_mul_f32 v[60:61], v[50:51], v[64:65]
	v_mul_f32_e32 v50, 0xbfb8aa3b, v53
	v_exp_f32_e32 v50, v50
	s_nop 0
	v_add_f32_e32 v50, 1.0, v50
	v_rcp_f32_e32 v63, v50
	s_nop 0
	v_pk_mul_f32 v[50:51], v[52:53], v[62:63]
	s_nop 0
	v_pk_mul_f32 v[56:57], v[50:51], v[56:57]
	v_mad_i64_i32 v[50:51], s[6:7], v70, s10, v[114:115]
	v_lshl_add_u64 v[50:51], v[50:51], 0, s[90:91]
	v_lshl_add_u64 v[50:51], v[50:51], 0, v[0:1]
	v_lshl_add_u64 v[62:63], v[50:51], 0, v[130:131]
	v_cvt_pk_bf16_f32 v50, v58, v59
	v_cvt_pk_bf16_f32 v51, v60, v61
	v_cvt_pk_bf16_f32 v52, v54, v55
	v_cvt_pk_bf16_f32 v53, v56, v57
	global_store_dwordx4 v[62:63], v[50:53], off sc0 sc1
	v_add_u32_e32 v54, 0x90, v132
	s_nop 0
	v_mul_f32_e32 v51, 0xbfb8aa3b, v34
	v_exp_f32_e32 v51, v51
	v_mul_f32_e32 v50, 0xbfb8aa3b, v42
	v_exp_f32_e32 v50, v50
	v_add_f32_e32 v51, 1.0, v51
	v_rcp_f32_e32 v52, v51
	v_mul_f32_e32 v51, 0xbfb8aa3b, v43
	v_exp_f32_e32 v51, v51
	v_add_f32_e32 v50, 1.0, v50
	v_rcp_f32_e32 v50, v50
	v_add_f32_e32 v51, 1.0, v51
	v_rcp_f32_e32 v51, v51
	s_nop 0
	v_pk_mul_f32 v[42:43], v[42:43], v[50:51]
	s_nop 0
	v_pk_mul_f32 v[42:43], v[42:43], v[46:47]
	v_mul_f32_e32 v46, 0xbfb8aa3b, v35
	v_exp_f32_e32 v46, v46
	s_nop 0
	v_add_f32_e32 v46, 1.0, v46
	v_rcp_f32_e32 v53, v46
	s_nop 0
	v_pk_mul_f32 v[34:35], v[34:35], v[52:53]
	s_nop 0
	v_pk_mul_f32 v[38:39], v[34:35], v[38:39]
	v_mul_f32_e32 v35, 0xbfb8aa3b, v36
	v_exp_f32_e32 v35, v35
	v_mul_f32_e32 v34, 0xbfb8aa3b, v44
	v_exp_f32_e32 v34, v34
	v_add_f32_e32 v35, 1.0, v35
	v_rcp_f32_e32 v46, v35
	v_mul_f32_e32 v35, 0xbfb8aa3b, v45
	v_exp_f32_e32 v35, v35
	v_add_f32_e32 v34, 1.0, v34
	v_rcp_f32_e32 v34, v34
	v_add_f32_e32 v35, 1.0, v35
	v_rcp_f32_e32 v35, v35
	s_nop 0
	v_pk_mul_f32 v[34:35], v[44:45], v[34:35]
	s_nop 0
	v_pk_mul_f32 v[44:45], v[34:35], v[48:49]
	v_mul_f32_e32 v34, 0xbfb8aa3b, v37
	v_exp_f32_e32 v34, v34
	s_nop 0
	v_add_f32_e32 v34, 1.0, v34
	v_rcp_f32_e32 v47, v34
	s_nop 0
	v_pk_mul_f32 v[34:35], v[36:37], v[46:47]
	s_nop 0
	v_pk_mul_f32 v[40:41], v[34:35], v[40:41]
	v_mad_i64_i32 v[34:35], s[6:7], v54, s10, v[114:115]
	v_lshl_add_u64 v[34:35], v[34:35], 0, s[90:91]
	v_lshl_add_u64 v[34:35], v[34:35], 0, v[0:1]
	v_lshl_add_u64 v[46:47], v[34:35], 0, v[130:131]
; __device__ __forceinline__ unsigned cvt_pk_bf16(float lo, float hi) { const f32x2 v = {lo, hi}; return __builtin_bit_cast(unsigned, __builtin_convertvector(v, bf16v2)); }
; #define WAIT_V(n) asm volatile("s_waitcnt vmcnt(" #n ")" ::: "memory")
;   __device__ __forceinline__ void operator()(int row, int cb, int fq, f32x4 a, f32x4 b, f32x4 c, f32x4 d) const { group(row, cb, fq, a, b); group(row, cb + 128, fq, c, d); }
;   __device__ __forceinline__ void operator()(int row, int cb, int fq, f32x4 a, f32x4 b, f32x4 c, f32x4 d) const { group(row, cb, fq, a, b); group(row, cb + 128, fq, c, d); }
; __device__ __forceinline__ float silu_mul(float g, float u) { return g * __builtin_amdgcn_rcpf(1.0f + __builtin_amdgcn_exp2f(-g * LOG2E)) * u; }
;     ...
; #pragma unroll
;     for (int ai = 0; ai < 2; ++ai)
; #pragma unroll
;       for (int m = 0; m < 4; ++m)
;         epi(brow + ai * HALF + wr * 64 + m * 16 + fr, bcol + wc * 32, fq, acc[ai][0][m][0], acc[ai][0][m][1], acc[ai][1][m][0], acc[ai][1][m][1]);
;   }
;   if (!have_next) { WAIT_V(0); __syncthreads(); }
;   __device__ __forceinline__ void operator()(int row, int cb, int fq, f32x4 g0, f32x4 g1, f32x4 u0, f32x4 u1) const {
;     bf16_t* p = act + (size_t)row * DFF + (cb >> 8) * 128 + (cb & 255) + fq * 8; f32x4 o0, o1;
; #pragma unroll
;     for (int j = 0; j < 4; ++j) { o0[j] = silu_mul(g0[j], u0[j]); o1[j] = silu_mul(g1[j], u1[j]); }
;     u32x4 w; w.x = cvt_pk_bf16(o0[0], o0[1]); w.y = cvt_pk_bf16(o0[2], o0[3]); w.z = cvt_pk_bf16(o1[0], o1[1]); w.w = cvt_pk_bf16(o1[2], o1[3]);
;     *(u32x4*)p = w;
; __global__ void __launch_bounds__(512) mega(Params P) {
;     ...
;     grid.sync();
	v_cvt_pk_bf16_f32 v34, v42, v43
	v_cvt_pk_bf16_f32 v35, v44, v45
	v_cvt_pk_bf16_f32 v36, v38, v39
	v_cvt_pk_bf16_f32 v37, v40, v41
	global_store_dwordx4 v[46:47], v[34:37], off sc0 sc1
	v_add_u32_e32 v38, 0xa0, v132
	s_nop 0
	v_mul_f32_e32 v35, 0xbfb8aa3b, v18
	v_exp_f32_e32 v35, v35
	v_mul_f32_e32 v34, 0xbfb8aa3b, v26
	v_exp_f32_e32 v34, v34
	v_add_f32_e32 v35, 1.0, v35
	v_rcp_f32_e32 v36, v35
	v_mul_f32_e32 v35, 0xbfb8aa3b, v27
	v_exp_f32_e32 v35, v35
	v_add_f32_e32 v34, 1.0, v34
	v_rcp_f32_e32 v34, v34
	v_add_f32_e32 v35, 1.0, v35
	v_rcp_f32_e32 v35, v35
	s_nop 0
	v_pk_mul_f32 v[26:27], v[26:27], v[34:35]
	s_nop 0
	v_pk_mul_f32 v[26:27], v[26:27], v[30:31]
	v_mul_f32_e32 v30, 0xbfb8aa3b, v19
	v_exp_f32_e32 v30, v30
	s_nop 0
	v_add_f32_e32 v30, 1.0, v30
	v_rcp_f32_e32 v37, v30
	s_nop 0
	v_pk_mul_f32 v[18:19], v[18:19], v[36:37]
	s_nop 0
	v_pk_mul_f32 v[22:23], v[18:19], v[22:23]
	v_mul_f32_e32 v19, 0xbfb8aa3b, v20
	v_exp_f32_e32 v19, v19
	v_mul_f32_e32 v18, 0xbfb8aa3b, v28
	v_exp_f32_e32 v18, v18
	v_add_f32_e32 v19, 1.0, v19
	v_rcp_f32_e32 v30, v19
	v_mul_f32_e32 v19, 0xbfb8aa3b, v29
	v_exp_f32_e32 v19, v19
	v_add_f32_e32 v18, 1.0, v18
	v_rcp_f32_e32 v18, v18
	v_add_f32_e32 v19, 1.0, v19
	v_rcp_f32_e32 v19, v19
	s_nop 0
	v_pk_mul_f32 v[18:19], v[28:29], v[18:19]
	s_nop 0
	v_pk_mul_f32 v[28:29], v[18:19], v[32:33]
	v_mul_f32_e32 v18, 0xbfb8aa3b, v21
	v_exp_f32_e32 v18, v18
	s_nop 0
	v_add_f32_e32 v18, 1.0, v18
	v_rcp_f32_e32 v31, v18
	s_nop 0
	v_pk_mul_f32 v[18:19], v[20:21], v[30:31]
	s_nop 0
	v_pk_mul_f32 v[24:25], v[18:19], v[24:25]
	v_mad_i64_i32 v[18:19], s[6:7], v38, s10, v[114:115]
	v_lshl_add_u64 v[18:19], v[18:19], 0, s[90:91]
	v_lshl_add_u64 v[18:19], v[18:19], 0, v[0:1]
	v_lshl_add_u64 v[30:31], v[18:19], 0, v[130:131]
	v_cvt_pk_bf16_f32 v18, v26, v27
	v_cvt_pk_bf16_f32 v19, v28, v29
	v_cvt_pk_bf16_f32 v20, v22, v23
	v_cvt_pk_bf16_f32 v21, v24, v25
	global_store_dwordx4 v[30:31], v[18:21], off sc0 sc1
	v_add_u32_e32 v22, 0xb0, v132
	s_nop 0
	v_mul_f32_e32 v19, 0xbfb8aa3b, v2
	v_exp_f32_e32 v19, v19
	v_mul_f32_e32 v18, 0xbfb8aa3b, v10
	v_exp_f32_e32 v18, v18
	v_add_f32_e32 v19, 1.0, v19
	v_rcp_f32_e32 v20, v19
	v_mul_f32_e32 v19, 0xbfb8aa3b, v11
	v_exp_f32_e32 v19, v19
	v_add_f32_e32 v18, 1.0, v18
	v_rcp_f32_e32 v18, v18
	v_add_f32_e32 v19, 1.0, v19
	v_rcp_f32_e32 v19, v19
	s_nop 0
	v_pk_mul_f32 v[10:11], v[10:11], v[18:19]
	s_nop 0
	v_pk_mul_f32 v[10:11], v[10:11], v[14:15]
	v_mul_f32_e32 v14, 0xbfb8aa3b, v3
	v_exp_f32_e32 v14, v14
	s_nop 0
	v_add_f32_e32 v14, 1.0, v14
	v_rcp_f32_e32 v21, v14
	s_nop 0
	v_pk_mul_f32 v[2:3], v[2:3], v[20:21]
	s_nop 0
	v_pk_mul_f32 v[6:7], v[2:3], v[6:7]
	v_mul_f32_e32 v3, 0xbfb8aa3b, v4
	v_exp_f32_e32 v3, v3
	v_mul_f32_e32 v2, 0xbfb8aa3b, v12
	v_exp_f32_e32 v2, v2
	v_add_f32_e32 v3, 1.0, v3
	v_rcp_f32_e32 v14, v3
	v_mul_f32_e32 v3, 0xbfb8aa3b, v13
	v_exp_f32_e32 v3, v3
	v_add_f32_e32 v2, 1.0, v2
	v_rcp_f32_e32 v2, v2
	v_add_f32_e32 v3, 1.0, v3
	v_rcp_f32_e32 v3, v3
	s_nop 0
	v_pk_mul_f32 v[2:3], v[12:13], v[2:3]
	s_nop 0
	v_pk_mul_f32 v[12:13], v[2:3], v[16:17]
	v_mul_f32_e32 v2, 0xbfb8aa3b, v5
	v_exp_f32_e32 v2, v2
	s_nop 0
	v_add_f32_e32 v2, 1.0, v2
	v_rcp_f32_e32 v15, v2
	s_nop 0
	v_pk_mul_f32 v[2:3], v[4:5], v[14:15]
	s_nop 0
	v_pk_mul_f32 v[8:9], v[2:3], v[8:9]
	v_mad_i64_i32 v[2:3], s[6:7], v22, s10, v[114:115]
	v_lshl_add_u64 v[2:3], v[2:3], 0, s[90:91]
	v_lshl_add_u64 v[2:3], v[2:3], 0, v[0:1]
	v_cndmask_b32_e64 v0, 0, 1, s[4:5]
	v_lshl_add_u64 v[14:15], v[2:3], 0, v[130:131]
	v_cvt_pk_bf16_f32 v2, v10, v11
	v_cvt_pk_bf16_f32 v3, v12, v13
	v_cvt_pk_bf16_f32 v4, v6, v7
	v_cvt_pk_bf16_f32 v5, v8, v9
	v_cmp_ne_u32_e64 s[6:7], 1, v0
	global_store_dwordx4 v[14:15], v[2:5], off sc0 sc1
	s_cbranch_vccnz .LBB0_1519
	s_waitcnt vmcnt(0)
	s_waitcnt vmcnt(0) lgkmcnt(0)
	s_barrier
	s_branch .LBB0_1519
.LBB0_1534:
	s_waitcnt vmcnt(0) lgkmcnt(0)
	s_barrier
	s_mov_b64 s[4:5], exec
	v_readlane_b32 s0, v253, 57
	v_readlane_b32 s1, v253, 58
	s_and_b64 s[0:1], s[4:5], s[0:1]
	s_mov_b64 exec, s[0:1]
	s_cbranch_execz .LBB0_1544
	buffer_wbl2 sc1
	s_load_dwordx2 s[6:7], s[56:57], -0x8
	s_load_dword s0, s[56:57], 0x0
	v_readlane_b32 s1, v253, 55
	s_waitcnt lgkmcnt(0)
	s_and_b32 s1, s1, 7
	s_add_i32 s8, s0, 7
	s_sub_i32 s8, s8, s1
	s_lshr_b32 s8, s8, 3
	s_min_u32 s9, s0, 8
	s_lshl_b32 s1, s1, 2
	s_addk_i32 s1, 0x88
	v_mov_b32_e32 v2, s1
	global_load_dword v0, v1, s[6:7] sc1
	v_mov_b32_e32 v3, 1
	s_waitcnt vmcnt(0)
	v_and_b32_e32 v0, 0xffff0000, v0
	global_atomic_add v3, v2, v3, s[6:7] sc0
	s_waitcnt vmcnt(0)
	v_and_b32_e32 v3, 0xffff, v3
	s_nop 0
	v_readfirstlane_b32 s1, v3
	s_nop 3
	s_add_i32 s0, s8, -1
	s_cmp_lg_u32 s1, s0
	s_cbranch_scc1 .Lgb_poll_6
	s_sub_i32 s1, 0x10000, s8
	v_mov_b32_e32 v3, s1
	global_atomic_add v3, v2, v3, s[6:7] sc0
	s_waitcnt vmcnt(0)
	v_mov_b32_e32 v3, 1
	global_atomic_add v3, v1, v3, s[6:7] sc0
	s_waitcnt vmcnt(0)
	v_and_b32_e32 v3, 0xffff, v3
	s_nop 0
	v_readfirstlane_b32 s1, v3
	s_nop 3
	s_add_i32 s0, s9, -1
	s_cmp_lg_u32 s1, s0
	s_cbranch_scc1 .Lgb_poll_6
	s_sub_i32 s1, 0x10000, s9
	v_mov_b32_e32 v3, s1
	global_atomic_add v1, v3, s[6:7]

; template <class Epi, class Pre>
; __device__ __forceinline__ void meta_gemm(const bf16_t* __restrict__ A, int lda, const bf16_t* __restrict__ Bt, int ldb, int N, int K, Epi& epi, Pre pre) {
;     ...
;     const bf16_t* ap = A + (size_t)(NREAL + fr) * lda + wid * ks + fq * 8;
;     const bf16_t* bp = Bt + (size_t)(cb + fr) * ldb + wid * ks + fq * 8;
; #pragma unroll 4
;     for (int k0 = 0; k0 < ks; k0 += 32) {
;       const bf16x8 a = *(const bf16x8*)(ap + k0);
; #pragma unroll
;       for (int bj = 0; bj < 2; ++bj)
; #pragma unroll
;         for (int n = 0; n < 2; ++n) { const bf16x8 b = *(const bf16x8*)(bp + (size_t)(bj * 128 + n * 16) * ldb + k0); acc[bj][n] = __builtin_amdgcn_mfma_f32_16x16x32_bf16(b, a, acc[bj][n], 0, 0, 0); }
.LBB0_1547:
	s_and_b32 s4, s10, 0x60
	s_and_b32 s5, s1, 0xffffff00
	s_or_b32 s4, s5, s4
	v_or_b32_e32 v2, s4, v0
	s_movk_i32 s5, 0x1600
	v_mad_i64_i32 v[34:35], s[8:9], v2, s5, v[24:25]
	v_add_co_u32_e32 v32, vcc, 0x16000, v34
	s_mov_b32 s5, 0xb0000
	s_nop 0
	v_addc_co_u32_e32 v33, vcc, 0, v35, vcc
	v_add_co_u32_e32 v30, vcc, s5, v34
	global_load_dwordx4 v[2:5], v[22:23], off
	global_load_dwordx4 v[6:9], v[34:35], off
	v_addc_co_u32_e32 v31, vcc, 0, v35, vcc
	v_add_co_u32_e32 v28, vcc, 0xc6000, v34
	global_load_dwordx4 v[10:13], v[32:33], off
	s_nop 0
	v_addc_co_u32_e32 v29, vcc, 0, v35, vcc
	global_load_dwordx4 v[14:17], v[30:31], off
	global_load_dwordx4 v[18:21], v[28:29], off
	s_waitcnt vmcnt(3)
	v_mfma_f32_16x16x32_bf16 v[6:9], v[6:9], v[2:5], 0
	s_waitcnt vmcnt(2)
	v_mfma_f32_16x16x32_bf16 v[10:13], v[10:13], v[2:5], 0
	s_waitcnt vmcnt(1)
	v_mfma_f32_16x16x32_bf16 v[14:17], v[14:17], v[2:5], 0
	s_waitcnt vmcnt(0)
	v_mfma_f32_16x16x32_bf16 v[2:5], v[18:21], v[2:5], 0
	global_load_dwordx4 v[18:21], v[22:23], off offset:64
	global_load_dwordx4 v[36:39], v[34:35], off offset:64
	s_waitcnt vmcnt(0)
	v_mfma_f32_16x16x32_bf16 v[6:9], v[36:39], v[18:21], v[6:9]
	global_load_dwordx4 v[36:39], v[32:33], off offset:64
	s_waitcnt vmcnt(0)
	v_mfma_f32_16x16x32_bf16 v[10:13], v[36:39], v[18:21], v[10:13]
	global_load_dwordx4 v[36:39], v[30:31], off offset:64
	s_waitcnt vmcnt(0)
	v_mfma_f32_16x16x32_bf16 v[14:17], v[36:39], v[18:21], v[14:17]
	global_load_dwordx4 v[36:39], v[28:29], off offset:64
	s_waitcnt vmcnt(0)
	v_mfma_f32_16x16x32_bf16 v[2:5], v[36:39], v[18:21], v[2:5]
	global_load_dwordx4 v[18:21], v[22:23], off offset:128
	global_load_dwordx4 v[36:39], v[34:35], off offset:128
	s_waitcnt vmcnt(0)
	v_mfma_f32_16x16x32_bf16 v[6:9], v[36:39], v[18:21], v[6:9]
	global_load_dwordx4 v[36:39], v[32:33], off offset:128
	s_waitcnt vmcnt(0)
	v_mfma_f32_16x16x32_bf16 v[10:13], v[36:39], v[18:21], v[10:13]
	global_load_dwordx4 v[36:39], v[30:31], off offset:128
	s_waitcnt vmcnt(0)
	v_mfma_f32_16x16x32_bf16 v[14:17], v[36:39], v[18:21], v[14:17]
	global_load_dwordx4 v[36:39], v[28:29], off offset:128
	s_waitcnt vmcnt(0)
	v_mfma_f32_16x16x32_bf16 v[2:5], v[36:39], v[18:21], v[2:5]
	global_load_dwordx4 v[18:21], v[22:23], off offset:192
	global_load_dwordx4 v[36:39], v[34:35], off offset:192
	s_waitcnt vmcnt(0)
	v_mfma_f32_16x16x32_bf16 v[6:9], v[36:39], v[18:21], v[6:9]
	global_load_dwordx4 v[36:39], v[32:33], off offset:192
	s_waitcnt vmcnt(0)
	v_mfma_f32_16x16x32_bf16 v[10:13], v[36:39], v[18:21], v[10:13]
	global_load_dwordx4 v[36:39], v[30:31], off offset:192
	s_waitcnt vmcnt(0)
	v_mfma_f32_16x16x32_bf16 v[14:17], v[36:39], v[18:21], v[14:17]
	global_load_dwordx4 v[36:39], v[28:29], off offset:192
	s_waitcnt vmcnt(0)
	v_mfma_f32_16x16x32_bf16 v[2:5], v[36:39], v[18:21], v[2:5]
	global_load_dwordx4 v[18:21], v[22:23], off offset:256
	global_load_dwordx4 v[36:39], v[34:35], off offset:256
	s_waitcnt vmcnt(0)
	v_mfma_f32_16x16x32_bf16 v[6:9], v[36:39], v[18:21], v[6:9]
	global_load_dwordx4 v[36:39], v[32:33], off offset:256
	s_waitcnt vmcnt(0)
	v_mfma_f32_16x16x32_bf16 v[10:13], v[36:39], v[18:21], v[10:13]
	global_load_dwordx4 v[36:39], v[30:31], off offset:256
	s_waitcnt vmcnt(0)
	v_mfma_f32_16x16x32_bf16 v[14:17], v[36:39], v[18:21], v[14:17]
	global_load_dwordx4 v[36:39], v[28:29], off offset:256
	s_waitcnt vmcnt(0)
	v_mfma_f32_16x16x32_bf16 v[2:5], v[36:39], v[18:21], v[2:5]
	global_load_dwordx4 v[18:21], v[22:23], off offset:320
	global_load_dwordx4 v[36:39], v[34:35], off offset:320
	s_waitcnt vmcnt(0)
	v_mfma_f32_16x16x32_bf16 v[6:9], v[36:39], v[18:21], v[6:9]
	global_load_dwordx4 v[36:39], v[32:33], off offset:320
	s_waitcnt vmcnt(0)
	v_mfma_f32_16x16x32_bf16 v[10:13], v[36:39], v[18:21], v[10:13]
	global_load_dwordx4 v[36:39], v[30:31], off offset:320
	s_waitcnt vmcnt(0)
	v_mfma_f32_16x16x32_bf16 v[14:17], v[36:39], v[18:21], v[14:17]
	global_load_dwordx4 v[36:39], v[28:29], off offset:320
	s_waitcnt vmcnt(0)
	v_mfma_f32_16x16x32_bf16 v[2:5], v[36:39], v[18:21], v[2:5]
	global_load_dwordx4 v[18:21], v[22:23], off offset:384
	global_load_dwordx4 v[36:39], v[34:35], off offset:384
	s_waitcnt vmcnt(0)
	v_mfma_f32_16x16x32_bf16 v[6:9], v[36:39], v[18:21], v[6:9]
	global_load_dwordx4 v[36:39], v[32:33], off offset:384
	s_waitcnt vmcnt(0)
	v_mfma_f32_16x16x32_bf16 v[10:13], v[36:39], v[18:21], v[10:13]
	global_load_dwordx4 v[36:39], v[30:31], off offset:384
	s_waitcnt vmcnt(0)
	v_mfma_f32_16x16x32_bf16 v[14:17], v[36:39], v[18:21], v[14:17]
	global_load_dwordx4 v[36:39], v[28:29], off offset:384
	s_waitcnt vmcnt(0)
	v_mfma_f32_16x16x32_bf16 v[2:5], v[36:39], v[18:21], v[2:5]
	global_load_dwordx4 v[18:21], v[22:23], off offset:448
	global_load_dwordx4 v[36:39], v[34:35], off offset:448
	s_waitcnt vmcnt(0)
	v_mfma_f32_16x16x32_bf16 v[6:9], v[36:39], v[18:21], v[6:9]
	global_load_dwordx4 v[36:39], v[32:33], off offset:448
	s_waitcnt vmcnt(0)
	v_mfma_f32_16x16x32_bf16 v[10:13], v[36:39], v[18:21], v[10:13]
	global_load_dwordx4 v[36:39], v[30:31], off offset:448
	s_waitcnt vmcnt(0)
	v_mfma_f32_16x16x32_bf16 v[14:17], v[36:39], v[18:21], v[14:17]
	global_load_dwordx4 v[36:39], v[28:29], off offset:448
	s_waitcnt vmcnt(0)
	v_mfma_f32_16x16x32_bf16 v[2:5], v[36:39], v[18:21], v[2:5]
	global_load_dwordx4 v[18:21], v[22:23], off offset:512
	global_load_dwordx4 v[36:39], v[34:35], off offset:512
	s_waitcnt vmcnt(0)
	v_mfma_f32_16x16x32_bf16 v[6:9], v[36:39], v[18:21], v[6:9]
	global_load_dwordx4 v[36:39], v[32:33], off offset:512
	s_waitcnt vmcnt(0)
	v_mfma_f32_16x16x32_bf16 v[36:39], v[36:39], v[18:21], v[10:13]
	s_nop 2
	global_load_dwordx4 v[10:13], v[30:31], off offset:512
	s_waitcnt vmcnt(0)
; template <class Epi, class Pre>
; __device__ __forceinline__ void meta_gemm(const bf16_t* __restrict__ A, int lda, const bf16_t* __restrict__ Bt, int ldb, int N, int K, Epi& epi, Pre pre) {
;     ...
;         for (int n = 0; n < 2; ++n) { const bf16x8 b = *(const bf16x8*)(bp + (size_t)(bj * 128 + n * 16) * ldb + k0); acc[bj][n] = __builtin_amdgcn_mfma_f32_16x16x32_bf16(b, a, acc[bj][n], 0, 0, 0); }
;     }
; #pragma unroll
;     for (int bj = 0; bj < 2; ++bj)
; #pragma unroll
;       for (int n = 0; n < 2; ++n)
; #pragma unroll
;         for (int j = 0; j < 4; ++j) part[(wid * 16 + (bj * 2 + n) * 4 + j) * 64 + lane] = acc[bj][n][j];
;     __syncthreads();
;     if (wid < 4) {
;       f32x4 v[2][2];
; #pragma unroll
;       for (int bj = 0; bj < 2; ++bj)
; #pragma unroll
;         for (int n = 0; n < 2; ++n)
; #pragma unroll
;           for (int j = 0; j < 4; ++j) { float s = 0.f;
; #pragma unroll
;             for (int w = 0; w < 8; ++w) s += part[(w * 16 + (bj * 2 + n) * 4 + j) * 64 + lane];
	v_mfma_f32_16x16x32_bf16 v[44:47], v[10:13], v[18:21], v[14:17]
	global_load_dwordx4 v[10:13], v[28:29], off offset:512
	s_waitcnt vmcnt(0)
	v_mfma_f32_16x16x32_bf16 v[2:5], v[10:13], v[18:21], v[2:5]
	global_load_dwordx4 v[18:21], v[22:23], off offset:576
	global_load_dwordx4 v[10:13], v[34:35], off offset:576
	s_waitcnt vmcnt(0)
	v_mfma_f32_16x16x32_bf16 v[10:13], v[10:13], v[18:21], v[6:9]
	s_nop 2
	global_load_dwordx4 v[6:9], v[32:33], off offset:576
	s_waitcnt vmcnt(0)
	v_mfma_f32_16x16x32_bf16 v[14:17], v[6:9], v[18:21], v[36:39]
	global_load_dwordx4 v[6:9], v[30:31], off offset:576
	s_nop 1
	global_load_dwordx4 v[36:39], v[28:29], off offset:576
	s_waitcnt vmcnt(1)
	v_mfma_f32_16x16x32_bf16 v[6:9], v[6:9], v[18:21], v[44:47]
	s_waitcnt vmcnt(0)
	v_mfma_f32_16x16x32_bf16 v[2:5], v[36:39], v[18:21], v[2:5]
	global_load_dwordx4 v[18:21], v[22:23], off offset:640
	s_nop 0
	global_load_dwordx4 v[34:37], v[34:35], off offset:640
	s_waitcnt vmcnt(0)
	v_mfma_f32_16x16x32_bf16 v[10:13], v[34:37], v[18:21], v[10:13]
	global_load_dwordx4 v[32:35], v[32:33], off offset:640
	s_waitcnt vmcnt(0)
	v_mfma_f32_16x16x32_bf16 v[14:17], v[32:35], v[18:21], v[14:17]
	global_load_dwordx4 v[30:33], v[30:31], off offset:640
	s_waitcnt vmcnt(0)
	v_mfma_f32_16x16x32_bf16 v[6:9], v[30:33], v[18:21], v[6:9]
	global_load_dwordx4 v[28:31], v[28:29], off offset:640
	s_waitcnt vmcnt(0)
	v_mfma_f32_16x16x32_bf16 v[2:5], v[28:31], v[18:21], v[2:5]
	ds_write2st64_b32 v43, v10, v11 offset1:1
	ds_write2st64_b32 v43, v12, v13 offset0:2 offset1:3
	ds_write2st64_b32 v43, v14, v15 offset0:4 offset1:5
	ds_write2st64_b32 v43, v16, v17 offset0:6 offset1:7
	s_nop 0
	ds_write2st64_b32 v43, v6, v7 offset0:8 offset1:9
	ds_write2st64_b32 v43, v8, v9 offset0:10 offset1:11
	s_nop 0
	ds_write2st64_b32 v43, v2, v3 offset0:12 offset1:13
	ds_write2st64_b32 v43, v4, v5 offset0:14 offset1:15
	s_waitcnt lgkmcnt(0)
	s_barrier
	s_and_saveexec_b64 s[8:9], s[2:3]
	s_cbranch_execz .LBB0_1546
	ds_read2st64_b32 v[2:3], v42 offset1:1
	ds_read2st64_b32 v[4:5], v42 offset0:16 offset1:17
	ds_read2st64_b32 v[6:7], v42 offset0:32 offset1:33
	ds_read2st64_b32 v[8:9], v42 offset0:48 offset1:49
	ds_read2st64_b32 v[10:11], v42 offset0:64 offset1:65
	ds_read2st64_b32 v[12:13], v42 offset0:80 offset1:81
	ds_read2st64_b32 v[14:15], v42 offset0:96 offset1:97
	ds_read2st64_b32 v[16:17], v42 offset0:112 offset1:113
	ds_read2st64_b32 v[18:19], v42 offset0:2 offset1:3
	ds_read2st64_b32 v[20:21], v42 offset0:18 offset1:19
	ds_read2st64_b32 v[28:29], v42 offset0:34 offset1:35
	ds_read2st64_b32 v[30:31], v42 offset0:50 offset1:51
	ds_read2st64_b32 v[32:33], v42 offset0:66 offset1:67
	ds_read2st64_b32 v[34:35], v42 offset0:82 offset1:83
	ds_read2st64_b32 v[36:37], v42 offset0:98 offset1:99
	ds_read2st64_b32 v[38:39], v42 offset0:114 offset1:115
	s_waitcnt lgkmcnt(7)
	v_pk_add_f32 v[18:19], v[18:19], 0 op_sel_hi:[1,0]
	v_pk_add_f32 v[2:3], v[2:3], 0 op_sel_hi:[1,0]
	s_ashr_i32 s5, s4, 31
	v_pk_add_f32 v[2:3], v[2:3], v[4:5]
	s_waitcnt lgkmcnt(6)
	v_pk_add_f32 v[4:5], v[18:19], v[20:21]
	v_pk_add_f32 v[2:3], v[2:3], v[6:7]
	s_waitcnt lgkmcnt(5)
	v_pk_add_f32 v[4:5], v[4:5], v[28:29]
	v_pk_add_f32 v[2:3], v[2:3], v[8:9]
	s_waitcnt lgkmcnt(4)
	v_pk_add_f32 v[4:5], v[4:5], v[30:31]
	v_pk_add_f32 v[2:3], v[2:3], v[10:11]
	s_waitcnt lgkmcnt(3)
	v_pk_add_f32 v[4:5], v[4:5], v[32:33]
	v_pk_add_f32 v[2:3], v[2:3], v[12:13]
	s_waitcnt lgkmcnt(2)
	v_pk_add_f32 v[4:5], v[4:5], v[34:35]
	v_pk_add_f32 v[2:3], v[2:3], v[14:15]
	s_waitcnt lgkmcnt(1)
	v_pk_add_f32 v[4:5], v[4:5], v[36:37]
	v_pk_add_f32 v[18:19], v[2:3], v[16:17]
	s_waitcnt lgkmcnt(0)
	v_pk_add_f32 v[20:21], v[4:5], v[38:39]
	ds_read2st64_b32 v[2:3], v42 offset0:4 offset1:5
	ds_read2st64_b32 v[4:5], v42 offset0:20 offset1:21
	ds_read2st64_b32 v[6:7], v42 offset0:36 offset1:37
	ds_read2st64_b32 v[8:9], v42 offset0:52 offset1:53
	ds_read2st64_b32 v[10:11], v42 offset0:68 offset1:69
	ds_read2st64_b32 v[12:13], v42 offset0:84 offset1:85
	ds_read2st64_b32 v[14:15], v42 offset0:100 offset1:101
	ds_read2st64_b32 v[16:17], v42 offset0:116 offset1:117
	ds_read2st64_b32 v[28:29], v42 offset0:6 offset1:7
	ds_read2st64_b32 v[30:31], v42 offset0:22 offset1:23
	ds_read2st64_b32 v[32:33], v42 offset0:38 offset1:39
	ds_read2st64_b32 v[34:35], v42 offset0:54 offset1:55
	ds_read2st64_b32 v[36:37], v42 offset0:70 offset1:71
	ds_read2st64_b32 v[38:39], v42 offset0:86 offset1:87
	ds_read2st64_b32 v[40:41], v42 offset0:102 offset1:103
	ds_read2st64_b32 v[44:45], v42 offset0:118 offset1:119
	s_waitcnt lgkmcnt(7)
	v_pk_add_f32 v[28:29], v[28:29], 0 op_sel_hi:[1,0]
	v_pk_add_f32 v[2:3], v[2:3], 0 op_sel_hi:[1,0]
	s_nop 0
	v_pk_add_f32 v[2:3], v[2:3], v[4:5]
	s_waitcnt lgkmcnt(6)
	v_pk_add_f32 v[4:5], v[28:29], v[30:31]
	v_pk_add_f32 v[2:3], v[2:3], v[6:7]
	s_waitcnt lgkmcnt(5)
; template <class Epi, class Pre>
; __device__ __forceinline__ void meta_gemm(const bf16_t* __restrict__ A, int lda, const bf16_t* __restrict__ Bt, int ldb, int N, int K, Epi& epi, Pre pre) {
;     ...
;           for (int j = 0; j < 4; ++j) { float s = 0.f;
; #pragma unroll
;             for (int w = 0; w < 8; ++w) s += part[(w * 16 + (bj * 2 + n) * 4 + j) * 64 + lane];
;             v[bj][n][j] = s; }
;       pre(fr, fq);
;       epi(NREAL + 16 * wid + fr, cb, fq, v[0][0], v[0][1], v[1][0], v[1][1]);
	v_pk_add_f32 v[4:5], v[4:5], v[32:33]
	v_pk_add_f32 v[2:3], v[2:3], v[8:9]
	s_waitcnt lgkmcnt(4)
	v_pk_add_f32 v[4:5], v[4:5], v[34:35]
	v_pk_add_f32 v[2:3], v[2:3], v[10:11]
	s_waitcnt lgkmcnt(3)
	v_pk_add_f32 v[4:5], v[4:5], v[36:37]
	v_pk_add_f32 v[2:3], v[2:3], v[12:13]
	s_waitcnt lgkmcnt(2)
	v_pk_add_f32 v[4:5], v[4:5], v[38:39]
	v_pk_add_f32 v[2:3], v[2:3], v[14:15]
	s_waitcnt lgkmcnt(1)
	v_pk_add_f32 v[4:5], v[4:5], v[40:41]
	v_pk_add_f32 v[28:29], v[2:3], v[16:17]
	s_waitcnt lgkmcnt(0)
	v_pk_add_f32 v[30:31], v[4:5], v[44:45]
	ds_read2st64_b32 v[2:3], v42 offset0:8 offset1:9
	ds_read2st64_b32 v[4:5], v42 offset0:24 offset1:25
	ds_read2st64_b32 v[6:7], v42 offset0:40 offset1:41
	ds_read2st64_b32 v[8:9], v42 offset0:56 offset1:57
	ds_read2st64_b32 v[10:11], v42 offset0:72 offset1:73
	ds_read2st64_b32 v[12:13], v42 offset0:88 offset1:89
	ds_read2st64_b32 v[14:15], v42 offset0:104 offset1:105
	ds_read2st64_b32 v[16:17], v42 offset0:120 offset1:121
	ds_read2st64_b32 v[32:33], v42 offset0:10 offset1:11
	ds_read2st64_b32 v[34:35], v42 offset0:26 offset1:27
	ds_read2st64_b32 v[36:37], v42 offset0:42 offset1:43
	ds_read2st64_b32 v[38:39], v42 offset0:58 offset1:59
	ds_read2st64_b32 v[40:41], v42 offset0:74 offset1:75
	ds_read2st64_b32 v[44:45], v42 offset0:90 offset1:91
	ds_read2st64_b32 v[46:47], v42 offset0:106 offset1:107
	ds_read2st64_b32 v[48:49], v42 offset0:122 offset1:123
	s_waitcnt lgkmcnt(7)
	v_pk_add_f32 v[32:33], v[32:33], 0 op_sel_hi:[1,0]
	v_pk_add_f32 v[2:3], v[2:3], 0 op_sel_hi:[1,0]
	s_nop 0
	v_pk_add_f32 v[2:3], v[2:3], v[4:5]
	s_waitcnt lgkmcnt(6)
	v_pk_add_f32 v[4:5], v[32:33], v[34:35]
	v_pk_add_f32 v[2:3], v[2:3], v[6:7]
	s_waitcnt lgkmcnt(5)
	v_pk_add_f32 v[4:5], v[4:5], v[36:37]
	v_pk_add_f32 v[2:3], v[2:3], v[8:9]
	s_waitcnt lgkmcnt(4)
	v_pk_add_f32 v[4:5], v[4:5], v[38:39]
	v_pk_add_f32 v[2:3], v[2:3], v[10:11]
	s_waitcnt lgkmcnt(3)
	v_pk_add_f32 v[4:5], v[4:5], v[40:41]
	v_pk_add_f32 v[2:3], v[2:3], v[12:13]
	s_waitcnt lgkmcnt(2)
	v_pk_add_f32 v[4:5], v[4:5], v[44:45]
	v_pk_add_f32 v[2:3], v[2:3], v[14:15]
	s_waitcnt lgkmcnt(1)
	v_pk_add_f32 v[4:5], v[4:5], v[46:47]
	v_pk_add_f32 v[32:33], v[2:3], v[16:17]
	s_waitcnt lgkmcnt(0)
	v_pk_add_f32 v[34:35], v[4:5], v[48:49]
	ds_read2st64_b32 v[2:3], v42 offset0:12 offset1:13
	ds_read2st64_b32 v[4:5], v42 offset0:28 offset1:29
	ds_read2st64_b32 v[6:7], v42 offset0:44 offset1:45
	ds_read2st64_b32 v[8:9], v42 offset0:60 offset1:61
	ds_read2st64_b32 v[10:11], v42 offset0:76 offset1:77
	ds_read2st64_b32 v[12:13], v42 offset0:92 offset1:93
	ds_read2st64_b32 v[14:15], v42 offset0:108 offset1:109
	ds_read2st64_b32 v[16:17], v42 offset0:124 offset1:125
	ds_read2st64_b32 v[36:37], v42 offset0:14 offset1:15
	ds_read2st64_b32 v[38:39], v42 offset0:30 offset1:31
	ds_read2st64_b32 v[40:41], v42 offset0:46 offset1:47
	ds_read2st64_b32 v[44:45], v42 offset0:62 offset1:63
	ds_read2st64_b32 v[46:47], v42 offset0:78 offset1:79
	ds_read2st64_b32 v[48:49], v42 offset0:94 offset1:95
	ds_read2st64_b32 v[50:51], v42 offset0:110 offset1:111
	ds_read2st64_b32 v[52:53], v42 offset0:126 offset1:127
	s_waitcnt lgkmcnt(7)
	v_pk_add_f32 v[36:37], v[36:37], 0 op_sel_hi:[1,0]
	v_pk_add_f32 v[2:3], v[2:3], 0 op_sel_hi:[1,0]
	s_nop 0
	v_pk_add_f32 v[2:3], v[2:3], v[4:5]
	s_waitcnt lgkmcnt(6)
	v_pk_add_f32 v[4:5], v[36:37], v[38:39]
	v_pk_add_f32 v[2:3], v[2:3], v[6:7]
	s_waitcnt lgkmcnt(5)
	v_pk_add_f32 v[4:5], v[4:5], v[40:41]
	v_pk_add_f32 v[2:3], v[2:3], v[8:9]
	s_waitcnt lgkmcnt(4)
	v_pk_add_f32 v[4:5], v[4:5], v[44:45]
	v_pk_add_f32 v[2:3], v[2:3], v[10:11]
	s_waitcnt lgkmcnt(3)
	v_pk_add_f32 v[4:5], v[4:5], v[46:47]
	v_pk_add_f32 v[2:3], v[2:3], v[12:13]
	s_waitcnt lgkmcnt(2)
	v_pk_add_f32 v[4:5], v[4:5], v[48:49]
	v_pk_add_f32 v[2:3], v[2:3], v[14:15]
	s_waitcnt lgkmcnt(1)
	v_pk_add_f32 v[4:5], v[4:5], v[50:51]
	v_lshl_add_u64 v[40:41], s[4:5], 2, v[26:27]
	v_pk_add_f32 v[36:37], v[2:3], v[16:17]
	s_waitcnt lgkmcnt(0)
	v_pk_add_f32 v[38:39], v[4:5], v[52:53]
	global_load_dwordx4 v[2:5], v[40:41], off
	global_load_dwordx4 v[6:9], v[40:41], off offset:64
	global_load_dwordx4 v[10:13], v[40:41], off offset:512
	global_load_dwordx4 v[14:17], v[40:41], off offset:576
	s_waitcnt vmcnt(3)
	v_pk_add_f32 v[4:5], v[20:21], v[4:5]
	v_pk_add_f32 v[2:3], v[18:19], v[2:3]
	global_store_dwordx4 v[40:41], v[2:5], off sc0 sc1
	s_waitcnt vmcnt(3)
	s_nop 0
	v_pk_add_f32 v[4:5], v[30:31], v[8:9]
	v_pk_add_f32 v[2:3], v[28:29], v[6:7]
	global_store_dwordx4 v[40:41], v[2:5], off offset:64 sc0 sc1
	s_waitcnt vmcnt(3)
	s_nop 0
	v_pk_add_f32 v[4:5], v[34:35], v[12:13]
	v_pk_add_f32 v[2:3], v[32:33], v[10:11]
	global_store_dwordx4 v[40:41], v[2:5], off offset:512 sc0 sc1
	s_waitcnt vmcnt(3)
	s_nop 0
	v_pk_add_f32 v[4:5], v[38:39], v[16:17]
	v_pk_add_f32 v[2:3], v[36:37], v[14:15]
	global_store_dwordx4 v[40:41], v[2:5], off offset:576 sc0 sc1
	s_branch .LBB0_1546

;     ...
; #pragma unroll
;     for (int ai = 0; ai < 2; ++ai)
; #pragma unroll
;       for (int m = 0; m < 4; ++m)
;         epi(brow + ai * HALF + wr * 64 + m * 16 + fr, bcol + wc * 32, fq, acc[ai][0][m][0], acc[ai][0][m][1], acc[ai][1][m][0], acc[ai][1][m][1]);
;   }
.LBB0_1564:
	v_or_b32_e32 v0, s16, v140
	v_add_u32_e32 v136, v0, v141
	v_ashrrev_i32_e32 v137, 31, v136
	v_readlane_b32 s4, v253, 60
	v_lshl_or_b32 v0, v139, 5, s15
	v_lshlrev_b64 v[132:133], 12, v[136:137]
	v_readlane_b32 s5, v253, 61
	v_lshlrev_b64 v[134:135], 2, v[0:1]
	v_mov_b32_e32 v131, v1
	v_lshl_add_u64 v[132:133], s[4:5], 0, v[132:133]
	v_lshl_add_u64 v[132:133], v[132:133], 0, v[134:135]
	v_lshl_add_u64 v[132:133], v[132:133], 0, v[130:131]
	global_load_dwordx4 v[138:141], v[132:133], off
	global_load_dwordx4 v[142:145], v[132:133], off offset:64
	global_load_dwordx4 v[146:149], v[132:133], off offset:512
	global_load_dwordx4 v[150:153], v[132:133], off offset:576
	v_cndmask_b32_e64 v0, 0, 1, s[2:3]
	s_waitcnt vmcnt(0)
	v_pk_add_f32 v[120:121], v[120:121], v[140:141]
	v_pk_add_f32 v[116:117], v[116:117], v[144:145]
	v_pk_add_f32 v[114:115], v[114:115], v[142:143]
	global_store_dwordx4 v[132:133], v[114:117], off offset:64 sc0 sc1
	v_pk_add_f32 v[118:119], v[118:119], v[138:139]
	global_store_dwordx4 v[132:133], v[118:121], off sc0 sc1
	v_pk_add_f32 v[116:117], v[128:129], v[148:149]
	v_pk_add_f32 v[114:115], v[126:127], v[146:147]
	global_store_dwordx4 v[132:133], v[114:117], off offset:512 sc0 sc1
	s_nop 1
	v_pk_add_f32 v[116:117], v[124:125], v[152:153]
	v_pk_add_f32 v[114:115], v[122:123], v[150:151]
	global_store_dwordx4 v[132:133], v[114:117], off offset:576 sc0 sc1
	s_nop 1
	v_or_b32_e32 v114, 16, v136
	v_ashrrev_i32_e32 v115, 31, v114
	v_lshlrev_b64 v[114:115], 12, v[114:115]
	v_lshl_add_u64 v[114:115], s[4:5], 0, v[114:115]
	v_lshl_add_u64 v[114:115], v[114:115], 0, v[134:135]
	v_lshl_add_u64 v[138:139], v[114:115], 0, v[130:131]
	global_load_dwordx4 v[114:117], v[138:139], off
	global_load_dwordx4 v[118:121], v[138:139], off offset:64
	global_load_dwordx4 v[122:125], v[138:139], off offset:512
	global_load_dwordx4 v[126:129], v[138:139], off offset:576
	s_waitcnt vmcnt(0)
	v_pk_add_f32 v[104:105], v[104:105], v[116:117]
	v_pk_add_f32 v[100:101], v[100:101], v[120:121]
	v_pk_add_f32 v[98:99], v[98:99], v[118:119]
	global_store_dwordx4 v[138:139], v[98:101], off offset:64 sc0 sc1
	v_pk_add_f32 v[102:103], v[102:103], v[114:115]
	global_store_dwordx4 v[138:139], v[102:105], off sc0 sc1
	v_pk_add_f32 v[100:101], v[112:113], v[124:125]
	v_pk_add_f32 v[98:99], v[110:111], v[122:123]
	global_store_dwordx4 v[138:139], v[98:101], off offset:512 sc0 sc1
	s_nop 1
	v_pk_add_f32 v[100:101], v[108:109], v[128:129]
	v_pk_add_f32 v[98:99], v[106:107], v[126:127]
	global_store_dwordx4 v[138:139], v[98:101], off offset:576 sc0 sc1
	s_nop 1
	v_or_b32_e32 v98, 32, v136
	v_ashrrev_i32_e32 v99, 31, v98
	v_lshlrev_b64 v[98:99], 12, v[98:99]
	v_lshl_add_u64 v[98:99], s[4:5], 0, v[98:99]
	v_lshl_add_u64 v[98:99], v[98:99], 0, v[134:135]
	v_lshl_add_u64 v[114:115], v[98:99], 0, v[130:131]
	global_load_dwordx4 v[98:101], v[114:115], off
	global_load_dwordx4 v[102:105], v[114:115], off offset:64
	global_load_dwordx4 v[106:109], v[114:115], off offset:512
	global_load_dwordx4 v[110:113], v[114:115], off offset:576
	s_waitcnt vmcnt(0)
	v_pk_add_f32 v[88:89], v[88:89], v[100:101]
	v_pk_add_f32 v[84:85], v[84:85], v[104:105]
	v_pk_add_f32 v[82:83], v[82:83], v[102:103]
	global_store_dwordx4 v[114:115], v[82:85], off offset:64 sc0 sc1
	v_pk_add_f32 v[86:87], v[86:87], v[98:99]
	global_store_dwordx4 v[114:115], v[86:89], off sc0 sc1
	v_pk_add_f32 v[84:85], v[96:97], v[108:109]
	v_pk_add_f32 v[82:83], v[94:95], v[106:107]
	global_store_dwordx4 v[114:115], v[82:85], off offset:512 sc0 sc1
	s_nop 1
	v_pk_add_f32 v[84:85], v[92:93], v[112:113]
	v_pk_add_f32 v[82:83], v[90:91], v[110:111]
	global_store_dwordx4 v[114:115], v[82:85], off offset:576 sc0 sc1
	s_nop 1
	v_or_b32_e32 v82, 48, v136
	v_ashrrev_i32_e32 v83, 31, v82
	v_lshlrev_b64 v[82:83], 12, v[82:83]
	v_lshl_add_u64 v[82:83], s[4:5], 0, v[82:83]
	v_lshl_add_u64 v[82:83], v[82:83], 0, v[134:135]
	v_lshl_add_u64 v[98:99], v[82:83], 0, v[130:131]
	global_load_dwordx4 v[82:85], v[98:99], off
	global_load_dwordx4 v[86:89], v[98:99], off offset:64
	global_load_dwordx4 v[90:93], v[98:99], off offset:512
	global_load_dwordx4 v[94:97], v[98:99], off offset:576
	s_mov_b64 s[4:5], 0x80000
	s_waitcnt vmcnt(0)
; #define WAIT_V(n) asm volatile("s_waitcnt vmcnt(" #n ")" ::: "memory")
;     ...
; #pragma unroll
;     for (int ai = 0; ai < 2; ++ai)
; #pragma unroll
;       for (int m = 0; m < 4; ++m)
;         epi(brow + ai * HALF + wr * 64 + m * 16 + fr, bcol + wc * 32, fq, acc[ai][0][m][0], acc[ai][0][m][1], acc[ai][1][m][0], acc[ai][1][m][1]);
;   }
;   if (!have_next) { WAIT_V(0); __syncthreads(); }
	v_pk_add_f32 v[70:71], v[70:71], v[82:83]
	v_pk_add_f32 v[68:69], v[68:69], v[88:89]
	v_pk_add_f32 v[66:67], v[66:67], v[86:87]
	global_store_dwordx4 v[98:99], v[66:69], off offset:64 sc0 sc1
	v_lshl_add_u64 v[82:83], v[132:133], 0, s[4:5]
	s_mov_b32 s4, 0x80000
	v_pk_add_f32 v[68:69], v[80:81], v[92:93]
	v_pk_add_f32 v[66:67], v[78:79], v[90:91]
	v_pk_add_f32 v[72:73], v[72:73], v[84:85]
	global_store_dwordx4 v[98:99], v[66:69], off offset:512 sc0 sc1
	v_add_co_u32_e32 v84, vcc, s4, v132
	s_nop 0
	v_pk_add_f32 v[68:69], v[76:77], v[96:97]
	v_pk_add_f32 v[66:67], v[74:75], v[94:95]
	global_store_dwordx4 v[98:99], v[70:73], off sc0 sc1
	global_store_dwordx4 v[98:99], v[66:69], off offset:576 sc0 sc1
	v_addc_co_u32_e32 v85, vcc, 0, v133, vcc
	global_load_dwordx4 v[66:69], v[84:85], off
	global_load_dwordx4 v[70:73], v[82:83], off offset:64
	global_load_dwordx4 v[74:77], v[82:83], off offset:512
	global_load_dwordx4 v[78:81], v[82:83], off offset:576
	s_mov_b64 s[4:5], 0x90000
	s_waitcnt vmcnt(0)
	v_pk_add_f32 v[54:55], v[54:55], v[66:67]
	v_pk_add_f32 v[52:53], v[52:53], v[72:73]
	v_pk_add_f32 v[50:51], v[50:51], v[70:71]
	global_store_dwordx4 v[82:83], v[50:53], off offset:64 sc0 sc1
	v_lshl_add_u64 v[66:67], v[132:133], 0, s[4:5]
	s_mov_b32 s4, 0x90000
	v_pk_add_f32 v[52:53], v[64:65], v[76:77]
	v_pk_add_f32 v[50:51], v[62:63], v[74:75]
	v_pk_add_f32 v[56:57], v[56:57], v[68:69]
	global_store_dwordx4 v[82:83], v[50:53], off offset:512 sc0 sc1
	v_add_co_u32_e32 v68, vcc, s4, v132
	s_nop 0
	v_pk_add_f32 v[52:53], v[60:61], v[80:81]
	v_pk_add_f32 v[50:51], v[58:59], v[78:79]
	global_store_dwordx4 v[84:85], v[54:57], off sc0 sc1
	global_store_dwordx4 v[82:83], v[50:53], off offset:576 sc0 sc1
	v_addc_co_u32_e32 v69, vcc, 0, v133, vcc
	global_load_dwordx4 v[50:53], v[68:69], off
	global_load_dwordx4 v[54:57], v[66:67], off offset:64
	global_load_dwordx4 v[58:61], v[66:67], off offset:512
	global_load_dwordx4 v[62:65], v[66:67], off offset:576
	s_mov_b64 s[4:5], 0xa0000
	s_waitcnt vmcnt(0)
	v_pk_add_f32 v[38:39], v[38:39], v[50:51]
	v_pk_add_f32 v[36:37], v[36:37], v[56:57]
	v_pk_add_f32 v[34:35], v[34:35], v[54:55]
	global_store_dwordx4 v[66:67], v[34:37], off offset:64 sc0 sc1
	v_lshl_add_u64 v[50:51], v[132:133], 0, s[4:5]
	s_mov_b32 s4, 0xa0000
	v_pk_add_f32 v[36:37], v[48:49], v[60:61]
	v_pk_add_f32 v[34:35], v[46:47], v[58:59]
	v_pk_add_f32 v[40:41], v[40:41], v[52:53]
	global_store_dwordx4 v[66:67], v[34:37], off offset:512 sc0 sc1
	v_add_co_u32_e32 v52, vcc, s4, v132
	s_nop 0
	v_pk_add_f32 v[36:37], v[44:45], v[64:65]
	v_pk_add_f32 v[34:35], v[42:43], v[62:63]
	global_store_dwordx4 v[68:69], v[38:41], off sc0 sc1
	global_store_dwordx4 v[66:67], v[34:37], off offset:576 sc0 sc1
	v_addc_co_u32_e32 v53, vcc, 0, v133, vcc
	global_load_dwordx4 v[34:37], v[52:53], off
	global_load_dwordx4 v[38:41], v[50:51], off offset:64
	global_load_dwordx4 v[42:45], v[50:51], off offset:512
	global_load_dwordx4 v[46:49], v[50:51], off offset:576
	s_mov_b64 s[4:5], 0xb0000
	s_waitcnt vmcnt(0)
	v_pk_add_f32 v[22:23], v[22:23], v[34:35]
	v_pk_add_f32 v[20:21], v[20:21], v[40:41]
	v_pk_add_f32 v[18:19], v[18:19], v[38:39]
	global_store_dwordx4 v[50:51], v[18:21], off offset:64 sc0 sc1
	v_lshl_add_u64 v[34:35], v[132:133], 0, s[4:5]
	s_mov_b32 s4, 0xb0000
	v_pk_add_f32 v[20:21], v[32:33], v[44:45]
	v_pk_add_f32 v[18:19], v[30:31], v[42:43]
	v_pk_add_f32 v[24:25], v[24:25], v[36:37]
	global_store_dwordx4 v[50:51], v[18:21], off offset:512 sc0 sc1
	v_add_co_u32_e32 v36, vcc, s4, v132
	s_nop 0
	v_pk_add_f32 v[20:21], v[28:29], v[48:49]
	v_pk_add_f32 v[18:19], v[26:27], v[46:47]
	global_store_dwordx4 v[52:53], v[22:25], off sc0 sc1
	global_store_dwordx4 v[50:51], v[18:21], off offset:576 sc0 sc1
	v_addc_co_u32_e32 v37, vcc, 0, v133, vcc
	global_load_dwordx4 v[30:33], v[36:37], off
	global_load_dwordx4 v[26:29], v[34:35], off offset:64
	global_load_dwordx4 v[22:25], v[34:35], off offset:512
	global_load_dwordx4 v[18:21], v[34:35], off offset:576
	v_cmp_ne_u32_e64 s[4:5], 1, v0
	s_andn2_b64 vcc, exec, s[2:3]
	s_waitcnt vmcnt(0)
	v_pk_add_f32 v[16:17], v[16:17], v[32:33]
	v_pk_add_f32 v[8:9], v[8:9], v[28:29]
	v_pk_add_f32 v[6:7], v[6:7], v[26:27]
	v_pk_add_f32 v[14:15], v[14:15], v[30:31]
	global_store_dwordx4 v[34:35], v[6:9], off offset:64 sc0 sc1
	v_pk_add_f32 v[4:5], v[4:5], v[20:21]
	v_pk_add_f32 v[2:3], v[2:3], v[18:19]
	v_pk_add_f32 v[8:9], v[12:13], v[24:25]
	v_pk_add_f32 v[6:7], v[10:11], v[22:23]
	global_store_dwordx4 v[36:37], v[14:17], off sc0 sc1
	global_store_dwordx4 v[34:35], v[6:9], off offset:512 sc0 sc1
	global_store_dwordx4 v[34:35], v[2:5], off offset:576 sc0 sc1
	s_cbranch_vccnz .LBB0_1551
	s_waitcnt vmcnt(0)
	s_waitcnt lgkmcnt(0)
	s_barrier
	s_branch .LBB0_1551

; __global__ void __launch_bounds__(512) mega(Params P) {
;     ...
;     grid.sync();
.LBB0_1567:
	buffer_wbl2 sc1
	s_load_dwordx2 s[4:5], s[56:57], -0x8
	s_load_dword s0, s[56:57], 0x0
	v_readlane_b32 s1, v253, 55
	s_waitcnt lgkmcnt(0)
	s_and_b32 s1, s1, 7
	s_add_i32 s6, s0, 7
	s_sub_i32 s6, s6, s1
	s_lshr_b32 s6, s6, 3
	s_min_u32 s7, s0, 8
	s_lshl_b32 s1, s1, 2
	s_addk_i32 s1, 0x88
	v_mov_b32_e32 v2, s1
	global_load_dword v0, v1, s[4:5] sc1
	v_mov_b32_e32 v3, 1
	s_waitcnt vmcnt(0)
	v_and_b32_e32 v0, 0xffff0000, v0
	global_atomic_add v3, v2, v3, s[4:5] sc0
	s_waitcnt vmcnt(0)
	v_and_b32_e32 v3, 0xffff, v3
	s_nop 0
	v_readfirstlane_b32 s1, v3
	s_nop 3
	s_add_i32 s0, s6, -1
	s_cmp_lg_u32 s1, s0
	s_cbranch_scc1 .Lgb_poll_7
	s_sub_i32 s1, 0x10000, s6
	v_mov_b32_e32 v3, s1
	global_atomic_add v3, v2, v3, s[4:5] sc0
	s_waitcnt vmcnt(0)
	v_mov_b32_e32 v3, 1
	global_atomic_add v3, v1, v3, s[4:5] sc0
	s_waitcnt vmcnt(0)
	v_and_b32_e32 v3, 0xffff, v3
	s_nop 0
	v_readfirstlane_b32 s1, v3
	s_nop 3
	s_add_i32 s0, s7, -1
	s_cmp_lg_u32 s1, s0
	s_cbranch_scc1 .Lgb_poll_7
	s_sub_i32 s1, 0x10000, s7
	v_mov_b32_e32 v3, s1
	global_atomic_add v1, v3, s[4:5]

; __global__ void __launch_bounds__(512) mega(Params P) {
;     ...
;     grid.sync();
.Lgb_done_7:
	s_getpc_b64 s[98:99]

; __device__ __forceinline__ void final_phase(const float* H, const float* g, float* out) {
;     ...
;   for (int row = gw; row < NREAL; row += 2 * nw) {
;     const int row2 = row + nw < NREAL ? row + nw : row;
;     const float* p = H + (size_t)row * DM + lane * 4; const float* p2 = H + (size_t)row2 * DM + lane * 4; f32x4 v[4], u[4]; float ss = 0.f, ss2 = 0.f;
; #pragma unroll
;     for (int i = 0; i < 4; ++i) { v[i] = *(const f32x4*)(p + 256 * i); u[i] = *(const f32x4*)(p2 + 256 * i); }
; #pragma unroll
;     for (int i = 0; i < 4; ++i) { ss += v[i][0] * v[i][0] + v[i][1] * v[i][1] + v[i][2] * v[i][2] + v[i][3] * v[i][3]; ss2 += u[i][0] * u[i][0] + u[i][1] * u[i][1] + u[i][2] * u[i][2] + u[i][3] * u[i][3]; }
;     ss = wave_sum(ss); ss2 = wave_sum(ss2); const float rs = rsqrtf(ss * (1.0f / 1024.0f) + 1e-6f), rs2 = rsqrtf(ss2 * (1.0f / 1024.0f) + 1e-6f);
;     float* q = out + (size_t)row * DM + lane * 4; float* q2 = out + (size_t)row2 * DM + lane * 4;
; #pragma unroll
;     for (int i = 0; i < 4; ++i) { *(f32x4*)(q + 256 * i) = v[i] * rs * gv[i]; *(f32x4*)(q2 + 256 * i) = u[i] * rs2 * gv[i]; }
;   }
.LBB0_1577:
	v_add_u32_e32 v21, s16, v22
	v_ashrrev_i32_e32 v23, 31, v22
	v_cmp_gt_i32_e32 vcc, s5, v21
	v_lshlrev_b64 v[24:25], 12, v[22:23]
	v_lshl_add_u64 v[42:43], v[16:17], 0, v[24:25]
	v_cndmask_b32_e32 v40, v22, v21, vcc
	v_ashrrev_i32_e32 v41, 31, v40
	v_lshl_add_u64 v[56:57], v[18:19], 0, v[24:25]
	global_load_dwordx4 v[24:27], v[42:43], off
	global_load_dwordx4 v[28:31], v[42:43], off offset:1024
	global_load_dwordx4 v[32:35], v[42:43], off offset:2048
	global_load_dwordx4 v[36:39], v[42:43], off offset:3072
	v_lshlrev_b64 v[40:41], 12, v[40:41]
	v_lshl_add_u64 v[58:59], v[16:17], 0, v[40:41]
	v_lshl_add_u64 v[60:61], v[18:19], 0, v[40:41]
	global_load_dwordx4 v[40:43], v[58:59], off
	global_load_dwordx4 v[44:47], v[58:59], off offset:1024
	global_load_dwordx4 v[48:51], v[58:59], off offset:2048
	global_load_dwordx4 v[52:55], v[58:59], off offset:3072
	v_mov_b32_e32 v62, v210
	v_mov_b32_e32 v63, v210
	v_add_u32_e32 v22, s16, v21
	v_lshlrev_b32_e32 v21, 2, v62
	v_lshlrev_b32_e32 v23, 2, v63
	v_xor_b32_e32 v21, 0x80, v21
	v_xor_b32_e32 v23, 0x80, v23
	v_cmp_lt_i32_e32 vcc, s7, v22
	s_or_b64 s[2:3], vcc, s[2:3]
	s_waitcnt vmcnt(7)
	v_mov_b32_e32 v62, v25
	s_waitcnt vmcnt(6)
	v_mov_b32_e32 v63, v29
	s_waitcnt vmcnt(5)
	v_mov_b32_e32 v70, v33
	s_waitcnt vmcnt(4)
	v_mov_b32_e32 v71, v37
	v_mov_b32_e32 v58, v24
	v_mov_b32_e32 v59, v28
	v_mov_b32_e32 v68, v32
	v_mov_b32_e32 v69, v36
	v_pk_mul_f32 v[62:63], v[62:63], v[62:63]
	v_pk_mul_f32 v[70:71], v[70:71], v[70:71]
	v_mov_b32_e32 v64, v26
	v_mov_b32_e32 v65, v30
	v_pk_fma_f32 v[58:59], v[58:59], v[58:59], v[62:63]
	v_pk_fma_f32 v[62:63], v[68:69], v[68:69], v[70:71]
	s_waitcnt vmcnt(3)
	v_mov_b32_e32 v70, v41
	s_waitcnt vmcnt(2)
	v_mov_b32_e32 v71, v45
	v_mov_b32_e32 v68, v40
	v_mov_b32_e32 v69, v44
	s_waitcnt vmcnt(1)
	v_mov_b32_e32 v80, v49
	s_waitcnt vmcnt(0)
	v_mov_b32_e32 v81, v53
	v_pk_fma_f32 v[58:59], v[64:65], v[64:65], v[58:59]
	v_pk_mul_f32 v[64:65], v[70:71], v[70:71]
	v_mov_b32_e32 v66, v27
	v_mov_b32_e32 v67, v31
	v_mov_b32_e32 v76, v42
	v_mov_b32_e32 v77, v46
	v_mov_b32_e32 v78, v48
	v_mov_b32_e32 v79, v52
	v_pk_mul_f32 v[70:71], v[80:81], v[80:81]
	v_pk_fma_f32 v[64:65], v[68:69], v[68:69], v[64:65]
	v_mov_b32_e32 v72, v34
	v_mov_b32_e32 v73, v38
	v_mov_b32_e32 v82, v43
	v_mov_b32_e32 v83, v47
	v_mov_b32_e32 v84, v50
	v_mov_b32_e32 v85, v54
	v_pk_fma_f32 v[58:59], v[66:67], v[66:67], v[58:59]
	v_pk_fma_f32 v[66:67], v[78:79], v[78:79], v[70:71]
	v_pk_fma_f32 v[64:65], v[76:77], v[76:77], v[64:65]
	v_mov_b32_e32 v74, v35
	v_mov_b32_e32 v75, v39
	v_mov_b32_e32 v86, v51
	v_mov_b32_e32 v87, v55
	v_pk_fma_f32 v[62:63], v[72:73], v[72:73], v[62:63]
	v_pk_fma_f32 v[66:67], v[84:85], v[84:85], v[66:67]
	v_pk_fma_f32 v[64:65], v[82:83], v[82:83], v[64:65]
	v_pk_fma_f32 v[62:63], v[74:75], v[74:75], v[62:63]
	v_mov_b32_e32 v69, v58
	v_pk_fma_f32 v[66:67], v[86:87], v[86:87], v[66:67]
	v_mov_b32_e32 v68, v64
	v_mov_b32_e32 v58, v65
	v_mov_b32_e32 v71, v62
	v_mov_b32_e32 v70, v66
	v_pk_add_f32 v[58:59], v[68:69], v[58:59]
	v_mov_b32_e32 v62, v67
	v_pk_add_f32 v[58:59], v[58:59], v[70:71]
	s_nop 0
	v_pk_add_f32 v[58:59], v[58:59], v[62:63]
	ds_swizzle_b32 v63, v59 offset:swizzle(SWAP,16)
	ds_swizzle_b32 v62, v58 offset:swizzle(SWAP,16)
	s_waitcnt lgkmcnt(0)
	v_pk_add_f32 v[58:59], v[58:59], v[62:63]
	ds_swizzle_b32 v63, v59 offset:swizzle(SWAP,8)
	ds_swizzle_b32 v62, v58 offset:swizzle(SWAP,8)
	s_waitcnt lgkmcnt(0)
	v_pk_add_f32 v[58:59], v[58:59], v[62:63]
	ds_swizzle_b32 v63, v59 offset:swizzle(SWAP,4)
	ds_swizzle_b32 v62, v58 offset:swizzle(SWAP,4)
	s_waitcnt lgkmcnt(0)
	v_pk_add_f32 v[58:59], v[58:59], v[62:63]
	ds_swizzle_b32 v63, v59 offset:swizzle(SWAP,2)
	ds_swizzle_b32 v62, v58 offset:swizzle(SWAP,2)
	s_waitcnt lgkmcnt(0)
	v_pk_add_f32 v[58:59], v[58:59], v[62:63]
	ds_swizzle_b32 v63, v59 offset:swizzle(SWAP,1)
	ds_swizzle_b32 v62, v58 offset:swizzle(SWAP,1)
	s_waitcnt lgkmcnt(0)
	v_pk_add_f32 v[58:59], v[58:59], v[62:63]
	ds_bpermute_b32 v63, v21, v59
	ds_bpermute_b32 v62, v23, v58
	s_waitcnt lgkmcnt(0)
	v_pk_add_f32 v[58:59], v[58:59], v[62:63]
	s_nop 0
	v_pk_fma_f32 v[58:59], v[58:59], s[4:5], v[20:21] op_sel_hi:[1,0,0]
	s_nop 0
	v_mul_f32_e32 v21, 0x4b800000, v59
	v_cmp_gt_f32_e64 s[0:1], s6, v59
	v_mul_f32_e32 v23, 0x4b800000, v58
	v_cmp_gt_f32_e32 vcc, s6, v58
	v_cndmask_b32_e64 v21, v59, v21, s[0:1]
	v_rsq_f32_e32 v21, v21
	v_cndmask_b32_e32 v23, v58, v23, vcc
	v_rsq_f32_e32 v23, v23
	v_mul_f32_e32 v58, 0x45800000, v21
	v_cndmask_b32_e64 v58, v21, v58, s[0:1]
	v_mul_f32_e32 v59, 0x45800000, v23
	v_cndmask_b32_e32 v62, v23, v59, vcc
	v_pk_mul_f32 v[24:25], v[24:25], v[58:59] op_sel_hi:[1,0]
	v_pk_mul_f32 v[26:27], v[26:27], v[58:59] op_sel_hi:[1,0]
	v_pk_mul_f32 v[40:41], v[40:41], v[62:63] op_sel_hi:[1,0]
	v_pk_mul_f32 v[42:43], v[42:43], v[62:63] op_sel_hi:[1,0]
	v_pk_mul_f32 v[64:65], v[28:29], v[58:59] op_sel_hi:[1,0]
	v_pk_mul_f32 v[66:67], v[30:31], v[58:59] op_sel_hi:[1,0]
	v_pk_mul_f32 v[44:45], v[44:45], v[62:63] op_sel_hi:[1,0]
	v_pk_mul_f32 v[46:47], v[46:47], v[62:63] op_sel_hi:[1,0]
	v_pk_mul_f32 v[68:69], v[32:33], v[58:59] op_sel_hi:[1,0]
	v_pk_mul_f32 v[70:71], v[34:35], v[58:59] op_sel_hi:[1,0]
	v_pk_mul_f32 v[48:49], v[48:49], v[62:63] op_sel_hi:[1,0]
	v_pk_mul_f32 v[50:51], v[50:51], v[62:63] op_sel_hi:[1,0]
	v_pk_mul_f32 v[72:73], v[36:37], v[58:59] op_sel_hi:[1,0]
	v_pk_mul_f32 v[58:59], v[38:39], v[58:59] op_sel_hi:[1,0]
	v_pk_mul_f32 v[52:53], v[52:53], v[62:63] op_sel_hi:[1,0]
	v_pk_mul_f32 v[54:55], v[54:55], v[62:63] op_sel_hi:[1,0]
	v_pk_mul_f32 v[26:27], v[2:3], v[26:27]
	v_pk_mul_f32 v[24:25], v[0:1], v[24:25]
	v_pk_mul_f32 v[30:31], v[2:3], v[42:43]
	v_pk_mul_f32 v[28:29], v[0:1], v[40:41]
	v_pk_mul_f32 v[34:35], v[6:7], v[66:67]
	v_pk_mul_f32 v[32:33], v[4:5], v[64:65]
	v_pk_mul_f32 v[38:39], v[6:7], v[46:47]
	v_pk_mul_f32 v[36:37], v[4:5], v[44:45]
	v_pk_mul_f32 v[42:43], v[10:11], v[70:71]
	v_pk_mul_f32 v[40:41], v[8:9], v[68:69]
	v_pk_mul_f32 v[46:47], v[10:11], v[50:51]
	v_pk_mul_f32 v[44:45], v[8:9], v[48:49]
	v_pk_mul_f32 v[50:51], v[14:15], v[58:59]
	v_pk_mul_f32 v[48:49], v[12:13], v[72:73]
	v_pk_mul_f32 v[54:55], v[14:15], v[54:55]
	v_pk_mul_f32 v[52:53], v[12:13], v[52:53]
	global_store_dwordx4 v[56:57], v[24:27], off sc0 sc1
	global_store_dwordx4 v[60:61], v[28:31], off sc0 sc1
	global_store_dwordx4 v[56:57], v[32:35], off offset:1024 sc0 sc1
	global_store_dwordx4 v[60:61], v[36:39], off offset:1024 sc0 sc1
	global_store_dwordx4 v[56:57], v[40:43], off offset:2048 sc0 sc1
	global_store_dwordx4 v[60:61], v[44:47], off offset:2048 sc0 sc1
	global_store_dwordx4 v[56:57], v[48:51], off offset:3072 sc0 sc1
	global_store_dwordx4 v[60:61], v[52:55], off offset:3072 sc0 sc1
	s_andn2_b64 exec, exec, s[2:3]
	s_cbranch_execnz .LBB0_1577
